# dual-tile K-loop (two N-tiles share the A tile, 5-slot LDS ring) in the gate/up GEMM; other GEMM K-loops software-pipelined with loads spread between MFMAs
# speedup vs baseline: 1.2649x; 1.2649x over previous
; DEVINL f32x4 mfma16(bf16x8 a, bf16x8 b, f32x4 c) { return __builtin_amdgcn_mfma_f32_16x16x32_bf16(a, b, c, 0, 0, 0); }
; DEVINL void gemm_loop(f32x4 (&acc)[4][4], const u16* __restrict__ A, int lda, const u16* __restrict__ Bt, int ldb,
;                       int m0, int n0, int k0, int nk, char* smem) {
;     ...
;   for (int kt = 0; kt < nk; ++kt) {
;     __syncthreads();
;     char* cur = smem + (kt & 1) * 32768;
;     if (kt + 1 < nk) {
;       char* nxt = smem + ((kt + 1) & 1) * 32768;
; #pragma unroll
;       for (int i = 0; i < 4; ++i) {
;         glds16(ga[i] + (kt + 1) * 64, nxt + i * 4096 + wid * 1024);
;         glds16(gb[i] + (kt + 1) * 64, nxt + 16384 + i * 4096 + wid * 1024);
;       }
;     }
;     bf16x8 af[2][4], bfr[2][4];
; #pragma unroll
;     for (int ks = 0; ks < 2; ++ks)
; #pragma unroll
;       for (int f = 0; f < 4; ++f) {
;         int ra = wr * 64 + f * 16 + fr, rb = wc * 64 + f * 16 + fr;
;         int ch = ks * 4 + fq;
;         af[ks][f] = *(const bf16x8*)(cur + ra * 128 + ((ch ^ ((ra >> 1) & 7)) << 4));
;         bfr[ks][f] = *(const bf16x8*)(cur + 16384 + rb * 128 + ((ch ^ ((rb >> 1) & 7)) << 4));
;       }
;     __builtin_amdgcn_sched_barrier(0);
; #pragma unroll
;     for (int ks = 0; ks < 2; ++ks)
; #pragma unroll
;       for (int mf = 0; mf < 4; ++mf)
; #pragma unroll
;         for (int nf = 0; nf < 4; ++nf) acc[mf][nf] = mfma16(af[ks][mf], bfr[ks][nf], acc[mf][nf]);
.LBB0_93:
	v_readfirstlane_b32 s100, v86
	v_add_u32_e32 v196, v90, v87
	v_add_u32_e32 v197, v90, v88
	v_add_u32_e32 v198, v89, v87
	v_add_u32_e32 v199, v89, v88
	s_mov_b32 s101, s100
	v_lshlrev_b32_e32 v202, 4, v0
	s_waitcnt vmcnt(0)
	s_barrier
	s_add_u32 m0, s100, 0x8000
	v_lshl_add_u64 v[200:201], v[68:69], 0, s[38:39]
	global_load_lds_dwordx4 v[200:201], off
	s_add_u32 m0, s100, 0xc000
	v_lshl_add_u64 v[200:201], v[70:71], 0, s[38:39]
	global_load_lds_dwordx4 v[200:201], off
	s_add_u32 m0, s100, 0x9000
	v_lshl_add_u64 v[200:201], v[72:73], 0, s[38:39]
	global_load_lds_dwordx4 v[200:201], off
	s_add_u32 m0, s100, 0xd000
	v_lshl_add_u64 v[200:201], v[74:75], 0, s[38:39]
	global_load_lds_dwordx4 v[200:201], off
	s_add_u32 m0, s100, 0xa000
	v_lshl_add_u64 v[200:201], v[76:77], 0, s[38:39]
	global_load_lds_dwordx4 v[200:201], off
	s_add_u32 m0, s100, 0xe000
	v_lshl_add_u64 v[200:201], v[78:79], 0, s[38:39]
	global_load_lds_dwordx4 v[200:201], off
	s_add_u32 m0, s100, 0xb000
	v_lshl_add_u64 v[200:201], v[80:81], 0, s[38:39]
	global_load_lds_dwordx4 v[200:201], off
	s_add_u32 m0, s100, 0xf000
	v_lshl_add_u64 v[200:201], v[82:83], 0, s[38:39]
	global_load_lds_dwordx4 v[200:201], off
	ds_read_b128 v[106:109], v196
	ds_read_b128 v[110:113], v196 offset:2048
	ds_read_b128 v[132:135], v197 offset:16384
	ds_read_b128 v[136:139], v197 offset:18432
	ds_read_b128 v[140:143], v196 offset:4096
	ds_read_b128 v[144:147], v196 offset:6144
	ds_read_b128 v[148:151], v197 offset:20480
	ds_read_b128 v[152:155], v197 offset:22528
	ds_read_b128 v[156:159], v198
	ds_read_b128 v[160:163], v198 offset:2048
	ds_read_b128 v[164:167], v199 offset:16384
	ds_read_b128 v[168:171], v199 offset:18432
	ds_read_b128 v[172:175], v198 offset:4096
	ds_read_b128 v[176:179], v198 offset:6144
	ds_read_b128 v[180:183], v199 offset:20480
	ds_read_b128 v[184:187], v199 offset:22528
	s_waitcnt lgkmcnt(8)
	v_mfma_f32_16x16x32_bf16 v[64:67], v[106:109], v[132:135], v[64:67]
	v_mfma_f32_16x16x32_bf16 v[60:63], v[106:109], v[136:139], v[60:63]
	v_mfma_f32_16x16x32_bf16 v[52:55], v[106:109], v[148:151], v[52:55]
	v_mfma_f32_16x16x32_bf16 v[48:51], v[106:109], v[152:155], v[48:51]
	v_mfma_f32_16x16x32_bf16 v[44:47], v[110:113], v[132:135], v[44:47]
	v_mfma_f32_16x16x32_bf16 v[40:43], v[110:113], v[136:139], v[40:43]
	v_mfma_f32_16x16x32_bf16 v[36:39], v[110:113], v[148:151], v[36:39]
	v_mfma_f32_16x16x32_bf16 v[32:35], v[110:113], v[152:155], v[32:35]
	v_mfma_f32_16x16x32_bf16 v[28:31], v[140:143], v[132:135], v[28:31]
	v_mfma_f32_16x16x32_bf16 v[24:27], v[140:143], v[136:139], v[24:27]
	v_mfma_f32_16x16x32_bf16 v[20:23], v[140:143], v[148:151], v[20:23]
	v_mfma_f32_16x16x32_bf16 v[16:19], v[140:143], v[152:155], v[16:19]
	v_mfma_f32_16x16x32_bf16 v[12:15], v[144:147], v[132:135], v[12:15]
	v_mfma_f32_16x16x32_bf16 v[8:11], v[144:147], v[136:139], v[8:11]
	v_mfma_f32_16x16x32_bf16 v[4:7], v[144:147], v[148:151], v[4:7]
	v_mfma_f32_16x16x32_bf16 v[56:59], v[144:147], v[152:155], v[56:59]
	v_xor_b32_e32 v196, 0x8000, v196
	v_xor_b32_e32 v197, 0x8000, v197
	v_xor_b32_e32 v198, 0x8000, v198
	v_xor_b32_e32 v199, 0x8000, v199
	s_waitcnt vmcnt(0) lgkmcnt(0)
	s_barrier
.Lkp_b93_loop:
	s_add_u32 s38, s38, 0x80
	s_addc_u32 s39, s39, 0
	s_cmpk_eq_i32 s38, 0xa80
	s_cbranch_scc1 .Lkp_b93_last
	v_mfma_f32_16x16x32_bf16 v[64:67], v[156:159], v[164:167], v[64:67]
	s_add_u32 m0, s101, 0x0
	v_lshl_add_u64 v[200:201], v[68:69], 0, s[38:39]
	global_load_lds_dwordx4 v[200:201], off
	v_mfma_f32_16x16x32_bf16 v[60:63], v[156:159], v[168:171], v[60:63]
	s_add_u32 m0, s101, 0x4000
	v_lshl_add_u64 v[200:201], v[70:71], 0, s[38:39]
	global_load_lds_dwordx4 v[200:201], off
	v_mfma_f32_16x16x32_bf16 v[52:55], v[156:159], v[180:183], v[52:55]
	s_add_u32 m0, s101, 0x1000
	v_lshl_add_u64 v[200:201], v[72:73], 0, s[38:39]
	global_load_lds_dwordx4 v[200:201], off
	v_mfma_f32_16x16x32_bf16 v[48:51], v[156:159], v[184:187], v[48:51]
	s_add_u32 m0, s101, 0x5000
	v_lshl_add_u64 v[200:201], v[74:75], 0, s[38:39]
	global_load_lds_dwordx4 v[200:201], off
	v_mfma_f32_16x16x32_bf16 v[44:47], v[160:163], v[164:167], v[44:47]
	s_add_u32 m0, s101, 0x2000
	v_lshl_add_u64 v[200:201], v[76:77], 0, s[38:39]
	global_load_lds_dwordx4 v[200:201], off
	ds_read_b128 v[106:109], v196
	v_mfma_f32_16x16x32_bf16 v[40:43], v[160:163], v[168:171], v[40:43]
	s_add_u32 m0, s101, 0x6000
	v_lshl_add_u64 v[200:201], v[78:79], 0, s[38:39]
	global_load_lds_dwordx4 v[200:201], off
	ds_read_b128 v[110:113], v196 offset:2048
	v_mfma_f32_16x16x32_bf16 v[36:39], v[160:163], v[180:183], v[36:39]
	s_add_u32 m0, s101, 0x3000
	v_lshl_add_u64 v[200:201], v[80:81], 0, s[38:39]
	global_load_lds_dwordx4 v[200:201], off
	ds_read_b128 v[132:135], v197 offset:16384
	v_mfma_f32_16x16x32_bf16 v[32:35], v[160:163], v[184:187], v[32:35]
	s_add_u32 m0, s101, 0x7000
	v_lshl_add_u64 v[200:201], v[82:83], 0, s[38:39]
	global_load_lds_dwordx4 v[200:201], off
	ds_read_b128 v[136:139], v197 offset:18432
	v_mfma_f32_16x16x32_bf16 v[28:31], v[172:175], v[164:167], v[28:31]
	ds_read_b128 v[140:143], v196 offset:4096
	v_mfma_f32_16x16x32_bf16 v[24:27], v[172:175], v[168:171], v[24:27]
	ds_read_b128 v[144:147], v196 offset:6144
	v_mfma_f32_16x16x32_bf16 v[20:23], v[172:175], v[180:183], v[20:23]
	ds_read_b128 v[148:151], v197 offset:20480
	v_mfma_f32_16x16x32_bf16 v[16:19], v[172:175], v[184:187], v[16:19]
	ds_read_b128 v[152:155], v197 offset:22528
	v_mfma_f32_16x16x32_bf16 v[12:15], v[176:179], v[164:167], v[12:15]
	v_mfma_f32_16x16x32_bf16 v[8:11], v[176:179], v[168:171], v[8:11]
	v_mfma_f32_16x16x32_bf16 v[4:7], v[176:179], v[180:183], v[4:7]
	v_mfma_f32_16x16x32_bf16 v[56:59], v[176:179], v[184:187], v[56:59]
	s_xor_b32 s101, s101, 0x8000
	s_waitcnt lgkmcnt(0)
; DEVINL int tidx() { int t = threadIdx.x; asm volatile("" : "+v"(t)); return t; }
; DEVINL f32x4 mfma16(bf16x8 a, bf16x8 b, f32x4 c) { return __builtin_amdgcn_mfma_f32_16x16x32_bf16(a, b, c, 0, 0, 0); }
; DEVINL void gemm_loop(f32x4 (&acc)[4][4], const u16* __restrict__ A, int lda, const u16* __restrict__ Bt, int ldb,
;                       int m0, int n0, int k0, int nk, char* smem) {
;     ...
;   for (int kt = 0; kt < nk; ++kt) {
;     __syncthreads();
;     char* cur = smem + (kt & 1) * 32768;
;     if (kt + 1 < nk) {
;       char* nxt = smem + ((kt + 1) & 1) * 32768;
; #pragma unroll
;       for (int i = 0; i < 4; ++i) {
;         glds16(ga[i] + (kt + 1) * 64, nxt + i * 4096 + wid * 1024);
;         glds16(gb[i] + (kt + 1) * 64, nxt + 16384 + i * 4096 + wid * 1024);
;       }
;     }
;     bf16x8 af[2][4], bfr[2][4];
; #pragma unroll
;     for (int ks = 0; ks < 2; ++ks)
; #pragma unroll
;       for (int f = 0; f < 4; ++f) {
;         int ra = wr * 64 + f * 16 + fr, rb = wc * 64 + f * 16 + fr;
;         int ch = ks * 4 + fq;
;         af[ks][f] = *(const bf16x8*)(cur + ra * 128 + ((ch ^ ((ra >> 1) & 7)) << 4));
;         bfr[ks][f] = *(const bf16x8*)(cur + 16384 + rb * 128 + ((ch ^ ((rb >> 1) & 7)) << 4));
;       }
;     __builtin_amdgcn_sched_barrier(0);
; #pragma unroll
;     for (int ks = 0; ks < 2; ++ks)
; #pragma unroll
;       for (int mf = 0; mf < 4; ++mf)
; #pragma unroll
;         for (int nf = 0; nf < 4; ++nf) acc[mf][nf] = mfma16(af[ks][mf], bfr[ks][nf], acc[mf][nf]);
; DEVINL void p7_tile(const Params& p, char* smem, int mt, int ntp) {
;     ...
;   const int lane = tidx() & 63, wid = tidx() >> 6, wr = wid >> 1, wc = wid & 1;
;   u16* fb = (u16*)(p.ws + (khalf ? OFF_FB1 : OFF_FB));
; #pragma unroll
;   for (int mf = 0; mf < 4; ++mf) {
;     const int rb = m0 + wr * 64 + mf * 16 + (lane >> 4) * 4;
; #pragma unroll
;     for (int nf = 0; nf < 4; ++nf) {
;       const int col = n0 + wc * 64 + nf * 16 + (lane & 15);
;       store_pairs(fb, 1024, rb, col, acc[mf][nf][0], acc[mf][nf][1], acc[mf][nf][2], acc[mf][nf][3]);
	v_mfma_f32_16x16x32_bf16 v[64:67], v[106:109], v[132:135], v[64:67]
	ds_read_b128 v[156:159], v198
	v_mfma_f32_16x16x32_bf16 v[60:63], v[106:109], v[136:139], v[60:63]
	ds_read_b128 v[160:163], v198 offset:2048
	v_mfma_f32_16x16x32_bf16 v[52:55], v[106:109], v[148:151], v[52:55]
	ds_read_b128 v[164:167], v199 offset:16384
	v_mfma_f32_16x16x32_bf16 v[48:51], v[106:109], v[152:155], v[48:51]
	ds_read_b128 v[168:171], v199 offset:18432
	v_mfma_f32_16x16x32_bf16 v[44:47], v[110:113], v[132:135], v[44:47]
	ds_read_b128 v[172:175], v198 offset:4096
	v_mfma_f32_16x16x32_bf16 v[40:43], v[110:113], v[136:139], v[40:43]
	ds_read_b128 v[176:179], v198 offset:6144
	v_mfma_f32_16x16x32_bf16 v[36:39], v[110:113], v[148:151], v[36:39]
	ds_read_b128 v[180:183], v199 offset:20480
	v_mfma_f32_16x16x32_bf16 v[32:35], v[110:113], v[152:155], v[32:35]
	ds_read_b128 v[184:187], v199 offset:22528
	v_mfma_f32_16x16x32_bf16 v[28:31], v[140:143], v[132:135], v[28:31]
	v_mfma_f32_16x16x32_bf16 v[24:27], v[140:143], v[136:139], v[24:27]
	v_mfma_f32_16x16x32_bf16 v[20:23], v[140:143], v[148:151], v[20:23]
	v_mfma_f32_16x16x32_bf16 v[16:19], v[140:143], v[152:155], v[16:19]
	v_mfma_f32_16x16x32_bf16 v[12:15], v[144:147], v[132:135], v[12:15]
	v_mfma_f32_16x16x32_bf16 v[8:11], v[144:147], v[136:139], v[8:11]
	v_mfma_f32_16x16x32_bf16 v[4:7], v[144:147], v[148:151], v[4:7]
	v_mfma_f32_16x16x32_bf16 v[56:59], v[144:147], v[152:155], v[56:59]
	v_xor_b32_e32 v196, 0x8000, v196
	v_xor_b32_e32 v197, 0x8000, v197
	v_xor_b32_e32 v198, 0x8000, v198
	v_xor_b32_e32 v199, 0x8000, v199
	s_waitcnt vmcnt(0) lgkmcnt(0)
	s_barrier
	s_branch .Lkp_b93_loop
.Lkp_b93_last:
	v_mfma_f32_16x16x32_bf16 v[64:67], v[156:159], v[164:167], v[64:67]
	v_mfma_f32_16x16x32_bf16 v[60:63], v[156:159], v[168:171], v[60:63]
	v_mfma_f32_16x16x32_bf16 v[52:55], v[156:159], v[180:183], v[52:55]
	v_mfma_f32_16x16x32_bf16 v[48:51], v[156:159], v[184:187], v[48:51]
	v_mfma_f32_16x16x32_bf16 v[44:47], v[160:163], v[164:167], v[44:47]
	v_mfma_f32_16x16x32_bf16 v[40:43], v[160:163], v[168:171], v[40:43]
	v_mfma_f32_16x16x32_bf16 v[36:39], v[160:163], v[180:183], v[36:39]
	v_mfma_f32_16x16x32_bf16 v[32:35], v[160:163], v[184:187], v[32:35]
	v_mfma_f32_16x16x32_bf16 v[28:31], v[172:175], v[164:167], v[28:31]
	v_mfma_f32_16x16x32_bf16 v[24:27], v[172:175], v[168:171], v[24:27]
	v_mfma_f32_16x16x32_bf16 v[20:23], v[172:175], v[180:183], v[20:23]
	v_mfma_f32_16x16x32_bf16 v[16:19], v[172:175], v[184:187], v[16:19]
	v_mfma_f32_16x16x32_bf16 v[12:15], v[176:179], v[164:167], v[12:15]
	v_mfma_f32_16x16x32_bf16 v[8:11], v[176:179], v[168:171], v[8:11]
	v_mfma_f32_16x16x32_bf16 v[4:7], v[176:179], v[180:183], v[4:7]
	v_mfma_f32_16x16x32_bf16 v[56:59], v[176:179], v[184:187], v[56:59]
	s_mov_b32 s40, 0x8000
	v_add_u32_e32 v68, s40, v90
	v_add_u32_e32 v86, v68, v87
	s_waitcnt vmcnt(0)
	s_barrier
	v_add_u32_e32 v90, v68, v88
	ds_read_b128 v[68:71], v86
	ds_read_b128 v[72:75], v86 offset:2048
	ds_read_b128 v[76:79], v90 offset:16384
	ds_read_b128 v[80:83], v90 offset:18432
	ds_read_b128 v[106:109], v86 offset:4096
	ds_read_b128 v[110:113], v86 offset:6144
	ds_read_b128 v[132:135], v90 offset:20480
	ds_read_b128 v[136:139], v90 offset:22528
	v_add_u32_e32 v86, s40, v89
	v_add_u32_e32 v90, v86, v87
	v_add_u32_e32 v91, v86, v88
	ds_read_b128 v[86:89], v90
	ds_read_b128 v[140:143], v90 offset:2048
	ds_read_b128 v[144:147], v91 offset:16384
	ds_read_b128 v[148:151], v91 offset:18432
	ds_read_b128 v[152:155], v90 offset:4096
	ds_read_b128 v[156:159], v90 offset:6144
	ds_read_b128 v[160:163], v91 offset:20480
	ds_read_b128 v[164:167], v91 offset:22528
	s_waitcnt lgkmcnt(12)
	v_mfma_f32_16x16x32_bf16 v[60:63], v[68:71], v[80:83], v[60:63]
	v_cmp_gt_u32_e32 vcc, 8, v85
	v_add_u32_e32 v1, v1, v104
	s_movk_i32 s1, 0x88f
	v_mfma_f32_16x16x32_bf16 v[64:67], v[68:71], v[76:79], v[64:67]
	s_waitcnt lgkmcnt(9)
	v_mfma_f32_16x16x32_bf16 v[52:55], v[68:71], v[132:135], v[52:55]
	s_waitcnt lgkmcnt(8)
	v_mfma_f32_16x16x32_bf16 v[48:51], v[68:71], v[136:139], v[48:51]
	v_mfma_f32_16x16x32_bf16 v[44:47], v[72:75], v[76:79], v[44:47]
	v_mfma_f32_16x16x32_bf16 v[40:43], v[72:75], v[80:83], v[40:43]
	v_mfma_f32_16x16x32_bf16 v[36:39], v[72:75], v[132:135], v[36:39]
	v_mfma_f32_16x16x32_bf16 v[32:35], v[72:75], v[136:139], v[32:35]
	v_mfma_f32_16x16x32_bf16 v[28:31], v[106:109], v[76:79], v[28:31]
	v_mfma_f32_16x16x32_bf16 v[24:27], v[106:109], v[80:83], v[24:27]
	v_mfma_f32_16x16x32_bf16 v[20:23], v[106:109], v[132:135], v[20:23]
	v_mfma_f32_16x16x32_bf16 v[16:19], v[106:109], v[136:139], v[16:19]
	v_mfma_f32_16x16x32_bf16 v[12:15], v[110:113], v[76:79], v[12:15]
	v_mfma_f32_16x16x32_bf16 v[8:11], v[110:113], v[80:83], v[8:11]
	v_mfma_f32_16x16x32_bf16 v[4:7], v[110:113], v[132:135], v[4:7]
	v_mfma_f32_16x16x32_bf16 v[68:71], v[110:113], v[136:139], v[56:59]
	s_waitcnt lgkmcnt(4)
	v_mfma_f32_16x16x32_bf16 v[72:75], v[86:89], v[148:151], v[60:63]
	s_nop 2
	v_mov_b32_e32 v62, v0
	v_mov_b32_e32 v63, v0
	s_waitcnt lgkmcnt(1)
	v_mfma_f32_16x16x32_bf16 v[56:59], v[86:89], v[160:163], v[52:55]
	v_cndmask_b32_e32 v60, v120, v121, vcc
	v_mov_b32_e32 v61, v2
	v_lshl_add_u64 v[60:61], s[50:51], 0, v[60:61]
	s_waitcnt lgkmcnt(0)
; DEVINL float lane_xor1(float v) { return dpp_f<0xB1>(v); }
; DEVINL void store_pairs(u16* base, size_t ld, int rb, int col, float v0, float v1, float v2, float v3) {
;   const float p0 = lane_xor1(v0), p1 = lane_xor1(v1), p2 = lane_xor1(v2), p3 = lane_xor1(v3);
;   const bool odd = (col & 1) != 0;
;   const int r0 = odd ? rb + 2 : rb, c0 = col & ~1;
;   const unsigned w0 = odd ? pack2(p2, v2) : pack2(v0, p0);
;   const unsigned w1 = odd ? pack2(p3, v3) : pack2(v1, p1);
;   *(unsigned*)(base + (size_t)r0 * ld + c0) = w0;
;   *(unsigned*)(base + (size_t)(r0 + 1) * ld + c0) = w1;
; DEVINL void p7_tile(const Params& p, char* smem, int mt, int ntp) {
;     ...
;   for (int mf = 0; mf < 4; ++mf) {
;     const int rb = m0 + wr * 64 + mf * 16 + (lane >> 4) * 4;
; #pragma unroll
;     for (int nf = 0; nf < 4; ++nf) {
;       const int col = n0 + wc * 64 + nf * 16 + (lane & 15);
;       store_pairs(fb, 1024, rb, col, acc[mf][nf][0], acc[mf][nf][1], acc[mf][nf][2], acc[mf][nf][3]);
;     }
	v_mfma_f32_16x16x32_bf16 v[52:55], v[86:89], v[164:167], v[48:51]
	v_mfma_f32_16x16x32_bf16 v[48:51], v[140:143], v[144:147], v[44:47]
	v_mfma_f32_16x16x32_bf16 v[44:47], v[140:143], v[148:151], v[40:43]
	v_mfma_f32_16x16x32_bf16 v[40:43], v[140:143], v[160:163], v[36:39]
	v_mfma_f32_16x16x32_bf16 v[36:39], v[140:143], v[164:167], v[32:35]
	v_mfma_f32_16x16x32_bf16 v[32:35], v[152:155], v[144:147], v[28:31]
	v_mfma_f32_16x16x32_bf16 v[28:31], v[152:155], v[148:151], v[24:27]
	v_mfma_f32_16x16x32_bf16 v[24:27], v[152:155], v[160:163], v[20:23]
	v_mfma_f32_16x16x32_bf16 v[20:23], v[152:155], v[164:167], v[16:19]
	v_mfma_f32_16x16x32_bf16 v[16:19], v[156:159], v[144:147], v[12:15]
	v_mfma_f32_16x16x32_bf16 v[12:15], v[156:159], v[148:151], v[8:11]
	v_mfma_f32_16x16x32_bf16 v[8:11], v[156:159], v[160:163], v[4:7]
	v_mfma_f32_16x16x32_bf16 v[4:7], v[156:159], v[164:167], v[68:71]
	s_nop 2
	v_and_b32_e32 v68, 64, v63
	v_ashrrev_i32_e32 v63, 1, v63
	v_mfma_f32_16x16x32_bf16 v[64:67], v[86:89], v[144:147], v[64:67]
	v_and_b32_e32 v63, 0xffffffc0, v63
	v_lshrrev_b32_e32 v69, 2, v62
	v_and_b32_e32 v70, 14, v62
	v_and_b32_e32 v62, 1, v62
	v_add_u32_e32 v63, v63, v84
	v_and_b32_e32 v69, 12, v69
	v_cmp_eq_u32_e32 vcc, 0, v62
	v_lshlrev_b32_e32 v62, 1, v62
	v_or3_b32 v62, v63, v69, v62
	v_ashrrev_i32_e32 v63, 31, v62
	v_or3_b32 v3, v70, v68, v3
	v_lshlrev_b64 v[68:69], 11, v[62:63]
	v_mov_b32_dpp v63, v64 quad_perm:[1,0,3,2] row_mask:0xf bank_mask:0xf bound_ctrl:1
	v_mov_b32_dpp v77, v66 quad_perm:[1,0,3,2] row_mask:0xf bank_mask:0xf bound_ctrl:1
	v_cndmask_b32_e32 v63, v66, v63, vcc
	v_cndmask_b32_e32 v64, v77, v64, vcc
	v_or_b32_e32 v70, 1, v62
	v_mov_b32_dpp v76, v65 quad_perm:[1,0,3,2] row_mask:0xf bank_mask:0xf bound_ctrl:1
	v_mov_b32_dpp v78, v67 quad_perm:[1,0,3,2] row_mask:0xf bank_mask:0xf bound_ctrl:1
	v_add_u32_e32 v63, 0x8000, v63
	v_add_u32_e32 v64, 0x8000, v64
	v_ashrrev_i32_e32 v71, 31, v70
	v_perm_b32 v63, v63, v64, s25
	v_cndmask_b32_e32 v64, v67, v76, vcc
	v_cndmask_b32_e32 v65, v78, v65, vcc
	v_lshlrev_b64 v[70:71], 11, v[70:71]
	v_add_u32_e32 v64, 0x8000, v64
	v_add_u32_e32 v65, 0x8000, v65
	v_lshl_add_u64 v[68:69], v[60:61], 0, v[68:69]
	v_lshl_add_u64 v[70:71], v[60:61], 0, v[70:71]
	v_perm_b32 v76, v64, v65, s25
	v_lshlrev_b32_e32 v64, 1, v3
	v_mov_b32_e32 v65, v2
	v_lshl_add_u64 v[66:67], v[68:69], 0, v[64:65]
	v_lshl_add_u64 v[68:69], v[70:71], 0, v[64:65]
	v_mov_b32_dpp v3, v72 quad_perm:[1,0,3,2] row_mask:0xf bank_mask:0xf bound_ctrl:1
	v_mov_b32_dpp v70, v74 quad_perm:[1,0,3,2] row_mask:0xf bank_mask:0xf bound_ctrl:1
	v_cndmask_b32_e32 v3, v74, v3, vcc
	v_cndmask_b32_e32 v70, v70, v72, vcc
	global_store_dword v[66:67], v63, off
	v_mov_b32_dpp v63, v73 quad_perm:[1,0,3,2] row_mask:0xf bank_mask:0xf bound_ctrl:1
	v_mov_b32_dpp v71, v75 quad_perm:[1,0,3,2] row_mask:0xf bank_mask:0xf bound_ctrl:1
	v_add_u32_e32 v3, 0x8000, v3
	v_add_u32_e32 v70, 0x8000, v70
	v_perm_b32 v3, v3, v70, s25
	v_cndmask_b32_e32 v63, v75, v63, vcc
	v_cndmask_b32_e32 v70, v71, v73, vcc
	v_add_u32_e32 v63, 0x8000, v63
	v_add_u32_e32 v70, 0x8000, v70
	global_store_dword v[68:69], v76, off
	v_perm_b32 v63, v63, v70, s25
	global_store_dword v[66:67], v3, off offset:32
	global_store_dword v[68:69], v63, off offset:32
	v_mov_b32_dpp v3, v56 quad_perm:[1,0,3,2] row_mask:0xf bank_mask:0xf bound_ctrl:1
	v_mov_b32_dpp v70, v58 quad_perm:[1,0,3,2] row_mask:0xf bank_mask:0xf bound_ctrl:1
	v_cndmask_b32_e32 v3, v58, v3, vcc
	v_cndmask_b32_e32 v56, v70, v56, vcc
	v_mov_b32_dpp v63, v57 quad_perm:[1,0,3,2] row_mask:0xf bank_mask:0xf bound_ctrl:1
	v_mov_b32_dpp v71, v59 quad_perm:[1,0,3,2] row_mask:0xf bank_mask:0xf bound_ctrl:1
	v_add_u32_e32 v3, 0x8000, v3
	v_add_u32_e32 v56, 0x8000, v56
	v_perm_b32 v3, v3, v56, s25
	v_cndmask_b32_e32 v56, v59, v63, vcc
	v_cndmask_b32_e32 v57, v71, v57, vcc
	v_add_u32_e32 v56, 0x8000, v56
	v_add_u32_e32 v57, 0x8000, v57
	v_perm_b32 v56, v56, v57, s25
	global_store_dword v[66:67], v3, off offset:64
	global_store_dword v[68:69], v56, off offset:64
	v_mov_b32_dpp v3, v52 quad_perm:[1,0,3,2] row_mask:0xf bank_mask:0xf bound_ctrl:1
	v_mov_b32_dpp v57, v54 quad_perm:[1,0,3,2] row_mask:0xf bank_mask:0xf bound_ctrl:1
	v_cndmask_b32_e32 v3, v54, v3, vcc
	v_cndmask_b32_e32 v52, v57, v52, vcc
	v_mov_b32_dpp v56, v53 quad_perm:[1,0,3,2] row_mask:0xf bank_mask:0xf bound_ctrl:1
	v_mov_b32_dpp v58, v55 quad_perm:[1,0,3,2] row_mask:0xf bank_mask:0xf bound_ctrl:1
	v_add_u32_e32 v3, 0x8000, v3
	v_add_u32_e32 v52, 0x8000, v52
	v_perm_b32 v3, v3, v52, s25
	v_cndmask_b32_e32 v52, v55, v56, vcc
	v_cndmask_b32_e32 v53, v58, v53, vcc
	v_add_u32_e32 v52, 0x8000, v52
	v_add_u32_e32 v53, 0x8000, v53
	v_perm_b32 v52, v52, v53, s25
	global_store_dword v[66:67], v3, off offset:96
	global_store_dword v[68:69], v52, off offset:96
	v_mov_b32_dpp v3, v48 quad_perm:[1,0,3,2] row_mask:0xf bank_mask:0xf bound_ctrl:1
	v_mov_b32_dpp v57, v50 quad_perm:[1,0,3,2] row_mask:0xf bank_mask:0xf bound_ctrl:1
	v_or_b32_e32 v52, 16, v62
	v_cndmask_b32_e32 v3, v50, v3, vcc
	v_cndmask_b32_e32 v48, v57, v48, vcc
	v_ashrrev_i32_e32 v53, 31, v52
	v_mov_b32_dpp v56, v49 quad_perm:[1,0,3,2] row_mask:0xf bank_mask:0xf bound_ctrl:1
	v_mov_b32_dpp v58, v51 quad_perm:[1,0,3,2] row_mask:0xf bank_mask:0xf bound_ctrl:1
	v_add_u32_e32 v3, 0x8000, v3
	v_add_u32_e32 v48, 0x8000, v48
	v_lshlrev_b64 v[52:53], 11, v[52:53]
	v_perm_b32 v3, v3, v48, s25
	v_cndmask_b32_e32 v48, v51, v56, vcc
	v_cndmask_b32_e32 v49, v58, v49, vcc
	v_lshl_add_u64 v[52:53], v[60:61], 0, v[52:53]
	v_or_b32_e32 v54, 17, v62
	v_add_u32_e32 v48, 0x8000, v48
	v_add_u32_e32 v49, 0x8000, v49
	v_ashrrev_i32_e32 v55, 31, v54
; DEVINL float lane_xor1(float v) { return dpp_f<0xB1>(v); }
; DEVINL void store_pairs(u16* base, size_t ld, int rb, int col, float v0, float v1, float v2, float v3) {
;   const float p0 = lane_xor1(v0), p1 = lane_xor1(v1), p2 = lane_xor1(v2), p3 = lane_xor1(v3);
;   const bool odd = (col & 1) != 0;
;   const int r0 = odd ? rb + 2 : rb, c0 = col & ~1;
;   const unsigned w0 = odd ? pack2(p2, v2) : pack2(v0, p0);
;   const unsigned w1 = odd ? pack2(p3, v3) : pack2(v1, p1);
;   *(unsigned*)(base + (size_t)r0 * ld + c0) = w0;
;   *(unsigned*)(base + (size_t)(r0 + 1) * ld + c0) = w1;
; DEVINL void p7_tile(const Params& p, char* smem, int mt, int ntp) {
;     ...
;   for (int mf = 0; mf < 4; ++mf) {
;     const int rb = m0 + wr * 64 + mf * 16 + (lane >> 4) * 4;
; #pragma unroll
;     for (int nf = 0; nf < 4; ++nf) {
;       const int col = n0 + wc * 64 + nf * 16 + (lane & 15);
;       store_pairs(fb, 1024, rb, col, acc[mf][nf][0], acc[mf][nf][1], acc[mf][nf][2], acc[mf][nf][3]);
;     }
	v_perm_b32 v56, v48, v49, s25
	v_lshl_add_u64 v[48:49], v[52:53], 0, v[64:65]
	v_lshlrev_b64 v[54:55], 11, v[54:55]
	global_store_dword v[48:49], v3, off
	v_mov_b32_dpp v3, v44 quad_perm:[1,0,3,2] row_mask:0xf bank_mask:0xf bound_ctrl:1
	v_mov_b32_dpp v53, v46 quad_perm:[1,0,3,2] row_mask:0xf bank_mask:0xf bound_ctrl:1
	v_lshl_add_u64 v[54:55], v[60:61], 0, v[54:55]
	v_cndmask_b32_e32 v3, v46, v3, vcc
	v_cndmask_b32_e32 v44, v53, v44, vcc
	v_lshl_add_u64 v[50:51], v[54:55], 0, v[64:65]
	v_mov_b32_dpp v52, v45 quad_perm:[1,0,3,2] row_mask:0xf bank_mask:0xf bound_ctrl:1
	v_mov_b32_dpp v54, v47 quad_perm:[1,0,3,2] row_mask:0xf bank_mask:0xf bound_ctrl:1
	v_add_u32_e32 v3, 0x8000, v3
	v_add_u32_e32 v44, 0x8000, v44
	v_perm_b32 v3, v3, v44, s25
	v_cndmask_b32_e32 v44, v47, v52, vcc
	v_cndmask_b32_e32 v45, v54, v45, vcc
	v_add_u32_e32 v44, 0x8000, v44
	v_add_u32_e32 v45, 0x8000, v45
	global_store_dword v[50:51], v56, off
	v_perm_b32 v44, v44, v45, s25
	global_store_dword v[48:49], v3, off offset:32
	global_store_dword v[50:51], v44, off offset:32
	v_mov_b32_dpp v3, v40 quad_perm:[1,0,3,2] row_mask:0xf bank_mask:0xf bound_ctrl:1
	v_mov_b32_dpp v45, v42 quad_perm:[1,0,3,2] row_mask:0xf bank_mask:0xf bound_ctrl:1
	v_cndmask_b32_e32 v3, v42, v3, vcc
	v_cndmask_b32_e32 v40, v45, v40, vcc
	v_mov_b32_dpp v44, v41 quad_perm:[1,0,3,2] row_mask:0xf bank_mask:0xf bound_ctrl:1
	v_mov_b32_dpp v46, v43 quad_perm:[1,0,3,2] row_mask:0xf bank_mask:0xf bound_ctrl:1
	v_add_u32_e32 v3, 0x8000, v3
	v_add_u32_e32 v40, 0x8000, v40
	v_perm_b32 v3, v3, v40, s25
	v_cndmask_b32_e32 v40, v43, v44, vcc
	v_cndmask_b32_e32 v41, v46, v41, vcc
	v_add_u32_e32 v40, 0x8000, v40
	v_add_u32_e32 v41, 0x8000, v41
	v_perm_b32 v40, v40, v41, s25
	global_store_dword v[48:49], v3, off offset:64
	global_store_dword v[50:51], v40, off offset:64
	v_mov_b32_dpp v3, v36 quad_perm:[1,0,3,2] row_mask:0xf bank_mask:0xf bound_ctrl:1
	v_mov_b32_dpp v41, v38 quad_perm:[1,0,3,2] row_mask:0xf bank_mask:0xf bound_ctrl:1
	v_cndmask_b32_e32 v3, v38, v3, vcc
	v_cndmask_b32_e32 v36, v41, v36, vcc
	v_mov_b32_dpp v40, v37 quad_perm:[1,0,3,2] row_mask:0xf bank_mask:0xf bound_ctrl:1
	v_mov_b32_dpp v42, v39 quad_perm:[1,0,3,2] row_mask:0xf bank_mask:0xf bound_ctrl:1
	v_add_u32_e32 v3, 0x8000, v3
	v_add_u32_e32 v36, 0x8000, v36
	v_perm_b32 v3, v3, v36, s25
	v_cndmask_b32_e32 v36, v39, v40, vcc
	v_cndmask_b32_e32 v37, v42, v37, vcc
	v_add_u32_e32 v36, 0x8000, v36
	v_add_u32_e32 v37, 0x8000, v37
	v_perm_b32 v36, v36, v37, s25
	global_store_dword v[48:49], v3, off offset:96
	global_store_dword v[50:51], v36, off offset:96
	v_mov_b32_dpp v3, v32 quad_perm:[1,0,3,2] row_mask:0xf bank_mask:0xf bound_ctrl:1
	v_mov_b32_dpp v41, v34 quad_perm:[1,0,3,2] row_mask:0xf bank_mask:0xf bound_ctrl:1
	v_or_b32_e32 v36, 32, v62
	v_cndmask_b32_e32 v3, v34, v3, vcc
	v_cndmask_b32_e32 v32, v41, v32, vcc
	v_ashrrev_i32_e32 v37, 31, v36
	v_mov_b32_dpp v40, v33 quad_perm:[1,0,3,2] row_mask:0xf bank_mask:0xf bound_ctrl:1
	v_mov_b32_dpp v42, v35 quad_perm:[1,0,3,2] row_mask:0xf bank_mask:0xf bound_ctrl:1
	v_add_u32_e32 v3, 0x8000, v3
	v_add_u32_e32 v32, 0x8000, v32
	v_lshlrev_b64 v[36:37], 11, v[36:37]
	v_perm_b32 v3, v3, v32, s25
	v_cndmask_b32_e32 v32, v35, v40, vcc
	v_cndmask_b32_e32 v33, v42, v33, vcc
	v_lshl_add_u64 v[36:37], v[60:61], 0, v[36:37]
	v_or_b32_e32 v38, 33, v62
	v_add_u32_e32 v32, 0x8000, v32
	v_add_u32_e32 v33, 0x8000, v33
	v_ashrrev_i32_e32 v39, 31, v38
	v_perm_b32 v40, v32, v33, s25
	v_lshl_add_u64 v[32:33], v[36:37], 0, v[64:65]
	v_lshlrev_b64 v[38:39], 11, v[38:39]
	global_store_dword v[32:33], v3, off
	v_mov_b32_dpp v3, v28 quad_perm:[1,0,3,2] row_mask:0xf bank_mask:0xf bound_ctrl:1
	v_mov_b32_dpp v37, v30 quad_perm:[1,0,3,2] row_mask:0xf bank_mask:0xf bound_ctrl:1
	v_lshl_add_u64 v[38:39], v[60:61], 0, v[38:39]
	v_cndmask_b32_e32 v3, v30, v3, vcc
	v_cndmask_b32_e32 v28, v37, v28, vcc
	v_lshl_add_u64 v[34:35], v[38:39], 0, v[64:65]
	v_mov_b32_dpp v36, v29 quad_perm:[1,0,3,2] row_mask:0xf bank_mask:0xf bound_ctrl:1
	v_mov_b32_dpp v38, v31 quad_perm:[1,0,3,2] row_mask:0xf bank_mask:0xf bound_ctrl:1
	v_add_u32_e32 v3, 0x8000, v3
	v_add_u32_e32 v28, 0x8000, v28
	v_perm_b32 v3, v3, v28, s25
	v_cndmask_b32_e32 v28, v31, v36, vcc
	v_cndmask_b32_e32 v29, v38, v29, vcc
	v_add_u32_e32 v28, 0x8000, v28
	v_add_u32_e32 v29, 0x8000, v29
	global_store_dword v[34:35], v40, off
	v_perm_b32 v28, v28, v29, s25
	global_store_dword v[32:33], v3, off offset:32
	global_store_dword v[34:35], v28, off offset:32
	v_mov_b32_dpp v3, v24 quad_perm:[1,0,3,2] row_mask:0xf bank_mask:0xf bound_ctrl:1
	v_mov_b32_dpp v29, v26 quad_perm:[1,0,3,2] row_mask:0xf bank_mask:0xf bound_ctrl:1
	v_cndmask_b32_e32 v3, v26, v3, vcc
	v_cndmask_b32_e32 v24, v29, v24, vcc
	v_mov_b32_dpp v28, v25 quad_perm:[1,0,3,2] row_mask:0xf bank_mask:0xf bound_ctrl:1
; DEVINL float lane_xor1(float v) { return dpp_f<0xB1>(v); }
; DEVINL void store_pairs(u16* base, size_t ld, int rb, int col, float v0, float v1, float v2, float v3) {
;   const float p0 = lane_xor1(v0), p1 = lane_xor1(v1), p2 = lane_xor1(v2), p3 = lane_xor1(v3);
;   const bool odd = (col & 1) != 0;
;   const int r0 = odd ? rb + 2 : rb, c0 = col & ~1;
;   const unsigned w0 = odd ? pack2(p2, v2) : pack2(v0, p0);
;   const unsigned w1 = odd ? pack2(p3, v3) : pack2(v1, p1);
;   *(unsigned*)(base + (size_t)r0 * ld + c0) = w0;
;   *(unsigned*)(base + (size_t)(r0 + 1) * ld + c0) = w1;
; DEVINL void p7_tile(const Params& p, char* smem, int mt, int ntp) {
;     ...
;   for (int mf = 0; mf < 4; ++mf) {
;     const int rb = m0 + wr * 64 + mf * 16 + (lane >> 4) * 4;
; #pragma unroll
;     for (int nf = 0; nf < 4; ++nf) {
;       const int col = n0 + wc * 64 + nf * 16 + (lane & 15);
;       store_pairs(fb, 1024, rb, col, acc[mf][nf][0], acc[mf][nf][1], acc[mf][nf][2], acc[mf][nf][3]);
;     }
;   }
; template <class F>
; DEVINL void gemm_phase(int NT, F&& f) {
;     ...
;   for (int u = u0 + j; u < u1; u += nbx) {
	v_mov_b32_dpp v30, v27 quad_perm:[1,0,3,2] row_mask:0xf bank_mask:0xf bound_ctrl:1
	v_add_u32_e32 v3, 0x8000, v3
	v_add_u32_e32 v24, 0x8000, v24
	v_perm_b32 v3, v3, v24, s25
	v_cndmask_b32_e32 v24, v27, v28, vcc
	v_cndmask_b32_e32 v25, v30, v25, vcc
	v_add_u32_e32 v24, 0x8000, v24
	v_add_u32_e32 v25, 0x8000, v25
	v_perm_b32 v24, v24, v25, s25
	global_store_dword v[32:33], v3, off offset:64
	global_store_dword v[34:35], v24, off offset:64
	v_mov_b32_dpp v3, v20 quad_perm:[1,0,3,2] row_mask:0xf bank_mask:0xf bound_ctrl:1
	v_mov_b32_dpp v25, v22 quad_perm:[1,0,3,2] row_mask:0xf bank_mask:0xf bound_ctrl:1
	v_cndmask_b32_e32 v3, v22, v3, vcc
	v_cndmask_b32_e32 v20, v25, v20, vcc
	v_mov_b32_dpp v24, v21 quad_perm:[1,0,3,2] row_mask:0xf bank_mask:0xf bound_ctrl:1
	v_mov_b32_dpp v26, v23 quad_perm:[1,0,3,2] row_mask:0xf bank_mask:0xf bound_ctrl:1
	v_add_u32_e32 v3, 0x8000, v3
	v_add_u32_e32 v20, 0x8000, v20
	v_perm_b32 v3, v3, v20, s25
	v_cndmask_b32_e32 v20, v23, v24, vcc
	v_cndmask_b32_e32 v21, v26, v21, vcc
	v_add_u32_e32 v20, 0x8000, v20
	v_add_u32_e32 v21, 0x8000, v21
	v_perm_b32 v20, v20, v21, s25
	global_store_dword v[32:33], v3, off offset:96
	global_store_dword v[34:35], v20, off offset:96
	v_mov_b32_dpp v3, v16 quad_perm:[1,0,3,2] row_mask:0xf bank_mask:0xf bound_ctrl:1
	v_mov_b32_dpp v25, v18 quad_perm:[1,0,3,2] row_mask:0xf bank_mask:0xf bound_ctrl:1
	v_or_b32_e32 v20, 48, v62
	v_cndmask_b32_e32 v3, v18, v3, vcc
	v_cndmask_b32_e32 v16, v25, v16, vcc
	v_ashrrev_i32_e32 v21, 31, v20
	v_mov_b32_dpp v24, v17 quad_perm:[1,0,3,2] row_mask:0xf bank_mask:0xf bound_ctrl:1
	v_mov_b32_dpp v26, v19 quad_perm:[1,0,3,2] row_mask:0xf bank_mask:0xf bound_ctrl:1
	v_add_u32_e32 v3, 0x8000, v3
	v_add_u32_e32 v16, 0x8000, v16
	v_lshlrev_b64 v[20:21], 11, v[20:21]
	v_perm_b32 v3, v3, v16, s25
	v_cndmask_b32_e32 v16, v19, v24, vcc
	v_cndmask_b32_e32 v17, v26, v17, vcc
	v_lshl_add_u64 v[20:21], v[60:61], 0, v[20:21]
	v_or_b32_e32 v22, 49, v62
	v_add_u32_e32 v16, 0x8000, v16
	v_add_u32_e32 v17, 0x8000, v17
	v_ashrrev_i32_e32 v23, 31, v22
	v_perm_b32 v24, v16, v17, s25
	v_lshl_add_u64 v[16:17], v[20:21], 0, v[64:65]
	v_lshlrev_b64 v[22:23], 11, v[22:23]
	global_store_dword v[16:17], v3, off
	v_mov_b32_dpp v3, v12 quad_perm:[1,0,3,2] row_mask:0xf bank_mask:0xf bound_ctrl:1
	v_mov_b32_dpp v21, v14 quad_perm:[1,0,3,2] row_mask:0xf bank_mask:0xf bound_ctrl:1
	v_lshl_add_u64 v[22:23], v[60:61], 0, v[22:23]
	v_cndmask_b32_e32 v3, v14, v3, vcc
	v_cndmask_b32_e32 v12, v21, v12, vcc
	v_lshl_add_u64 v[18:19], v[22:23], 0, v[64:65]
	v_mov_b32_dpp v20, v13 quad_perm:[1,0,3,2] row_mask:0xf bank_mask:0xf bound_ctrl:1
	v_mov_b32_dpp v22, v15 quad_perm:[1,0,3,2] row_mask:0xf bank_mask:0xf bound_ctrl:1
	v_add_u32_e32 v3, 0x8000, v3
	v_add_u32_e32 v12, 0x8000, v12
	v_perm_b32 v3, v3, v12, s25
	v_cndmask_b32_e32 v12, v15, v20, vcc
	v_cndmask_b32_e32 v13, v22, v13, vcc
	v_add_u32_e32 v12, 0x8000, v12
	v_add_u32_e32 v13, 0x8000, v13
	global_store_dword v[18:19], v24, off
	v_perm_b32 v12, v12, v13, s25
	global_store_dword v[16:17], v3, off offset:32
	global_store_dword v[18:19], v12, off offset:32
	v_mov_b32_dpp v3, v8 quad_perm:[1,0,3,2] row_mask:0xf bank_mask:0xf bound_ctrl:1
	v_mov_b32_dpp v13, v10 quad_perm:[1,0,3,2] row_mask:0xf bank_mask:0xf bound_ctrl:1
	v_cndmask_b32_e32 v3, v10, v3, vcc
	v_cndmask_b32_e32 v8, v13, v8, vcc
	v_mov_b32_dpp v12, v9 quad_perm:[1,0,3,2] row_mask:0xf bank_mask:0xf bound_ctrl:1
	v_mov_b32_dpp v14, v11 quad_perm:[1,0,3,2] row_mask:0xf bank_mask:0xf bound_ctrl:1
	v_add_u32_e32 v3, 0x8000, v3
	v_add_u32_e32 v8, 0x8000, v8
	v_perm_b32 v3, v3, v8, s25
	v_cndmask_b32_e32 v8, v11, v12, vcc
	v_cndmask_b32_e32 v9, v14, v9, vcc
	v_add_u32_e32 v8, 0x8000, v8
	v_add_u32_e32 v9, 0x8000, v9
	v_perm_b32 v8, v8, v9, s25
	global_store_dword v[16:17], v3, off offset:64
	global_store_dword v[18:19], v8, off offset:64
	v_mov_b32_dpp v3, v4 quad_perm:[1,0,3,2] row_mask:0xf bank_mask:0xf bound_ctrl:1
	v_mov_b32_dpp v9, v6 quad_perm:[1,0,3,2] row_mask:0xf bank_mask:0xf bound_ctrl:1
	v_cndmask_b32_e32 v3, v6, v3, vcc
	v_cndmask_b32_e32 v4, v9, v4, vcc
	v_mov_b32_dpp v8, v5 quad_perm:[1,0,3,2] row_mask:0xf bank_mask:0xf bound_ctrl:1
	v_mov_b32_dpp v10, v7 quad_perm:[1,0,3,2] row_mask:0xf bank_mask:0xf bound_ctrl:1
	v_add_u32_e32 v3, 0x8000, v3
	v_add_u32_e32 v4, 0x8000, v4
	v_perm_b32 v3, v3, v4, s25
	v_cndmask_b32_e32 v4, v7, v8, vcc
	v_cndmask_b32_e32 v5, v10, v5, vcc
	v_cmp_lt_i32_e32 vcc, s1, v1
	v_add_u32_e32 v4, 0x8000, v4
	v_add_u32_e32 v5, 0x8000, v5
	s_or_b64 s[36:37], vcc, s[36:37]
	v_perm_b32 v4, v4, v5, s25
	global_store_dword v[16:17], v3, off offset:96
	global_store_dword v[18:19], v4, off offset:96
	s_andn2_b64 exec, exec, s[36:37]
	s_cbranch_execnz .LBB0_92
	s_or_b64 exec, exec, s[36:37]

; DEVINL f32x4 mfma16(bf16x8 a, bf16x8 b, f32x4 c) { return __builtin_amdgcn_mfma_f32_16x16x32_bf16(a, b, c, 0, 0, 0); }
; DEVINL void gemm_loop(f32x4 (&acc)[4][4], const u16* __restrict__ A, int lda, const u16* __restrict__ Bt, int ldb,
;                       int m0, int n0, int k0, int nk, char* smem) {
;     ...
;   for (int kt = 0; kt < nk; ++kt) {
;     __syncthreads();
;     char* cur = smem + (kt & 1) * 32768;
;     if (kt + 1 < nk) {
;       char* nxt = smem + ((kt + 1) & 1) * 32768;
; #pragma unroll
;       for (int i = 0; i < 4; ++i) {
;         glds16(ga[i] + (kt + 1) * 64, nxt + i * 4096 + wid * 1024);
;         glds16(gb[i] + (kt + 1) * 64, nxt + 16384 + i * 4096 + wid * 1024);
;       }
;     }
;     bf16x8 af[2][4], bfr[2][4];
; #pragma unroll
;     for (int ks = 0; ks < 2; ++ks)
; #pragma unroll
;       for (int f = 0; f < 4; ++f) {
;         int ra = wr * 64 + f * 16 + fr, rb = wc * 64 + f * 16 + fr;
;         int ch = ks * 4 + fq;
;         af[ks][f] = *(const bf16x8*)(cur + ra * 128 + ((ch ^ ((ra >> 1) & 7)) << 4));
;         bfr[ks][f] = *(const bf16x8*)(cur + 16384 + rb * 128 + ((ch ^ ((rb >> 1) & 7)) << 4));
;       }
;     __builtin_amdgcn_sched_barrier(0);
; #pragma unroll
;     for (int ks = 0; ks < 2; ++ks)
; #pragma unroll
;       for (int mf = 0; mf < 4; ++mf)
; #pragma unroll
;         for (int nf = 0; nf < 4; ++nf) acc[mf][nf] = mfma16(af[ks][mf], bfr[ks][nf], acc[mf][nf]);
.LBB0_100:
	v_readfirstlane_b32 s100, v87
	v_add_u32_e32 v196, v91, v88
	v_add_u32_e32 v197, v91, v89
	v_add_u32_e32 v198, v90, v88
	v_add_u32_e32 v199, v90, v89
	s_mov_b32 s101, s100
	v_lshlrev_b32_e32 v202, 4, v0
	s_waitcnt vmcnt(0)
	s_barrier
	s_add_u32 m0, s100, 0x8000
	v_lshl_add_u64 v[200:201], v[68:69], 0, s[38:39]
	global_load_lds_dwordx4 v[200:201], off
	s_add_u32 m0, s100, 0xc000
	v_lshl_add_u64 v[200:201], v[70:71], 0, s[38:39]
	global_load_lds_dwordx4 v[200:201], off
	s_add_u32 m0, s100, 0x9000
	v_lshl_add_u64 v[200:201], v[72:73], 0, s[38:39]
	global_load_lds_dwordx4 v[200:201], off
	s_add_u32 m0, s100, 0xd000
	v_lshl_add_u64 v[200:201], v[74:75], 0, s[38:39]
	global_load_lds_dwordx4 v[200:201], off
	s_add_u32 m0, s100, 0xa000
	v_lshl_add_u64 v[200:201], v[76:77], 0, s[38:39]
	global_load_lds_dwordx4 v[200:201], off
	s_add_u32 m0, s100, 0xe000
	v_lshl_add_u64 v[200:201], v[78:79], 0, s[38:39]
	global_load_lds_dwordx4 v[200:201], off
	s_add_u32 m0, s100, 0xb000
	v_lshl_add_u64 v[200:201], v[80:81], 0, s[38:39]
	global_load_lds_dwordx4 v[200:201], off
	s_add_u32 m0, s100, 0xf000
	v_lshl_add_u64 v[200:201], v[82:83], 0, s[38:39]
	global_load_lds_dwordx4 v[200:201], off
	ds_read_b128 v[106:109], v196
	ds_read_b128 v[110:113], v196 offset:2048
	ds_read_b128 v[132:135], v197 offset:16384
	ds_read_b128 v[136:139], v197 offset:18432
	ds_read_b128 v[140:143], v196 offset:4096
	ds_read_b128 v[144:147], v196 offset:6144
	ds_read_b128 v[148:151], v197 offset:20480
	ds_read_b128 v[152:155], v197 offset:22528
	ds_read_b128 v[156:159], v198
	ds_read_b128 v[160:163], v198 offset:2048
	ds_read_b128 v[164:167], v199 offset:16384
	ds_read_b128 v[168:171], v199 offset:18432
	ds_read_b128 v[172:175], v198 offset:4096
	ds_read_b128 v[176:179], v198 offset:6144
	ds_read_b128 v[180:183], v199 offset:20480
	ds_read_b128 v[184:187], v199 offset:22528
	s_waitcnt lgkmcnt(8)
	v_mfma_f32_16x16x32_bf16 v[64:67], v[106:109], v[132:135], v[64:67]
	v_mfma_f32_16x16x32_bf16 v[60:63], v[106:109], v[136:139], v[60:63]
	v_mfma_f32_16x16x32_bf16 v[52:55], v[106:109], v[148:151], v[52:55]
	v_mfma_f32_16x16x32_bf16 v[48:51], v[106:109], v[152:155], v[48:51]
	v_mfma_f32_16x16x32_bf16 v[44:47], v[110:113], v[132:135], v[44:47]
	v_mfma_f32_16x16x32_bf16 v[40:43], v[110:113], v[136:139], v[40:43]
	v_mfma_f32_16x16x32_bf16 v[36:39], v[110:113], v[148:151], v[36:39]
	v_mfma_f32_16x16x32_bf16 v[32:35], v[110:113], v[152:155], v[32:35]
	v_mfma_f32_16x16x32_bf16 v[28:31], v[140:143], v[132:135], v[28:31]
	v_mfma_f32_16x16x32_bf16 v[24:27], v[140:143], v[136:139], v[24:27]
	v_mfma_f32_16x16x32_bf16 v[20:23], v[140:143], v[148:151], v[20:23]
	v_mfma_f32_16x16x32_bf16 v[16:19], v[140:143], v[152:155], v[16:19]
	v_mfma_f32_16x16x32_bf16 v[12:15], v[144:147], v[132:135], v[12:15]
	v_mfma_f32_16x16x32_bf16 v[8:11], v[144:147], v[136:139], v[8:11]
	v_mfma_f32_16x16x32_bf16 v[4:7], v[144:147], v[148:151], v[4:7]
	v_mfma_f32_16x16x32_bf16 v[56:59], v[144:147], v[152:155], v[56:59]
	v_xor_b32_e32 v196, 0x8000, v196
	v_xor_b32_e32 v197, 0x8000, v197
	v_xor_b32_e32 v198, 0x8000, v198
	v_xor_b32_e32 v199, 0x8000, v199
	s_waitcnt vmcnt(0) lgkmcnt(0)
	s_barrier

; DEVINL int tidx() { int t = threadIdx.x; asm volatile("" : "+v"(t)); return t; }
; DEVINL f32x4 mfma16(bf16x8 a, bf16x8 b, f32x4 c) { return __builtin_amdgcn_mfma_f32_16x16x32_bf16(a, b, c, 0, 0, 0); }
; DEVINL void gemm_loop(f32x4 (&acc)[4][4], const u16* __restrict__ A, int lda, const u16* __restrict__ Bt, int ldb,
;                       int m0, int n0, int k0, int nk, char* smem) {
;     ...
;   for (int kt = 0; kt < nk; ++kt) {
;     __syncthreads();
;     char* cur = smem + (kt & 1) * 32768;
;     if (kt + 1 < nk) {
;       char* nxt = smem + ((kt + 1) & 1) * 32768;
; #pragma unroll
;       for (int i = 0; i < 4; ++i) {
;         glds16(ga[i] + (kt + 1) * 64, nxt + i * 4096 + wid * 1024);
;         glds16(gb[i] + (kt + 1) * 64, nxt + 16384 + i * 4096 + wid * 1024);
;       }
;     }
;     bf16x8 af[2][4], bfr[2][4];
; #pragma unroll
;     for (int ks = 0; ks < 2; ++ks)
; #pragma unroll
;       for (int f = 0; f < 4; ++f) {
;         int ra = wr * 64 + f * 16 + fr, rb = wc * 64 + f * 16 + fr;
;         int ch = ks * 4 + fq;
;         af[ks][f] = *(const bf16x8*)(cur + ra * 128 + ((ch ^ ((ra >> 1) & 7)) << 4));
;         bfr[ks][f] = *(const bf16x8*)(cur + 16384 + rb * 128 + ((ch ^ ((rb >> 1) & 7)) << 4));
;       }
;     __builtin_amdgcn_sched_barrier(0);
; #pragma unroll
;     for (int ks = 0; ks < 2; ++ks)
; #pragma unroll
;       for (int mf = 0; mf < 4; ++mf)
; #pragma unroll
;         for (int nf = 0; nf < 4; ++nf) acc[mf][nf] = mfma16(af[ks][mf], bfr[ks][nf], acc[mf][nf]);
; DEVINL void p7_tile(const Params& p, char* smem, int mt, int ntp) {
;     ...
;   const int lane = tidx() & 63, wid = tidx() >> 6, wr = wid >> 1, wc = wid & 1;
;   u16* fb = (u16*)(p.ws + (khalf ? OFF_FB1 : OFF_FB));
; #pragma unroll
;   for (int mf = 0; mf < 4; ++mf) {
;     const int rb = m0 + wr * 64 + mf * 16 + (lane >> 4) * 4;
; #pragma unroll
;     for (int nf = 0; nf < 4; ++nf) {
;       const int col = n0 + wc * 64 + nf * 16 + (lane & 15);
;       store_pairs(fb, 1024, rb, col, acc[mf][nf][0], acc[mf][nf][1], acc[mf][nf][2], acc[mf][nf][3]);
.Lkp_b100_last:
	v_mfma_f32_16x16x32_bf16 v[64:67], v[156:159], v[164:167], v[64:67]
	v_mfma_f32_16x16x32_bf16 v[60:63], v[156:159], v[168:171], v[60:63]
	v_mfma_f32_16x16x32_bf16 v[52:55], v[156:159], v[180:183], v[52:55]
	v_mfma_f32_16x16x32_bf16 v[48:51], v[156:159], v[184:187], v[48:51]
	v_mfma_f32_16x16x32_bf16 v[44:47], v[160:163], v[164:167], v[44:47]
	v_mfma_f32_16x16x32_bf16 v[40:43], v[160:163], v[168:171], v[40:43]
	v_mfma_f32_16x16x32_bf16 v[36:39], v[160:163], v[180:183], v[36:39]
	v_mfma_f32_16x16x32_bf16 v[32:35], v[160:163], v[184:187], v[32:35]
	v_mfma_f32_16x16x32_bf16 v[28:31], v[172:175], v[164:167], v[28:31]
	v_mfma_f32_16x16x32_bf16 v[24:27], v[172:175], v[168:171], v[24:27]
	v_mfma_f32_16x16x32_bf16 v[20:23], v[172:175], v[180:183], v[20:23]
	v_mfma_f32_16x16x32_bf16 v[16:19], v[172:175], v[184:187], v[16:19]
	v_mfma_f32_16x16x32_bf16 v[12:15], v[176:179], v[164:167], v[12:15]
	v_mfma_f32_16x16x32_bf16 v[8:11], v[176:179], v[168:171], v[8:11]
	v_mfma_f32_16x16x32_bf16 v[4:7], v[176:179], v[180:183], v[4:7]
	v_mfma_f32_16x16x32_bf16 v[56:59], v[176:179], v[184:187], v[56:59]
	s_mov_b32 s40, 0x8000
	v_add_u32_e32 v68, s40, v91
	v_add_u32_e32 v87, v68, v88
	s_waitcnt vmcnt(0)
	s_barrier
	v_add_u32_e32 v91, v68, v89
	ds_read_b128 v[68:71], v87
	ds_read_b128 v[72:75], v87 offset:2048
	ds_read_b128 v[76:79], v91 offset:16384
	ds_read_b128 v[80:83], v91 offset:18432
	ds_read_b128 v[106:109], v87 offset:4096
	ds_read_b128 v[110:113], v87 offset:6144
	ds_read_b128 v[132:135], v91 offset:20480
	ds_read_b128 v[136:139], v91 offset:22528
	v_add_u32_e32 v87, s40, v90
	v_add_u32_e32 v102, v87, v88
	v_add_u32_e32 v87, v87, v89
	ds_read_b128 v[88:91], v102
	ds_read_b128 v[140:143], v102 offset:2048
	ds_read_b128 v[144:147], v87 offset:16384
	ds_read_b128 v[148:151], v87 offset:18432
	ds_read_b128 v[152:155], v102 offset:4096
	ds_read_b128 v[156:159], v102 offset:6144
	ds_read_b128 v[160:163], v87 offset:20480
	ds_read_b128 v[164:167], v87 offset:22528
	s_waitcnt lgkmcnt(12)
	v_mfma_f32_16x16x32_bf16 v[60:63], v[68:71], v[80:83], v[60:63]
	v_cmp_gt_u32_e32 vcc, 8, v86
	v_add_u32_e32 v3, v3, v1
	v_mfma_f32_16x16x32_bf16 v[64:67], v[68:71], v[76:79], v[64:67]
	s_waitcnt lgkmcnt(9)
	v_mfma_f32_16x16x32_bf16 v[52:55], v[68:71], v[132:135], v[52:55]
	s_waitcnt lgkmcnt(8)
	v_mfma_f32_16x16x32_bf16 v[48:51], v[68:71], v[136:139], v[48:51]
	v_mfma_f32_16x16x32_bf16 v[44:47], v[72:75], v[76:79], v[44:47]
	v_mfma_f32_16x16x32_bf16 v[40:43], v[72:75], v[80:83], v[40:43]
	v_mfma_f32_16x16x32_bf16 v[36:39], v[72:75], v[132:135], v[36:39]
	v_mfma_f32_16x16x32_bf16 v[32:35], v[72:75], v[136:139], v[32:35]
	v_mfma_f32_16x16x32_bf16 v[28:31], v[106:109], v[76:79], v[28:31]
	v_mfma_f32_16x16x32_bf16 v[24:27], v[106:109], v[80:83], v[24:27]
	v_mfma_f32_16x16x32_bf16 v[20:23], v[106:109], v[132:135], v[20:23]
	v_mfma_f32_16x16x32_bf16 v[16:19], v[106:109], v[136:139], v[16:19]
	v_mfma_f32_16x16x32_bf16 v[12:15], v[110:113], v[76:79], v[12:15]
	v_mfma_f32_16x16x32_bf16 v[8:11], v[110:113], v[80:83], v[8:11]
	v_mfma_f32_16x16x32_bf16 v[4:7], v[110:113], v[132:135], v[4:7]
	v_mfma_f32_16x16x32_bf16 v[68:71], v[110:113], v[136:139], v[56:59]
	s_waitcnt lgkmcnt(4)
	v_mfma_f32_16x16x32_bf16 v[72:75], v[88:91], v[148:151], v[60:63]
	s_nop 2
	v_mov_b32_e32 v62, v0
	v_mov_b32_e32 v63, v0
	s_waitcnt lgkmcnt(1)
	v_mfma_f32_16x16x32_bf16 v[56:59], v[88:91], v[160:163], v[52:55]
	v_cndmask_b32_e32 v60, v120, v121, vcc
	v_mov_b32_e32 v61, v2
	v_lshl_add_u64 v[60:61], s[50:51], 0, v[60:61]
	s_waitcnt lgkmcnt(0)
	v_mfma_f32_16x16x32_bf16 v[52:55], v[88:91], v[164:167], v[48:51]
	v_mfma_f32_16x16x32_bf16 v[48:51], v[140:143], v[144:147], v[44:47]
	v_mfma_f32_16x16x32_bf16 v[44:47], v[140:143], v[148:151], v[40:43]
	v_mfma_f32_16x16x32_bf16 v[40:43], v[140:143], v[160:163], v[36:39]
	v_mfma_f32_16x16x32_bf16 v[36:39], v[140:143], v[164:167], v[32:35]
	v_mfma_f32_16x16x32_bf16 v[32:35], v[152:155], v[144:147], v[28:31]
	v_mfma_f32_16x16x32_bf16 v[28:31], v[152:155], v[148:151], v[24:27]
	v_mfma_f32_16x16x32_bf16 v[24:27], v[152:155], v[160:163], v[20:23]
	v_mfma_f32_16x16x32_bf16 v[20:23], v[152:155], v[164:167], v[16:19]
	v_mfma_f32_16x16x32_bf16 v[16:19], v[156:159], v[144:147], v[12:15]
	v_mfma_f32_16x16x32_bf16 v[12:15], v[156:159], v[148:151], v[8:11]
	v_mfma_f32_16x16x32_bf16 v[8:11], v[156:159], v[160:163], v[4:7]
	v_mfma_f32_16x16x32_bf16 v[4:7], v[156:159], v[164:167], v[68:71]
	s_nop 2
	v_and_b32_e32 v68, 64, v63
	v_ashrrev_i32_e32 v63, 1, v63
	v_mfma_f32_16x16x32_bf16 v[64:67], v[88:91], v[144:147], v[64:67]
	v_and_b32_e32 v63, 0xffffffc0, v63
	v_lshrrev_b32_e32 v69, 2, v62
	v_and_b32_e32 v70, 14, v62
	v_and_b32_e32 v62, 1, v62
	v_add_u32_e32 v63, v63, v85
	v_and_b32_e32 v69, 12, v69
	v_cmp_eq_u32_e32 vcc, 0, v62
	v_lshlrev_b32_e32 v62, 1, v62
	v_or3_b32 v62, v63, v69, v62
	v_ashrrev_i32_e32 v63, 31, v62
	v_or3_b32 v76, v70, v68, v84
	v_lshlrev_b64 v[68:69], 11, v[62:63]
	v_mov_b32_dpp v63, v64 quad_perm:[1,0,3,2] row_mask:0xf bank_mask:0xf bound_ctrl:1
	v_mov_b32_dpp v78, v66 quad_perm:[1,0,3,2] row_mask:0xf bank_mask:0xf bound_ctrl:1
	v_cndmask_b32_e32 v63, v66, v63, vcc
	v_cndmask_b32_e32 v64, v78, v64, vcc
	v_mov_b32_dpp v77, v65 quad_perm:[1,0,3,2] row_mask:0xf bank_mask:0xf bound_ctrl:1
	v_mov_b32_dpp v79, v67 quad_perm:[1,0,3,2] row_mask:0xf bank_mask:0xf bound_ctrl:1
	v_add_u32_e32 v63, 0x8000, v63
	v_add_u32_e32 v64, 0x8000, v64
	v_or_b32_e32 v70, 1, v62
	v_perm_b32 v63, v63, v64, s25
	v_cndmask_b32_e32 v64, v67, v77, vcc
	v_cndmask_b32_e32 v65, v79, v65, vcc
	v_ashrrev_i32_e32 v71, 31, v70
	v_add_u32_e32 v64, 0x8000, v64
	v_add_u32_e32 v65, 0x8000, v65
; DEVINL float lane_xor1(float v) { return dpp_f<0xB1>(v); }
; DEVINL void store_pairs(u16* base, size_t ld, int rb, int col, float v0, float v1, float v2, float v3) {
;   const float p0 = lane_xor1(v0), p1 = lane_xor1(v1), p2 = lane_xor1(v2), p3 = lane_xor1(v3);
;   const bool odd = (col & 1) != 0;
;   const int r0 = odd ? rb + 2 : rb, c0 = col & ~1;
;   const unsigned w0 = odd ? pack2(p2, v2) : pack2(v0, p0);
;   const unsigned w1 = odd ? pack2(p3, v3) : pack2(v1, p1);
;   *(unsigned*)(base + (size_t)r0 * ld + c0) = w0;
;   *(unsigned*)(base + (size_t)(r0 + 1) * ld + c0) = w1;
; DEVINL void p7_tile(const Params& p, char* smem, int mt, int ntp) {
;     ...
;   for (int mf = 0; mf < 4; ++mf) {
;     const int rb = m0 + wr * 64 + mf * 16 + (lane >> 4) * 4;
; #pragma unroll
;     for (int nf = 0; nf < 4; ++nf) {
;       const int col = n0 + wc * 64 + nf * 16 + (lane & 15);
;       store_pairs(fb, 1024, rb, col, acc[mf][nf][0], acc[mf][nf][1], acc[mf][nf][2], acc[mf][nf][3]);
;     }
	v_lshl_add_u64 v[68:69], v[60:61], 0, v[68:69]
	v_lshlrev_b64 v[70:71], 11, v[70:71]
	v_perm_b32 v77, v64, v65, s25
	v_lshlrev_b32_e32 v64, 1, v76
	v_mov_b32_e32 v65, v2
	v_lshl_add_u64 v[70:71], v[60:61], 0, v[70:71]
	v_lshl_add_u64 v[66:67], v[68:69], 0, v[64:65]
	global_store_dword v[66:67], v63, off
	v_lshl_add_u64 v[68:69], v[70:71], 0, v[64:65]
	v_mov_b32_dpp v63, v72 quad_perm:[1,0,3,2] row_mask:0xf bank_mask:0xf bound_ctrl:1
	v_mov_b32_dpp v71, v74 quad_perm:[1,0,3,2] row_mask:0xf bank_mask:0xf bound_ctrl:1
	v_cndmask_b32_e32 v63, v74, v63, vcc
	v_cndmask_b32_e32 v71, v71, v72, vcc
	v_mov_b32_dpp v70, v73 quad_perm:[1,0,3,2] row_mask:0xf bank_mask:0xf bound_ctrl:1
	v_mov_b32_dpp v76, v75 quad_perm:[1,0,3,2] row_mask:0xf bank_mask:0xf bound_ctrl:1
	v_add_u32_e32 v63, 0x8000, v63
	v_add_u32_e32 v71, 0x8000, v71
	v_perm_b32 v63, v63, v71, s25
	v_cndmask_b32_e32 v70, v75, v70, vcc
	v_cndmask_b32_e32 v71, v76, v73, vcc
	v_add_u32_e32 v70, 0x8000, v70
	v_add_u32_e32 v71, 0x8000, v71
	global_store_dword v[68:69], v77, off
	v_perm_b32 v70, v70, v71, s25
	global_store_dword v[66:67], v63, off offset:32
	global_store_dword v[68:69], v70, off offset:32
	v_mov_b32_dpp v63, v56 quad_perm:[1,0,3,2] row_mask:0xf bank_mask:0xf bound_ctrl:1
	v_mov_b32_dpp v71, v58 quad_perm:[1,0,3,2] row_mask:0xf bank_mask:0xf bound_ctrl:1
	v_cndmask_b32_e32 v58, v58, v63, vcc
	v_cndmask_b32_e32 v56, v71, v56, vcc
	v_mov_b32_dpp v70, v57 quad_perm:[1,0,3,2] row_mask:0xf bank_mask:0xf bound_ctrl:1
	v_mov_b32_dpp v72, v59 quad_perm:[1,0,3,2] row_mask:0xf bank_mask:0xf bound_ctrl:1
	v_add_u32_e32 v58, 0x8000, v58
	v_add_u32_e32 v56, 0x8000, v56
	v_perm_b32 v56, v58, v56, s25
	v_cndmask_b32_e32 v58, v59, v70, vcc
	v_cndmask_b32_e32 v57, v72, v57, vcc
	v_add_u32_e32 v58, 0x8000, v58
	v_add_u32_e32 v57, 0x8000, v57
	v_perm_b32 v57, v58, v57, s25
	global_store_dword v[66:67], v56, off offset:64
	global_store_dword v[68:69], v57, off offset:64
	v_mov_b32_dpp v56, v52 quad_perm:[1,0,3,2] row_mask:0xf bank_mask:0xf bound_ctrl:1
	v_mov_b32_dpp v58, v54 quad_perm:[1,0,3,2] row_mask:0xf bank_mask:0xf bound_ctrl:1
	v_cndmask_b32_e32 v54, v54, v56, vcc
	v_cndmask_b32_e32 v52, v58, v52, vcc
	v_mov_b32_dpp v57, v53 quad_perm:[1,0,3,2] row_mask:0xf bank_mask:0xf bound_ctrl:1
	v_mov_b32_dpp v59, v55 quad_perm:[1,0,3,2] row_mask:0xf bank_mask:0xf bound_ctrl:1
	v_add_u32_e32 v54, 0x8000, v54
	v_add_u32_e32 v52, 0x8000, v52
	v_perm_b32 v52, v54, v52, s25
	v_cndmask_b32_e32 v54, v55, v57, vcc
	v_cndmask_b32_e32 v53, v59, v53, vcc
	v_add_u32_e32 v54, 0x8000, v54
	v_add_u32_e32 v53, 0x8000, v53
	v_mov_b32_dpp v56, v48 quad_perm:[1,0,3,2] row_mask:0xf bank_mask:0xf bound_ctrl:1
	v_mov_b32_dpp v58, v50 quad_perm:[1,0,3,2] row_mask:0xf bank_mask:0xf bound_ctrl:1
	v_perm_b32 v53, v54, v53, s25
	global_store_dword v[66:67], v52, off offset:96
	global_store_dword v[68:69], v53, off offset:96
	v_or_b32_e32 v52, 16, v62
	v_cndmask_b32_e32 v50, v50, v56, vcc
	v_cndmask_b32_e32 v48, v58, v48, vcc
	v_ashrrev_i32_e32 v53, 31, v52
	v_or_b32_e32 v54, 17, v62
	v_mov_b32_dpp v57, v49 quad_perm:[1,0,3,2] row_mask:0xf bank_mask:0xf bound_ctrl:1
	v_mov_b32_dpp v59, v51 quad_perm:[1,0,3,2] row_mask:0xf bank_mask:0xf bound_ctrl:1
	v_add_u32_e32 v50, 0x8000, v50
	v_add_u32_e32 v48, 0x8000, v48
	v_lshlrev_b64 v[52:53], 11, v[52:53]
	v_ashrrev_i32_e32 v55, 31, v54
	v_perm_b32 v50, v50, v48, s25
	v_cndmask_b32_e32 v48, v51, v57, vcc
	v_cndmask_b32_e32 v49, v59, v49, vcc
	v_lshl_add_u64 v[52:53], v[60:61], 0, v[52:53]
	v_lshlrev_b64 v[54:55], 11, v[54:55]
	v_add_u32_e32 v48, 0x8000, v48
	v_add_u32_e32 v49, 0x8000, v49
	v_lshl_add_u64 v[54:55], v[60:61], 0, v[54:55]
	v_perm_b32 v56, v48, v49, s25
	v_lshl_add_u64 v[48:49], v[52:53], 0, v[64:65]
	global_store_dword v[48:49], v50, off
	v_lshl_add_u64 v[50:51], v[54:55], 0, v[64:65]
	v_mov_b32_dpp v52, v44 quad_perm:[1,0,3,2] row_mask:0xf bank_mask:0xf bound_ctrl:1
	v_mov_b32_dpp v54, v46 quad_perm:[1,0,3,2] row_mask:0xf bank_mask:0xf bound_ctrl:1
	v_cndmask_b32_e32 v46, v46, v52, vcc
	v_cndmask_b32_e32 v44, v54, v44, vcc
	v_mov_b32_dpp v53, v45 quad_perm:[1,0,3,2] row_mask:0xf bank_mask:0xf bound_ctrl:1
	v_mov_b32_dpp v55, v47 quad_perm:[1,0,3,2] row_mask:0xf bank_mask:0xf bound_ctrl:1
	v_add_u32_e32 v46, 0x8000, v46
	v_add_u32_e32 v44, 0x8000, v44
	v_perm_b32 v44, v46, v44, s25
	v_cndmask_b32_e32 v46, v47, v53, vcc
	v_cndmask_b32_e32 v45, v55, v45, vcc
	v_add_u32_e32 v46, 0x8000, v46
	v_add_u32_e32 v45, 0x8000, v45
	global_store_dword v[50:51], v56, off
	v_perm_b32 v45, v46, v45, s25
	global_store_dword v[48:49], v44, off offset:32
	global_store_dword v[50:51], v45, off offset:32
	v_mov_b32_dpp v44, v40 quad_perm:[1,0,3,2] row_mask:0xf bank_mask:0xf bound_ctrl:1
	v_mov_b32_dpp v46, v42 quad_perm:[1,0,3,2] row_mask:0xf bank_mask:0xf bound_ctrl:1
	v_cndmask_b32_e32 v42, v42, v44, vcc
	v_cndmask_b32_e32 v40, v46, v40, vcc
	v_mov_b32_dpp v45, v41 quad_perm:[1,0,3,2] row_mask:0xf bank_mask:0xf bound_ctrl:1
	v_mov_b32_dpp v47, v43 quad_perm:[1,0,3,2] row_mask:0xf bank_mask:0xf bound_ctrl:1
	v_add_u32_e32 v42, 0x8000, v42
	v_add_u32_e32 v40, 0x8000, v40
	v_perm_b32 v40, v42, v40, s25
	v_cndmask_b32_e32 v42, v43, v45, vcc
	v_cndmask_b32_e32 v41, v47, v41, vcc
	v_add_u32_e32 v42, 0x8000, v42
	v_add_u32_e32 v41, 0x8000, v41
	v_perm_b32 v41, v42, v41, s25
	global_store_dword v[48:49], v40, off offset:64
	global_store_dword v[50:51], v41, off offset:64
	v_mov_b32_dpp v40, v36 quad_perm:[1,0,3,2] row_mask:0xf bank_mask:0xf bound_ctrl:1
	v_mov_b32_dpp v42, v38 quad_perm:[1,0,3,2] row_mask:0xf bank_mask:0xf bound_ctrl:1
	v_cndmask_b32_e32 v38, v38, v40, vcc
; DEVINL float lane_xor1(float v) { return dpp_f<0xB1>(v); }
; DEVINL void store_pairs(u16* base, size_t ld, int rb, int col, float v0, float v1, float v2, float v3) {
;   const float p0 = lane_xor1(v0), p1 = lane_xor1(v1), p2 = lane_xor1(v2), p3 = lane_xor1(v3);
;   const bool odd = (col & 1) != 0;
;   const int r0 = odd ? rb + 2 : rb, c0 = col & ~1;
;   const unsigned w0 = odd ? pack2(p2, v2) : pack2(v0, p0);
;   const unsigned w1 = odd ? pack2(p3, v3) : pack2(v1, p1);
;   *(unsigned*)(base + (size_t)r0 * ld + c0) = w0;
;   *(unsigned*)(base + (size_t)(r0 + 1) * ld + c0) = w1;
; DEVINL void p7_tile(const Params& p, char* smem, int mt, int ntp) {
;     ...
;   for (int mf = 0; mf < 4; ++mf) {
;     const int rb = m0 + wr * 64 + mf * 16 + (lane >> 4) * 4;
; #pragma unroll
;     for (int nf = 0; nf < 4; ++nf) {
;       const int col = n0 + wc * 64 + nf * 16 + (lane & 15);
;       store_pairs(fb, 1024, rb, col, acc[mf][nf][0], acc[mf][nf][1], acc[mf][nf][2], acc[mf][nf][3]);
;     }
	v_cndmask_b32_e32 v36, v42, v36, vcc
	v_mov_b32_dpp v41, v37 quad_perm:[1,0,3,2] row_mask:0xf bank_mask:0xf bound_ctrl:1
	v_mov_b32_dpp v43, v39 quad_perm:[1,0,3,2] row_mask:0xf bank_mask:0xf bound_ctrl:1
	v_add_u32_e32 v38, 0x8000, v38
	v_add_u32_e32 v36, 0x8000, v36
	v_perm_b32 v36, v38, v36, s25
	v_cndmask_b32_e32 v38, v39, v41, vcc
	v_cndmask_b32_e32 v37, v43, v37, vcc
	v_add_u32_e32 v38, 0x8000, v38
	v_add_u32_e32 v37, 0x8000, v37
	v_mov_b32_dpp v40, v32 quad_perm:[1,0,3,2] row_mask:0xf bank_mask:0xf bound_ctrl:1
	v_mov_b32_dpp v42, v34 quad_perm:[1,0,3,2] row_mask:0xf bank_mask:0xf bound_ctrl:1
	v_perm_b32 v37, v38, v37, s25
	global_store_dword v[48:49], v36, off offset:96
	global_store_dword v[50:51], v37, off offset:96
	v_or_b32_e32 v36, 32, v62
	v_cndmask_b32_e32 v34, v34, v40, vcc
	v_cndmask_b32_e32 v32, v42, v32, vcc
	v_ashrrev_i32_e32 v37, 31, v36
	v_or_b32_e32 v38, 33, v62
	v_mov_b32_dpp v41, v33 quad_perm:[1,0,3,2] row_mask:0xf bank_mask:0xf bound_ctrl:1
	v_mov_b32_dpp v43, v35 quad_perm:[1,0,3,2] row_mask:0xf bank_mask:0xf bound_ctrl:1
	v_add_u32_e32 v34, 0x8000, v34
	v_add_u32_e32 v32, 0x8000, v32
	v_lshlrev_b64 v[36:37], 11, v[36:37]
	v_ashrrev_i32_e32 v39, 31, v38
	v_perm_b32 v34, v34, v32, s25
	v_cndmask_b32_e32 v32, v35, v41, vcc
	v_cndmask_b32_e32 v33, v43, v33, vcc
	v_lshl_add_u64 v[36:37], v[60:61], 0, v[36:37]
	v_lshlrev_b64 v[38:39], 11, v[38:39]
	v_add_u32_e32 v32, 0x8000, v32
	v_add_u32_e32 v33, 0x8000, v33
	v_lshl_add_u64 v[38:39], v[60:61], 0, v[38:39]
	v_perm_b32 v40, v32, v33, s25
	v_lshl_add_u64 v[32:33], v[36:37], 0, v[64:65]
	global_store_dword v[32:33], v34, off
	v_lshl_add_u64 v[34:35], v[38:39], 0, v[64:65]
	v_mov_b32_dpp v36, v28 quad_perm:[1,0,3,2] row_mask:0xf bank_mask:0xf bound_ctrl:1
	v_mov_b32_dpp v38, v30 quad_perm:[1,0,3,2] row_mask:0xf bank_mask:0xf bound_ctrl:1
	v_cndmask_b32_e32 v30, v30, v36, vcc
	v_cndmask_b32_e32 v28, v38, v28, vcc
	v_mov_b32_dpp v37, v29 quad_perm:[1,0,3,2] row_mask:0xf bank_mask:0xf bound_ctrl:1
	v_mov_b32_dpp v39, v31 quad_perm:[1,0,3,2] row_mask:0xf bank_mask:0xf bound_ctrl:1
	v_add_u32_e32 v30, 0x8000, v30
	v_add_u32_e32 v28, 0x8000, v28
	v_perm_b32 v28, v30, v28, s25
	v_cndmask_b32_e32 v30, v31, v37, vcc
	v_cndmask_b32_e32 v29, v39, v29, vcc
	v_add_u32_e32 v30, 0x8000, v30
	v_add_u32_e32 v29, 0x8000, v29
	global_store_dword v[34:35], v40, off
	v_perm_b32 v29, v30, v29, s25
	global_store_dword v[32:33], v28, off offset:32
	global_store_dword v[34:35], v29, off offset:32
	v_mov_b32_dpp v28, v24 quad_perm:[1,0,3,2] row_mask:0xf bank_mask:0xf bound_ctrl:1
	v_mov_b32_dpp v30, v26 quad_perm:[1,0,3,2] row_mask:0xf bank_mask:0xf bound_ctrl:1
	v_cndmask_b32_e32 v26, v26, v28, vcc
	v_cndmask_b32_e32 v24, v30, v24, vcc
	v_mov_b32_dpp v29, v25 quad_perm:[1,0,3,2] row_mask:0xf bank_mask:0xf bound_ctrl:1
	v_mov_b32_dpp v31, v27 quad_perm:[1,0,3,2] row_mask:0xf bank_mask:0xf bound_ctrl:1
	v_add_u32_e32 v26, 0x8000, v26
	v_add_u32_e32 v24, 0x8000, v24
	v_perm_b32 v24, v26, v24, s25
	v_cndmask_b32_e32 v26, v27, v29, vcc
	v_cndmask_b32_e32 v25, v31, v25, vcc
	v_add_u32_e32 v26, 0x8000, v26
	v_add_u32_e32 v25, 0x8000, v25
	v_perm_b32 v25, v26, v25, s25
	global_store_dword v[32:33], v24, off offset:64
	global_store_dword v[34:35], v25, off offset:64
	v_mov_b32_dpp v24, v20 quad_perm:[1,0,3,2] row_mask:0xf bank_mask:0xf bound_ctrl:1
	v_mov_b32_dpp v26, v22 quad_perm:[1,0,3,2] row_mask:0xf bank_mask:0xf bound_ctrl:1
	v_cndmask_b32_e32 v22, v22, v24, vcc
	v_cndmask_b32_e32 v20, v26, v20, vcc
	v_mov_b32_dpp v25, v21 quad_perm:[1,0,3,2] row_mask:0xf bank_mask:0xf bound_ctrl:1
	v_mov_b32_dpp v27, v23 quad_perm:[1,0,3,2] row_mask:0xf bank_mask:0xf bound_ctrl:1
	v_add_u32_e32 v22, 0x8000, v22
	v_add_u32_e32 v20, 0x8000, v20
	v_perm_b32 v20, v22, v20, s25
	v_cndmask_b32_e32 v22, v23, v25, vcc
; DEVINL float lane_xor1(float v) { return dpp_f<0xB1>(v); }
; DEVINL void store_pairs(u16* base, size_t ld, int rb, int col, float v0, float v1, float v2, float v3) {
;   const float p0 = lane_xor1(v0), p1 = lane_xor1(v1), p2 = lane_xor1(v2), p3 = lane_xor1(v3);
;   const bool odd = (col & 1) != 0;
;   const int r0 = odd ? rb + 2 : rb, c0 = col & ~1;
;   const unsigned w0 = odd ? pack2(p2, v2) : pack2(v0, p0);
;   const unsigned w1 = odd ? pack2(p3, v3) : pack2(v1, p1);
;   *(unsigned*)(base + (size_t)r0 * ld + c0) = w0;
;   *(unsigned*)(base + (size_t)(r0 + 1) * ld + c0) = w1;
; DEVINL void p7_tile(const Params& p, char* smem, int mt, int ntp) {
;     ...
;   for (int mf = 0; mf < 4; ++mf) {
;     const int rb = m0 + wr * 64 + mf * 16 + (lane >> 4) * 4;
; #pragma unroll
;     for (int nf = 0; nf < 4; ++nf) {
;       const int col = n0 + wc * 64 + nf * 16 + (lane & 15);
;       store_pairs(fb, 1024, rb, col, acc[mf][nf][0], acc[mf][nf][1], acc[mf][nf][2], acc[mf][nf][3]);
;     }
; template <class F>
; DEVINL void gemm_phase(int NT, F&& f) {
;     ...
;     for (int t = bid; t < U; t += nb) f(t / NT, t % NT);
	v_cndmask_b32_e32 v21, v27, v21, vcc
	v_add_u32_e32 v22, 0x8000, v22
	v_add_u32_e32 v21, 0x8000, v21
	v_mov_b32_dpp v24, v16 quad_perm:[1,0,3,2] row_mask:0xf bank_mask:0xf bound_ctrl:1
	v_mov_b32_dpp v26, v18 quad_perm:[1,0,3,2] row_mask:0xf bank_mask:0xf bound_ctrl:1
	v_perm_b32 v21, v22, v21, s25
	global_store_dword v[32:33], v20, off offset:96
	global_store_dword v[34:35], v21, off offset:96
	v_or_b32_e32 v20, 48, v62
	v_cndmask_b32_e32 v18, v18, v24, vcc
	v_cndmask_b32_e32 v16, v26, v16, vcc
	v_ashrrev_i32_e32 v21, 31, v20
	v_or_b32_e32 v22, 49, v62
	v_mov_b32_dpp v25, v17 quad_perm:[1,0,3,2] row_mask:0xf bank_mask:0xf bound_ctrl:1
	v_mov_b32_dpp v27, v19 quad_perm:[1,0,3,2] row_mask:0xf bank_mask:0xf bound_ctrl:1
	v_add_u32_e32 v18, 0x8000, v18
	v_add_u32_e32 v16, 0x8000, v16
	v_lshlrev_b64 v[20:21], 11, v[20:21]
	v_ashrrev_i32_e32 v23, 31, v22
	v_perm_b32 v18, v18, v16, s25
	v_cndmask_b32_e32 v16, v19, v25, vcc
	v_cndmask_b32_e32 v17, v27, v17, vcc
	v_lshl_add_u64 v[20:21], v[60:61], 0, v[20:21]
	v_lshlrev_b64 v[22:23], 11, v[22:23]
	v_add_u32_e32 v16, 0x8000, v16
	v_add_u32_e32 v17, 0x8000, v17
	v_lshl_add_u64 v[22:23], v[60:61], 0, v[22:23]
	v_perm_b32 v24, v16, v17, s25
	v_lshl_add_u64 v[16:17], v[20:21], 0, v[64:65]
	global_store_dword v[16:17], v18, off
	v_lshl_add_u64 v[18:19], v[22:23], 0, v[64:65]
	v_mov_b32_dpp v20, v12 quad_perm:[1,0,3,2] row_mask:0xf bank_mask:0xf bound_ctrl:1
	v_mov_b32_dpp v22, v14 quad_perm:[1,0,3,2] row_mask:0xf bank_mask:0xf bound_ctrl:1
	v_cndmask_b32_e32 v14, v14, v20, vcc
	v_cndmask_b32_e32 v12, v22, v12, vcc
	v_mov_b32_dpp v21, v13 quad_perm:[1,0,3,2] row_mask:0xf bank_mask:0xf bound_ctrl:1
	v_mov_b32_dpp v23, v15 quad_perm:[1,0,3,2] row_mask:0xf bank_mask:0xf bound_ctrl:1
	v_add_u32_e32 v14, 0x8000, v14
	v_add_u32_e32 v12, 0x8000, v12
	v_perm_b32 v12, v14, v12, s25
	v_cndmask_b32_e32 v14, v15, v21, vcc
	v_cndmask_b32_e32 v13, v23, v13, vcc
	v_add_u32_e32 v14, 0x8000, v14
	v_add_u32_e32 v13, 0x8000, v13
	global_store_dword v[18:19], v24, off
	v_perm_b32 v13, v14, v13, s25
	global_store_dword v[16:17], v12, off offset:32
	global_store_dword v[18:19], v13, off offset:32
	v_mov_b32_dpp v12, v8 quad_perm:[1,0,3,2] row_mask:0xf bank_mask:0xf bound_ctrl:1
	v_mov_b32_dpp v14, v10 quad_perm:[1,0,3,2] row_mask:0xf bank_mask:0xf bound_ctrl:1
	v_cndmask_b32_e32 v10, v10, v12, vcc
	v_cndmask_b32_e32 v8, v14, v8, vcc
	v_mov_b32_dpp v13, v9 quad_perm:[1,0,3,2] row_mask:0xf bank_mask:0xf bound_ctrl:1
	v_mov_b32_dpp v15, v11 quad_perm:[1,0,3,2] row_mask:0xf bank_mask:0xf bound_ctrl:1
	v_add_u32_e32 v10, 0x8000, v10
	v_add_u32_e32 v8, 0x8000, v8
	v_perm_b32 v8, v10, v8, s25
	v_cndmask_b32_e32 v10, v11, v13, vcc
	v_cndmask_b32_e32 v9, v15, v9, vcc
	v_add_u32_e32 v10, 0x8000, v10
	v_add_u32_e32 v9, 0x8000, v9
	v_perm_b32 v9, v10, v9, s25
	global_store_dword v[16:17], v8, off offset:64
	global_store_dword v[18:19], v9, off offset:64
	v_mov_b32_dpp v8, v4 quad_perm:[1,0,3,2] row_mask:0xf bank_mask:0xf bound_ctrl:1
	v_mov_b32_dpp v10, v6 quad_perm:[1,0,3,2] row_mask:0xf bank_mask:0xf bound_ctrl:1
	v_cndmask_b32_e32 v6, v6, v8, vcc
	v_cndmask_b32_e32 v4, v10, v4, vcc
	v_mov_b32_dpp v9, v5 quad_perm:[1,0,3,2] row_mask:0xf bank_mask:0xf bound_ctrl:1
	v_mov_b32_dpp v11, v7 quad_perm:[1,0,3,2] row_mask:0xf bank_mask:0xf bound_ctrl:1
	v_add_u32_e32 v6, 0x8000, v6
	v_add_u32_e32 v4, 0x8000, v4
	v_perm_b32 v4, v6, v4, s25
	v_cndmask_b32_e32 v6, v7, v9, vcc
	v_cndmask_b32_e32 v5, v11, v5, vcc
	v_cmp_le_i32_e32 vcc, s0, v3
	v_add_u32_e32 v6, 0x8000, v6
	v_add_u32_e32 v5, 0x8000, v5
	s_or_b64 s[36:37], vcc, s[36:37]
	v_perm_b32 v5, v6, v5, s25
	global_store_dword v[16:17], v4, off offset:96
	global_store_dword v[18:19], v5, off offset:96
	s_andn2_b64 exec, exec, s[36:37]
	s_cbranch_execnz .LBB0_99
	s_or_b64 exec, exec, s[36:37]

; DEVINL int tidx() { int t = threadIdx.x; asm volatile("" : "+v"(t)); return t; }
; DEVINL void gemm_loop(f32x4 (&acc)[4][4], const u16* __restrict__ A, int lda, const u16* __restrict__ Bt, int ldb,
;                       int m0, int n0, int k0, int nk, char* smem) {
;   const int tid = tidx(), wid = tid >> 6, lane = tid & 63;
;   const int wr = wid >> 1, wc = wid & 1;
;   const u16* ga[4]; const u16* gb[4];
; #pragma unroll
;   for (int i = 0; i < 4; ++i) {
;     int s = i * 256 + tid, r = s >> 3, c = (s & 7) ^ ((r >> 1) & 7);
;     ga[i] = A + (size_t)(m0 + r) * lda + k0 + c * 8;
;     gb[i] = Bt + (size_t)(n0 + r) * ldb + k0 + c * 8;
;   }
;   const int fr = lane & 15, fq = lane >> 4;
;   __syncthreads();
; #pragma unroll
;   for (int i = 0; i < 4; ++i) {
;     glds16(ga[i], smem + i * 4096 + wid * 1024);
;     glds16(gb[i], smem + 16384 + i * 4096 + wid * 1024);
;   }
; template <class F>
; DEVINL void gemm_phase(int NT, F&& f) {
;     ...
;   const int x = bid & 7, j = bid >> 3, nbx = nb >> 3;
;   const int u0 = (int)(((long)U * x) >> 3), u1 = (int)(((long)U * (x + 1)) >> 3);
;   for (int u = u0 + j; u < u1; u += nbx) {
;     const int band = u / (8 * MT), v = u - band * 8 * MT;
;     const int w = min(8, NT - band * 8);
;     f(v / w, band * 8 + v % w);
.LBB0_112:
	s_andn2_saveexec_b64 s[34:35], s[34:35]
	s_cbranch_execz .LBB0_119
	s_and_b32 s1, s0, 7
	s_ashr_i32 s36, s0, 3
	s_mul_i32 s0, s1, 0xbc6
	s_lshr_b32 s1, s0, 3
	s_addk_i32 s0, 0xbc6
	s_lshr_b32 s0, s0, 3
	s_add_i32 s1, s1, s36
	s_lshl_b32 s1, s1, 1
	s_lshl_b32 s0, s0, 1
	s_cmp_ge_i32 s1, s0
	s_cbranch_scc1 .LBB0_119
	v_ashrrev_i32_e32 v1, 2, v104
	s_mov_b32 s101, 0
	s_mov_b64 s[36:37], 0
	v_mov_b32_e32 v3, s1
.LBB0_115:
	s_mov_b32 s1, 0x77975b9
	s_waitcnt lgkmcnt(0)
	v_mul_hi_i32 v4, v3, s1
	v_lshrrev_b32_e32 v5, 31, v4
	v_ashrrev_i32_e32 v4, 5, v4
	v_add_u32_e32 v4, v4, v5
	v_lshlrev_b32_e32 v5, 3, v4
	v_sub_u32_e32 v6, 44, v5
	v_min_u32_e32 v6, 8, v6
	v_cvt_f32_ubyte0_e32 v7, v6
	v_rcp_iflag_f32_e32 v7, v7
	v_mul_i32_i24_e32 v4, 0xfffffbb8, v4
	v_sub_u32_e32 v10, 0, v6
	v_add_u32_e32 v4, v4, v3
	v_mul_f32_e32 v7, 0x4f7ffffe, v7
	v_cvt_u32_f32_e32 v7, v7
	v_sub_u32_e32 v9, 0, v4
	v_max_i32_e32 v9, v4, v9
	v_ashrrev_i32_e32 v8, 31, v4
	v_mul_lo_u32 v10, v10, v7
	v_mul_hi_u32 v10, v7, v10
	v_add_u32_e32 v7, v7, v10
	v_mul_hi_u32 v7, v9, v7
	v_mul_lo_u32 v10, v7, v6
	v_sub_u32_e32 v9, v9, v10
	v_add_u32_e32 v10, 1, v7
	v_cmp_ge_u32_e32 vcc, v9, v6
	v_mov_b32_e32 v36, v0
	v_readlane_b32 s38, v194, 11
	v_cndmask_b32_e32 v7, v7, v10, vcc
	v_sub_u32_e32 v10, v9, v6
	v_cndmask_b32_e32 v9, v9, v10, vcc
	v_add_u32_e32 v10, 1, v7
	v_cmp_ge_u32_e32 vcc, v9, v6
	v_lshrrev_b32_e32 v37, 4, v36
	v_ashrrev_i32_e32 v12, 3, v36
	v_cndmask_b32_e32 v7, v7, v10, vcc
	v_xor_b32_e32 v7, v7, v8
	v_sub_u32_e32 v7, v7, v8
	v_mul_lo_u32 v6, v7, v6
	v_sub_u32_e32 v4, v4, v6
	v_add_u32_e32 v102, v4, v5
	v_lshlrev_b32_e32 v105, 7, v7
	v_xor_b32_e32 v4, v37, v36
	v_lshlrev_b32_e32 v4, 4, v4
	v_add_u32_e32 v8, v12, v105
	v_lshlrev_b32_e32 v38, 4, v36
	v_lshlrev_b32_e32 v34, 7, v102
	v_and_b32_e32 v4, 0x70, v4
	v_mov_b32_e32 v5, v2
	v_ashrrev_i32_e32 v9, 31, v8
	v_add_u32_e32 v16, 0x100, v36
	v_and_b32_e32 v84, 0xfffffc00, v38
	v_lshl_add_u64 v[6:7], s[94:95], 0, v[4:5]
	v_lshlrev_b64 v[8:9], 11, v[8:9]
	v_add_u32_e32 v12, v12, v34
	v_ashrrev_i32_e32 v20, 3, v16
	v_readfirstlane_b32 s1, v84
	v_readlane_b32 s39, v194, 12
	v_lshl_add_u64 v[10:11], v[6:7], 0, v[8:9]
	v_ashrrev_i32_e32 v13, 31, v12
	v_add_u32_e32 v16, v20, v105
	v_add_u32_e32 v24, 0x200, v36
	v_add_u32_e32 v38, 0x4000, v84
	s_mov_b32 m0, s1
	v_lshl_add_u64 v[4:5], s[38:39], 0, v[4:5]
	v_lshlrev_b64 v[12:13], 11, v[12:13]
	v_ashrrev_i32_e32 v17, 31, v16
	v_add_u32_e32 v20, v20, v34
	v_ashrrev_i32_e32 v28, 3, v24
	s_barrier
	s_nop 0
	v_readfirstlane_b32 s1, v38
	v_add_u32_e32 v10, 0x1000, v84
	v_lshl_add_u64 v[14:15], v[4:5], 0, v[12:13]
	v_lshlrev_b64 v[16:17], 11, v[16:17]
	v_ashrrev_i32_e32 v21, 31, v20
	v_add_u32_e32 v24, v28, v105
	v_add_u32_e32 v32, 0x300, v36
	s_mov_b32 m0, s1
	v_readfirstlane_b32 s1, v10
	v_add_u32_e32 v10, 0x5000, v84
	v_lshl_add_u64 v[18:19], v[6:7], 0, v[16:17]
	v_lshlrev_b64 v[20:21], 11, v[20:21]
	v_ashrrev_i32_e32 v25, 31, v24
	v_add_u32_e32 v28, v28, v34
	v_ashrrev_i32_e32 v35, 3, v32
	s_nop 0
	s_mov_b32 m0, s1
	v_readfirstlane_b32 s1, v10
	v_add_u32_e32 v10, 0x2000, v84
	v_lshl_add_u64 v[22:23], v[4:5], 0, v[20:21]
	v_lshlrev_b64 v[24:25], 11, v[24:25]
	v_ashrrev_i32_e32 v29, 31, v28
	v_add_u32_e32 v32, v35, v105
	s_nop 0
	s_mov_b32 m0, s1
	v_readfirstlane_b32 s1, v10
	v_add_u32_e32 v10, 0x6000, v84
	v_lshl_add_u64 v[26:27], v[6:7], 0, v[24:25]
	v_lshlrev_b64 v[28:29], 11, v[28:29]
	v_ashrrev_i32_e32 v33, 31, v32
	s_nop 0
	s_mov_b32 m0, s1
	v_readfirstlane_b32 s1, v10
	v_add_u32_e32 v10, 0x3000, v84
	v_lshl_add_u64 v[30:31], v[4:5], 0, v[28:29]
	v_lshlrev_b64 v[32:33], 11, v[32:33]
	s_nop 0
	s_mov_b32 m0, s1
	v_readfirstlane_b32 s1, v10
	v_lshl_add_u64 v[6:7], v[6:7], 0, v[32:33]
	v_add_u32_e32 v34, v35, v34
	s_nop 0
	s_mov_b32 m0, s1
	v_ashrrev_i32_e32 v35, 31, v34
	s_nop 0
	v_add_u32_e32 v6, 0x7000, v84
	v_lshlrev_b64 v[34:35], 11, v[34:35]
	v_readfirstlane_b32 s1, v6
	v_lshl_add_u64 v[4:5], v[4:5], 0, v[34:35]
	s_mov_b32 m0, s1
	v_lshrrev_b32_e32 v6, 1, v36
	s_nop 0
	v_and_b32_e32 v4, 15, v36
	s_mov_b32 s1, 0x1ffffc0
	v_bfe_u32 v7, v36, 1, 3
	v_and_or_b32 v4, v6, s1, v4
	v_lshlrev_b32_e32 v85, 7, v4
	v_bitop3_b32 v4, v37, v7, 3 bitop3:0x6c
	v_bfe_u32 v5, v36, 4, 2
	v_lshlrev_b32_e32 v88, 4, v4
	v_lshlrev_b32_e32 v4, 7, v36
	v_and_b32_e32 v86, 0x2780, v4
	v_bitop3_b32 v4, v5, v7, 4 bitop3:0x36
	v_lshlrev_b32_e32 v87, 4, v4
	v_bitop3_b32 v4, v37, 7, v36 bitop3:0x48
	v_lshlrev_b32_e32 v14, 4, v4
	v_readlane_b32 s38, v192, 7
	v_readlane_b32 s39, v192, 8
	v_readlane_b32 s40, v192, 9
	v_or_b32_e32 v32, v32, v14
	v_or_b32_e32 v8, v8, v14
	v_or_b32_e32 v12, v12, v14
	v_readlane_b32 s41, v192, 10
	v_or_b32_e32 v16, v16, v14
	v_or_b32_e32 v20, v20, v14
	v_or_b32_e32 v24, v24, v14
	v_or_b32_e32 v28, v28, v14
	v_lshl_add_u64 v[80:81], s[38:39], 0, v[32:33]
	v_or_b32_e32 v34, v34, v14
	v_mov_b32_e32 v32, 0
	v_lshl_add_u64 v[4:5], s[38:39], 0, v[8:9]
	v_lshl_add_u64 v[6:7], s[40:41], 0, v[12:13]
	v_lshl_add_u64 v[8:9], s[38:39], 0, v[16:17]
	v_lshl_add_u64 v[10:11], s[40:41], 0, v[20:21]
	v_lshl_add_u64 v[16:17], s[38:39], 0, v[24:25]
	v_lshl_add_u64 v[18:19], s[40:41], 0, v[28:29]
	v_lshl_add_u64 v[82:83], s[40:41], 0, v[34:35]
	s_mov_b32 s1, 0x8000
	s_mov_b64 s[38:39], 0
	v_mov_b32_e32 v33, v32
	v_mov_b32_e32 v34, v32
	v_mov_b32_e32 v35, v32
	v_mov_b32_e32 v12, v32
	v_mov_b32_e32 v13, v32
	v_mov_b32_e32 v14, v32
	v_mov_b32_e32 v15, v32
	v_mov_b32_e32 v20, v32
	v_mov_b32_e32 v21, v32
	v_mov_b32_e32 v22, v32
	v_mov_b32_e32 v23, v32
	v_mov_b32_e32 v24, v32
	v_mov_b32_e32 v25, v32
	v_mov_b32_e32 v26, v32
	v_mov_b32_e32 v27, v32
	v_mov_b32_e32 v28, v32
	v_mov_b32_e32 v29, v32
	v_mov_b32_e32 v30, v32
	v_mov_b32_e32 v31, v32
	v_mov_b32_e32 v36, v32
	v_mov_b32_e32 v37, v32
	v_mov_b32_e32 v38, v32
	v_mov_b32_e32 v39, v32
	v_mov_b32_e32 v40, v32
	v_mov_b32_e32 v41, v32
	v_mov_b32_e32 v42, v32
	v_mov_b32_e32 v43, v32
	v_mov_b32_e32 v44, v32
	v_mov_b32_e32 v45, v32
	v_mov_b32_e32 v46, v32
	v_mov_b32_e32 v47, v32
	v_mov_b32_e32 v48, v32
	v_mov_b32_e32 v49, v32
	v_mov_b32_e32 v50, v32
	v_mov_b32_e32 v51, v32
	v_mov_b32_e32 v52, v32
	v_mov_b32_e32 v53, v32
	v_mov_b32_e32 v54, v32
	v_mov_b32_e32 v55, v32
	v_mov_b32_e32 v56, v32
	v_mov_b32_e32 v57, v32
	v_mov_b32_e32 v58, v32
	v_mov_b32_e32 v59, v32
	v_mov_b32_e32 v60, v32
	v_mov_b32_e32 v61, v32
	v_mov_b32_e32 v62, v32
	v_mov_b32_e32 v63, v32
	v_mov_b32_e32 v64, v32
	v_mov_b32_e32 v65, v32
	v_mov_b32_e32 v66, v32
	v_mov_b32_e32 v67, v32
	v_mov_b32_e32 v68, v32
	v_mov_b32_e32 v69, v32
	v_mov_b32_e32 v70, v32
	v_mov_b32_e32 v71, v32
	v_mov_b32_e32 v72, v32
	v_mov_b32_e32 v73, v32
	v_mov_b32_e32 v74, v32
	v_mov_b32_e32 v75, v32
	v_mov_b32_e32 v76, v32
	v_mov_b32_e32 v77, v32
	v_mov_b32_e32 v78, v32
	v_mov_b32_e32 v79, v32
; DEVINL void gemm_loop(f32x4 (&acc)[4][4], const u16* __restrict__ A, int lda, const u16* __restrict__ Bt, int ldb,
;                       int m0, int n0, int k0, int nk, char* smem) {
;     ...
;   __syncthreads();
; #pragma unroll
;   for (int i = 0; i < 4; ++i) {
;     glds16(ga[i], smem + i * 4096 + wid * 1024);
;     glds16(gb[i], smem + 16384 + i * 4096 + wid * 1024);
;   }
;   for (int kt = 0; kt < nk; ++kt) {
;     __syncthreads();
;     char* cur = smem + (kt & 1) * 32768;
;     if (kt + 1 < nk) {
;       char* nxt = smem + ((kt + 1) & 1) * 32768;
; #pragma unroll
;       for (int i = 0; i < 4; ++i) {
;         glds16(ga[i] + (kt + 1) * 64, nxt + i * 4096 + wid * 1024);
;         glds16(gb[i] + (kt + 1) * 64, nxt + 16384 + i * 4096 + wid * 1024);
;       }
;     }
;     bf16x8 af[2][4], bfr[2][4];
; #pragma unroll
;     for (int ks = 0; ks < 2; ++ks)
; #pragma unroll
;       for (int f = 0; f < 4; ++f) {
;         int ra = wr * 64 + f * 16 + fr, rb = wc * 64 + f * 16 + fr;
;         int ch = ks * 4 + fq;
;         af[ks][f] = *(const bf16x8*)(cur + ra * 128 + ((ch ^ ((ra >> 1) & 7)) << 4));
;         bfr[ks][f] = *(const bf16x8*)(cur + 16384 + rb * 128 + ((ch ^ ((rb >> 1) & 7)) << 4));
;       }
.LBB0_116:
	s_cmp_eq_u32 s101, 1
	s_cbranch_scc1 .Ldt_b116_second
	v_writelane_b32 v195, s52, 0
	v_writelane_b32 v195, s53, 1
	v_writelane_b32 v195, s54, 2
	v_writelane_b32 v195, s55, 3
	v_writelane_b32 v195, s56, 4
	v_writelane_b32 v195, s57, 5
	v_writelane_b32 v195, s58, 6
	v_writelane_b32 v195, s59, 7
	v_readfirstlane_b32 s40, v84
	v_mov_b32_e32 v188, 0
	v_mov_b32_e32 v189, 0
	v_mov_b32_e32 v190, 0
	v_mov_b32_e32 v191, 0
	v_mov_b32_e32 v196, 0
	v_mov_b32_e32 v197, 0
	v_mov_b32_e32 v198, 0
	v_mov_b32_e32 v199, 0
	v_mov_b32_e32 v200, 0
	v_mov_b32_e32 v201, 0
	v_mov_b32_e32 v202, 0
	v_mov_b32_e32 v203, 0
	v_mov_b32_e32 v204, 0
	v_mov_b32_e32 v205, 0
	v_mov_b32_e32 v206, 0
	v_mov_b32_e32 v207, 0
	v_mov_b32_e32 v208, 0
	v_mov_b32_e32 v209, 0
	v_mov_b32_e32 v210, 0
	v_mov_b32_e32 v211, 0
	v_mov_b32_e32 v212, 0
	v_mov_b32_e32 v213, 0
	v_mov_b32_e32 v214, 0
	v_mov_b32_e32 v215, 0
	v_mov_b32_e32 v216, 0
	v_mov_b32_e32 v217, 0
	v_mov_b32_e32 v218, 0
	v_mov_b32_e32 v219, 0
	v_mov_b32_e32 v220, 0
	v_mov_b32_e32 v221, 0
	v_mov_b32_e32 v222, 0
	v_mov_b32_e32 v223, 0
	v_mov_b32_e32 v224, 0
	v_mov_b32_e32 v225, 0
	v_mov_b32_e32 v226, 0
	v_mov_b32_e32 v227, 0
	v_mov_b32_e32 v228, 0
	v_mov_b32_e32 v229, 0
	v_mov_b32_e32 v230, 0
	v_mov_b32_e32 v231, 0
	v_mov_b32_e32 v232, 0
	v_mov_b32_e32 v233, 0
	v_mov_b32_e32 v234, 0
	v_mov_b32_e32 v235, 0
	v_mov_b32_e32 v236, 0
	v_mov_b32_e32 v237, 0
	v_mov_b32_e32 v238, 0
	v_mov_b32_e32 v239, 0
	v_mov_b32_e32 v240, 0
	v_mov_b32_e32 v241, 0
	v_mov_b32_e32 v242, 0
	v_mov_b32_e32 v243, 0
	v_mov_b32_e32 v244, 0
	v_mov_b32_e32 v245, 0
	v_mov_b32_e32 v246, 0
	v_mov_b32_e32 v247, 0
	v_mov_b32_e32 v248, 0
	v_mov_b32_e32 v249, 0
	v_mov_b32_e32 v250, 0
	v_mov_b32_e32 v251, 0
	v_mov_b32_e32 v252, 0
	v_mov_b32_e32 v253, 0
	v_mov_b32_e32 v254, 0
	v_mov_b32_e32 v255, 0
	s_mov_b32 s52, 0x0
	s_mov_b32 s53, 0x4000
	s_mov_b32 s54, 0x8000
	s_mov_b32 s55, 0xc000
	s_mov_b32 s56, 0x10000
	s_mov_b32 s58, 0xffffff80
	s_mov_b32 s59, -1
	s_mov_b32 s38, 0x3ff80
	s_mov_b32 s39, 0
	s_add_u32 s41, s52, s40
	s_add_u32 m0, s41, 0x0
	v_lshl_add_u64 v[122:123], v[4:5], 0, s[58:59]
	global_load_lds_dwordx4 v[122:123], off
	s_add_u32 m0, s41, 0x1000
	v_lshl_add_u64 v[122:123], v[8:9], 0, s[58:59]
	global_load_lds_dwordx4 v[122:123], off
	s_add_u32 m0, s41, 0x2000
	v_lshl_add_u64 v[122:123], v[16:17], 0, s[58:59]
	global_load_lds_dwordx4 v[122:123], off
	s_add_u32 m0, s41, 0x3000
	v_lshl_add_u64 v[122:123], v[80:81], 0, s[58:59]
	global_load_lds_dwordx4 v[122:123], off
	s_add_u32 s41, s53, s40
	s_add_u32 m0, s41, 0x0
	v_lshl_add_u64 v[122:123], v[6:7], 0, s[58:59]
	global_load_lds_dwordx4 v[122:123], off
	s_add_u32 m0, s41, 0x1000
	v_lshl_add_u64 v[122:123], v[10:11], 0, s[58:59]
	global_load_lds_dwordx4 v[122:123], off
	s_add_u32 m0, s41, 0x2000
	v_lshl_add_u64 v[122:123], v[18:19], 0, s[58:59]
	global_load_lds_dwordx4 v[122:123], off
	s_add_u32 m0, s41, 0x3000
	v_lshl_add_u64 v[122:123], v[82:83], 0, s[58:59]
	global_load_lds_dwordx4 v[122:123], off
	s_add_u32 s41, s54, s40
	s_add_u32 m0, s41, 0x0
	v_lshl_add_u64 v[122:123], v[6:7], 0, s[38:39]
	global_load_lds_dwordx4 v[122:123], off
	s_add_u32 m0, s41, 0x1000
	v_lshl_add_u64 v[122:123], v[10:11], 0, s[38:39]
	global_load_lds_dwordx4 v[122:123], off
	s_add_u32 m0, s41, 0x2000
	v_lshl_add_u64 v[122:123], v[18:19], 0, s[38:39]
	global_load_lds_dwordx4 v[122:123], off
	s_add_u32 m0, s41, 0x3000
	v_lshl_add_u64 v[122:123], v[82:83], 0, s[38:39]
	global_load_lds_dwordx4 v[122:123], off
	s_mov_b64 s[58:59], 0
	s_add_u32 s41, s55, s40
	s_add_u32 m0, s41, 0x0
	v_lshl_add_u64 v[122:123], v[4:5], 0, s[58:59]
	global_load_lds_dwordx4 v[122:123], off
	s_add_u32 m0, s41, 0x1000
	v_lshl_add_u64 v[122:123], v[8:9], 0, s[58:59]
	global_load_lds_dwordx4 v[122:123], off
	s_add_u32 m0, s41, 0x2000
	v_lshl_add_u64 v[122:123], v[16:17], 0, s[58:59]
	global_load_lds_dwordx4 v[122:123], off
	s_add_u32 m0, s41, 0x3000
	v_lshl_add_u64 v[122:123], v[80:81], 0, s[58:59]
	global_load_lds_dwordx4 v[122:123], off
	s_add_u32 s41, s56, s40
	s_add_u32 m0, s41, 0x0
	v_lshl_add_u64 v[122:123], v[6:7], 0, s[58:59]
	global_load_lds_dwordx4 v[122:123], off
	s_add_u32 m0, s41, 0x1000
	v_lshl_add_u64 v[122:123], v[10:11], 0, s[58:59]
	global_load_lds_dwordx4 v[122:123], off
	s_add_u32 m0, s41, 0x2000
	v_lshl_add_u64 v[122:123], v[18:19], 0, s[58:59]
	global_load_lds_dwordx4 v[122:123], off
	s_add_u32 m0, s41, 0x3000
	v_lshl_add_u64 v[122:123], v[82:83], 0, s[58:59]
	global_load_lds_dwordx4 v[122:123], off
	s_mov_b32 s38, 0x40000
	s_mov_b32 s58, 0x80
	s_mov_b32 s1, 14
	s_waitcnt vmcnt(12)
	s_barrier
	v_add3_u32 v124, v85, v88, s52
	v_add3_u32 v125, v86, v88, s53
	ds_read_b128 v[106:109], v124
	ds_read_b128 v[110:113], v124 offset:2048
	ds_read_b128 v[140:143], v124 offset:4096
	ds_read_b128 v[144:147], v124 offset:6144
	ds_read_b128 v[132:135], v125
	ds_read_b128 v[136:139], v125 offset:2048
	ds_read_b128 v[148:151], v125 offset:4096
	ds_read_b128 v[152:155], v125 offset:6144
; DEVINL f32x4 mfma16(bf16x8 a, bf16x8 b, f32x4 c) { return __builtin_amdgcn_mfma_f32_16x16x32_bf16(a, b, c, 0, 0, 0); }
; DEVINL void gemm_loop(f32x4 (&acc)[4][4], const u16* __restrict__ A, int lda, const u16* __restrict__ Bt, int ldb,
;                       int m0, int n0, int k0, int nk, char* smem) {
;     ...
;   for (int kt = 0; kt < nk; ++kt) {
;     __syncthreads();
;     char* cur = smem + (kt & 1) * 32768;
;     if (kt + 1 < nk) {
;       char* nxt = smem + ((kt + 1) & 1) * 32768;
; #pragma unroll
;       for (int i = 0; i < 4; ++i) {
;         glds16(ga[i] + (kt + 1) * 64, nxt + i * 4096 + wid * 1024);
;         glds16(gb[i] + (kt + 1) * 64, nxt + 16384 + i * 4096 + wid * 1024);
;       }
;     }
;     bf16x8 af[2][4], bfr[2][4];
; #pragma unroll
;     for (int ks = 0; ks < 2; ++ks)
; #pragma unroll
;       for (int f = 0; f < 4; ++f) {
;         int ra = wr * 64 + f * 16 + fr, rb = wc * 64 + f * 16 + fr;
;         int ch = ks * 4 + fq;
;         af[ks][f] = *(const bf16x8*)(cur + ra * 128 + ((ch ^ ((ra >> 1) & 7)) << 4));
;         bfr[ks][f] = *(const bf16x8*)(cur + 16384 + rb * 128 + ((ch ^ ((rb >> 1) & 7)) << 4));
;       }
;     __builtin_amdgcn_sched_barrier(0);
; #pragma unroll
;     for (int ks = 0; ks < 2; ++ks)
; #pragma unroll
;       for (int mf = 0; mf < 4; ++mf)
; #pragma unroll
;         for (int nf = 0; nf < 4; ++nf) acc[mf][nf] = mfma16(af[ks][mf], bfr[ks][nf], acc[mf][nf]);
.Ldt_b116_loop:
	v_add3_u32 v124, v85, v87, s52
	v_add3_u32 v125, v86, v87, s53
	ds_read_b128 v[156:159], v124
	ds_read_b128 v[160:163], v124 offset:2048
	ds_read_b128 v[172:175], v124 offset:4096
	ds_read_b128 v[176:179], v124 offset:6144
	ds_read_b128 v[164:167], v125
	ds_read_b128 v[168:171], v125 offset:2048
	ds_read_b128 v[180:183], v125 offset:4096
	ds_read_b128 v[184:187], v125 offset:6144
	s_waitcnt lgkmcnt(8)
	v_mfma_f32_16x16x32_bf16 v[76:79], v[106:109], v[132:135], v[76:79]
	v_mfma_f32_16x16x32_bf16 v[72:75], v[106:109], v[136:139], v[72:75]
	v_mfma_f32_16x16x32_bf16 v[68:71], v[106:109], v[148:151], v[68:71]
	v_mfma_f32_16x16x32_bf16 v[64:67], v[106:109], v[152:155], v[64:67]
	v_mfma_f32_16x16x32_bf16 v[60:63], v[110:113], v[132:135], v[60:63]
	v_mfma_f32_16x16x32_bf16 v[56:59], v[110:113], v[136:139], v[56:59]
	v_mfma_f32_16x16x32_bf16 v[52:55], v[110:113], v[148:151], v[52:55]
	v_mfma_f32_16x16x32_bf16 v[48:51], v[110:113], v[152:155], v[48:51]
	v_mfma_f32_16x16x32_bf16 v[44:47], v[140:143], v[132:135], v[44:47]
	v_mfma_f32_16x16x32_bf16 v[40:43], v[140:143], v[136:139], v[40:43]
	v_mfma_f32_16x16x32_bf16 v[36:39], v[140:143], v[148:151], v[36:39]
	v_mfma_f32_16x16x32_bf16 v[28:31], v[140:143], v[152:155], v[28:31]
	v_mfma_f32_16x16x32_bf16 v[24:27], v[144:147], v[132:135], v[24:27]
	v_mfma_f32_16x16x32_bf16 v[20:23], v[144:147], v[136:139], v[20:23]
	v_mfma_f32_16x16x32_bf16 v[12:15], v[144:147], v[148:151], v[12:15]
	v_mfma_f32_16x16x32_bf16 v[32:35], v[144:147], v[152:155], v[32:35]
	s_waitcnt vmcnt(8) lgkmcnt(0)
	s_barrier
	s_add_u32 s41, s52, s40
	s_add_u32 m0, s41, 0x0
	v_lshl_add_u64 v[122:123], v[6:7], 0, s[38:39]
	global_load_lds_dwordx4 v[122:123], off
	s_add_u32 m0, s41, 0x1000
	v_lshl_add_u64 v[122:123], v[10:11], 0, s[38:39]
	global_load_lds_dwordx4 v[122:123], off
	s_add_u32 m0, s41, 0x2000
	v_lshl_add_u64 v[122:123], v[18:19], 0, s[38:39]
	global_load_lds_dwordx4 v[122:123], off
	s_add_u32 m0, s41, 0x3000
	v_lshl_add_u64 v[122:123], v[82:83], 0, s[38:39]
	global_load_lds_dwordx4 v[122:123], off
	s_add_u32 s41, s53, s40
	s_add_u32 m0, s41, 0x0
	v_lshl_add_u64 v[122:123], v[4:5], 0, s[58:59]
	global_load_lds_dwordx4 v[122:123], off
	s_add_u32 m0, s41, 0x1000
	v_lshl_add_u64 v[122:123], v[8:9], 0, s[58:59]
	global_load_lds_dwordx4 v[122:123], off
	s_add_u32 m0, s41, 0x2000
	v_lshl_add_u64 v[122:123], v[16:17], 0, s[58:59]
	global_load_lds_dwordx4 v[122:123], off
	s_add_u32 m0, s41, 0x3000
	v_lshl_add_u64 v[122:123], v[80:81], 0, s[58:59]
	global_load_lds_dwordx4 v[122:123], off
	v_add3_u32 v125, v86, v88, s54
	ds_read_b128 v[132:135], v125
	ds_read_b128 v[136:139], v125 offset:2048
	ds_read_b128 v[148:151], v125 offset:4096
	ds_read_b128 v[152:155], v125 offset:6144
	v_mfma_f32_16x16x32_bf16 v[76:79], v[156:159], v[164:167], v[76:79]
	v_mfma_f32_16x16x32_bf16 v[72:75], v[156:159], v[168:171], v[72:75]
	v_mfma_f32_16x16x32_bf16 v[68:71], v[156:159], v[180:183], v[68:71]
	v_mfma_f32_16x16x32_bf16 v[64:67], v[156:159], v[184:187], v[64:67]
	v_mfma_f32_16x16x32_bf16 v[60:63], v[160:163], v[164:167], v[60:63]
	v_mfma_f32_16x16x32_bf16 v[56:59], v[160:163], v[168:171], v[56:59]
	v_mfma_f32_16x16x32_bf16 v[52:55], v[160:163], v[180:183], v[52:55]
	v_mfma_f32_16x16x32_bf16 v[48:51], v[160:163], v[184:187], v[48:51]
	v_mfma_f32_16x16x32_bf16 v[44:47], v[172:175], v[164:167], v[44:47]
	v_mfma_f32_16x16x32_bf16 v[40:43], v[172:175], v[168:171], v[40:43]
	v_mfma_f32_16x16x32_bf16 v[36:39], v[172:175], v[180:183], v[36:39]
	v_mfma_f32_16x16x32_bf16 v[28:31], v[172:175], v[184:187], v[28:31]
	v_mfma_f32_16x16x32_bf16 v[24:27], v[176:179], v[164:167], v[24:27]
	v_mfma_f32_16x16x32_bf16 v[20:23], v[176:179], v[168:171], v[20:23]
	v_mfma_f32_16x16x32_bf16 v[12:15], v[176:179], v[180:183], v[12:15]
	v_mfma_f32_16x16x32_bf16 v[32:35], v[176:179], v[184:187], v[32:35]
	s_waitcnt lgkmcnt(0)
	v_add3_u32 v125, v86, v87, s54
	ds_read_b128 v[164:167], v125
	ds_read_b128 v[168:171], v125 offset:2048
	ds_read_b128 v[180:183], v125 offset:4096
	ds_read_b128 v[184:187], v125 offset:6144
	v_mfma_f32_16x16x32_bf16 v[188:191], v[106:109], v[132:135], v[188:191]
	v_mfma_f32_16x16x32_bf16 v[196:199], v[106:109], v[136:139], v[196:199]
	v_mfma_f32_16x16x32_bf16 v[200:203], v[106:109], v[148:151], v[200:203]
	v_mfma_f32_16x16x32_bf16 v[204:207], v[106:109], v[152:155], v[204:207]
	v_mfma_f32_16x16x32_bf16 v[208:211], v[110:113], v[132:135], v[208:211]
	v_mfma_f32_16x16x32_bf16 v[212:215], v[110:113], v[136:139], v[212:215]
	v_mfma_f32_16x16x32_bf16 v[216:219], v[110:113], v[148:151], v[216:219]
	v_mfma_f32_16x16x32_bf16 v[220:223], v[110:113], v[152:155], v[220:223]
	v_mfma_f32_16x16x32_bf16 v[224:227], v[140:143], v[132:135], v[224:227]
	v_mfma_f32_16x16x32_bf16 v[228:231], v[140:143], v[136:139], v[228:231]
	v_mfma_f32_16x16x32_bf16 v[232:235], v[140:143], v[148:151], v[232:235]
	v_mfma_f32_16x16x32_bf16 v[236:239], v[140:143], v[152:155], v[236:239]
	v_mfma_f32_16x16x32_bf16 v[240:243], v[144:147], v[132:135], v[240:243]
	v_mfma_f32_16x16x32_bf16 v[244:247], v[144:147], v[136:139], v[244:247]
	v_mfma_f32_16x16x32_bf16 v[248:251], v[144:147], v[148:151], v[248:251]
	v_mfma_f32_16x16x32_bf16 v[252:255], v[144:147], v[152:155], v[252:255]
	s_waitcnt vmcnt(8) lgkmcnt(0)
	s_barrier
; DEVINL f32x4 mfma16(bf16x8 a, bf16x8 b, f32x4 c) { return __builtin_amdgcn_mfma_f32_16x16x32_bf16(a, b, c, 0, 0, 0); }
; DEVINL void gemm_loop(f32x4 (&acc)[4][4], const u16* __restrict__ A, int lda, const u16* __restrict__ Bt, int ldb,
;                       int m0, int n0, int k0, int nk, char* smem) {
;     ...
;   for (int kt = 0; kt < nk; ++kt) {
;     __syncthreads();
;     char* cur = smem + (kt & 1) * 32768;
;     if (kt + 1 < nk) {
;       char* nxt = smem + ((kt + 1) & 1) * 32768;
; #pragma unroll
;       for (int i = 0; i < 4; ++i) {
;         glds16(ga[i] + (kt + 1) * 64, nxt + i * 4096 + wid * 1024);
;         glds16(gb[i] + (kt + 1) * 64, nxt + 16384 + i * 4096 + wid * 1024);
;       }
;     }
;     bf16x8 af[2][4], bfr[2][4];
; #pragma unroll
;     for (int ks = 0; ks < 2; ++ks)
; #pragma unroll
;       for (int f = 0; f < 4; ++f) {
;         int ra = wr * 64 + f * 16 + fr, rb = wc * 64 + f * 16 + fr;
;         int ch = ks * 4 + fq;
;         af[ks][f] = *(const bf16x8*)(cur + ra * 128 + ((ch ^ ((ra >> 1) & 7)) << 4));
;         bfr[ks][f] = *(const bf16x8*)(cur + 16384 + rb * 128 + ((ch ^ ((rb >> 1) & 7)) << 4));
;       }
;     __builtin_amdgcn_sched_barrier(0);
; #pragma unroll
;     for (int ks = 0; ks < 2; ++ks)
; #pragma unroll
;       for (int mf = 0; mf < 4; ++mf)
; #pragma unroll
;         for (int nf = 0; nf < 4; ++nf) acc[mf][nf] = mfma16(af[ks][mf], bfr[ks][nf], acc[mf][nf]);
	s_add_u32 s41, s54, s40
	s_add_u32 m0, s41, 0x0
	v_lshl_add_u64 v[122:123], v[6:7], 0, s[58:59]
	global_load_lds_dwordx4 v[122:123], off
	s_add_u32 m0, s41, 0x1000
	v_lshl_add_u64 v[122:123], v[10:11], 0, s[58:59]
	global_load_lds_dwordx4 v[122:123], off
	s_add_u32 m0, s41, 0x2000
	v_lshl_add_u64 v[122:123], v[18:19], 0, s[58:59]
	global_load_lds_dwordx4 v[122:123], off
	s_add_u32 m0, s41, 0x3000
	v_lshl_add_u64 v[122:123], v[82:83], 0, s[58:59]
	global_load_lds_dwordx4 v[122:123], off
	v_add3_u32 v124, v85, v88, s55
	v_add3_u32 v125, v86, v88, s56
	ds_read_b128 v[106:109], v124
	ds_read_b128 v[110:113], v124 offset:2048
	ds_read_b128 v[140:143], v124 offset:4096
	ds_read_b128 v[144:147], v124 offset:6144
	ds_read_b128 v[132:135], v125
	ds_read_b128 v[136:139], v125 offset:2048
	ds_read_b128 v[148:151], v125 offset:4096
	ds_read_b128 v[152:155], v125 offset:6144
	v_mfma_f32_16x16x32_bf16 v[188:191], v[156:159], v[164:167], v[188:191]
	v_mfma_f32_16x16x32_bf16 v[196:199], v[156:159], v[168:171], v[196:199]
	v_mfma_f32_16x16x32_bf16 v[200:203], v[156:159], v[180:183], v[200:203]
	v_mfma_f32_16x16x32_bf16 v[204:207], v[156:159], v[184:187], v[204:207]
	v_mfma_f32_16x16x32_bf16 v[208:211], v[160:163], v[164:167], v[208:211]
	v_mfma_f32_16x16x32_bf16 v[212:215], v[160:163], v[168:171], v[212:215]
	v_mfma_f32_16x16x32_bf16 v[216:219], v[160:163], v[180:183], v[216:219]
	v_mfma_f32_16x16x32_bf16 v[220:223], v[160:163], v[184:187], v[220:223]
	v_mfma_f32_16x16x32_bf16 v[224:227], v[172:175], v[164:167], v[224:227]
	v_mfma_f32_16x16x32_bf16 v[228:231], v[172:175], v[168:171], v[228:231]
	v_mfma_f32_16x16x32_bf16 v[232:235], v[172:175], v[180:183], v[232:235]
	v_mfma_f32_16x16x32_bf16 v[236:239], v[172:175], v[184:187], v[236:239]
	v_mfma_f32_16x16x32_bf16 v[240:243], v[176:179], v[164:167], v[240:243]
	v_mfma_f32_16x16x32_bf16 v[244:247], v[176:179], v[168:171], v[244:247]
	v_mfma_f32_16x16x32_bf16 v[248:251], v[176:179], v[180:183], v[248:251]
	v_mfma_f32_16x16x32_bf16 v[252:255], v[176:179], v[184:187], v[252:255]
	s_mov_b32 s41, s52
	s_mov_b32 s100, s53
	s_mov_b32 s52, s55
	s_mov_b32 s53, s56
	s_mov_b32 s55, s100
	s_mov_b32 s100, s54
	s_mov_b32 s54, s41
	s_mov_b32 s56, s100
	s_add_u32 s38, s38, 0x80
	s_addc_u32 s39, s39, 0
	s_add_u32 s58, s58, 0x80
	s_addc_u32 s59, s59, 0
	s_sub_u32 s1, s1, 1
	s_cmp_lg_u32 s1, 0
	s_cbranch_scc1 .Ldt_b116_loop
	v_add3_u32 v124, v85, v87, s52
	v_add3_u32 v125, v86, v87, s53
	ds_read_b128 v[156:159], v124
	ds_read_b128 v[160:163], v124 offset:2048
	ds_read_b128 v[172:175], v124 offset:4096
	ds_read_b128 v[176:179], v124 offset:6144
	ds_read_b128 v[164:167], v125
	ds_read_b128 v[168:171], v125 offset:2048
	ds_read_b128 v[180:183], v125 offset:4096
	ds_read_b128 v[184:187], v125 offset:6144
	s_waitcnt lgkmcnt(8)
	v_mfma_f32_16x16x32_bf16 v[76:79], v[106:109], v[132:135], v[76:79]
	v_mfma_f32_16x16x32_bf16 v[72:75], v[106:109], v[136:139], v[72:75]
	v_mfma_f32_16x16x32_bf16 v[68:71], v[106:109], v[148:151], v[68:71]
	v_mfma_f32_16x16x32_bf16 v[64:67], v[106:109], v[152:155], v[64:67]
	v_mfma_f32_16x16x32_bf16 v[60:63], v[110:113], v[132:135], v[60:63]
	v_mfma_f32_16x16x32_bf16 v[56:59], v[110:113], v[136:139], v[56:59]
	v_mfma_f32_16x16x32_bf16 v[52:55], v[110:113], v[148:151], v[52:55]
	v_mfma_f32_16x16x32_bf16 v[48:51], v[110:113], v[152:155], v[48:51]
	v_mfma_f32_16x16x32_bf16 v[44:47], v[140:143], v[132:135], v[44:47]
	v_mfma_f32_16x16x32_bf16 v[40:43], v[140:143], v[136:139], v[40:43]
	v_mfma_f32_16x16x32_bf16 v[36:39], v[140:143], v[148:151], v[36:39]
	v_mfma_f32_16x16x32_bf16 v[28:31], v[140:143], v[152:155], v[28:31]
	v_mfma_f32_16x16x32_bf16 v[24:27], v[144:147], v[132:135], v[24:27]
	v_mfma_f32_16x16x32_bf16 v[20:23], v[144:147], v[136:139], v[20:23]
	v_mfma_f32_16x16x32_bf16 v[12:15], v[144:147], v[148:151], v[12:15]
	v_mfma_f32_16x16x32_bf16 v[32:35], v[144:147], v[152:155], v[32:35]
	s_waitcnt vmcnt(8) lgkmcnt(0)
	s_barrier
	s_add_u32 s41, s52, s40
	s_add_u32 m0, s41, 0x0
	v_lshl_add_u64 v[122:123], v[6:7], 0, s[38:39]
	global_load_lds_dwordx4 v[122:123], off
	s_add_u32 m0, s41, 0x1000
	v_lshl_add_u64 v[122:123], v[10:11], 0, s[38:39]
	global_load_lds_dwordx4 v[122:123], off
	s_add_u32 m0, s41, 0x2000
	v_lshl_add_u64 v[122:123], v[18:19], 0, s[38:39]
	global_load_lds_dwordx4 v[122:123], off
	s_add_u32 m0, s41, 0x3000
	v_lshl_add_u64 v[122:123], v[82:83], 0, s[38:39]
	global_load_lds_dwordx4 v[122:123], off
	v_add3_u32 v125, v86, v88, s54
	ds_read_b128 v[132:135], v125
	ds_read_b128 v[136:139], v125 offset:2048
	ds_read_b128 v[148:151], v125 offset:4096
	ds_read_b128 v[152:155], v125 offset:6144
	v_mfma_f32_16x16x32_bf16 v[76:79], v[156:159], v[164:167], v[76:79]
	v_mfma_f32_16x16x32_bf16 v[72:75], v[156:159], v[168:171], v[72:75]
	v_mfma_f32_16x16x32_bf16 v[68:71], v[156:159], v[180:183], v[68:71]
	v_mfma_f32_16x16x32_bf16 v[64:67], v[156:159], v[184:187], v[64:67]
	v_mfma_f32_16x16x32_bf16 v[60:63], v[160:163], v[164:167], v[60:63]
	v_mfma_f32_16x16x32_bf16 v[56:59], v[160:163], v[168:171], v[56:59]
	v_mfma_f32_16x16x32_bf16 v[52:55], v[160:163], v[180:183], v[52:55]
	v_mfma_f32_16x16x32_bf16 v[48:51], v[160:163], v[184:187], v[48:51]
	v_mfma_f32_16x16x32_bf16 v[44:47], v[172:175], v[164:167], v[44:47]
	v_mfma_f32_16x16x32_bf16 v[40:43], v[172:175], v[168:171], v[40:43]
	v_mfma_f32_16x16x32_bf16 v[36:39], v[172:175], v[180:183], v[36:39]
	v_mfma_f32_16x16x32_bf16 v[28:31], v[172:175], v[184:187], v[28:31]
	v_mfma_f32_16x16x32_bf16 v[24:27], v[176:179], v[164:167], v[24:27]
	v_mfma_f32_16x16x32_bf16 v[20:23], v[176:179], v[168:171], v[20:23]
	v_mfma_f32_16x16x32_bf16 v[12:15], v[176:179], v[180:183], v[12:15]
	v_mfma_f32_16x16x32_bf16 v[32:35], v[176:179], v[184:187], v[32:35]
	s_waitcnt lgkmcnt(0)
; DEVINL f32x4 mfma16(bf16x8 a, bf16x8 b, f32x4 c) { return __builtin_amdgcn_mfma_f32_16x16x32_bf16(a, b, c, 0, 0, 0); }
; DEVINL void gemm_loop(f32x4 (&acc)[4][4], const u16* __restrict__ A, int lda, const u16* __restrict__ Bt, int ldb,
;                       int m0, int n0, int k0, int nk, char* smem) {
;     ...
;   for (int kt = 0; kt < nk; ++kt) {
;     __syncthreads();
;     char* cur = smem + (kt & 1) * 32768;
;     if (kt + 1 < nk) {
;       char* nxt = smem + ((kt + 1) & 1) * 32768;
; #pragma unroll
;       for (int i = 0; i < 4; ++i) {
;         glds16(ga[i] + (kt + 1) * 64, nxt + i * 4096 + wid * 1024);
;         glds16(gb[i] + (kt + 1) * 64, nxt + 16384 + i * 4096 + wid * 1024);
;       }
;     }
;     bf16x8 af[2][4], bfr[2][4];
; #pragma unroll
;     for (int ks = 0; ks < 2; ++ks)
; #pragma unroll
;       for (int f = 0; f < 4; ++f) {
;         int ra = wr * 64 + f * 16 + fr, rb = wc * 64 + f * 16 + fr;
;         int ch = ks * 4 + fq;
;         af[ks][f] = *(const bf16x8*)(cur + ra * 128 + ((ch ^ ((ra >> 1) & 7)) << 4));
;         bfr[ks][f] = *(const bf16x8*)(cur + 16384 + rb * 128 + ((ch ^ ((rb >> 1) & 7)) << 4));
;       }
;     __builtin_amdgcn_sched_barrier(0);
; #pragma unroll
;     for (int ks = 0; ks < 2; ++ks)
; #pragma unroll
;       for (int mf = 0; mf < 4; ++mf)
; #pragma unroll
;         for (int nf = 0; nf < 4; ++nf) acc[mf][nf] = mfma16(af[ks][mf], bfr[ks][nf], acc[mf][nf]);
	v_add3_u32 v125, v86, v87, s54
	ds_read_b128 v[164:167], v125
	ds_read_b128 v[168:171], v125 offset:2048
	ds_read_b128 v[180:183], v125 offset:4096
	ds_read_b128 v[184:187], v125 offset:6144
	v_mfma_f32_16x16x32_bf16 v[188:191], v[106:109], v[132:135], v[188:191]
	v_mfma_f32_16x16x32_bf16 v[196:199], v[106:109], v[136:139], v[196:199]
	v_mfma_f32_16x16x32_bf16 v[200:203], v[106:109], v[148:151], v[200:203]
	v_mfma_f32_16x16x32_bf16 v[204:207], v[106:109], v[152:155], v[204:207]
	v_mfma_f32_16x16x32_bf16 v[208:211], v[110:113], v[132:135], v[208:211]
	v_mfma_f32_16x16x32_bf16 v[212:215], v[110:113], v[136:139], v[212:215]
	v_mfma_f32_16x16x32_bf16 v[216:219], v[110:113], v[148:151], v[216:219]
	v_mfma_f32_16x16x32_bf16 v[220:223], v[110:113], v[152:155], v[220:223]
	v_mfma_f32_16x16x32_bf16 v[224:227], v[140:143], v[132:135], v[224:227]
	v_mfma_f32_16x16x32_bf16 v[228:231], v[140:143], v[136:139], v[228:231]
	v_mfma_f32_16x16x32_bf16 v[232:235], v[140:143], v[148:151], v[232:235]
	v_mfma_f32_16x16x32_bf16 v[236:239], v[140:143], v[152:155], v[236:239]
	v_mfma_f32_16x16x32_bf16 v[240:243], v[144:147], v[132:135], v[240:243]
	v_mfma_f32_16x16x32_bf16 v[244:247], v[144:147], v[136:139], v[244:247]
	v_mfma_f32_16x16x32_bf16 v[248:251], v[144:147], v[148:151], v[248:251]
	v_mfma_f32_16x16x32_bf16 v[252:255], v[144:147], v[152:155], v[252:255]
	s_waitcnt vmcnt(4) lgkmcnt(0)
	s_barrier
	v_add3_u32 v124, v85, v88, s55
	v_add3_u32 v125, v86, v88, s56
	ds_read_b128 v[106:109], v124
	ds_read_b128 v[110:113], v124 offset:2048
	ds_read_b128 v[140:143], v124 offset:4096
	ds_read_b128 v[144:147], v124 offset:6144
	ds_read_b128 v[132:135], v125
	ds_read_b128 v[136:139], v125 offset:2048
	ds_read_b128 v[148:151], v125 offset:4096
	ds_read_b128 v[152:155], v125 offset:6144
	v_mfma_f32_16x16x32_bf16 v[188:191], v[156:159], v[164:167], v[188:191]
	v_mfma_f32_16x16x32_bf16 v[196:199], v[156:159], v[168:171], v[196:199]
	v_mfma_f32_16x16x32_bf16 v[200:203], v[156:159], v[180:183], v[200:203]
	v_mfma_f32_16x16x32_bf16 v[204:207], v[156:159], v[184:187], v[204:207]
	v_mfma_f32_16x16x32_bf16 v[208:211], v[160:163], v[164:167], v[208:211]
	v_mfma_f32_16x16x32_bf16 v[212:215], v[160:163], v[168:171], v[212:215]
	v_mfma_f32_16x16x32_bf16 v[216:219], v[160:163], v[180:183], v[216:219]
	v_mfma_f32_16x16x32_bf16 v[220:223], v[160:163], v[184:187], v[220:223]
	v_mfma_f32_16x16x32_bf16 v[224:227], v[172:175], v[164:167], v[224:227]
	v_mfma_f32_16x16x32_bf16 v[228:231], v[172:175], v[168:171], v[228:231]
	v_mfma_f32_16x16x32_bf16 v[232:235], v[172:175], v[180:183], v[232:235]
	v_mfma_f32_16x16x32_bf16 v[236:239], v[172:175], v[184:187], v[236:239]
	v_mfma_f32_16x16x32_bf16 v[240:243], v[176:179], v[164:167], v[240:243]
	v_mfma_f32_16x16x32_bf16 v[244:247], v[176:179], v[168:171], v[244:247]
	v_mfma_f32_16x16x32_bf16 v[248:251], v[176:179], v[180:183], v[248:251]
	v_mfma_f32_16x16x32_bf16 v[252:255], v[176:179], v[184:187], v[252:255]
	s_mov_b32 s41, s52
	s_mov_b32 s100, s53
	s_mov_b32 s52, s55
	s_mov_b32 s53, s56
	s_mov_b32 s55, s100
	s_mov_b32 s100, s54
	s_mov_b32 s54, s41
	s_mov_b32 s56, s100
	s_add_u32 s38, s38, 0x80
	s_addc_u32 s39, s39, 0
	s_add_u32 s58, s58, 0x80
	s_addc_u32 s59, s59, 0
	v_add3_u32 v124, v85, v87, s52
	v_add3_u32 v125, v86, v87, s53
	ds_read_b128 v[156:159], v124
	ds_read_b128 v[160:163], v124 offset:2048
	ds_read_b128 v[172:175], v124 offset:4096
	ds_read_b128 v[176:179], v124 offset:6144
	ds_read_b128 v[164:167], v125
	ds_read_b128 v[168:171], v125 offset:2048
	ds_read_b128 v[180:183], v125 offset:4096
	ds_read_b128 v[184:187], v125 offset:6144
	s_waitcnt lgkmcnt(8)
	v_mfma_f32_16x16x32_bf16 v[76:79], v[106:109], v[132:135], v[76:79]
	v_mfma_f32_16x16x32_bf16 v[72:75], v[106:109], v[136:139], v[72:75]
	v_mfma_f32_16x16x32_bf16 v[68:71], v[106:109], v[148:151], v[68:71]
	v_mfma_f32_16x16x32_bf16 v[64:67], v[106:109], v[152:155], v[64:67]
	v_mfma_f32_16x16x32_bf16 v[60:63], v[110:113], v[132:135], v[60:63]
	v_mfma_f32_16x16x32_bf16 v[56:59], v[110:113], v[136:139], v[56:59]
	v_mfma_f32_16x16x32_bf16 v[52:55], v[110:113], v[148:151], v[52:55]
	v_mfma_f32_16x16x32_bf16 v[48:51], v[110:113], v[152:155], v[48:51]
	v_mfma_f32_16x16x32_bf16 v[44:47], v[140:143], v[132:135], v[44:47]
	v_mfma_f32_16x16x32_bf16 v[40:43], v[140:143], v[136:139], v[40:43]
	v_mfma_f32_16x16x32_bf16 v[36:39], v[140:143], v[148:151], v[36:39]
	v_mfma_f32_16x16x32_bf16 v[28:31], v[140:143], v[152:155], v[28:31]
	v_mfma_f32_16x16x32_bf16 v[24:27], v[144:147], v[132:135], v[24:27]
	v_mfma_f32_16x16x32_bf16 v[20:23], v[144:147], v[136:139], v[20:23]
	v_mfma_f32_16x16x32_bf16 v[12:15], v[144:147], v[148:151], v[12:15]
	v_mfma_f32_16x16x32_bf16 v[32:35], v[144:147], v[152:155], v[32:35]
	s_waitcnt vmcnt(0) lgkmcnt(0)
	s_barrier
; DEVINL f32x4 mfma16(bf16x8 a, bf16x8 b, f32x4 c) { return __builtin_amdgcn_mfma_f32_16x16x32_bf16(a, b, c, 0, 0, 0); }
; DEVINL void gemm_loop(f32x4 (&acc)[4][4], const u16* __restrict__ A, int lda, const u16* __restrict__ Bt, int ldb,
;                       int m0, int n0, int k0, int nk, char* smem) {
;     ...
;   for (int kt = 0; kt < nk; ++kt) {
;     __syncthreads();
;     char* cur = smem + (kt & 1) * 32768;
;     if (kt + 1 < nk) {
;       char* nxt = smem + ((kt + 1) & 1) * 32768;
; #pragma unroll
;       for (int i = 0; i < 4; ++i) {
;         glds16(ga[i] + (kt + 1) * 64, nxt + i * 4096 + wid * 1024);
;         glds16(gb[i] + (kt + 1) * 64, nxt + 16384 + i * 4096 + wid * 1024);
;       }
;     }
;     bf16x8 af[2][4], bfr[2][4];
; #pragma unroll
;     for (int ks = 0; ks < 2; ++ks)
; #pragma unroll
;       for (int f = 0; f < 4; ++f) {
;         int ra = wr * 64 + f * 16 + fr, rb = wc * 64 + f * 16 + fr;
;         int ch = ks * 4 + fq;
;         af[ks][f] = *(const bf16x8*)(cur + ra * 128 + ((ch ^ ((ra >> 1) & 7)) << 4));
;         bfr[ks][f] = *(const bf16x8*)(cur + 16384 + rb * 128 + ((ch ^ ((rb >> 1) & 7)) << 4));
;       }
;     __builtin_amdgcn_sched_barrier(0);
; #pragma unroll
;     for (int ks = 0; ks < 2; ++ks)
; #pragma unroll
;       for (int mf = 0; mf < 4; ++mf)
; #pragma unroll
;         for (int nf = 0; nf < 4; ++nf) acc[mf][nf] = mfma16(af[ks][mf], bfr[ks][nf], acc[mf][nf]);
	v_add3_u32 v125, v86, v88, s54
	ds_read_b128 v[132:135], v125
	ds_read_b128 v[136:139], v125 offset:2048
	ds_read_b128 v[148:151], v125 offset:4096
	ds_read_b128 v[152:155], v125 offset:6144
	v_mfma_f32_16x16x32_bf16 v[76:79], v[156:159], v[164:167], v[76:79]
	v_mfma_f32_16x16x32_bf16 v[72:75], v[156:159], v[168:171], v[72:75]
	v_mfma_f32_16x16x32_bf16 v[68:71], v[156:159], v[180:183], v[68:71]
	v_mfma_f32_16x16x32_bf16 v[64:67], v[156:159], v[184:187], v[64:67]
	v_mfma_f32_16x16x32_bf16 v[60:63], v[160:163], v[164:167], v[60:63]
	v_mfma_f32_16x16x32_bf16 v[56:59], v[160:163], v[168:171], v[56:59]
	v_mfma_f32_16x16x32_bf16 v[52:55], v[160:163], v[180:183], v[52:55]
	v_mfma_f32_16x16x32_bf16 v[48:51], v[160:163], v[184:187], v[48:51]
	v_mfma_f32_16x16x32_bf16 v[44:47], v[172:175], v[164:167], v[44:47]
	v_mfma_f32_16x16x32_bf16 v[40:43], v[172:175], v[168:171], v[40:43]
	v_mfma_f32_16x16x32_bf16 v[36:39], v[172:175], v[180:183], v[36:39]
	v_mfma_f32_16x16x32_bf16 v[28:31], v[172:175], v[184:187], v[28:31]
	v_mfma_f32_16x16x32_bf16 v[24:27], v[176:179], v[164:167], v[24:27]
	v_mfma_f32_16x16x32_bf16 v[20:23], v[176:179], v[168:171], v[20:23]
	v_mfma_f32_16x16x32_bf16 v[12:15], v[176:179], v[180:183], v[12:15]
	v_mfma_f32_16x16x32_bf16 v[32:35], v[176:179], v[184:187], v[32:35]
	s_waitcnt lgkmcnt(0)
	v_add3_u32 v125, v86, v87, s54
	ds_read_b128 v[164:167], v125
	ds_read_b128 v[168:171], v125 offset:2048
	ds_read_b128 v[180:183], v125 offset:4096
	ds_read_b128 v[184:187], v125 offset:6144
	v_mfma_f32_16x16x32_bf16 v[188:191], v[106:109], v[132:135], v[188:191]
	v_mfma_f32_16x16x32_bf16 v[196:199], v[106:109], v[136:139], v[196:199]
	v_mfma_f32_16x16x32_bf16 v[200:203], v[106:109], v[148:151], v[200:203]
	v_mfma_f32_16x16x32_bf16 v[204:207], v[106:109], v[152:155], v[204:207]
	v_mfma_f32_16x16x32_bf16 v[208:211], v[110:113], v[132:135], v[208:211]
	v_mfma_f32_16x16x32_bf16 v[212:215], v[110:113], v[136:139], v[212:215]
	v_mfma_f32_16x16x32_bf16 v[216:219], v[110:113], v[148:151], v[216:219]
	v_mfma_f32_16x16x32_bf16 v[220:223], v[110:113], v[152:155], v[220:223]
	v_mfma_f32_16x16x32_bf16 v[224:227], v[140:143], v[132:135], v[224:227]
	v_mfma_f32_16x16x32_bf16 v[228:231], v[140:143], v[136:139], v[228:231]
	v_mfma_f32_16x16x32_bf16 v[232:235], v[140:143], v[148:151], v[232:235]
	v_mfma_f32_16x16x32_bf16 v[236:239], v[140:143], v[152:155], v[236:239]
	v_mfma_f32_16x16x32_bf16 v[240:243], v[144:147], v[132:135], v[240:243]
	v_mfma_f32_16x16x32_bf16 v[244:247], v[144:147], v[136:139], v[244:247]
	v_mfma_f32_16x16x32_bf16 v[248:251], v[144:147], v[148:151], v[248:251]
	v_mfma_f32_16x16x32_bf16 v[252:255], v[144:147], v[152:155], v[252:255]
	s_waitcnt lgkmcnt(0)
	v_mfma_f32_16x16x32_bf16 v[188:191], v[156:159], v[164:167], v[188:191]
	v_mfma_f32_16x16x32_bf16 v[196:199], v[156:159], v[168:171], v[196:199]
	v_mfma_f32_16x16x32_bf16 v[200:203], v[156:159], v[180:183], v[200:203]
	v_mfma_f32_16x16x32_bf16 v[204:207], v[156:159], v[184:187], v[204:207]
	v_mfma_f32_16x16x32_bf16 v[208:211], v[160:163], v[164:167], v[208:211]
	v_mfma_f32_16x16x32_bf16 v[212:215], v[160:163], v[168:171], v[212:215]
	v_mfma_f32_16x16x32_bf16 v[216:219], v[160:163], v[180:183], v[216:219]
	v_mfma_f32_16x16x32_bf16 v[220:223], v[160:163], v[184:187], v[220:223]
	v_mfma_f32_16x16x32_bf16 v[224:227], v[172:175], v[164:167], v[224:227]
	v_mfma_f32_16x16x32_bf16 v[228:231], v[172:175], v[168:171], v[228:231]
	v_mfma_f32_16x16x32_bf16 v[232:235], v[172:175], v[180:183], v[232:235]
	v_mfma_f32_16x16x32_bf16 v[236:239], v[172:175], v[184:187], v[236:239]
	v_mfma_f32_16x16x32_bf16 v[240:243], v[176:179], v[164:167], v[240:243]
	v_mfma_f32_16x16x32_bf16 v[244:247], v[176:179], v[168:171], v[244:247]
	v_mfma_f32_16x16x32_bf16 v[248:251], v[176:179], v[180:183], v[248:251]
	v_mfma_f32_16x16x32_bf16 v[252:255], v[176:179], v[184:187], v[252:255]
	s_nop 15
	v_readlane_b32 s52, v195, 0
	v_readlane_b32 s53, v195, 1
	v_readlane_b32 s54, v195, 2
	v_readlane_b32 s55, v195, 3
	v_readlane_b32 s56, v195, 4
	v_readlane_b32 s57, v195, 5
	v_readlane_b32 s58, v195, 6
	v_readlane_b32 s59, v195, 7
	v_mov_b32_e32 v122, 0x4480
	v_mov_b32_e32 v123, 0x380
	v_mov_b32_e32 v124, 0x100
	v_mov_b32_e32 v125, 0x110
	s_nop 4
	s_branch .Ldt_b116_tail
.Ldt_b116_second:
	v_mov_b32_e32 v76, v188
	v_mov_b32_e32 v77, v189
	v_mov_b32_e32 v78, v190
	v_mov_b32_e32 v79, v191
	v_mov_b32_e32 v72, v196
	v_mov_b32_e32 v73, v197
	v_mov_b32_e32 v74, v198
	v_mov_b32_e32 v75, v199
	v_mov_b32_e32 v68, v200
	v_mov_b32_e32 v69, v201
	v_mov_b32_e32 v70, v202
	v_mov_b32_e32 v71, v203
	v_mov_b32_e32 v64, v204
	v_mov_b32_e32 v65, v205
	v_mov_b32_e32 v66, v206
	v_mov_b32_e32 v67, v207
	v_mov_b32_e32 v60, v208
	v_mov_b32_e32 v61, v209
	v_mov_b32_e32 v62, v210
	v_mov_b32_e32 v63, v211
	v_mov_b32_e32 v56, v212
	v_mov_b32_e32 v57, v213
	v_mov_b32_e32 v58, v214
	v_mov_b32_e32 v59, v215
	v_mov_b32_e32 v52, v216
	v_mov_b32_e32 v53, v217
	v_mov_b32_e32 v54, v218
	v_mov_b32_e32 v55, v219
	v_mov_b32_e32 v48, v220
	v_mov_b32_e32 v49, v221
	v_mov_b32_e32 v50, v222
	v_mov_b32_e32 v51, v223
	v_mov_b32_e32 v44, v224
	v_mov_b32_e32 v45, v225
	v_mov_b32_e32 v46, v226
	v_mov_b32_e32 v47, v227
	v_mov_b32_e32 v40, v228
	v_mov_b32_e32 v41, v229
	v_mov_b32_e32 v42, v230
	v_mov_b32_e32 v43, v231
	v_mov_b32_e32 v36, v232
	v_mov_b32_e32 v37, v233
	v_mov_b32_e32 v38, v234
	v_mov_b32_e32 v39, v235
	v_mov_b32_e32 v28, v236
	v_mov_b32_e32 v29, v237
	v_mov_b32_e32 v30, v238
	v_mov_b32_e32 v31, v239
	v_mov_b32_e32 v24, v240
	v_mov_b32_e32 v25, v241
	v_mov_b32_e32 v26, v242
	v_mov_b32_e32 v27, v243
	v_mov_b32_e32 v20, v244
	v_mov_b32_e32 v21, v245
	v_mov_b32_e32 v22, v246
	v_mov_b32_e32 v23, v247
	v_mov_b32_e32 v12, v248
	v_mov_b32_e32 v13, v249
	v_mov_b32_e32 v14, v250
	v_mov_b32_e32 v15, v251
	v_mov_b32_e32 v32, v252
	v_mov_b32_e32 v33, v253
	v_mov_b32_e32 v34, v254
	v_mov_b32_e32 v35, v255
; DEVINL float siluf_(float x) { return x * __builtin_amdgcn_rcpf(1.f + __expf(-x)); }
; DEVINL int ridx(int r) { return ((r >> 4) << 5) | (r & 15); }
; DEVINL void p6_tile(const Params& p, char* smem, int mt, int nt) {
;     ...
;   for (int mf = 0; mf < 4; ++mf) {
;     const int rb = m0 + wr * 64 + mf * 16 + (lane >> 4) * 4;
;     float rs[4];
; #pragma unroll
;     for (int j = 0; j < 4; ++j) rs[j] = rstd1[ridx(rb) + j];
; #pragma unroll
;     for (int nf = 0; nf < 2; ++nf) {
;       const int hid = nt * 64 + wc * 32 + nf * 16 + (lane & 15);
;       float a[4];
; #pragma unroll
;       for (int j = 0; j < 4; ++j) {
;         float g = acc[mf][nf][j] * rs[j], u = acc[mf][nf + 2][j] * rs[j];
;         a[j] = siluf_(g) * u;
;       }
;       store_pairs(actb, DFF, rb, hid, a[0], a[1], a[2], a[3]);
;     }
.Ldt_b116_tail:
	s_waitcnt vmcnt(0)
	s_barrier
	s_waitcnt lgkmcnt(9)
	v_mov_b32_e32 v176, v52
	v_mov_b32_e32 v177, v53
	v_mov_b32_e32 v178, v54
	v_mov_b32_e32 v179, v55
	v_readlane_b32 s40, v194, 13
	v_readlane_b32 s41, v194, 14
	v_add_u32_e32 v3, v3, v1
	v_mov_b32_e32 v52, v36
	v_mov_b32_e32 v53, v37
	v_mov_b32_e32 v54, v38
	v_mov_b32_e32 v55, v39
	s_waitcnt lgkmcnt(8)
	v_mov_b32_e32 v36, v28
	v_mov_b32_e32 v37, v29
	v_mov_b32_e32 v38, v30
	v_mov_b32_e32 v39, v31
	s_nop 2
	v_mov_b32_e32 v28, v0
	v_mov_b32_e32 v29, v0
	v_mov_b32_e32 v168, v64
	v_mov_b32_e32 v169, v65
	v_mov_b32_e32 v170, v66
	v_mov_b32_e32 v171, v67
	v_lshlrev_b32_e32 v30, 6, v102
	v_mov_b32_e32 v64, v24
	v_mov_b32_e32 v65, v25
	v_mov_b32_e32 v66, v26
	v_mov_b32_e32 v67, v27
	v_and_b32_e32 v31, 14, v28
	s_nop 1
	v_ashrrev_i32_e32 v24, 1, v29
	v_mov_b32_e32 v184, v44
	v_mov_b32_e32 v185, v45
	v_mov_b32_e32 v186, v46
	v_mov_b32_e32 v187, v47
	v_and_b32_e32 v24, 0xffffffc0, v24
	v_add_u32_e32 v105, v24, v105
	v_lshrrev_b32_e32 v29, 1, v29
	v_mov_b32_e32 v44, v20
	v_mov_b32_e32 v45, v21
	v_mov_b32_e32 v46, v22
	v_mov_b32_e32 v47, v23
	v_and_b32_e32 v29, 32, v29
	s_nop 1
	v_lshrrev_b32_e32 v20, 2, v28
	v_and_b32_e32 v131, 12, v20
	v_mov_b32_e32 v20, v12
	v_mov_b32_e32 v21, v13
	v_mov_b32_e32 v22, v14
	v_mov_b32_e32 v23, v15
	s_nop 2
	v_lshl_or_b32 v12, v105, 1, v131
	v_ashrrev_i32_e32 v13, 31, v12
	v_lshl_add_u64 v[24:25], v[12:13], 2, s[40:41]
	v_mov_b32_e32 v12, v32
	v_mov_b32_e32 v13, v33
	v_mov_b32_e32 v14, v34
	v_mov_b32_e32 v15, v35
	s_nop 2
	global_load_dwordx4 v[32:35], v[24:25], off
	v_mov_b32_e32 v164, v68
	v_mov_b32_e32 v165, v69
	v_mov_b32_e32 v166, v70
	v_mov_b32_e32 v167, v71
	v_mov_b64_e32 v[108:109], s[84:85]
	s_waitcnt lgkmcnt(5)
	v_mov_b32_e32 v24, v76
	v_mov_b32_e32 v25, v77
	v_mov_b32_e32 v26, v78
	v_mov_b32_e32 v27, v79
	s_waitcnt lgkmcnt(4)
	v_mov_b32_e32 v68, v72
	v_mov_b32_e32 v69, v73
	v_mov_b32_e32 v70, v74
	v_mov_b32_e32 v71, v75
	s_nop 2
	v_and_b32_e32 v72, 1, v28
	v_lshl_or_b32 v102, v72, 1, v131
	v_mov_b32_e32 v172, v56
	v_mov_b32_e32 v173, v57
	v_mov_b32_e32 v174, v58
	v_mov_b32_e32 v175, v59
	v_or3_b32 v28, v29, v30, v31
	v_cmp_eq_u32_e32 vcc, 0, v72
	v_ashrrev_i32_e32 v29, 31, v28
	v_or_b32_e32 v56, v105, v102
	v_or_b32_e32 v73, 1, v56
	v_mad_i64_i32 v[30:31], s[38:39], v56, s24, v[108:109]
	v_mov_b32_e32 v56, v60
	v_mov_b32_e32 v57, v61
	v_mov_b32_e32 v58, v62
	v_mov_b32_e32 v59, v63
	v_lshlrev_b64 v[106:107], 1, v[28:29]
	s_waitcnt vmcnt(0)
	v_mul_f32_e32 v75, v25, v33
	v_mad_i64_i32 v[60:61], s[38:39], v73, s24, v[108:109]
	v_mul_f32_e32 v73, v24, v32
	v_mul_f32_e32 v133, v26, v34
	v_mul_f32_e32 v135, v27, v35
	v_mul_f32_e32 v24, 0xbfb8aa3b, v73
	v_mul_f32_e32 v25, 0xbfb8aa3b, v75
	v_mul_f32_e32 v26, 0xbfb8aa3b, v133
	v_mul_f32_e32 v27, 0xbfb8aa3b, v135
	v_exp_f32_e32 v24, v24
	v_exp_f32_e32 v25, v25
	v_exp_f32_e32 v26, v26
	v_exp_f32_e32 v27, v27
	v_add_f32_e32 v24, 1.0, v24
	v_add_f32_e32 v25, 1.0, v25
	v_add_f32_e32 v26, 1.0, v26
	v_add_f32_e32 v27, 1.0, v27
	v_mov_b32_e32 v180, v48
	v_mov_b32_e32 v181, v49
	v_mov_b32_e32 v182, v50
	v_mov_b32_e32 v183, v51
	v_lshl_add_u64 v[110:111], v[30:31], 0, v[106:107]
	v_mul_f32_e32 v68, v68, v32
	v_lshl_add_u64 v[112:113], v[60:61], 0, v[106:107]
	v_mov_b32_e32 v48, v40
	v_mov_b32_e32 v49, v41
	v_mov_b32_e32 v50, v42
	v_mov_b32_e32 v51, v43
	v_rcp_f32_e32 v137, v24
	v_rcp_f32_e32 v138, v25
	v_rcp_f32_e32 v139, v26
	s_waitcnt lgkmcnt(1)
	v_mov_b32_e32 v40, v164
	v_mov_b32_e32 v41, v165
	v_mov_b32_e32 v42, v166
	v_mov_b32_e32 v43, v167
	v_rcp_f32_e32 v140, v27
	v_mul_f32_e32 v73, v73, v137
	v_mul_f32_e32 v75, v75, v138
	v_mul_f32_e32 v133, v133, v139
	v_mul_f32_e32 v135, v135, v140
	s_nop 2
	v_mul_f32_e32 v74, v40, v32
	v_mul_f32_e32 v132, v41, v33
	v_mul_f32_e32 v134, v42, v34
	v_mul_f32_e32 v136, v43, v35
	v_mul_f32_e32 v73, v74, v73
	v_mul_f32_e32 v74, v132, v75
	v_mul_f32_e32 v75, v134, v133
	v_mul_f32_e32 v132, v136, v135
	v_mov_b32_dpp v133, v73 quad_perm:[1,0,3,2] row_mask:0xf bank_mask:0xf bound_ctrl:1
	v_mov_b32_dpp v134, v74 quad_perm:[1,0,3,2] row_mask:0xf bank_mask:0xf bound_ctrl:1
	v_mov_b32_dpp v135, v75 quad_perm:[1,0,3,2] row_mask:0xf bank_mask:0xf bound_ctrl:1
	v_mov_b32_dpp v136, v132 quad_perm:[1,0,3,2] row_mask:0xf bank_mask:0xf bound_ctrl:1
	v_cndmask_b32_e32 v72, v75, v133, vcc
	v_cndmask_b32_e32 v73, v135, v73, vcc
	v_cndmask_b32_e32 v75, v132, v134, vcc
	v_cndmask_b32_e32 v74, v136, v74, vcc
	v_add_u32_e32 v72, 0x8000, v72
	v_add_u32_e32 v73, 0x8000, v73
	v_add_u32_e32 v75, 0x8000, v75
	v_add_u32_e32 v74, 0x8000, v74
	v_perm_b32 v72, v72, v73, s25
	v_perm_b32 v73, v75, v74, s25
	global_store_dword v[110:111], v72, off
	global_store_dword v[112:113], v73, off
	v_mov_b32_e32 v72, v52
	v_mov_b32_e32 v73, v53
	v_mov_b32_e32 v74, v54
	v_mov_b32_e32 v75, v55
	v_mul_f32_e32 v69, v69, v33
	s_nop 1
	v_mul_f32_e32 v52, 0xbfb8aa3b, v68
	v_exp_f32_e32 v132, v52
	s_waitcnt lgkmcnt(0)
; DEVINL float siluf_(float x) { return x * __builtin_amdgcn_rcpf(1.f + __expf(-x)); }
; DEVINL int ridx(int r) { return ((r >> 4) << 5) | (r & 15); }
; DEVINL void p6_tile(const Params& p, char* smem, int mt, int nt) {
;     ...
;   for (int mf = 0; mf < 4; ++mf) {
;     const int rb = m0 + wr * 64 + mf * 16 + (lane >> 4) * 4;
;     float rs[4];
; #pragma unroll
;     for (int j = 0; j < 4; ++j) rs[j] = rstd1[ridx(rb) + j];
; #pragma unroll
;     for (int nf = 0; nf < 2; ++nf) {
;       const int hid = nt * 64 + wc * 32 + nf * 16 + (lane & 15);
;       float a[4];
; #pragma unroll
;       for (int j = 0; j < 4; ++j) {
;         float g = acc[mf][nf][j] * rs[j], u = acc[mf][nf + 2][j] * rs[j];
;         a[j] = siluf_(g) * u;
;       }
;       store_pairs(actb, DFF, rb, hid, a[0], a[1], a[2], a[3]);
;     }
	v_mov_b32_e32 v52, v36
	v_mov_b32_e32 v53, v37
	v_mov_b32_e32 v54, v38
	v_mov_b32_e32 v55, v39
	s_nop 2
	v_mul_f32_e32 v36, 0xbfb8aa3b, v69
	v_mov_b32_e32 v24, v184
	v_mov_b32_e32 v25, v185
	v_mov_b32_e32 v26, v186
	v_mov_b32_e32 v27, v187
	v_exp_f32_e32 v88, v36
	v_mov_b32_e32 v36, v64
	v_mov_b32_e32 v37, v65
	v_mov_b32_e32 v38, v66
	v_mov_b32_e32 v39, v67
	s_nop 2
	v_add_f32_e32 v64, 1.0, v132
	v_mov_b32_e32 v76, v168
	v_mov_b32_e32 v77, v169
	v_mov_b32_e32 v78, v170
	v_mov_b32_e32 v79, v171
	v_rcp_f32_e32 v64, v64
	v_add_f32_e32 v65, 1.0, v88
	v_rcp_f32_e32 v65, v65
	v_mul_f32_e32 v66, v71, v35
	v_mul_f32_e32 v64, v68, v64
	s_nop 2
	v_mul_f32_e32 v32, v76, v32
	v_mul_f32_e32 v32, v32, v64
	v_mul_f32_e32 v33, v77, v33
	v_mul_f32_e32 v64, v69, v65
	v_mul_f32_e32 v33, v33, v64
	v_mul_f32_e32 v64, v70, v34
	v_mul_f32_e32 v65, 0xbfb8aa3b, v64
	v_exp_f32_e32 v65, v65
	v_mul_f32_e32 v67, 0xbfb8aa3b, v66
	v_exp_f32_e32 v67, v67
	v_mul_f32_e32 v34, v78, v34
	v_add_f32_e32 v65, 1.0, v65
	v_rcp_f32_e32 v65, v65
	v_add_f32_e32 v67, 1.0, v67
	v_rcp_f32_e32 v67, v67
	v_mul_f32_e32 v35, v79, v35
	v_mul_f32_e32 v64, v64, v65
	v_mul_f32_e32 v34, v34, v64
	v_mul_f32_e32 v64, v66, v67
	v_mul_f32_e32 v35, v35, v64
	v_mov_b32_dpp v66, v34 quad_perm:[1,0,3,2] row_mask:0xf bank_mask:0xf bound_ctrl:1
	v_mov_b32_dpp v64, v32 quad_perm:[1,0,3,2] row_mask:0xf bank_mask:0xf bound_ctrl:1
	v_cndmask_b32_e32 v34, v34, v64, vcc
	v_cndmask_b32_e32 v32, v66, v32, vcc
	v_mov_b32_dpp v65, v33 quad_perm:[1,0,3,2] row_mask:0xf bank_mask:0xf bound_ctrl:1
	v_mov_b32_dpp v67, v35 quad_perm:[1,0,3,2] row_mask:0xf bank_mask:0xf bound_ctrl:1
	v_add_u32_e32 v34, 0x8000, v34
	v_add_u32_e32 v32, 0x8000, v32
	v_perm_b32 v32, v34, v32, s25
	v_cndmask_b32_e32 v34, v35, v65, vcc
	v_cndmask_b32_e32 v33, v67, v33, vcc
	v_add_u32_e32 v34, 0x8000, v34
	v_add_u32_e32 v33, 0x8000, v33
	v_or_b32_e32 v68, 16, v105
	v_perm_b32 v33, v34, v33, s25
	global_store_dword v[110:111], v32, off offset:32
	global_store_dword v[112:113], v33, off offset:32
	v_lshl_or_b32 v32, v68, 1, v131
	v_ashrrev_i32_e32 v33, 31, v32
	v_lshl_add_u64 v[32:33], v[32:33], 2, s[40:41]
	global_load_dwordx4 v[64:67], v[32:33], off
	v_mov_b32_e32 v60, v176
	v_mov_b32_e32 v61, v177
	v_mov_b32_e32 v62, v178
	v_mov_b32_e32 v63, v179
	v_mov_b32_e32 v32, v44
	v_mov_b32_e32 v33, v45
	v_mov_b32_e32 v34, v46
	v_mov_b32_e32 v35, v47
	s_nop 2
	v_or_b32_e32 v44, v68, v102
	v_mad_i64_i32 v[68:69], s[38:39], v44, s24, v[108:109]
	v_or_b32_e32 v44, 1, v44
	v_mad_i64_i32 v[70:71], s[38:39], v44, s24, v[108:109]
	v_mov_b32_e32 v28, v172
	v_mov_b32_e32 v29, v173
	v_mov_b32_e32 v30, v174
	v_mov_b32_e32 v31, v175
	s_waitcnt vmcnt(0)
	v_mov_b32_e32 v44, v65
	v_mov_b32_e32 v45, v66
	v_mul_f32_e32 v47, v56, v64
	v_mul_f32_e32 v56, v60, v64
	v_mul_f32_e32 v60, 0xbfb8aa3b, v47
	v_mul_f32_e32 v57, v57, v44
	v_mul_f32_e32 v58, v58, v45
	v_mov_b32_e32 v46, v67
	v_exp_f32_e32 v60, v60
	v_mul_f32_e32 v65, 0xbfb8aa3b, v57
	v_mul_f32_e32 v66, 0xbfb8aa3b, v58
	v_mul_f32_e32 v59, v59, v46
	v_exp_f32_e32 v65, v65
	v_exp_f32_e32 v66, v66
	v_mul_f32_e32 v67, 0xbfb8aa3b, v59
	v_exp_f32_e32 v67, v67
	v_add_f32_e32 v60, 1.0, v60
	v_rcp_f32_e32 v60, v60
	v_add_f32_e32 v65, 1.0, v65
	v_add_f32_e32 v66, 1.0, v66
	v_rcp_f32_e32 v65, v65
	v_rcp_f32_e32 v66, v66
	v_add_f32_e32 v67, 1.0, v67
	v_rcp_f32_e32 v67, v67
	v_mul_f32_e32 v47, v47, v60
	v_mul_f32_e32 v62, v62, v45
	v_mul_f32_e32 v47, v56, v47
	v_mul_f32_e32 v56, v57, v65
	v_mul_f32_e32 v57, v58, v66
	v_mul_f32_e32 v61, v61, v44
	v_mul_f32_e32 v57, v62, v57
	v_mul_f32_e32 v63, v63, v46
	v_mul_f32_e32 v56, v61, v56
	v_mul_f32_e32 v58, v59, v67
	v_mov_b32_dpp v59, v47 quad_perm:[1,0,3,2] row_mask:0xf bank_mask:0xf bound_ctrl:1
	v_mov_b32_dpp v61, v57 quad_perm:[1,0,3,2] row_mask:0xf bank_mask:0xf bound_ctrl:1
	v_mul_f32_e32 v58, v63, v58
	v_cndmask_b32_e32 v57, v57, v59, vcc
	v_cndmask_b32_e32 v47, v61, v47, vcc
	v_mov_b32_dpp v60, v56 quad_perm:[1,0,3,2] row_mask:0xf bank_mask:0xf bound_ctrl:1
	v_mov_b32_dpp v62, v58 quad_perm:[1,0,3,2] row_mask:0xf bank_mask:0xf bound_ctrl:1
	v_add_u32_e32 v57, 0x8000, v57
	v_add_u32_e32 v47, 0x8000, v47
	v_perm_b32 v47, v57, v47, s25
	v_cndmask_b32_e32 v57, v58, v60, vcc
	v_cndmask_b32_e32 v56, v62, v56, vcc
	v_add_u32_e32 v57, 0x8000, v57
	v_add_u32_e32 v56, 0x8000, v56
	v_perm_b32 v60, v57, v56, s25
	v_lshl_add_u64 v[56:57], v[68:69], 0, v[106:107]
	v_mul_f32_e32 v28, v28, v64
	global_store_dword v[56:57], v47, off
	v_lshl_add_u64 v[58:59], v[70:71], 0, v[106:107]
	v_mul_f32_e32 v47, 0xbfb8aa3b, v28
	v_mul_f32_e32 v29, v29, v44
	global_store_dword v[58:59], v60, off
	v_exp_f32_e32 v47, v47
	v_mul_f32_e32 v60, 0xbfb8aa3b, v29
	v_exp_f32_e32 v60, v60
	v_mov_b32_e32 v40, v180
	v_mov_b32_e32 v41, v181
	v_mov_b32_e32 v42, v182
	v_mov_b32_e32 v43, v183
	v_add_f32_e32 v47, 1.0, v47
	v_rcp_f32_e32 v47, v47
	v_add_f32_e32 v60, 1.0, v60
	v_rcp_f32_e32 v60, v60
	v_mul_f32_e32 v30, v30, v45
	s_nop 2
	v_mul_f32_e32 v40, v40, v64
	v_mul_f32_e32 v28, v28, v47
	v_mul_f32_e32 v28, v40, v28
	v_mul_f32_e32 v40, v41, v44
	v_mul_f32_e32 v29, v29, v60
	v_mul_f32_e32 v29, v40, v29
	v_mul_f32_e32 v40, 0xbfb8aa3b, v30
	v_mul_f32_e32 v31, v31, v46
	v_exp_f32_e32 v40, v40
	v_mul_f32_e32 v41, 0xbfb8aa3b, v31
	v_exp_f32_e32 v41, v41
	v_mul_f32_e32 v42, v42, v45
	v_add_f32_e32 v40, 1.0, v40
	v_rcp_f32_e32 v40, v40
	v_add_f32_e32 v41, 1.0, v41
	v_rcp_f32_e32 v41, v41
	v_mov_b32_e32 v16, v20
	v_mov_b32_e32 v17, v21
	v_mov_b32_e32 v18, v22
	v_mov_b32_e32 v19, v23
	v_mul_f32_e32 v30, v30, v40
	v_mul_f32_e32 v30, v42, v30
	v_mul_f32_e32 v40, v43, v46
	v_mul_f32_e32 v31, v31, v41
	v_mul_f32_e32 v31, v40, v31
	v_mov_b32_dpp v40, v28 quad_perm:[1,0,3,2] row_mask:0xf bank_mask:0xf bound_ctrl:1
	v_mov_b32_dpp v42, v30 quad_perm:[1,0,3,2] row_mask:0xf bank_mask:0xf bound_ctrl:1
	v_cndmask_b32_e32 v30, v30, v40, vcc
	v_cndmask_b32_e32 v28, v42, v28, vcc
	v_mov_b32_dpp v41, v29 quad_perm:[1,0,3,2] row_mask:0xf bank_mask:0xf bound_ctrl:1
	v_mov_b32_dpp v43, v31 quad_perm:[1,0,3,2] row_mask:0xf bank_mask:0xf bound_ctrl:1
	v_add_u32_e32 v30, 0x8000, v30
	v_add_u32_e32 v28, 0x8000, v28
	v_perm_b32 v28, v30, v28, s25
	v_cndmask_b32_e32 v30, v31, v41, vcc
	v_cndmask_b32_e32 v29, v43, v29, vcc
	v_add_u32_e32 v30, 0x8000, v30
	v_add_u32_e32 v29, 0x8000, v29
	v_or_b32_e32 v40, 32, v105
	v_perm_b32 v29, v30, v29, s25
	global_store_dword v[56:57], v28, off offset:32
	global_store_dword v[58:59], v29, off offset:32
	v_lshl_or_b32 v28, v40, 1, v131
	v_ashrrev_i32_e32 v29, 31, v28
	v_lshl_add_u64 v[28:29], v[28:29], 2, s[40:41]
	global_load_dwordx4 v[28:31], v[28:29], off
	v_or_b32_e32 v20, v40, v102
	v_mad_i64_i32 v[40:41], s[38:39], v20, s24, v[108:109]
	v_or_b32_e32 v20, 1, v20
	v_mad_i64_i32 v[42:43], s[38:39], v20, s24, v[108:109]
	v_mov_b32_e32 v4, v12
	v_mov_b32_e32 v5, v13
	v_mov_b32_e32 v6, v14
	v_mov_b32_e32 v7, v15
	s_waitcnt vmcnt(0)
; DEVINL float siluf_(float x) { return x * __builtin_amdgcn_rcpf(1.f + __expf(-x)); }
; DEVINL int ridx(int r) { return ((r >> 4) << 5) | (r & 15); }
; DEVINL void p6_tile(const Params& p, char* smem, int mt, int nt) {
;     ...
;   for (int mf = 0; mf < 4; ++mf) {
;     const int rb = m0 + wr * 64 + mf * 16 + (lane >> 4) * 4;
;     float rs[4];
; #pragma unroll
;     for (int j = 0; j < 4; ++j) rs[j] = rstd1[ridx(rb) + j];
; #pragma unroll
;     for (int nf = 0; nf < 2; ++nf) {
;       const int hid = nt * 64 + wc * 32 + nf * 16 + (lane & 15);
;       float a[4];
; #pragma unroll
;       for (int j = 0; j < 4; ++j) {
;         float g = acc[mf][nf][j] * rs[j], u = acc[mf][nf + 2][j] * rs[j];
;         a[j] = siluf_(g) * u;
;       }
;       store_pairs(actb, DFF, rb, hid, a[0], a[1], a[2], a[3]);
;     }
	v_mov_b32_e32 v20, v29
	v_mul_f32_e32 v23, v24, v28
	v_mov_b32_e32 v21, v30
	v_mov_b32_e32 v22, v31
	v_mul_f32_e32 v29, 0xbfb8aa3b, v23
	v_mul_f32_e32 v25, v25, v20
	v_exp_f32_e32 v29, v29
	v_mul_f32_e32 v31, 0xbfb8aa3b, v25
	v_exp_f32_e32 v31, v31
	v_mul_f32_e32 v26, v26, v21
	v_add_f32_e32 v29, 1.0, v29
	v_rcp_f32_e32 v29, v29
	v_add_f32_e32 v31, 1.0, v31
	v_rcp_f32_e32 v31, v31
	v_mul_f32_e32 v24, v72, v28
	v_mul_f32_e32 v44, 0xbfb8aa3b, v26
	v_mul_f32_e32 v23, v23, v29
	v_mul_f32_e32 v27, v27, v22
	v_mul_f32_e32 v23, v24, v23
	v_mul_f32_e32 v24, v25, v31
	v_exp_f32_e32 v25, v44
	v_mul_f32_e32 v29, 0xbfb8aa3b, v27
	v_exp_f32_e32 v29, v29
	v_mul_f32_e32 v30, v73, v20
	v_add_f32_e32 v25, 1.0, v25
	v_rcp_f32_e32 v25, v25
	v_add_f32_e32 v29, 1.0, v29
	v_rcp_f32_e32 v29, v29
	v_mul_f32_e32 v24, v30, v24
	v_mul_f32_e32 v30, v74, v21
	v_mul_f32_e32 v25, v26, v25
	v_mul_f32_e32 v25, v30, v25
	v_mul_f32_e32 v26, v75, v22
	v_mul_f32_e32 v27, v27, v29
	v_mul_f32_e32 v26, v26, v27
	v_mov_b32_dpp v30, v25 quad_perm:[1,0,3,2] row_mask:0xf bank_mask:0xf bound_ctrl:1
	v_mov_b32_dpp v27, v23 quad_perm:[1,0,3,2] row_mask:0xf bank_mask:0xf bound_ctrl:1
	v_cndmask_b32_e32 v25, v25, v27, vcc
	v_cndmask_b32_e32 v23, v30, v23, vcc
	v_mov_b32_dpp v29, v24 quad_perm:[1,0,3,2] row_mask:0xf bank_mask:0xf bound_ctrl:1
	v_mov_b32_dpp v31, v26 quad_perm:[1,0,3,2] row_mask:0xf bank_mask:0xf bound_ctrl:1
	v_add_u32_e32 v25, 0x8000, v25
	v_add_u32_e32 v23, 0x8000, v23
	v_perm_b32 v23, v25, v23, s25
	v_cndmask_b32_e32 v25, v26, v29, vcc
	v_cndmask_b32_e32 v24, v31, v24, vcc
	v_add_u32_e32 v25, 0x8000, v25
	v_add_u32_e32 v24, 0x8000, v24
	v_perm_b32 v29, v25, v24, s25
	v_lshl_add_u64 v[24:25], v[40:41], 0, v[106:107]
	global_store_dword v[24:25], v23, off
	v_lshl_add_u64 v[26:27], v[42:43], 0, v[106:107]
	v_mul_f32_e32 v23, v48, v28
	global_store_dword v[26:27], v29, off
	v_mul_f32_e32 v29, 0xbfb8aa3b, v23
	v_mul_f32_e32 v30, v49, v20
	v_exp_f32_e32 v29, v29
	v_mul_f32_e32 v31, 0xbfb8aa3b, v30
	v_exp_f32_e32 v31, v31
	v_mul_f32_e32 v28, v52, v28
	v_add_f32_e32 v29, 1.0, v29
	v_rcp_f32_e32 v29, v29
	v_add_f32_e32 v31, 1.0, v31
	v_rcp_f32_e32 v31, v31
	v_mul_f32_e32 v20, v53, v20
	v_mul_f32_e32 v23, v23, v29
	v_mul_f32_e32 v23, v28, v23
	v_mul_f32_e32 v28, v30, v31
	v_mul_f32_e32 v20, v20, v28
	v_mul_f32_e32 v28, v50, v21
	v_mul_f32_e32 v29, 0xbfb8aa3b, v28
	v_mul_f32_e32 v30, v51, v22
	v_exp_f32_e32 v29, v29
	v_mul_f32_e32 v31, 0xbfb8aa3b, v30
	v_exp_f32_e32 v31, v31
	v_mul_f32_e32 v21, v54, v21
	v_add_f32_e32 v29, 1.0, v29
	v_rcp_f32_e32 v29, v29
	v_add_f32_e32 v31, 1.0, v31
	v_rcp_f32_e32 v31, v31
	v_mul_f32_e32 v22, v55, v22
	v_mul_f32_e32 v28, v28, v29
	v_mul_f32_e32 v21, v21, v28
	v_mul_f32_e32 v28, v30, v31
	v_mul_f32_e32 v22, v22, v28
	v_mov_b32_dpp v30, v21 quad_perm:[1,0,3,2] row_mask:0xf bank_mask:0xf bound_ctrl:1
	v_mov_b32_dpp v28, v23 quad_perm:[1,0,3,2] row_mask:0xf bank_mask:0xf bound_ctrl:1
	v_mov_b32_dpp v29, v20 quad_perm:[1,0,3,2] row_mask:0xf bank_mask:0xf bound_ctrl:1
	v_mov_b32_dpp v31, v22 quad_perm:[1,0,3,2] row_mask:0xf bank_mask:0xf bound_ctrl:1
	v_cndmask_b32_e32 v21, v21, v28, vcc
	v_cndmask_b32_e32 v23, v30, v23, vcc
	v_add_u32_e32 v21, 0x8000, v21
	v_add_u32_e32 v23, 0x8000, v23
	v_cndmask_b32_e32 v22, v22, v29, vcc
	v_cndmask_b32_e32 v20, v31, v20, vcc
	v_perm_b32 v21, v21, v23, s25
	v_add_u32_e32 v22, 0x8000, v22
	v_add_u32_e32 v20, 0x8000, v20
	v_perm_b32 v20, v22, v20, s25
	global_store_dword v[24:25], v21, off offset:32
	global_store_dword v[26:27], v20, off offset:32
	v_or_b32_e32 v24, 48, v105
	v_lshl_or_b32 v20, v24, 1, v131
	v_ashrrev_i32_e32 v21, 31, v20
	v_lshl_add_u64 v[20:21], v[20:21], 2, s[40:41]
	global_load_dwordx4 v[20:23], v[20:21], off
	v_or_b32_e32 v11, v24, v102
	v_mad_i64_i32 v[12:13], s[38:39], v11, s24, v[108:109]
	v_or_b32_e32 v11, 1, v11
	v_mad_i64_i32 v[14:15], s[38:39], v11, s24, v[108:109]
	v_lshl_add_u64 v[12:13], v[12:13], 0, v[106:107]
	v_lshl_add_u64 v[14:15], v[14:15], 0, v[106:107]
	s_waitcnt vmcnt(0)
; DEVINL float siluf_(float x) { return x * __builtin_amdgcn_rcpf(1.f + __expf(-x)); }
; DEVINL int ridx(int r) { return ((r >> 4) << 5) | (r & 15); }
; DEVINL void p6_tile(const Params& p, char* smem, int mt, int nt) {
;     ...
;   for (int mf = 0; mf < 4; ++mf) {
;     const int rb = m0 + wr * 64 + mf * 16 + (lane >> 4) * 4;
;     float rs[4];
; #pragma unroll
;     for (int j = 0; j < 4; ++j) rs[j] = rstd1[ridx(rb) + j];
; #pragma unroll
;     for (int nf = 0; nf < 2; ++nf) {
;       const int hid = nt * 64 + wc * 32 + nf * 16 + (lane & 15);
;       float a[4];
; #pragma unroll
;       for (int j = 0; j < 4; ++j) {
;         float g = acc[mf][nf][j] * rs[j], u = acc[mf][nf + 2][j] * rs[j];
;         a[j] = siluf_(g) * u;
;       }
;       store_pairs(actb, DFF, rb, hid, a[0], a[1], a[2], a[3]);
;     }
;   }
; template <class F>
; DEVINL void gemm_phase(int NT, F&& f) {
;     ...
;   for (int u = u0 + j; u < u1; u += nbx) {
;     const int band = u / (8 * MT), v = u - band * 8 * MT;
;     const int w = min(8, NT - band * 8);
;     f(v / w, band * 8 + v % w);
	v_mov_b32_e32 v8, v21
	v_mul_f32_e32 v11, v36, v20
	v_mov_b32_e32 v9, v22
	v_mov_b32_e32 v10, v23
	v_mul_f32_e32 v21, 0xbfb8aa3b, v11
	v_mul_f32_e32 v22, v37, v8
	v_exp_f32_e32 v21, v21
	v_mul_f32_e32 v23, 0xbfb8aa3b, v22
	v_exp_f32_e32 v23, v23
	v_mul_f32_e32 v16, v16, v20
	v_add_f32_e32 v21, 1.0, v21
	v_rcp_f32_e32 v21, v21
	v_add_f32_e32 v23, 1.0, v23
	v_rcp_f32_e32 v23, v23
	v_mul_f32_e32 v18, v18, v9
	v_mul_f32_e32 v11, v11, v21
	v_mul_f32_e32 v11, v16, v11
	v_mul_f32_e32 v16, v17, v8
	v_mul_f32_e32 v17, v22, v23
	v_mul_f32_e32 v16, v16, v17
	v_mul_f32_e32 v17, v38, v9
	v_mul_f32_e32 v21, 0xbfb8aa3b, v17
	v_mul_f32_e32 v22, v39, v10
	v_exp_f32_e32 v21, v21
	v_mul_f32_e32 v23, 0xbfb8aa3b, v22
	v_exp_f32_e32 v23, v23
	v_mul_f32_e32 v5, v5, v8
	v_add_f32_e32 v21, 1.0, v21
	v_rcp_f32_e32 v21, v21
	v_add_f32_e32 v23, 1.0, v23
	v_rcp_f32_e32 v23, v23
	v_mul_f32_e32 v4, v4, v20
	v_mul_f32_e32 v17, v17, v21
	v_mul_f32_e32 v17, v18, v17
	v_mul_f32_e32 v18, v19, v10
	v_mul_f32_e32 v19, v22, v23
	v_mul_f32_e32 v18, v18, v19
	v_mov_b32_dpp v22, v17 quad_perm:[1,0,3,2] row_mask:0xf bank_mask:0xf bound_ctrl:1
	v_mov_b32_dpp v19, v11 quad_perm:[1,0,3,2] row_mask:0xf bank_mask:0xf bound_ctrl:1
	v_cndmask_b32_e32 v17, v17, v19, vcc
	v_cndmask_b32_e32 v11, v22, v11, vcc
	v_mov_b32_dpp v21, v16 quad_perm:[1,0,3,2] row_mask:0xf bank_mask:0xf bound_ctrl:1
	v_mov_b32_dpp v23, v18 quad_perm:[1,0,3,2] row_mask:0xf bank_mask:0xf bound_ctrl:1
	v_add_u32_e32 v17, 0x8000, v17
	v_add_u32_e32 v11, 0x8000, v11
	v_perm_b32 v11, v17, v11, s25
	v_cndmask_b32_e32 v17, v18, v21, vcc
	v_cndmask_b32_e32 v16, v23, v16, vcc
	v_add_u32_e32 v17, 0x8000, v17
	v_add_u32_e32 v16, 0x8000, v16
	v_perm_b32 v16, v17, v16, s25
	v_mul_f32_e32 v17, v33, v8
	global_store_dword v[12:13], v11, off
	v_mul_f32_e32 v11, v32, v20
	v_mul_f32_e32 v18, 0xbfb8aa3b, v17
	global_store_dword v[14:15], v16, off
	v_mul_f32_e32 v16, 0xbfb8aa3b, v11
	v_exp_f32_e32 v18, v18
	v_exp_f32_e32 v16, v16
	v_mul_f32_e32 v6, v6, v9
	v_mul_f32_e32 v7, v7, v10
	v_add_f32_e32 v18, 1.0, v18
	v_add_f32_e32 v16, 1.0, v16
	v_rcp_f32_e32 v18, v18
	v_rcp_f32_e32 v16, v16
	v_mul_f32_e32 v8, v17, v18
	v_mul_f32_e32 v11, v11, v16
	v_mul_f32_e32 v5, v5, v8
	v_mul_f32_e32 v8, v34, v9
	v_mul_f32_e32 v4, v4, v11
	v_mul_f32_e32 v11, 0xbfb8aa3b, v8
	v_mul_f32_e32 v16, v35, v10
	v_exp_f32_e32 v11, v11
	v_mul_f32_e32 v17, 0xbfb8aa3b, v16
	v_exp_f32_e32 v17, v17
	v_add_f32_e32 v11, 1.0, v11
	v_rcp_f32_e32 v11, v11
	v_add_f32_e32 v9, 1.0, v17
	v_rcp_f32_e32 v9, v9
	v_mul_f32_e32 v8, v8, v11
	v_mul_f32_e32 v6, v6, v8
	v_mul_f32_e32 v8, v16, v9
	v_mul_f32_e32 v7, v7, v8
	v_mov_b32_dpp v10, v6 quad_perm:[1,0,3,2] row_mask:0xf bank_mask:0xf bound_ctrl:1
	v_mov_b32_dpp v8, v4 quad_perm:[1,0,3,2] row_mask:0xf bank_mask:0xf bound_ctrl:1
	v_cndmask_b32_e32 v6, v6, v8, vcc
	v_cndmask_b32_e32 v4, v10, v4, vcc
	v_mov_b32_dpp v9, v5 quad_perm:[1,0,3,2] row_mask:0xf bank_mask:0xf bound_ctrl:1
	v_mov_b32_dpp v11, v7 quad_perm:[1,0,3,2] row_mask:0xf bank_mask:0xf bound_ctrl:1
	v_add_u32_e32 v6, 0x8000, v6
	v_add_u32_e32 v4, 0x8000, v4
	v_perm_b32 v4, v6, v4, s25
	v_cndmask_b32_e32 v6, v7, v9, vcc
	v_cndmask_b32_e32 v5, v11, v5, vcc
	v_add_u32_e32 v6, 0x8000, v6
	v_add_u32_e32 v5, 0x8000, v5
	v_cmp_le_i32_e32 vcc, s0, v3
	v_perm_b32 v5, v6, v5, s25
	s_or_b64 s[36:37], vcc, s[36:37]
	global_store_dword v[12:13], v4, off offset:32
	global_store_dword v[14:15], v5, off offset:32
	s_cmp_eq_u32 s101, 0
	s_cbranch_scc0 .Ldt_b116_latch2
	s_mov_b32 s101, 1
	v_subrev_u32_e32 v3, 127, v3
	s_branch .LBB0_115
.Ldt_b116_latch2:
	s_mov_b32 s101, 0
	v_subrev_u32_e32 v3, 1, v3
	s_andn2_b64 exec, exec, s[36:37]
	s_cbranch_execnz .LBB0_115
	s_or_b64 exec, exec, s[36:37]

; DEVINL f32x4 mfma16(bf16x8 a, bf16x8 b, f32x4 c) { return __builtin_amdgcn_mfma_f32_16x16x32_bf16(a, b, c, 0, 0, 0); }
; DEVINL void gemm_loop(f32x4 (&acc)[4][4], const u16* __restrict__ A, int lda, const u16* __restrict__ Bt, int ldb,
;                       int m0, int n0, int k0, int nk, char* smem) {
;     ...
;   for (int kt = 0; kt < nk; ++kt) {
;     __syncthreads();
;     char* cur = smem + (kt & 1) * 32768;
;     if (kt + 1 < nk) {
;       char* nxt = smem + ((kt + 1) & 1) * 32768;
; #pragma unroll
;       for (int i = 0; i < 4; ++i) {
;         glds16(ga[i] + (kt + 1) * 64, nxt + i * 4096 + wid * 1024);
;         glds16(gb[i] + (kt + 1) * 64, nxt + 16384 + i * 4096 + wid * 1024);
;       }
;     }
;     bf16x8 af[2][4], bfr[2][4];
; #pragma unroll
;     for (int ks = 0; ks < 2; ++ks)
; #pragma unroll
;       for (int f = 0; f < 4; ++f) {
;         int ra = wr * 64 + f * 16 + fr, rb = wc * 64 + f * 16 + fr;
;         int ch = ks * 4 + fq;
;         af[ks][f] = *(const bf16x8*)(cur + ra * 128 + ((ch ^ ((ra >> 1) & 7)) << 4));
;         bfr[ks][f] = *(const bf16x8*)(cur + 16384 + rb * 128 + ((ch ^ ((rb >> 1) & 7)) << 4));
;       }
;     __builtin_amdgcn_sched_barrier(0);
; #pragma unroll
;     for (int ks = 0; ks < 2; ++ks)
; #pragma unroll
;       for (int mf = 0; mf < 4; ++mf)
; #pragma unroll
;         for (int nf = 0; nf < 4; ++nf) acc[mf][nf] = mfma16(af[ks][mf], bfr[ks][nf], acc[mf][nf]);
.LBB0_172:
	v_readfirstlane_b32 s100, v69
	v_add_u32_e32 v196, v89, v86
	v_add_u32_e32 v197, v89, v87
	v_add_u32_e32 v198, v88, v86
	v_add_u32_e32 v199, v88, v87
	s_mov_b32 s101, s100
	v_lshlrev_b32_e32 v202, 4, v0
	s_waitcnt vmcnt(0)
	s_barrier
	s_add_u32 m0, s100, 0x8000
	v_lshl_add_u64 v[200:201], v[70:71], 0, s[34:35]
	global_load_lds_dwordx4 v[200:201], off
	s_add_u32 m0, s100, 0xc000
	v_lshl_add_u64 v[200:201], v[72:73], 0, s[34:35]
	global_load_lds_dwordx4 v[200:201], off
	s_add_u32 m0, s100, 0x9000
	v_lshl_add_u64 v[200:201], v[74:75], 0, s[34:35]
	global_load_lds_dwordx4 v[200:201], off
	s_add_u32 m0, s100, 0xd000
	v_lshl_add_u64 v[200:201], v[76:77], 0, s[34:35]
	global_load_lds_dwordx4 v[200:201], off
	s_add_u32 m0, s100, 0xa000
	v_lshl_add_u64 v[200:201], v[78:79], 0, s[34:35]
	global_load_lds_dwordx4 v[200:201], off
	s_add_u32 m0, s100, 0xe000
	v_lshl_add_u64 v[200:201], v[80:81], 0, s[34:35]
	global_load_lds_dwordx4 v[200:201], off
	s_add_u32 m0, s100, 0xb000
	v_lshl_add_u64 v[200:201], v[82:83], 0, s[34:35]
	global_load_lds_dwordx4 v[200:201], off
	s_add_u32 m0, s100, 0xf000
	v_lshl_add_u64 v[200:201], v[84:85], 0, s[34:35]
	global_load_lds_dwordx4 v[200:201], off
	ds_read_b128 v[106:109], v196
	ds_read_b128 v[110:113], v196 offset:2048
	ds_read_b128 v[132:135], v197 offset:16384
	ds_read_b128 v[136:139], v197 offset:18432
	ds_read_b128 v[140:143], v196 offset:4096
	ds_read_b128 v[144:147], v196 offset:6144
	ds_read_b128 v[148:151], v197 offset:20480
	ds_read_b128 v[152:155], v197 offset:22528
	ds_read_b128 v[156:159], v198
	ds_read_b128 v[160:163], v198 offset:2048
	ds_read_b128 v[164:167], v199 offset:16384
	ds_read_b128 v[168:171], v199 offset:18432
	ds_read_b128 v[172:175], v198 offset:4096
	ds_read_b128 v[176:179], v198 offset:6144
	ds_read_b128 v[180:183], v199 offset:20480
	ds_read_b128 v[184:187], v199 offset:22528
	s_waitcnt lgkmcnt(8)
	v_mfma_f32_16x16x32_bf16 v[64:67], v[106:109], v[132:135], v[64:67]
	v_mfma_f32_16x16x32_bf16 v[60:63], v[106:109], v[136:139], v[60:63]
	v_mfma_f32_16x16x32_bf16 v[52:55], v[106:109], v[148:151], v[52:55]
	v_mfma_f32_16x16x32_bf16 v[48:51], v[106:109], v[152:155], v[48:51]
	v_mfma_f32_16x16x32_bf16 v[44:47], v[110:113], v[132:135], v[44:47]
	v_mfma_f32_16x16x32_bf16 v[40:43], v[110:113], v[136:139], v[40:43]
	v_mfma_f32_16x16x32_bf16 v[36:39], v[110:113], v[148:151], v[36:39]
	v_mfma_f32_16x16x32_bf16 v[32:35], v[110:113], v[152:155], v[32:35]
	v_mfma_f32_16x16x32_bf16 v[28:31], v[140:143], v[132:135], v[28:31]
	v_mfma_f32_16x16x32_bf16 v[24:27], v[140:143], v[136:139], v[24:27]
	v_mfma_f32_16x16x32_bf16 v[20:23], v[140:143], v[148:151], v[20:23]
	v_mfma_f32_16x16x32_bf16 v[16:19], v[140:143], v[152:155], v[16:19]
	v_mfma_f32_16x16x32_bf16 v[12:15], v[144:147], v[132:135], v[12:15]
	v_mfma_f32_16x16x32_bf16 v[8:11], v[144:147], v[136:139], v[8:11]
	v_mfma_f32_16x16x32_bf16 v[4:7], v[144:147], v[148:151], v[4:7]
	v_mfma_f32_16x16x32_bf16 v[56:59], v[144:147], v[152:155], v[56:59]
	v_xor_b32_e32 v196, 0x8000, v196
	v_xor_b32_e32 v197, 0x8000, v197
	v_xor_b32_e32 v198, 0x8000, v198
	v_xor_b32_e32 v199, 0x8000, v199
	s_waitcnt vmcnt(0) lgkmcnt(0)
	s_barrier
.Lkp_b172_loop:
	s_add_u32 s34, s34, 0x80
	s_addc_u32 s35, s35, 0
	s_cmpk_eq_i32 s34, 0x380
	s_cbranch_scc1 .Lkp_b172_last
	v_mfma_f32_16x16x32_bf16 v[64:67], v[156:159], v[164:167], v[64:67]
	s_add_u32 m0, s101, 0x0
	v_lshl_add_u64 v[200:201], v[70:71], 0, s[34:35]
	global_load_lds_dwordx4 v[200:201], off
	v_mfma_f32_16x16x32_bf16 v[60:63], v[156:159], v[168:171], v[60:63]
	s_add_u32 m0, s101, 0x4000
	v_lshl_add_u64 v[200:201], v[72:73], 0, s[34:35]
	global_load_lds_dwordx4 v[200:201], off
	v_mfma_f32_16x16x32_bf16 v[52:55], v[156:159], v[180:183], v[52:55]
	s_add_u32 m0, s101, 0x1000
	v_lshl_add_u64 v[200:201], v[74:75], 0, s[34:35]
	global_load_lds_dwordx4 v[200:201], off
	v_mfma_f32_16x16x32_bf16 v[48:51], v[156:159], v[184:187], v[48:51]
	s_add_u32 m0, s101, 0x5000
	v_lshl_add_u64 v[200:201], v[76:77], 0, s[34:35]
	global_load_lds_dwordx4 v[200:201], off
	v_mfma_f32_16x16x32_bf16 v[44:47], v[160:163], v[164:167], v[44:47]
	s_add_u32 m0, s101, 0x2000
	v_lshl_add_u64 v[200:201], v[78:79], 0, s[34:35]
	global_load_lds_dwordx4 v[200:201], off
	ds_read_b128 v[106:109], v196
	v_mfma_f32_16x16x32_bf16 v[40:43], v[160:163], v[168:171], v[40:43]
	s_add_u32 m0, s101, 0x6000
	v_lshl_add_u64 v[200:201], v[80:81], 0, s[34:35]
	global_load_lds_dwordx4 v[200:201], off
	ds_read_b128 v[110:113], v196 offset:2048
	v_mfma_f32_16x16x32_bf16 v[36:39], v[160:163], v[180:183], v[36:39]
	s_add_u32 m0, s101, 0x3000
	v_lshl_add_u64 v[200:201], v[82:83], 0, s[34:35]
	global_load_lds_dwordx4 v[200:201], off
	ds_read_b128 v[132:135], v197 offset:16384
	v_mfma_f32_16x16x32_bf16 v[32:35], v[160:163], v[184:187], v[32:35]
	s_add_u32 m0, s101, 0x7000
	v_lshl_add_u64 v[200:201], v[84:85], 0, s[34:35]
	global_load_lds_dwordx4 v[200:201], off
	ds_read_b128 v[136:139], v197 offset:18432
	v_mfma_f32_16x16x32_bf16 v[28:31], v[172:175], v[164:167], v[28:31]
	ds_read_b128 v[140:143], v196 offset:4096
	v_mfma_f32_16x16x32_bf16 v[24:27], v[172:175], v[168:171], v[24:27]
	ds_read_b128 v[144:147], v196 offset:6144
	v_mfma_f32_16x16x32_bf16 v[20:23], v[172:175], v[180:183], v[20:23]
	ds_read_b128 v[148:151], v197 offset:20480
	v_mfma_f32_16x16x32_bf16 v[16:19], v[172:175], v[184:187], v[16:19]
	ds_read_b128 v[152:155], v197 offset:22528
	v_mfma_f32_16x16x32_bf16 v[12:15], v[176:179], v[164:167], v[12:15]
	v_mfma_f32_16x16x32_bf16 v[8:11], v[176:179], v[168:171], v[8:11]
	v_mfma_f32_16x16x32_bf16 v[4:7], v[176:179], v[180:183], v[4:7]
	v_mfma_f32_16x16x32_bf16 v[56:59], v[176:179], v[184:187], v[56:59]
	s_xor_b32 s101, s101, 0x8000
	s_waitcnt lgkmcnt(0)
; DEVINL f32x4 mfma16(bf16x8 a, bf16x8 b, f32x4 c) { return __builtin_amdgcn_mfma_f32_16x16x32_bf16(a, b, c, 0, 0, 0); }
; DEVINL void gemm_loop(f32x4 (&acc)[4][4], const u16* __restrict__ A, int lda, const u16* __restrict__ Bt, int ldb,
;                       int m0, int n0, int k0, int nk, char* smem) {
;     ...
;   for (int kt = 0; kt < nk; ++kt) {
;     __syncthreads();
;     char* cur = smem + (kt & 1) * 32768;
;     if (kt + 1 < nk) {
;       char* nxt = smem + ((kt + 1) & 1) * 32768;
; #pragma unroll
;       for (int i = 0; i < 4; ++i) {
;         glds16(ga[i] + (kt + 1) * 64, nxt + i * 4096 + wid * 1024);
;         glds16(gb[i] + (kt + 1) * 64, nxt + 16384 + i * 4096 + wid * 1024);
;       }
;     }
;     bf16x8 af[2][4], bfr[2][4];
; #pragma unroll
;     for (int ks = 0; ks < 2; ++ks)
; #pragma unroll
;       for (int f = 0; f < 4; ++f) {
;         int ra = wr * 64 + f * 16 + fr, rb = wc * 64 + f * 16 + fr;
;         int ch = ks * 4 + fq;
;         af[ks][f] = *(const bf16x8*)(cur + ra * 128 + ((ch ^ ((ra >> 1) & 7)) << 4));
;         bfr[ks][f] = *(const bf16x8*)(cur + 16384 + rb * 128 + ((ch ^ ((rb >> 1) & 7)) << 4));
;       }
;     __builtin_amdgcn_sched_barrier(0);
; #pragma unroll
;     for (int ks = 0; ks < 2; ++ks)
; #pragma unroll
;       for (int mf = 0; mf < 4; ++mf)
; #pragma unroll
;         for (int nf = 0; nf < 4; ++nf) acc[mf][nf] = mfma16(af[ks][mf], bfr[ks][nf], acc[mf][nf]);
	v_mfma_f32_16x16x32_bf16 v[64:67], v[106:109], v[132:135], v[64:67]
	ds_read_b128 v[156:159], v198
	v_mfma_f32_16x16x32_bf16 v[60:63], v[106:109], v[136:139], v[60:63]
	ds_read_b128 v[160:163], v198 offset:2048
	v_mfma_f32_16x16x32_bf16 v[52:55], v[106:109], v[148:151], v[52:55]
	ds_read_b128 v[164:167], v199 offset:16384
	v_mfma_f32_16x16x32_bf16 v[48:51], v[106:109], v[152:155], v[48:51]
	ds_read_b128 v[168:171], v199 offset:18432
	v_mfma_f32_16x16x32_bf16 v[44:47], v[110:113], v[132:135], v[44:47]
	ds_read_b128 v[172:175], v198 offset:4096
	v_mfma_f32_16x16x32_bf16 v[40:43], v[110:113], v[136:139], v[40:43]
	ds_read_b128 v[176:179], v198 offset:6144
	v_mfma_f32_16x16x32_bf16 v[36:39], v[110:113], v[148:151], v[36:39]
	ds_read_b128 v[180:183], v199 offset:20480
	v_mfma_f32_16x16x32_bf16 v[32:35], v[110:113], v[152:155], v[32:35]
	ds_read_b128 v[184:187], v199 offset:22528
	v_mfma_f32_16x16x32_bf16 v[28:31], v[140:143], v[132:135], v[28:31]
	v_mfma_f32_16x16x32_bf16 v[24:27], v[140:143], v[136:139], v[24:27]
	v_mfma_f32_16x16x32_bf16 v[20:23], v[140:143], v[148:151], v[20:23]
	v_mfma_f32_16x16x32_bf16 v[16:19], v[140:143], v[152:155], v[16:19]
	v_mfma_f32_16x16x32_bf16 v[12:15], v[144:147], v[132:135], v[12:15]
	v_mfma_f32_16x16x32_bf16 v[8:11], v[144:147], v[136:139], v[8:11]
	v_mfma_f32_16x16x32_bf16 v[4:7], v[144:147], v[148:151], v[4:7]
	v_mfma_f32_16x16x32_bf16 v[56:59], v[144:147], v[152:155], v[56:59]
	v_xor_b32_e32 v196, 0x8000, v196
	v_xor_b32_e32 v197, 0x8000, v197
	v_xor_b32_e32 v198, 0x8000, v198
	v_xor_b32_e32 v199, 0x8000, v199
	s_waitcnt vmcnt(0) lgkmcnt(0)
	s_barrier
	s_branch .Lkp_b172_loop
; DEVINL int tidx() { int t = threadIdx.x; asm volatile("" : "+v"(t)); return t; }
; DEVINL float lane_xor1(float v) { return dpp_f<0xB1>(v); }
; DEVINL f32x4 mfma16(bf16x8 a, bf16x8 b, f32x4 c) { return __builtin_amdgcn_mfma_f32_16x16x32_bf16(a, b, c, 0, 0, 0); }
; DEVINL void gemm_loop(f32x4 (&acc)[4][4], const u16* __restrict__ A, int lda, const u16* __restrict__ Bt, int ldb,
;                       int m0, int n0, int k0, int nk, char* smem) {
;     ...
;   for (int kt = 0; kt < nk; ++kt) {
;     __syncthreads();
;     char* cur = smem + (kt & 1) * 32768;
;     if (kt + 1 < nk) {
;       char* nxt = smem + ((kt + 1) & 1) * 32768;
; #pragma unroll
;       for (int i = 0; i < 4; ++i) {
;         glds16(ga[i] + (kt + 1) * 64, nxt + i * 4096 + wid * 1024);
;         glds16(gb[i] + (kt + 1) * 64, nxt + 16384 + i * 4096 + wid * 1024);
;       }
;     }
;     bf16x8 af[2][4], bfr[2][4];
; #pragma unroll
;     for (int ks = 0; ks < 2; ++ks)
; #pragma unroll
;       for (int f = 0; f < 4; ++f) {
;         int ra = wr * 64 + f * 16 + fr, rb = wc * 64 + f * 16 + fr;
;         int ch = ks * 4 + fq;
;         af[ks][f] = *(const bf16x8*)(cur + ra * 128 + ((ch ^ ((ra >> 1) & 7)) << 4));
;         bfr[ks][f] = *(const bf16x8*)(cur + 16384 + rb * 128 + ((ch ^ ((rb >> 1) & 7)) << 4));
;       }
;     __builtin_amdgcn_sched_barrier(0);
; #pragma unroll
;     for (int ks = 0; ks < 2; ++ks)
; #pragma unroll
;       for (int mf = 0; mf < 4; ++mf)
; #pragma unroll
;         for (int nf = 0; nf < 4; ++nf) acc[mf][nf] = mfma16(af[ks][mf], bfr[ks][nf], acc[mf][nf]);
; DEVINL void p4_tile(const Params& p, char* smem, int mt, int nt) {
;     ...
;   {
;     const int tid = tidx(), row = tid >> 1, half = tid & 1;
;     const float* ss5p = (const float*)(p.ws + OFF_SS5P);
;     float ssq = 0.f;
; #pragma unroll
;     for (int q = 0; q < 2; ++q) {
;       const float2 v = *(const float2*)(ss5p + ((size_t)(half * 2 + q) * M + m0 + row) * 2);
;       ssq += v.x + v.y;
;     }
;     ssq += lane_xor1(ssq);
;     __syncthreads();
;     float* rs5 = (float*)smem;
;     if (half == 0) rs5[row] = rsqrtf(ssq * (1.f / 512.f) + EPS);
.Lkp_b172_last:
	v_mfma_f32_16x16x32_bf16 v[64:67], v[156:159], v[164:167], v[64:67]
	v_mfma_f32_16x16x32_bf16 v[60:63], v[156:159], v[168:171], v[60:63]
	v_mfma_f32_16x16x32_bf16 v[52:55], v[156:159], v[180:183], v[52:55]
	v_mfma_f32_16x16x32_bf16 v[48:51], v[156:159], v[184:187], v[48:51]
	v_mfma_f32_16x16x32_bf16 v[44:47], v[160:163], v[164:167], v[44:47]
	v_mfma_f32_16x16x32_bf16 v[40:43], v[160:163], v[168:171], v[40:43]
	v_mfma_f32_16x16x32_bf16 v[36:39], v[160:163], v[180:183], v[36:39]
	v_mfma_f32_16x16x32_bf16 v[32:35], v[160:163], v[184:187], v[32:35]
	v_mfma_f32_16x16x32_bf16 v[28:31], v[172:175], v[164:167], v[28:31]
	v_mfma_f32_16x16x32_bf16 v[24:27], v[172:175], v[168:171], v[24:27]
	v_mfma_f32_16x16x32_bf16 v[20:23], v[172:175], v[180:183], v[20:23]
	v_mfma_f32_16x16x32_bf16 v[16:19], v[172:175], v[184:187], v[16:19]
	v_mfma_f32_16x16x32_bf16 v[12:15], v[176:179], v[164:167], v[12:15]
	v_mfma_f32_16x16x32_bf16 v[8:11], v[176:179], v[168:171], v[8:11]
	v_mfma_f32_16x16x32_bf16 v[4:7], v[176:179], v[180:183], v[4:7]
	v_mfma_f32_16x16x32_bf16 v[56:59], v[176:179], v[184:187], v[56:59]
	s_mov_b32 s1, 0x8000
	v_add_u32_e32 v69, s1, v89
	v_add_u32_e32 v89, v69, v86
	v_add_u32_e32 v69, v69, v87
	s_waitcnt vmcnt(0)
	s_barrier
	ds_read_b128 v[70:73], v89
	ds_read_b128 v[74:77], v89 offset:2048
	ds_read_b128 v[78:81], v69 offset:16384
	ds_read_b128 v[82:85], v69 offset:18432
	ds_read_b128 v[106:109], v89 offset:4096
	ds_read_b128 v[110:113], v89 offset:6144
	ds_read_b128 v[132:135], v69 offset:20480
	ds_read_b128 v[136:139], v69 offset:22528
	v_add_u32_e32 v69, s1, v88
	v_add_u32_e32 v90, v69, v86
	v_add_u32_e32 v69, v69, v87
	ds_read_b128 v[86:89], v90
	ds_read_b128 v[140:143], v90 offset:2048
	ds_read_b128 v[144:147], v69 offset:16384
	ds_read_b128 v[148:151], v69 offset:18432
	ds_read_b128 v[152:155], v90 offset:4096
	ds_read_b128 v[156:159], v90 offset:6144
	ds_read_b128 v[160:163], v69 offset:20480
	ds_read_b128 v[164:167], v69 offset:22528
	s_waitcnt lgkmcnt(13)
	v_mfma_f32_16x16x32_bf16 v[64:67], v[70:73], v[78:81], v[64:67]
	v_ashrrev_i32_e32 v69, 31, v68
	v_readlane_b32 s0, v194, 21
	s_mov_b32 s34, 0x8900
	s_waitcnt lgkmcnt(12)
	v_mfma_f32_16x16x32_bf16 v[60:63], v[70:73], v[82:85], v[60:63]
	v_readlane_b32 s1, v194, 22
	s_waitcnt lgkmcnt(9)
	v_mfma_f32_16x16x32_bf16 v[52:55], v[70:73], v[132:135], v[52:55]
	s_waitcnt lgkmcnt(8)
	v_mfma_f32_16x16x32_bf16 v[48:51], v[70:73], v[136:139], v[48:51]
	v_mfma_f32_16x16x32_bf16 v[36:39], v[74:77], v[132:135], v[36:39]
	v_mfma_f32_16x16x32_bf16 v[44:47], v[74:77], v[78:81], v[44:47]
	v_mfma_f32_16x16x32_bf16 v[40:43], v[74:77], v[82:85], v[40:43]
	v_mfma_f32_16x16x32_bf16 v[32:35], v[74:77], v[136:139], v[32:35]
	v_mfma_f32_16x16x32_bf16 v[72:75], v[106:109], v[78:81], v[28:31]
	v_mfma_f32_16x16x32_bf16 v[168:171], v[106:109], v[82:85], v[24:27]
	v_mfma_f32_16x16x32_bf16 v[172:175], v[106:109], v[132:135], v[20:23]
	v_mfma_f32_16x16x32_bf16 v[106:109], v[106:109], v[136:139], v[16:19]
	v_mfma_f32_16x16x32_bf16 v[76:79], v[110:113], v[78:81], v[12:15]
	v_mfma_f32_16x16x32_bf16 v[80:83], v[110:113], v[82:85], v[8:11]
	v_mfma_f32_16x16x32_bf16 v[132:135], v[110:113], v[132:135], v[4:7]
	s_waitcnt lgkmcnt(5)
	v_mfma_f32_16x16x32_bf16 v[4:7], v[86:89], v[144:147], v[64:67]
	s_waitcnt lgkmcnt(4)
	v_mfma_f32_16x16x32_bf16 v[8:11], v[86:89], v[148:151], v[60:63]
	s_waitcnt lgkmcnt(1)
	v_mfma_f32_16x16x32_bf16 v[12:15], v[86:89], v[160:163], v[52:55]
	s_waitcnt lgkmcnt(0)
	v_mfma_f32_16x16x32_bf16 v[16:19], v[86:89], v[164:167], v[48:51]
	v_mov_b32_e32 v86, v0
	v_mov_b32_e32 v88, v0
	v_mfma_f32_16x16x32_bf16 v[28:31], v[140:143], v[160:163], v[36:39]
	v_mov_b32_e32 v55, v2
	v_mfma_f32_16x16x32_bf16 v[20:23], v[140:143], v[144:147], v[44:47]
	s_nop 0
	v_mov_b32_e32 v36, v0
	s_nop 0
	v_ashrrev_i32_e32 v70, 1, v36
	v_and_b32_e32 v64, 1, v36
	v_ashrrev_i32_e32 v71, 31, v70
	v_lshl_add_u64 v[52:53], v[70:71], 0, v[68:69]
	v_mul_u32_u24_e32 v44, 0x8900, v64
	v_mov_b32_e32 v45, v2
	v_lshl_add_u64 v[48:49], v[52:53], 0, v[44:45]
	v_mad_u32_u24 v54, v64, s34, v122
	v_lshl_add_u64 v[48:49], v[48:49], 3, s[0:1]
	v_lshl_add_u64 v[52:53], v[52:53], 0, v[54:55]
	v_mfma_f32_16x16x32_bf16 v[110:113], v[110:113], v[136:139], v[56:59]
	v_cmp_eq_u32_e64 s[34:35], 0, v64
	s_nop 1
	global_load_dwordx2 v[56:57], v[48:49], off
	v_lshl_add_u64 v[58:59], v[52:53], 3, s[0:1]
	global_load_dwordx2 v[60:61], v[58:59], off
	v_mfma_f32_16x16x32_bf16 v[24:27], v[140:143], v[148:151], v[40:43]
	s_barrier
	v_mfma_f32_16x16x32_bf16 v[32:35], v[140:143], v[164:167], v[32:35]
	s_waitcnt vmcnt(1)
	v_add_f32_e32 v56, v56, v57
	v_add_f32_e32 v62, 0, v56
	s_waitcnt vmcnt(0)
	v_add_f32_e32 v60, v60, v61
	v_mfma_f32_16x16x32_bf16 v[36:39], v[152:155], v[144:147], v[72:75]
	v_add_f32_e32 v69, v62, v60
	v_mfma_f32_16x16x32_bf16 v[40:43], v[152:155], v[148:151], v[168:171]
	s_nop 0
	v_mov_b32_dpp v71, v69 quad_perm:[1,0,3,2] row_mask:0xf bank_mask:0xf bound_ctrl:1
	v_mfma_f32_16x16x32_bf16 v[44:47], v[152:155], v[160:163], v[172:175]
	v_mfma_f32_16x16x32_bf16 v[48:51], v[152:155], v[164:167], v[106:109]
	v_mfma_f32_16x16x32_bf16 v[52:55], v[156:159], v[144:147], v[76:79]
	v_mfma_f32_16x16x32_bf16 v[56:59], v[156:159], v[148:151], v[80:83]
	v_mfma_f32_16x16x32_bf16 v[60:63], v[156:159], v[160:163], v[132:135]
	v_mfma_f32_16x16x32_bf16 v[64:67], v[156:159], v[164:167], v[110:113]
	s_and_saveexec_b64 s[0:1], s[34:35]
	s_cbranch_execz .LBB0_175
	v_add_f32_e32 v69, v69, v71
	v_fmamk_f32 v69, v69, 0x3b000000, v93
	v_mul_f32_e32 v71, 0x4b800000, v69
	v_cmp_gt_f32_e64 s[34:35], s33, v69
	v_lshlrev_b32_e32 v70, 2, v70
	s_nop 0
	v_cndmask_b32_e64 v69, v69, v71, s[34:35]
	v_rsq_f32_e32 v69, v69
	s_nop 0
	v_mul_f32_e32 v71, 0x45800000, v69
	v_cndmask_b32_e64 v69, v69, v71, s[34:35]
	ds_write_b32 v70, v69

; DEVINL f32x4 mfma16(bf16x8 a, bf16x8 b, f32x4 c) { return __builtin_amdgcn_mfma_f32_16x16x32_bf16(a, b, c, 0, 0, 0); }
; DEVINL void gemm_loop(f32x4 (&acc)[4][4], const u16* __restrict__ A, int lda, const u16* __restrict__ Bt, int ldb,
;                       int m0, int n0, int k0, int nk, char* smem) {
;     ...
;   __syncthreads();
; #pragma unroll
;   for (int i = 0; i < 4; ++i) {
;     glds16(ga[i], smem + i * 4096 + wid * 1024);
;     glds16(gb[i], smem + 16384 + i * 4096 + wid * 1024);
;   }
;   for (int kt = 0; kt < nk; ++kt) {
;     __syncthreads();
;     char* cur = smem + (kt & 1) * 32768;
;     if (kt + 1 < nk) {
;       char* nxt = smem + ((kt + 1) & 1) * 32768;
; #pragma unroll
;       for (int i = 0; i < 4; ++i) {
;         glds16(ga[i] + (kt + 1) * 64, nxt + i * 4096 + wid * 1024);
;         glds16(gb[i] + (kt + 1) * 64, nxt + 16384 + i * 4096 + wid * 1024);
;       }
;     }
;     bf16x8 af[2][4], bfr[2][4];
; #pragma unroll
;     for (int ks = 0; ks < 2; ++ks)
; #pragma unroll
;       for (int f = 0; f < 4; ++f) {
;         int ra = wr * 64 + f * 16 + fr, rb = wc * 64 + f * 16 + fr;
;         int ch = ks * 4 + fq;
;         af[ks][f] = *(const bf16x8*)(cur + ra * 128 + ((ch ^ ((ra >> 1) & 7)) << 4));
;         bfr[ks][f] = *(const bf16x8*)(cur + 16384 + rb * 128 + ((ch ^ ((rb >> 1) & 7)) << 4));
;       }
;     __builtin_amdgcn_sched_barrier(0);
; #pragma unroll
;     for (int ks = 0; ks < 2; ++ks)
; #pragma unroll
;       for (int mf = 0; mf < 4; ++mf)
; #pragma unroll
;         for (int nf = 0; nf < 4; ++nf) acc[mf][nf] = mfma16(af[ks][mf], bfr[ks][nf], acc[mf][nf]);
;   }
.LBB0_176:
	v_readfirstlane_b32 s100, v89
	v_add_u32_e32 v196, v105, v90
	v_add_u32_e32 v197, v105, v91
	v_add_u32_e32 v198, v102, v90
	v_add_u32_e32 v199, v102, v91
	s_mov_b32 s101, s100
	v_lshlrev_b32_e32 v202, 4, v0
	s_waitcnt vmcnt(0)
	s_barrier
	s_add_u32 m0, s100, 0x8000
	v_lshl_add_u64 v[200:201], v[70:71], 0, s[34:35]
	global_load_lds_dwordx4 v[200:201], off
	s_add_u32 m0, s100, 0xc000
	v_lshl_add_u64 v[200:201], v[72:73], 0, s[34:35]
	global_load_lds_dwordx4 v[200:201], off
	s_add_u32 m0, s100, 0x9000
	v_lshl_add_u64 v[200:201], v[74:75], 0, s[34:35]
	global_load_lds_dwordx4 v[200:201], off
	s_add_u32 m0, s100, 0xd000
	v_lshl_add_u64 v[200:201], v[76:77], 0, s[34:35]
	global_load_lds_dwordx4 v[200:201], off
	s_add_u32 m0, s100, 0xa000
	v_lshl_add_u64 v[200:201], v[78:79], 0, s[34:35]
	global_load_lds_dwordx4 v[200:201], off
	s_add_u32 m0, s100, 0xe000
	v_lshl_add_u64 v[200:201], v[80:81], 0, s[34:35]
	global_load_lds_dwordx4 v[200:201], off
	s_add_u32 m0, s100, 0xb000
	v_lshl_add_u64 v[200:201], v[82:83], 0, s[34:35]
	global_load_lds_dwordx4 v[200:201], off
	s_add_u32 m0, s100, 0xf000
	v_lshl_add_u64 v[200:201], v[84:85], 0, s[34:35]
	global_load_lds_dwordx4 v[200:201], off
	ds_read_b128 v[106:109], v196
	ds_read_b128 v[110:113], v196 offset:2048
	ds_read_b128 v[132:135], v197 offset:16384
	ds_read_b128 v[136:139], v197 offset:18432
	ds_read_b128 v[140:143], v196 offset:4096
	ds_read_b128 v[144:147], v196 offset:6144
	ds_read_b128 v[148:151], v197 offset:20480
	ds_read_b128 v[152:155], v197 offset:22528
	ds_read_b128 v[156:159], v198
	ds_read_b128 v[160:163], v198 offset:2048
	ds_read_b128 v[164:167], v199 offset:16384
	ds_read_b128 v[168:171], v199 offset:18432
	ds_read_b128 v[172:175], v198 offset:4096
	ds_read_b128 v[176:179], v198 offset:6144
	ds_read_b128 v[180:183], v199 offset:20480
	ds_read_b128 v[184:187], v199 offset:22528
	s_waitcnt lgkmcnt(8)
	v_mfma_f32_16x16x32_bf16 v[4:7], v[106:109], v[132:135], v[4:7]
	v_mfma_f32_16x16x32_bf16 v[8:11], v[106:109], v[136:139], v[8:11]
	v_mfma_f32_16x16x32_bf16 v[12:15], v[106:109], v[148:151], v[12:15]
	v_mfma_f32_16x16x32_bf16 v[16:19], v[106:109], v[152:155], v[16:19]
	v_mfma_f32_16x16x32_bf16 v[20:23], v[110:113], v[132:135], v[20:23]
	v_mfma_f32_16x16x32_bf16 v[24:27], v[110:113], v[136:139], v[24:27]
	v_mfma_f32_16x16x32_bf16 v[28:31], v[110:113], v[148:151], v[28:31]
	v_mfma_f32_16x16x32_bf16 v[32:35], v[110:113], v[152:155], v[32:35]
	v_mfma_f32_16x16x32_bf16 v[36:39], v[140:143], v[132:135], v[36:39]
	v_mfma_f32_16x16x32_bf16 v[40:43], v[140:143], v[136:139], v[40:43]
	v_mfma_f32_16x16x32_bf16 v[44:47], v[140:143], v[148:151], v[44:47]
	v_mfma_f32_16x16x32_bf16 v[48:51], v[140:143], v[152:155], v[48:51]
	v_mfma_f32_16x16x32_bf16 v[52:55], v[144:147], v[132:135], v[52:55]
	v_mfma_f32_16x16x32_bf16 v[56:59], v[144:147], v[136:139], v[56:59]
	v_mfma_f32_16x16x32_bf16 v[60:63], v[144:147], v[148:151], v[60:63]
	v_mfma_f32_16x16x32_bf16 v[64:67], v[144:147], v[152:155], v[64:67]
	v_xor_b32_e32 v196, 0x8000, v196
	v_xor_b32_e32 v197, 0x8000, v197
	v_xor_b32_e32 v198, 0x8000, v198
	v_xor_b32_e32 v199, 0x8000, v199
	s_waitcnt vmcnt(0) lgkmcnt(0)
	s_barrier
.Lkp_b176_loop:
	s_add_u32 s34, s34, 0x80
	s_addc_u32 s35, s35, 0
	s_cmpk_eq_i32 s34, 0x380
	s_cbranch_scc1 .Lkp_b176_last
	v_mfma_f32_16x16x32_bf16 v[4:7], v[156:159], v[164:167], v[4:7]
	s_add_u32 m0, s101, 0x0
	v_lshl_add_u64 v[200:201], v[70:71], 0, s[34:35]
	global_load_lds_dwordx4 v[200:201], off
	v_mfma_f32_16x16x32_bf16 v[8:11], v[156:159], v[168:171], v[8:11]
	s_add_u32 m0, s101, 0x4000
	v_lshl_add_u64 v[200:201], v[72:73], 0, s[34:35]
	global_load_lds_dwordx4 v[200:201], off
	v_mfma_f32_16x16x32_bf16 v[12:15], v[156:159], v[180:183], v[12:15]
	s_add_u32 m0, s101, 0x1000
	v_lshl_add_u64 v[200:201], v[74:75], 0, s[34:35]
	global_load_lds_dwordx4 v[200:201], off
	v_mfma_f32_16x16x32_bf16 v[16:19], v[156:159], v[184:187], v[16:19]
	s_add_u32 m0, s101, 0x5000
	v_lshl_add_u64 v[200:201], v[76:77], 0, s[34:35]
	global_load_lds_dwordx4 v[200:201], off
	v_mfma_f32_16x16x32_bf16 v[20:23], v[160:163], v[164:167], v[20:23]
	s_add_u32 m0, s101, 0x2000
	v_lshl_add_u64 v[200:201], v[78:79], 0, s[34:35]
	global_load_lds_dwordx4 v[200:201], off
	ds_read_b128 v[106:109], v196
	v_mfma_f32_16x16x32_bf16 v[24:27], v[160:163], v[168:171], v[24:27]
	s_add_u32 m0, s101, 0x6000
	v_lshl_add_u64 v[200:201], v[80:81], 0, s[34:35]
	global_load_lds_dwordx4 v[200:201], off
	ds_read_b128 v[110:113], v196 offset:2048
	v_mfma_f32_16x16x32_bf16 v[28:31], v[160:163], v[180:183], v[28:31]
	s_add_u32 m0, s101, 0x3000
	v_lshl_add_u64 v[200:201], v[82:83], 0, s[34:35]
	global_load_lds_dwordx4 v[200:201], off
	ds_read_b128 v[132:135], v197 offset:16384
	v_mfma_f32_16x16x32_bf16 v[32:35], v[160:163], v[184:187], v[32:35]
	s_add_u32 m0, s101, 0x7000
	v_lshl_add_u64 v[200:201], v[84:85], 0, s[34:35]
	global_load_lds_dwordx4 v[200:201], off
	ds_read_b128 v[136:139], v197 offset:18432
	v_mfma_f32_16x16x32_bf16 v[36:39], v[172:175], v[164:167], v[36:39]
	ds_read_b128 v[140:143], v196 offset:4096
	v_mfma_f32_16x16x32_bf16 v[40:43], v[172:175], v[168:171], v[40:43]
	ds_read_b128 v[144:147], v196 offset:6144
	v_mfma_f32_16x16x32_bf16 v[44:47], v[172:175], v[180:183], v[44:47]
	ds_read_b128 v[148:151], v197 offset:20480
	v_mfma_f32_16x16x32_bf16 v[48:51], v[172:175], v[184:187], v[48:51]
	ds_read_b128 v[152:155], v197 offset:22528
	v_mfma_f32_16x16x32_bf16 v[52:55], v[176:179], v[164:167], v[52:55]
	v_mfma_f32_16x16x32_bf16 v[56:59], v[176:179], v[168:171], v[56:59]
	v_mfma_f32_16x16x32_bf16 v[60:63], v[176:179], v[180:183], v[60:63]
	v_mfma_f32_16x16x32_bf16 v[64:67], v[176:179], v[184:187], v[64:67]
	s_xor_b32 s101, s101, 0x8000
	s_waitcnt lgkmcnt(0)
; DEVINL f32x4 mfma16(bf16x8 a, bf16x8 b, f32x4 c) { return __builtin_amdgcn_mfma_f32_16x16x32_bf16(a, b, c, 0, 0, 0); }
; DEVINL void gemm_loop(f32x4 (&acc)[4][4], const u16* __restrict__ A, int lda, const u16* __restrict__ Bt, int ldb,
;                       int m0, int n0, int k0, int nk, char* smem) {
;     ...
;   for (int kt = 0; kt < nk; ++kt) {
;     __syncthreads();
;     char* cur = smem + (kt & 1) * 32768;
;     if (kt + 1 < nk) {
;       char* nxt = smem + ((kt + 1) & 1) * 32768;
; #pragma unroll
;       for (int i = 0; i < 4; ++i) {
;         glds16(ga[i] + (kt + 1) * 64, nxt + i * 4096 + wid * 1024);
;         glds16(gb[i] + (kt + 1) * 64, nxt + 16384 + i * 4096 + wid * 1024);
;       }
;     }
;     bf16x8 af[2][4], bfr[2][4];
; #pragma unroll
;     for (int ks = 0; ks < 2; ++ks)
; #pragma unroll
;       for (int f = 0; f < 4; ++f) {
;         int ra = wr * 64 + f * 16 + fr, rb = wc * 64 + f * 16 + fr;
;         int ch = ks * 4 + fq;
;         af[ks][f] = *(const bf16x8*)(cur + ra * 128 + ((ch ^ ((ra >> 1) & 7)) << 4));
;         bfr[ks][f] = *(const bf16x8*)(cur + 16384 + rb * 128 + ((ch ^ ((rb >> 1) & 7)) << 4));
;       }
;     __builtin_amdgcn_sched_barrier(0);
; #pragma unroll
;     for (int ks = 0; ks < 2; ++ks)
; #pragma unroll
;       for (int mf = 0; mf < 4; ++mf)
; #pragma unroll
;         for (int nf = 0; nf < 4; ++nf) acc[mf][nf] = mfma16(af[ks][mf], bfr[ks][nf], acc[mf][nf]);
;   }
; DEVINL void p4_tile(const Params& p, char* smem, int mt, int nt) {
;     ...
;   u16* mixo = (u16*)(p.ws + OFF_MIXO);
; #pragma unroll
;   for (int mf = 0; mf < 4; ++mf) {
;     const int rb = m0 + wr * 64 + mf * 16 + (lane >> 4) * 4;
; #pragma unroll
;     for (int nf = 0; nf < 4; ++nf) {
;       const int col = n0 + wc * 64 + nf * 16 + (lane & 15);
;       store_pairs(mixo, 1024, rb, col, acc[mf][nf][0], acc[mf][nf][1], acc[mf][nf][2], acc[mf][nf][3]);
;     }
;   }
	v_mfma_f32_16x16x32_bf16 v[4:7], v[106:109], v[132:135], v[4:7]
	ds_read_b128 v[156:159], v198
	v_mfma_f32_16x16x32_bf16 v[8:11], v[106:109], v[136:139], v[8:11]
	ds_read_b128 v[160:163], v198 offset:2048
	v_mfma_f32_16x16x32_bf16 v[12:15], v[106:109], v[148:151], v[12:15]
	ds_read_b128 v[164:167], v199 offset:16384
	v_mfma_f32_16x16x32_bf16 v[16:19], v[106:109], v[152:155], v[16:19]
	ds_read_b128 v[168:171], v199 offset:18432
	v_mfma_f32_16x16x32_bf16 v[20:23], v[110:113], v[132:135], v[20:23]
	ds_read_b128 v[172:175], v198 offset:4096
	v_mfma_f32_16x16x32_bf16 v[24:27], v[110:113], v[136:139], v[24:27]
	ds_read_b128 v[176:179], v198 offset:6144
	v_mfma_f32_16x16x32_bf16 v[28:31], v[110:113], v[148:151], v[28:31]
	ds_read_b128 v[180:183], v199 offset:20480
	v_mfma_f32_16x16x32_bf16 v[32:35], v[110:113], v[152:155], v[32:35]
	ds_read_b128 v[184:187], v199 offset:22528
	v_mfma_f32_16x16x32_bf16 v[36:39], v[140:143], v[132:135], v[36:39]
	v_mfma_f32_16x16x32_bf16 v[40:43], v[140:143], v[136:139], v[40:43]
	v_mfma_f32_16x16x32_bf16 v[44:47], v[140:143], v[148:151], v[44:47]
	v_mfma_f32_16x16x32_bf16 v[48:51], v[140:143], v[152:155], v[48:51]
	v_mfma_f32_16x16x32_bf16 v[52:55], v[144:147], v[132:135], v[52:55]
	v_mfma_f32_16x16x32_bf16 v[56:59], v[144:147], v[136:139], v[56:59]
	v_mfma_f32_16x16x32_bf16 v[60:63], v[144:147], v[148:151], v[60:63]
	v_mfma_f32_16x16x32_bf16 v[64:67], v[144:147], v[152:155], v[64:67]
	v_xor_b32_e32 v196, 0x8000, v196
	v_xor_b32_e32 v197, 0x8000, v197
	v_xor_b32_e32 v198, 0x8000, v198
	v_xor_b32_e32 v199, 0x8000, v199
	s_waitcnt vmcnt(0) lgkmcnt(0)
	s_barrier
	s_branch .Lkp_b176_loop
.Lkp_b176_last:
	v_mfma_f32_16x16x32_bf16 v[4:7], v[156:159], v[164:167], v[4:7]
	v_mfma_f32_16x16x32_bf16 v[8:11], v[156:159], v[168:171], v[8:11]
	v_mfma_f32_16x16x32_bf16 v[12:15], v[156:159], v[180:183], v[12:15]
	v_mfma_f32_16x16x32_bf16 v[16:19], v[156:159], v[184:187], v[16:19]
	v_mfma_f32_16x16x32_bf16 v[20:23], v[160:163], v[164:167], v[20:23]
	v_mfma_f32_16x16x32_bf16 v[24:27], v[160:163], v[168:171], v[24:27]
	v_mfma_f32_16x16x32_bf16 v[28:31], v[160:163], v[180:183], v[28:31]
	v_mfma_f32_16x16x32_bf16 v[32:35], v[160:163], v[184:187], v[32:35]
	v_mfma_f32_16x16x32_bf16 v[36:39], v[172:175], v[164:167], v[36:39]
	v_mfma_f32_16x16x32_bf16 v[40:43], v[172:175], v[168:171], v[40:43]
	v_mfma_f32_16x16x32_bf16 v[44:47], v[172:175], v[180:183], v[44:47]
	v_mfma_f32_16x16x32_bf16 v[48:51], v[172:175], v[184:187], v[48:51]
	v_mfma_f32_16x16x32_bf16 v[52:55], v[176:179], v[164:167], v[52:55]
	v_mfma_f32_16x16x32_bf16 v[56:59], v[176:179], v[168:171], v[56:59]
	v_mfma_f32_16x16x32_bf16 v[60:63], v[176:179], v[180:183], v[60:63]
	v_mfma_f32_16x16x32_bf16 v[64:67], v[176:179], v[184:187], v[64:67]
	s_mov_b32 s1, 0x8000
	v_add_u32_e32 v70, s1, v105
	v_add_u32_e32 v89, v70, v90
	s_waitcnt vmcnt(0)
	s_barrier
	v_add_u32_e32 v105, v70, v91
	ds_read_b128 v[70:73], v89
	ds_read_b128 v[74:77], v89 offset:2048
	ds_read_b128 v[78:81], v105 offset:16384
	ds_read_b128 v[82:85], v105 offset:18432
	ds_read_b128 v[106:109], v89 offset:4096
	ds_read_b128 v[110:113], v89 offset:6144
	ds_read_b128 v[132:135], v105 offset:20480
	ds_read_b128 v[136:139], v105 offset:22528
	v_add_u32_e32 v89, s1, v102
	v_add_u32_e32 v90, v89, v90
	v_add_u32_e32 v89, v89, v91
	ds_read_b128 v[140:143], v90
	ds_read_b128 v[144:147], v90 offset:2048
	ds_read_b128 v[148:151], v89 offset:16384
	ds_read_b128 v[152:155], v89 offset:18432
	ds_read_b128 v[156:159], v90 offset:4096
	ds_read_b128 v[160:163], v90 offset:6144
	ds_read_b128 v[164:167], v89 offset:20480
	ds_read_b128 v[168:171], v89 offset:22528
	v_and_b32_e32 v102, 64, v88
	s_waitcnt lgkmcnt(13)
	v_mfma_f32_16x16x32_bf16 v[4:7], v[70:73], v[78:81], v[4:7]
	v_add_u32_e32 v1, v1, v104
	s_movk_i32 s0, 0x447
	s_waitcnt lgkmcnt(9)
	v_mfma_f32_16x16x32_bf16 v[12:15], v[70:73], v[132:135], v[12:15]
	v_mfma_f32_16x16x32_bf16 v[56:59], v[110:113], v[82:85], v[56:59]
	v_mfma_f32_16x16x32_bf16 v[8:11], v[70:73], v[82:85], v[8:11]
	v_mfma_f32_16x16x32_bf16 v[20:23], v[74:77], v[78:81], v[20:23]
	v_mfma_f32_16x16x32_bf16 v[24:27], v[74:77], v[82:85], v[24:27]
	v_mfma_f32_16x16x32_bf16 v[28:31], v[74:77], v[132:135], v[28:31]
	s_waitcnt lgkmcnt(8)
	v_mfma_f32_16x16x32_bf16 v[32:35], v[74:77], v[136:139], v[32:35]
	v_mfma_f32_16x16x32_bf16 v[74:77], v[106:109], v[82:85], v[40:43]
	s_waitcnt lgkmcnt(5)
	v_mfma_f32_16x16x32_bf16 v[82:85], v[140:143], v[148:151], v[4:7]
	v_mfma_f32_16x16x32_bf16 v[88:91], v[106:109], v[132:135], v[44:47]
	v_mfma_f32_16x16x32_bf16 v[60:63], v[110:113], v[132:135], v[60:63]
	s_waitcnt lgkmcnt(1)
	v_mfma_f32_16x16x32_bf16 v[132:135], v[140:143], v[164:167], v[12:15]
	v_mfma_f32_16x16x32_bf16 v[12:15], v[160:163], v[152:155], v[56:59]
	s_nop 2
	v_and_b32_e32 v57, 14, v86
	v_mfma_f32_16x16x32_bf16 v[64:67], v[110:113], v[136:139], v[64:67]
	v_or3_b32 v58, v57, v102, v3
	v_and_b32_e32 v3, 1, v86
	v_add_u32_e32 v56, v87, v68
	v_cmp_eq_u32_e64 s[34:35], 0, v3
	v_lshlrev_b32_e32 v3, 1, v3
	v_or3_b32 v56, v56, v3, v69
	v_mov_b32_dpp v59, v84 quad_perm:[1,0,3,2] row_mask:0xf bank_mask:0xf bound_ctrl:1
	v_mov_b32_dpp v3, v82 quad_perm:[1,0,3,2] row_mask:0xf bank_mask:0xf bound_ctrl:1
	v_ashrrev_i32_e32 v57, 31, v56
	v_cndmask_b32_e64 v3, v84, v3, s[34:35]
	v_cndmask_b32_e64 v59, v59, v82, s[34:35]
	v_mfma_f32_16x16x32_bf16 v[16:19], v[70:73], v[136:139], v[16:19]
	v_add_u32_e32 v3, 0x8000, v3
	v_add_u32_e32 v59, 0x8000, v59
	v_perm_b32 v3, v3, v59, s25
	v_mfma_f32_16x16x32_bf16 v[70:73], v[106:109], v[78:81], v[36:39]
	v_mfma_f32_16x16x32_bf16 v[78:81], v[110:113], v[78:81], v[52:55]
	v_mfma_f32_16x16x32_bf16 v[110:113], v[140:143], v[152:155], v[8:11]
	v_mfma_f32_16x16x32_bf16 v[8:11], v[160:163], v[164:167], v[60:63]
	s_waitcnt lgkmcnt(0)
; DEVINL void p4_tile(const Params& p, char* smem, int mt, int nt) {
;     ...
;   u16* mixo = (u16*)(p.ws + OFF_MIXO);
; #pragma unroll
;   for (int mf = 0; mf < 4; ++mf) {
;     const int rb = m0 + wr * 64 + mf * 16 + (lane >> 4) * 4;
; #pragma unroll
;     for (int nf = 0; nf < 4; ++nf) {
;       const int col = n0 + wc * 64 + nf * 16 + (lane & 15);
;       store_pairs(mixo, 1024, rb, col, acc[mf][nf][0], acc[mf][nf][1], acc[mf][nf][2], acc[mf][nf][3]);
;     }
;   }
	v_mfma_f32_16x16x32_bf16 v[4:7], v[160:163], v[168:171], v[64:67]
	s_nop 0
	v_lshlrev_b64 v[60:61], 11, v[56:57]
	v_mov_b32_dpp v57, v83 quad_perm:[1,0,3,2] row_mask:0xf bank_mask:0xf bound_ctrl:1
	v_cndmask_b32_e64 v57, v85, v57, s[34:35]
	v_mov_b32_dpp v64, v85 quad_perm:[1,0,3,2] row_mask:0xf bank_mask:0xf bound_ctrl:1
	v_cndmask_b32_e64 v59, v64, v83, s[34:35]
	v_add_u32_e32 v57, 0x8000, v57
	v_add_u32_e32 v59, 0x8000, v59
	v_or_b32_e32 v62, 1, v56
	v_perm_b32 v57, v57, v59, s25
	v_ashrrev_i32_e32 v59, 31, v58
	v_lshl_add_u64 v[60:61], s[22:23], 0, v[60:61]
	v_ashrrev_i32_e32 v63, 31, v62
	v_lshlrev_b64 v[58:59], 1, v[58:59]
	v_lshlrev_b64 v[62:63], 11, v[62:63]
	v_lshl_add_u64 v[60:61], v[60:61], 0, v[58:59]
	v_lshl_add_u64 v[62:63], s[22:23], 0, v[62:63]
	global_store_dword v[60:61], v3, off
	v_mov_b32_dpp v3, v110 quad_perm:[1,0,3,2] row_mask:0xf bank_mask:0xf bound_ctrl:1
	v_mov_b32_dpp v64, v112 quad_perm:[1,0,3,2] row_mask:0xf bank_mask:0xf bound_ctrl:1
	v_lshl_add_u64 v[62:63], v[62:63], 0, v[58:59]
	v_cndmask_b32_e64 v3, v112, v3, s[34:35]
	v_cndmask_b32_e64 v64, v64, v110, s[34:35]
	global_store_dword v[62:63], v57, off
	v_mov_b32_dpp v57, v111 quad_perm:[1,0,3,2] row_mask:0xf bank_mask:0xf bound_ctrl:1
	v_mov_b32_dpp v65, v113 quad_perm:[1,0,3,2] row_mask:0xf bank_mask:0xf bound_ctrl:1
	v_add_u32_e32 v3, 0x8000, v3
	v_add_u32_e32 v64, 0x8000, v64
	v_perm_b32 v3, v3, v64, s25
	v_cndmask_b32_e64 v57, v113, v57, s[34:35]
	v_cndmask_b32_e64 v64, v65, v111, s[34:35]
	v_add_u32_e32 v57, 0x8000, v57
	v_add_u32_e32 v64, 0x8000, v64
	v_perm_b32 v57, v57, v64, s25
	global_store_dword v[60:61], v3, off offset:32
	global_store_dword v[62:63], v57, off offset:32
	v_mov_b32_dpp v3, v132 quad_perm:[1,0,3,2] row_mask:0xf bank_mask:0xf bound_ctrl:1
	v_mov_b32_dpp v64, v134 quad_perm:[1,0,3,2] row_mask:0xf bank_mask:0xf bound_ctrl:1
	v_mfma_f32_16x16x32_bf16 v[52:55], v[140:143], v[168:171], v[16:19]
	v_cndmask_b32_e64 v3, v134, v3, s[34:35]
	v_cndmask_b32_e64 v64, v64, v132, s[34:35]
	v_mov_b32_dpp v57, v133 quad_perm:[1,0,3,2] row_mask:0xf bank_mask:0xf bound_ctrl:1
	v_mov_b32_dpp v65, v135 quad_perm:[1,0,3,2] row_mask:0xf bank_mask:0xf bound_ctrl:1
	v_add_u32_e32 v3, 0x8000, v3
	v_add_u32_e32 v64, 0x8000, v64
	v_perm_b32 v3, v3, v64, s25
	v_cndmask_b32_e64 v57, v135, v57, s[34:35]
	v_cndmask_b32_e64 v64, v65, v133, s[34:35]
	v_add_u32_e32 v57, 0x8000, v57
	v_add_u32_e32 v64, 0x8000, v64
	v_perm_b32 v57, v57, v64, s25
	global_store_dword v[60:61], v3, off offset:64
	global_store_dword v[62:63], v57, off offset:64
	v_mov_b32_dpp v3, v52 quad_perm:[1,0,3,2] row_mask:0xf bank_mask:0xf bound_ctrl:1
	v_mov_b32_dpp v64, v54 quad_perm:[1,0,3,2] row_mask:0xf bank_mask:0xf bound_ctrl:1
	v_mfma_f32_16x16x32_bf16 v[106:109], v[106:109], v[136:139], v[48:51]
	v_cndmask_b32_e64 v3, v54, v3, s[34:35]
	v_cndmask_b32_e64 v52, v64, v52, s[34:35]
	v_mov_b32_dpp v57, v53 quad_perm:[1,0,3,2] row_mask:0xf bank_mask:0xf bound_ctrl:1
	v_mfma_f32_16x16x32_bf16 v[48:51], v[144:147], v[148:151], v[20:23]
	v_mov_b32_dpp v65, v55 quad_perm:[1,0,3,2] row_mask:0xf bank_mask:0xf bound_ctrl:1
	v_add_u32_e32 v3, 0x8000, v3
	v_add_u32_e32 v52, 0x8000, v52
	v_perm_b32 v3, v3, v52, s25
	v_cndmask_b32_e64 v52, v55, v57, s[34:35]
	v_cndmask_b32_e64 v53, v65, v53, s[34:35]
	v_add_u32_e32 v52, 0x8000, v52
	v_add_u32_e32 v53, 0x8000, v53
	v_perm_b32 v52, v52, v53, s25
	global_store_dword v[60:61], v3, off offset:96
	global_store_dword v[62:63], v52, off offset:96
	v_mov_b32_dpp v3, v48 quad_perm:[1,0,3,2] row_mask:0xf bank_mask:0xf bound_ctrl:1
	v_mov_b32_dpp v60, v50 quad_perm:[1,0,3,2] row_mask:0xf bank_mask:0xf bound_ctrl:1
	v_or_b32_e32 v52, 16, v56
	v_cndmask_b32_e64 v3, v50, v3, s[34:35]
	v_cndmask_b32_e64 v48, v60, v48, s[34:35]
	v_mfma_f32_16x16x32_bf16 v[44:47], v[144:147], v[152:155], v[24:27]
	v_ashrrev_i32_e32 v53, 31, v52
	v_mov_b32_dpp v57, v49 quad_perm:[1,0,3,2] row_mask:0xf bank_mask:0xf bound_ctrl:1
	v_mov_b32_dpp v61, v51 quad_perm:[1,0,3,2] row_mask:0xf bank_mask:0xf bound_ctrl:1
	v_add_u32_e32 v3, 0x8000, v3
	v_add_u32_e32 v48, 0x8000, v48
	v_lshlrev_b64 v[52:53], 11, v[52:53]
	v_perm_b32 v3, v3, v48, s25
	v_cndmask_b32_e64 v48, v51, v57, s[34:35]
	v_cndmask_b32_e64 v49, v61, v49, s[34:35]
	v_lshl_add_u64 v[52:53], s[22:23], 0, v[52:53]
	v_or_b32_e32 v54, 17, v56
	v_add_u32_e32 v48, 0x8000, v48
	v_add_u32_e32 v49, 0x8000, v49
	v_ashrrev_i32_e32 v55, 31, v54
	v_perm_b32 v57, v48, v49, s25
	v_lshl_add_u64 v[48:49], v[52:53], 0, v[58:59]
	v_lshlrev_b64 v[54:55], 11, v[54:55]
	global_store_dword v[48:49], v3, off
	v_mov_b32_dpp v3, v44 quad_perm:[1,0,3,2] row_mask:0xf bank_mask:0xf bound_ctrl:1
	v_mov_b32_dpp v53, v46 quad_perm:[1,0,3,2] row_mask:0xf bank_mask:0xf bound_ctrl:1
	v_mfma_f32_16x16x32_bf16 v[40:43], v[144:147], v[164:167], v[28:31]
	v_lshl_add_u64 v[54:55], s[22:23], 0, v[54:55]
	v_cndmask_b32_e64 v3, v46, v3, s[34:35]
	v_cndmask_b32_e64 v44, v53, v44, s[34:35]
	v_lshl_add_u64 v[50:51], v[54:55], 0, v[58:59]
	v_mov_b32_dpp v52, v45 quad_perm:[1,0,3,2] row_mask:0xf bank_mask:0xf bound_ctrl:1
	v_mov_b32_dpp v54, v47 quad_perm:[1,0,3,2] row_mask:0xf bank_mask:0xf bound_ctrl:1
	v_add_u32_e32 v3, 0x8000, v3
	v_add_u32_e32 v44, 0x8000, v44
	v_perm_b32 v3, v3, v44, s25
	v_cndmask_b32_e64 v44, v47, v52, s[34:35]
	v_cndmask_b32_e64 v45, v54, v45, s[34:35]
	v_add_u32_e32 v44, 0x8000, v44
	v_add_u32_e32 v45, 0x8000, v45
	global_store_dword v[50:51], v57, off
	v_perm_b32 v44, v44, v45, s25
	global_store_dword v[48:49], v3, off offset:32
	global_store_dword v[50:51], v44, off offset:32
	v_mov_b32_dpp v3, v40 quad_perm:[1,0,3,2] row_mask:0xf bank_mask:0xf bound_ctrl:1
; DEVINL void p4_tile(const Params& p, char* smem, int mt, int nt) {
;     ...
;   u16* mixo = (u16*)(p.ws + OFF_MIXO);
; #pragma unroll
;   for (int mf = 0; mf < 4; ++mf) {
;     const int rb = m0 + wr * 64 + mf * 16 + (lane >> 4) * 4;
; #pragma unroll
;     for (int nf = 0; nf < 4; ++nf) {
;       const int col = n0 + wc * 64 + nf * 16 + (lane & 15);
;       store_pairs(mixo, 1024, rb, col, acc[mf][nf][0], acc[mf][nf][1], acc[mf][nf][2], acc[mf][nf][3]);
;     }
;   }
	v_mov_b32_dpp v45, v42 quad_perm:[1,0,3,2] row_mask:0xf bank_mask:0xf bound_ctrl:1
	v_mfma_f32_16x16x32_bf16 v[36:39], v[144:147], v[168:171], v[32:35]
	v_cndmask_b32_e64 v3, v42, v3, s[34:35]
	v_cndmask_b32_e64 v40, v45, v40, s[34:35]
	v_mov_b32_dpp v44, v41 quad_perm:[1,0,3,2] row_mask:0xf bank_mask:0xf bound_ctrl:1
	v_mov_b32_dpp v46, v43 quad_perm:[1,0,3,2] row_mask:0xf bank_mask:0xf bound_ctrl:1
	v_add_u32_e32 v3, 0x8000, v3
	v_add_u32_e32 v40, 0x8000, v40
	v_perm_b32 v3, v3, v40, s25
	v_cndmask_b32_e64 v40, v43, v44, s[34:35]
	v_cndmask_b32_e64 v41, v46, v41, s[34:35]
	v_add_u32_e32 v40, 0x8000, v40
	v_add_u32_e32 v41, 0x8000, v41
	v_perm_b32 v40, v40, v41, s25
	global_store_dword v[48:49], v3, off offset:64
	global_store_dword v[50:51], v40, off offset:64
	v_mov_b32_dpp v3, v36 quad_perm:[1,0,3,2] row_mask:0xf bank_mask:0xf bound_ctrl:1
	v_mov_b32_dpp v41, v38 quad_perm:[1,0,3,2] row_mask:0xf bank_mask:0xf bound_ctrl:1
	v_mfma_f32_16x16x32_bf16 v[32:35], v[156:159], v[148:151], v[70:73]
	v_cndmask_b32_e64 v3, v38, v3, s[34:35]
	v_cndmask_b32_e64 v36, v41, v36, s[34:35]
	v_mov_b32_dpp v40, v37 quad_perm:[1,0,3,2] row_mask:0xf bank_mask:0xf bound_ctrl:1
	v_mov_b32_dpp v42, v39 quad_perm:[1,0,3,2] row_mask:0xf bank_mask:0xf bound_ctrl:1
	v_add_u32_e32 v3, 0x8000, v3
	v_add_u32_e32 v36, 0x8000, v36
	v_perm_b32 v3, v3, v36, s25
	v_cndmask_b32_e64 v36, v39, v40, s[34:35]
	v_cndmask_b32_e64 v37, v42, v37, s[34:35]
	v_add_u32_e32 v36, 0x8000, v36
	v_add_u32_e32 v37, 0x8000, v37
	v_perm_b32 v36, v36, v37, s25
	global_store_dword v[48:49], v3, off offset:96
	global_store_dword v[50:51], v36, off offset:96
	v_mov_b32_dpp v3, v32 quad_perm:[1,0,3,2] row_mask:0xf bank_mask:0xf bound_ctrl:1
	v_mov_b32_dpp v41, v34 quad_perm:[1,0,3,2] row_mask:0xf bank_mask:0xf bound_ctrl:1
	v_or_b32_e32 v36, 32, v56
	v_cndmask_b32_e64 v3, v34, v3, s[34:35]
	v_cndmask_b32_e64 v32, v41, v32, s[34:35]
	v_mfma_f32_16x16x32_bf16 v[28:31], v[156:159], v[152:155], v[74:77]
	v_ashrrev_i32_e32 v37, 31, v36
	v_mov_b32_dpp v40, v33 quad_perm:[1,0,3,2] row_mask:0xf bank_mask:0xf bound_ctrl:1
	v_mov_b32_dpp v42, v35 quad_perm:[1,0,3,2] row_mask:0xf bank_mask:0xf bound_ctrl:1
	v_add_u32_e32 v3, 0x8000, v3
	v_add_u32_e32 v32, 0x8000, v32
	v_lshlrev_b64 v[36:37], 11, v[36:37]
	v_perm_b32 v3, v3, v32, s25
	v_cndmask_b32_e64 v32, v35, v40, s[34:35]
	v_cndmask_b32_e64 v33, v42, v33, s[34:35]
	v_lshl_add_u64 v[36:37], s[22:23], 0, v[36:37]
	v_or_b32_e32 v38, 33, v56
	v_add_u32_e32 v32, 0x8000, v32
	v_add_u32_e32 v33, 0x8000, v33
	v_ashrrev_i32_e32 v39, 31, v38
	v_perm_b32 v40, v32, v33, s25
	v_lshl_add_u64 v[32:33], v[36:37], 0, v[58:59]
	v_lshlrev_b64 v[38:39], 11, v[38:39]
	global_store_dword v[32:33], v3, off
	v_mov_b32_dpp v3, v28 quad_perm:[1,0,3,2] row_mask:0xf bank_mask:0xf bound_ctrl:1
	v_mov_b32_dpp v37, v30 quad_perm:[1,0,3,2] row_mask:0xf bank_mask:0xf bound_ctrl:1
	v_mfma_f32_16x16x32_bf16 v[24:27], v[156:159], v[164:167], v[88:91]
	v_lshl_add_u64 v[38:39], s[22:23], 0, v[38:39]
	v_cndmask_b32_e64 v3, v30, v3, s[34:35]
	v_cndmask_b32_e64 v28, v37, v28, s[34:35]
	v_lshl_add_u64 v[34:35], v[38:39], 0, v[58:59]
	v_mov_b32_dpp v36, v29 quad_perm:[1,0,3,2] row_mask:0xf bank_mask:0xf bound_ctrl:1
	v_mov_b32_dpp v38, v31 quad_perm:[1,0,3,2] row_mask:0xf bank_mask:0xf bound_ctrl:1
	v_add_u32_e32 v3, 0x8000, v3
	v_add_u32_e32 v28, 0x8000, v28
	v_perm_b32 v3, v3, v28, s25
	v_cndmask_b32_e64 v28, v31, v36, s[34:35]
	v_cndmask_b32_e64 v29, v38, v29, s[34:35]
	v_add_u32_e32 v28, 0x8000, v28
	v_add_u32_e32 v29, 0x8000, v29
	global_store_dword v[34:35], v40, off
	v_perm_b32 v28, v28, v29, s25
	global_store_dword v[32:33], v3, off offset:32
	global_store_dword v[34:35], v28, off offset:32
	v_mov_b32_dpp v3, v24 quad_perm:[1,0,3,2] row_mask:0xf bank_mask:0xf bound_ctrl:1
	v_mov_b32_dpp v29, v26 quad_perm:[1,0,3,2] row_mask:0xf bank_mask:0xf bound_ctrl:1
	v_mfma_f32_16x16x32_bf16 v[20:23], v[156:159], v[168:171], v[106:109]
	v_cndmask_b32_e64 v3, v26, v3, s[34:35]
	v_cndmask_b32_e64 v24, v29, v24, s[34:35]
	v_mov_b32_dpp v28, v25 quad_perm:[1,0,3,2] row_mask:0xf bank_mask:0xf bound_ctrl:1
	v_mov_b32_dpp v30, v27 quad_perm:[1,0,3,2] row_mask:0xf bank_mask:0xf bound_ctrl:1
	v_add_u32_e32 v3, 0x8000, v3
	v_add_u32_e32 v24, 0x8000, v24
	v_perm_b32 v3, v3, v24, s25
	v_cndmask_b32_e64 v24, v27, v28, s[34:35]
	v_cndmask_b32_e64 v25, v30, v25, s[34:35]
	v_add_u32_e32 v24, 0x8000, v24
	v_add_u32_e32 v25, 0x8000, v25
	v_perm_b32 v24, v24, v25, s25
	global_store_dword v[32:33], v3, off offset:64
; DEVINL void p4_tile(const Params& p, char* smem, int mt, int nt) {
;     ...
;   u16* mixo = (u16*)(p.ws + OFF_MIXO);
; #pragma unroll
;   for (int mf = 0; mf < 4; ++mf) {
;     const int rb = m0 + wr * 64 + mf * 16 + (lane >> 4) * 4;
; #pragma unroll
;     for (int nf = 0; nf < 4; ++nf) {
;       const int col = n0 + wc * 64 + nf * 16 + (lane & 15);
;       store_pairs(mixo, 1024, rb, col, acc[mf][nf][0], acc[mf][nf][1], acc[mf][nf][2], acc[mf][nf][3]);
;     }
;   }
; template <class F>
; DEVINL void gemm_phase(int NT, F&& f) {
;     ...
;     for (int t = bid; t < U; t += nb) f(t / NT, t % NT);
	global_store_dword v[34:35], v24, off offset:64
	v_mov_b32_dpp v3, v20 quad_perm:[1,0,3,2] row_mask:0xf bank_mask:0xf bound_ctrl:1
	v_mov_b32_dpp v25, v22 quad_perm:[1,0,3,2] row_mask:0xf bank_mask:0xf bound_ctrl:1
	v_mfma_f32_16x16x32_bf16 v[16:19], v[160:163], v[148:151], v[78:81]
	v_cndmask_b32_e64 v3, v22, v3, s[34:35]
	v_cndmask_b32_e64 v20, v25, v20, s[34:35]
	v_mov_b32_dpp v24, v21 quad_perm:[1,0,3,2] row_mask:0xf bank_mask:0xf bound_ctrl:1
	v_mov_b32_dpp v26, v23 quad_perm:[1,0,3,2] row_mask:0xf bank_mask:0xf bound_ctrl:1
	v_add_u32_e32 v3, 0x8000, v3
	v_add_u32_e32 v20, 0x8000, v20
	v_perm_b32 v3, v3, v20, s25
	v_cndmask_b32_e64 v20, v23, v24, s[34:35]
	v_cndmask_b32_e64 v21, v26, v21, s[34:35]
	v_add_u32_e32 v20, 0x8000, v20
	v_add_u32_e32 v21, 0x8000, v21
	v_perm_b32 v20, v20, v21, s25
	global_store_dword v[32:33], v3, off offset:96
	global_store_dword v[34:35], v20, off offset:96
	v_mov_b32_dpp v3, v16 quad_perm:[1,0,3,2] row_mask:0xf bank_mask:0xf bound_ctrl:1
	v_mov_b32_dpp v25, v18 quad_perm:[1,0,3,2] row_mask:0xf bank_mask:0xf bound_ctrl:1
	v_or_b32_e32 v20, 48, v56
	v_cndmask_b32_e64 v3, v18, v3, s[34:35]
	v_cndmask_b32_e64 v16, v25, v16, s[34:35]
	v_ashrrev_i32_e32 v21, 31, v20
	v_mov_b32_dpp v24, v17 quad_perm:[1,0,3,2] row_mask:0xf bank_mask:0xf bound_ctrl:1
	v_mov_b32_dpp v26, v19 quad_perm:[1,0,3,2] row_mask:0xf bank_mask:0xf bound_ctrl:1
	v_add_u32_e32 v3, 0x8000, v3
	v_add_u32_e32 v16, 0x8000, v16
	v_lshlrev_b64 v[20:21], 11, v[20:21]
	v_perm_b32 v3, v3, v16, s25
	v_cndmask_b32_e64 v16, v19, v24, s[34:35]
	v_cndmask_b32_e64 v17, v26, v17, s[34:35]
	v_lshl_add_u64 v[20:21], s[22:23], 0, v[20:21]
	v_or_b32_e32 v22, 49, v56
	v_add_u32_e32 v16, 0x8000, v16
	v_add_u32_e32 v17, 0x8000, v17
	v_ashrrev_i32_e32 v23, 31, v22
	v_perm_b32 v24, v16, v17, s25
	v_lshl_add_u64 v[16:17], v[20:21], 0, v[58:59]
	v_lshlrev_b64 v[22:23], 11, v[22:23]
	global_store_dword v[16:17], v3, off
	v_mov_b32_dpp v3, v12 quad_perm:[1,0,3,2] row_mask:0xf bank_mask:0xf bound_ctrl:1
	v_mov_b32_dpp v21, v14 quad_perm:[1,0,3,2] row_mask:0xf bank_mask:0xf bound_ctrl:1
	v_lshl_add_u64 v[22:23], s[22:23], 0, v[22:23]
	v_cndmask_b32_e64 v3, v14, v3, s[34:35]
	v_cndmask_b32_e64 v12, v21, v12, s[34:35]
	v_lshl_add_u64 v[18:19], v[22:23], 0, v[58:59]
	v_mov_b32_dpp v20, v13 quad_perm:[1,0,3,2] row_mask:0xf bank_mask:0xf bound_ctrl:1
	v_mov_b32_dpp v22, v15 quad_perm:[1,0,3,2] row_mask:0xf bank_mask:0xf bound_ctrl:1
	v_add_u32_e32 v3, 0x8000, v3
	v_add_u32_e32 v12, 0x8000, v12
	v_perm_b32 v3, v3, v12, s25
	v_cndmask_b32_e64 v12, v15, v20, s[34:35]
	v_cndmask_b32_e64 v13, v22, v13, s[34:35]
	v_add_u32_e32 v12, 0x8000, v12
	v_add_u32_e32 v13, 0x8000, v13
	global_store_dword v[18:19], v24, off
	v_perm_b32 v12, v12, v13, s25
	global_store_dword v[16:17], v3, off offset:32
	global_store_dword v[18:19], v12, off offset:32
	v_mov_b32_dpp v3, v8 quad_perm:[1,0,3,2] row_mask:0xf bank_mask:0xf bound_ctrl:1
	v_mov_b32_dpp v13, v10 quad_perm:[1,0,3,2] row_mask:0xf bank_mask:0xf bound_ctrl:1
	v_cndmask_b32_e64 v3, v10, v3, s[34:35]
	v_cndmask_b32_e64 v8, v13, v8, s[34:35]
	v_mov_b32_dpp v12, v9 quad_perm:[1,0,3,2] row_mask:0xf bank_mask:0xf bound_ctrl:1
	v_mov_b32_dpp v14, v11 quad_perm:[1,0,3,2] row_mask:0xf bank_mask:0xf bound_ctrl:1
	v_add_u32_e32 v3, 0x8000, v3
	v_add_u32_e32 v8, 0x8000, v8
	v_perm_b32 v3, v3, v8, s25
	v_cndmask_b32_e64 v8, v11, v12, s[34:35]
	v_cndmask_b32_e64 v9, v14, v9, s[34:35]
	v_add_u32_e32 v8, 0x8000, v8
	v_add_u32_e32 v9, 0x8000, v9
	v_perm_b32 v8, v8, v9, s25
	global_store_dword v[16:17], v3, off offset:64
	global_store_dword v[18:19], v8, off offset:64
	v_mov_b32_dpp v3, v4 quad_perm:[1,0,3,2] row_mask:0xf bank_mask:0xf bound_ctrl:1
	v_mov_b32_dpp v9, v6 quad_perm:[1,0,3,2] row_mask:0xf bank_mask:0xf bound_ctrl:1
	v_cndmask_b32_e64 v3, v6, v3, s[34:35]
	v_cndmask_b32_e64 v4, v9, v4, s[34:35]
	v_mov_b32_dpp v8, v5 quad_perm:[1,0,3,2] row_mask:0xf bank_mask:0xf bound_ctrl:1
	v_mov_b32_dpp v10, v7 quad_perm:[1,0,3,2] row_mask:0xf bank_mask:0xf bound_ctrl:1
	v_add_u32_e32 v3, 0x8000, v3
	v_add_u32_e32 v4, 0x8000, v4
	v_perm_b32 v3, v3, v4, s25
	v_cndmask_b32_e64 v4, v7, v8, s[34:35]
	v_cndmask_b32_e64 v5, v10, v5, s[34:35]
	v_cmp_lt_i32_e64 s[34:35], s0, v1
	v_add_u32_e32 v4, 0x8000, v4
	v_add_u32_e32 v5, 0x8000, v5
	s_or_b64 s[38:39], s[34:35], s[38:39]
	v_perm_b32 v4, v4, v5, s25
	global_store_dword v[16:17], v3, off offset:96
	global_store_dword v[18:19], v4, off offset:96
	s_andn2_b64 exec, exec, s[38:39]
	s_cbranch_execnz .LBB0_171
	s_or_b64 exec, exec, s[38:39]

; DEVINL f32x4 mfma16(bf16x8 a, bf16x8 b, f32x4 c) { return __builtin_amdgcn_mfma_f32_16x16x32_bf16(a, b, c, 0, 0, 0); }
; DEVINL void gemm_loop(f32x4 (&acc)[4][4], const u16* __restrict__ A, int lda, const u16* __restrict__ Bt, int ldb,
;                       int m0, int n0, int k0, int nk, char* smem) {
;     ...
;   __syncthreads();
; #pragma unroll
;   for (int i = 0; i < 4; ++i) {
;     glds16(ga[i], smem + i * 4096 + wid * 1024);
;     glds16(gb[i], smem + 16384 + i * 4096 + wid * 1024);
;   }
;   for (int kt = 0; kt < nk; ++kt) {
;     __syncthreads();
;     char* cur = smem + (kt & 1) * 32768;
;     if (kt + 1 < nk) {
;       char* nxt = smem + ((kt + 1) & 1) * 32768;
; #pragma unroll
;       for (int i = 0; i < 4; ++i) {
;         glds16(ga[i] + (kt + 1) * 64, nxt + i * 4096 + wid * 1024);
;         glds16(gb[i] + (kt + 1) * 64, nxt + 16384 + i * 4096 + wid * 1024);
;       }
;     }
;     bf16x8 af[2][4], bfr[2][4];
; #pragma unroll
;     for (int ks = 0; ks < 2; ++ks)
; #pragma unroll
;       for (int f = 0; f < 4; ++f) {
;         int ra = wr * 64 + f * 16 + fr, rb = wc * 64 + f * 16 + fr;
;         int ch = ks * 4 + fq;
;         af[ks][f] = *(const bf16x8*)(cur + ra * 128 + ((ch ^ ((ra >> 1) & 7)) << 4));
;         bfr[ks][f] = *(const bf16x8*)(cur + 16384 + rb * 128 + ((ch ^ ((rb >> 1) & 7)) << 4));
;       }
;     __builtin_amdgcn_sched_barrier(0);
; #pragma unroll
;     for (int ks = 0; ks < 2; ++ks)
; #pragma unroll
;       for (int mf = 0; mf < 4; ++mf)
; #pragma unroll
;         for (int nf = 0; nf < 4; ++nf) acc[mf][nf] = mfma16(af[ks][mf], bfr[ks][nf], acc[mf][nf]);
;   }
.LBB0_183:
	v_readfirstlane_b32 s100, v69
	v_add_u32_e32 v196, v90, v87
	v_add_u32_e32 v197, v90, v88
	v_add_u32_e32 v198, v89, v87
	v_add_u32_e32 v199, v89, v88
	s_mov_b32 s101, s100
	v_lshlrev_b32_e32 v202, 4, v0
	s_waitcnt vmcnt(0)
	s_barrier
	s_add_u32 m0, s100, 0x8000
	v_lshl_add_u64 v[200:201], v[70:71], 0, s[34:35]
	global_load_lds_dwordx4 v[200:201], off
	s_add_u32 m0, s100, 0xc000
	v_lshl_add_u64 v[200:201], v[72:73], 0, s[34:35]
	global_load_lds_dwordx4 v[200:201], off
	s_add_u32 m0, s100, 0x9000
	v_lshl_add_u64 v[200:201], v[74:75], 0, s[34:35]
	global_load_lds_dwordx4 v[200:201], off
	s_add_u32 m0, s100, 0xd000
	v_lshl_add_u64 v[200:201], v[76:77], 0, s[34:35]
	global_load_lds_dwordx4 v[200:201], off
	s_add_u32 m0, s100, 0xa000
	v_lshl_add_u64 v[200:201], v[78:79], 0, s[34:35]
	global_load_lds_dwordx4 v[200:201], off
	s_add_u32 m0, s100, 0xe000
	v_lshl_add_u64 v[200:201], v[80:81], 0, s[34:35]
	global_load_lds_dwordx4 v[200:201], off
	s_add_u32 m0, s100, 0xb000
	v_lshl_add_u64 v[200:201], v[82:83], 0, s[34:35]
	global_load_lds_dwordx4 v[200:201], off
	s_add_u32 m0, s100, 0xf000
	v_lshl_add_u64 v[200:201], v[84:85], 0, s[34:35]
	global_load_lds_dwordx4 v[200:201], off
	ds_read_b128 v[106:109], v196
	ds_read_b128 v[110:113], v196 offset:2048
	ds_read_b128 v[132:135], v197 offset:16384
	ds_read_b128 v[136:139], v197 offset:18432
	ds_read_b128 v[140:143], v196 offset:4096
	ds_read_b128 v[144:147], v196 offset:6144
	ds_read_b128 v[148:151], v197 offset:20480
	ds_read_b128 v[152:155], v197 offset:22528
	ds_read_b128 v[156:159], v198
	ds_read_b128 v[160:163], v198 offset:2048
	ds_read_b128 v[164:167], v199 offset:16384
	ds_read_b128 v[168:171], v199 offset:18432
	ds_read_b128 v[172:175], v198 offset:4096
	ds_read_b128 v[176:179], v198 offset:6144
	ds_read_b128 v[180:183], v199 offset:20480
	ds_read_b128 v[184:187], v199 offset:22528
	s_waitcnt lgkmcnt(8)
	v_mfma_f32_16x16x32_bf16 v[64:67], v[106:109], v[132:135], v[64:67]
	v_mfma_f32_16x16x32_bf16 v[60:63], v[106:109], v[136:139], v[60:63]
	v_mfma_f32_16x16x32_bf16 v[52:55], v[106:109], v[148:151], v[52:55]
	v_mfma_f32_16x16x32_bf16 v[48:51], v[106:109], v[152:155], v[48:51]
	v_mfma_f32_16x16x32_bf16 v[44:47], v[110:113], v[132:135], v[44:47]
	v_mfma_f32_16x16x32_bf16 v[40:43], v[110:113], v[136:139], v[40:43]
	v_mfma_f32_16x16x32_bf16 v[36:39], v[110:113], v[148:151], v[36:39]
	v_mfma_f32_16x16x32_bf16 v[32:35], v[110:113], v[152:155], v[32:35]
	v_mfma_f32_16x16x32_bf16 v[28:31], v[140:143], v[132:135], v[28:31]
	v_mfma_f32_16x16x32_bf16 v[24:27], v[140:143], v[136:139], v[24:27]
	v_mfma_f32_16x16x32_bf16 v[20:23], v[140:143], v[148:151], v[20:23]
	v_mfma_f32_16x16x32_bf16 v[16:19], v[140:143], v[152:155], v[16:19]
	v_mfma_f32_16x16x32_bf16 v[12:15], v[144:147], v[132:135], v[12:15]
	v_mfma_f32_16x16x32_bf16 v[8:11], v[144:147], v[136:139], v[8:11]
	v_mfma_f32_16x16x32_bf16 v[4:7], v[144:147], v[148:151], v[4:7]
	v_mfma_f32_16x16x32_bf16 v[56:59], v[144:147], v[152:155], v[56:59]
	v_xor_b32_e32 v196, 0x8000, v196
	v_xor_b32_e32 v197, 0x8000, v197
	v_xor_b32_e32 v198, 0x8000, v198
	v_xor_b32_e32 v199, 0x8000, v199
	s_waitcnt vmcnt(0) lgkmcnt(0)
	s_barrier

; DEVINL int tidx() { int t = threadIdx.x; asm volatile("" : "+v"(t)); return t; }
; DEVINL float lane_xor1(float v) { return dpp_f<0xB1>(v); }
; DEVINL f32x4 mfma16(bf16x8 a, bf16x8 b, f32x4 c) { return __builtin_amdgcn_mfma_f32_16x16x32_bf16(a, b, c, 0, 0, 0); }
; DEVINL void gemm_loop(f32x4 (&acc)[4][4], const u16* __restrict__ A, int lda, const u16* __restrict__ Bt, int ldb,
;                       int m0, int n0, int k0, int nk, char* smem) {
;     ...
;     __builtin_amdgcn_sched_barrier(0);
; #pragma unroll
;     for (int ks = 0; ks < 2; ++ks)
; #pragma unroll
;       for (int mf = 0; mf < 4; ++mf)
; #pragma unroll
;         for (int nf = 0; nf < 4; ++nf) acc[mf][nf] = mfma16(af[ks][mf], bfr[ks][nf], acc[mf][nf]);
;   }
; DEVINL void p4_tile(const Params& p, char* smem, int mt, int nt) {
;     ...
;   {
;     const int tid = tidx(), row = tid >> 1, half = tid & 1;
;     const float* ss5p = (const float*)(p.ws + OFF_SS5P);
;     float ssq = 0.f;
; #pragma unroll
;     for (int q = 0; q < 2; ++q) {
;       const float2 v = *(const float2*)(ss5p + ((size_t)(half * 2 + q) * M + m0 + row) * 2);
;       ssq += v.x + v.y;
;     }
;     ssq += lane_xor1(ssq);
;     __syncthreads();
;     float* rs5 = (float*)smem;
;     if (half == 0) rs5[row] = rsqrtf(ssq * (1.f / 512.f) + EPS);
;     __syncthreads();
.Lkp_b183_last:
	v_mfma_f32_16x16x32_bf16 v[64:67], v[156:159], v[164:167], v[64:67]
	v_mfma_f32_16x16x32_bf16 v[60:63], v[156:159], v[168:171], v[60:63]
	v_mfma_f32_16x16x32_bf16 v[52:55], v[156:159], v[180:183], v[52:55]
	v_mfma_f32_16x16x32_bf16 v[48:51], v[156:159], v[184:187], v[48:51]
	v_mfma_f32_16x16x32_bf16 v[44:47], v[160:163], v[164:167], v[44:47]
	v_mfma_f32_16x16x32_bf16 v[40:43], v[160:163], v[168:171], v[40:43]
	v_mfma_f32_16x16x32_bf16 v[36:39], v[160:163], v[180:183], v[36:39]
	v_mfma_f32_16x16x32_bf16 v[32:35], v[160:163], v[184:187], v[32:35]
	v_mfma_f32_16x16x32_bf16 v[28:31], v[172:175], v[164:167], v[28:31]
	v_mfma_f32_16x16x32_bf16 v[24:27], v[172:175], v[168:171], v[24:27]
	v_mfma_f32_16x16x32_bf16 v[20:23], v[172:175], v[180:183], v[20:23]
	v_mfma_f32_16x16x32_bf16 v[16:19], v[172:175], v[184:187], v[16:19]
	v_mfma_f32_16x16x32_bf16 v[12:15], v[176:179], v[164:167], v[12:15]
	v_mfma_f32_16x16x32_bf16 v[8:11], v[176:179], v[168:171], v[8:11]
	v_mfma_f32_16x16x32_bf16 v[4:7], v[176:179], v[180:183], v[4:7]
	v_mfma_f32_16x16x32_bf16 v[56:59], v[176:179], v[184:187], v[56:59]
	s_mov_b32 s1, 0x8000
	v_add_u32_e32 v69, s1, v90
	v_add_u32_e32 v90, v69, v87
	v_add_u32_e32 v69, v69, v88
	s_waitcnt vmcnt(0)
	s_barrier
	ds_read_b128 v[70:73], v90
	ds_read_b128 v[74:77], v90 offset:2048
	ds_read_b128 v[78:81], v69 offset:16384
	ds_read_b128 v[82:85], v69 offset:18432
	ds_read_b128 v[106:109], v90 offset:4096
	ds_read_b128 v[110:113], v90 offset:6144
	ds_read_b128 v[132:135], v69 offset:20480
	ds_read_b128 v[136:139], v69 offset:22528
	v_add_u32_e32 v69, s1, v89
	v_add_u32_e32 v87, v69, v87
	v_add_u32_e32 v69, v69, v88
	ds_read_b128 v[88:91], v87
	ds_read_b128 v[140:143], v87 offset:2048
	ds_read_b128 v[144:147], v69 offset:16384
	ds_read_b128 v[148:151], v69 offset:18432
	ds_read_b128 v[152:155], v87 offset:4096
	ds_read_b128 v[156:159], v87 offset:6144
	ds_read_b128 v[160:163], v69 offset:20480
	ds_read_b128 v[164:167], v69 offset:22528
	s_waitcnt lgkmcnt(13)
	v_mfma_f32_16x16x32_bf16 v[64:67], v[70:73], v[78:81], v[64:67]
	v_mov_b32_e32 v87, v0
	v_ashrrev_i32_e32 v69, 31, v68
	s_waitcnt lgkmcnt(12)
	v_mfma_f32_16x16x32_bf16 v[60:63], v[70:73], v[82:85], v[60:63]
	v_readlane_b32 s0, v194, 21
	s_mov_b32 s34, 0x8900
	v_readlane_b32 s1, v194, 22
	s_waitcnt lgkmcnt(9)
	v_mfma_f32_16x16x32_bf16 v[52:55], v[70:73], v[132:135], v[52:55]
	s_waitcnt lgkmcnt(8)
	v_mfma_f32_16x16x32_bf16 v[48:51], v[70:73], v[136:139], v[48:51]
	v_mfma_f32_16x16x32_bf16 v[36:39], v[74:77], v[132:135], v[36:39]
	v_mfma_f32_16x16x32_bf16 v[44:47], v[74:77], v[78:81], v[44:47]
	v_mfma_f32_16x16x32_bf16 v[40:43], v[74:77], v[82:85], v[40:43]
	v_mfma_f32_16x16x32_bf16 v[32:35], v[74:77], v[136:139], v[32:35]
	v_mfma_f32_16x16x32_bf16 v[72:75], v[106:109], v[78:81], v[28:31]
	v_mfma_f32_16x16x32_bf16 v[168:171], v[106:109], v[82:85], v[24:27]
	v_mfma_f32_16x16x32_bf16 v[172:175], v[106:109], v[132:135], v[20:23]
	v_mfma_f32_16x16x32_bf16 v[106:109], v[106:109], v[136:139], v[16:19]
	v_mfma_f32_16x16x32_bf16 v[76:79], v[110:113], v[78:81], v[12:15]
	v_mfma_f32_16x16x32_bf16 v[80:83], v[110:113], v[82:85], v[8:11]
	v_mfma_f32_16x16x32_bf16 v[132:135], v[110:113], v[132:135], v[4:7]
	s_waitcnt lgkmcnt(5)
	v_mfma_f32_16x16x32_bf16 v[4:7], v[88:91], v[144:147], v[64:67]
	s_waitcnt lgkmcnt(4)
	v_mfma_f32_16x16x32_bf16 v[8:11], v[88:91], v[148:151], v[60:63]
	s_waitcnt lgkmcnt(1)
	v_mfma_f32_16x16x32_bf16 v[12:15], v[88:91], v[160:163], v[52:55]
	s_waitcnt lgkmcnt(0)
	v_mfma_f32_16x16x32_bf16 v[16:19], v[88:91], v[164:167], v[48:51]
	v_mov_b32_e32 v89, v0
	v_mov_b32_e32 v55, v2
	v_mfma_f32_16x16x32_bf16 v[28:31], v[140:143], v[160:163], v[36:39]
	s_nop 2
	v_mov_b32_e32 v36, v0
	v_mfma_f32_16x16x32_bf16 v[20:23], v[140:143], v[144:147], v[44:47]
	v_ashrrev_i32_e32 v70, 1, v36
	v_and_b32_e32 v64, 1, v36
	v_ashrrev_i32_e32 v71, 31, v70
	v_lshl_add_u64 v[52:53], v[70:71], 0, v[68:69]
	v_mul_u32_u24_e32 v44, 0x8900, v64
	v_mov_b32_e32 v45, v2
	v_lshl_add_u64 v[48:49], v[52:53], 0, v[44:45]
	v_mad_u32_u24 v54, v64, s34, v122
	v_lshl_add_u64 v[48:49], v[48:49], 3, s[0:1]
	v_lshl_add_u64 v[52:53], v[52:53], 0, v[54:55]
	v_mfma_f32_16x16x32_bf16 v[110:113], v[110:113], v[136:139], v[56:59]
	v_cmp_eq_u32_e64 s[34:35], 0, v64
	s_nop 1
	global_load_dwordx2 v[56:57], v[48:49], off
	v_lshl_add_u64 v[58:59], v[52:53], 3, s[0:1]
	global_load_dwordx2 v[60:61], v[58:59], off
	v_mfma_f32_16x16x32_bf16 v[24:27], v[140:143], v[148:151], v[40:43]
	s_barrier
	v_mfma_f32_16x16x32_bf16 v[32:35], v[140:143], v[164:167], v[32:35]
	s_waitcnt vmcnt(1)
	v_add_f32_e32 v56, v56, v57
	v_add_f32_e32 v62, 0, v56
	s_waitcnt vmcnt(0)
	v_add_f32_e32 v60, v60, v61
	v_mfma_f32_16x16x32_bf16 v[36:39], v[152:155], v[144:147], v[72:75]
	v_add_f32_e32 v69, v62, v60
	v_mfma_f32_16x16x32_bf16 v[40:43], v[152:155], v[148:151], v[168:171]
	s_nop 0
	v_mov_b32_dpp v71, v69 quad_perm:[1,0,3,2] row_mask:0xf bank_mask:0xf bound_ctrl:1
	v_mfma_f32_16x16x32_bf16 v[44:47], v[152:155], v[160:163], v[172:175]
	v_mfma_f32_16x16x32_bf16 v[48:51], v[152:155], v[164:167], v[106:109]
	v_mfma_f32_16x16x32_bf16 v[52:55], v[156:159], v[144:147], v[76:79]
	v_mfma_f32_16x16x32_bf16 v[56:59], v[156:159], v[148:151], v[80:83]
	v_mfma_f32_16x16x32_bf16 v[60:63], v[156:159], v[160:163], v[132:135]
	v_mfma_f32_16x16x32_bf16 v[64:67], v[156:159], v[164:167], v[110:113]
	s_and_saveexec_b64 s[0:1], s[34:35]
	s_cbranch_execz .LBB0_186
	v_add_f32_e32 v69, v69, v71
	v_fmamk_f32 v69, v69, 0x3b000000, v93
	v_mul_f32_e32 v71, 0x4b800000, v69
	v_cmp_gt_f32_e64 s[34:35], s33, v69
	v_lshlrev_b32_e32 v70, 2, v70
	s_nop 0
	v_cndmask_b32_e64 v69, v69, v71, s[34:35]
	v_rsq_f32_e32 v69, v69
	s_nop 0
	v_mul_f32_e32 v71, 0x45800000, v69
	v_cndmask_b32_e64 v69, v69, v71, s[34:35]
	ds_write_b32 v70, v69

; DEVINL f32x4 mfma16(bf16x8 a, bf16x8 b, f32x4 c) { return __builtin_amdgcn_mfma_f32_16x16x32_bf16(a, b, c, 0, 0, 0); }
; DEVINL void gemm_loop(f32x4 (&acc)[4][4], const u16* __restrict__ A, int lda, const u16* __restrict__ Bt, int ldb,
;                       int m0, int n0, int k0, int nk, char* smem) {
;     ...
;   __syncthreads();
; #pragma unroll
;   for (int i = 0; i < 4; ++i) {
;     glds16(ga[i], smem + i * 4096 + wid * 1024);
;     glds16(gb[i], smem + 16384 + i * 4096 + wid * 1024);
;   }
;   for (int kt = 0; kt < nk; ++kt) {
;     __syncthreads();
;     char* cur = smem + (kt & 1) * 32768;
;     if (kt + 1 < nk) {
;       char* nxt = smem + ((kt + 1) & 1) * 32768;
; #pragma unroll
;       for (int i = 0; i < 4; ++i) {
;         glds16(ga[i] + (kt + 1) * 64, nxt + i * 4096 + wid * 1024);
;         glds16(gb[i] + (kt + 1) * 64, nxt + 16384 + i * 4096 + wid * 1024);
;       }
;     }
;     bf16x8 af[2][4], bfr[2][4];
; #pragma unroll
;     for (int ks = 0; ks < 2; ++ks)
; #pragma unroll
;       for (int f = 0; f < 4; ++f) {
;         int ra = wr * 64 + f * 16 + fr, rb = wc * 64 + f * 16 + fr;
;         int ch = ks * 4 + fq;
;         af[ks][f] = *(const bf16x8*)(cur + ra * 128 + ((ch ^ ((ra >> 1) & 7)) << 4));
;         bfr[ks][f] = *(const bf16x8*)(cur + 16384 + rb * 128 + ((ch ^ ((rb >> 1) & 7)) << 4));
;       }
;     __builtin_amdgcn_sched_barrier(0);
; #pragma unroll
;     for (int ks = 0; ks < 2; ++ks)
; #pragma unroll
;       for (int mf = 0; mf < 4; ++mf)
; #pragma unroll
;         for (int nf = 0; nf < 4; ++nf) acc[mf][nf] = mfma16(af[ks][mf], bfr[ks][nf], acc[mf][nf]);
;   }
.LBB0_187:
	v_readfirstlane_b32 s100, v90
	v_add_u32_e32 v196, v106, v91
	v_add_u32_e32 v197, v106, v102
	v_add_u32_e32 v198, v105, v91
	v_add_u32_e32 v199, v105, v102
	s_mov_b32 s101, s100
	v_lshlrev_b32_e32 v202, 4, v0
	s_waitcnt vmcnt(0)
	s_barrier
	s_add_u32 m0, s100, 0x8000
	v_lshl_add_u64 v[200:201], v[70:71], 0, s[34:35]
	global_load_lds_dwordx4 v[200:201], off
	s_add_u32 m0, s100, 0xc000
	v_lshl_add_u64 v[200:201], v[72:73], 0, s[34:35]
	global_load_lds_dwordx4 v[200:201], off
	s_add_u32 m0, s100, 0x9000
	v_lshl_add_u64 v[200:201], v[74:75], 0, s[34:35]
	global_load_lds_dwordx4 v[200:201], off
	s_add_u32 m0, s100, 0xd000
	v_lshl_add_u64 v[200:201], v[76:77], 0, s[34:35]
	global_load_lds_dwordx4 v[200:201], off
	s_add_u32 m0, s100, 0xa000
	v_lshl_add_u64 v[200:201], v[78:79], 0, s[34:35]
	global_load_lds_dwordx4 v[200:201], off
	s_add_u32 m0, s100, 0xe000
	v_lshl_add_u64 v[200:201], v[80:81], 0, s[34:35]
	global_load_lds_dwordx4 v[200:201], off
	s_add_u32 m0, s100, 0xb000
	v_lshl_add_u64 v[200:201], v[82:83], 0, s[34:35]
	global_load_lds_dwordx4 v[200:201], off
	s_add_u32 m0, s100, 0xf000
	v_lshl_add_u64 v[200:201], v[84:85], 0, s[34:35]
	global_load_lds_dwordx4 v[200:201], off
	ds_read_b128 v[108:111], v196
	ds_read_b128 v[132:135], v196 offset:2048
	ds_read_b128 v[136:139], v197 offset:16384
	ds_read_b128 v[140:143], v197 offset:18432
	ds_read_b128 v[144:147], v196 offset:4096
	ds_read_b128 v[148:151], v196 offset:6144
	ds_read_b128 v[152:155], v197 offset:20480
	ds_read_b128 v[156:159], v197 offset:22528
	ds_read_b128 v[160:163], v198
	ds_read_b128 v[164:167], v198 offset:2048
	ds_read_b128 v[168:171], v199 offset:16384
	ds_read_b128 v[172:175], v199 offset:18432
	ds_read_b128 v[176:179], v198 offset:4096
	ds_read_b128 v[180:183], v198 offset:6144
	ds_read_b128 v[184:187], v199 offset:20480
	ds_read_b128 v[188:191], v199 offset:22528
	s_waitcnt lgkmcnt(8)
	v_mfma_f32_16x16x32_bf16 v[4:7], v[108:111], v[136:139], v[4:7]
	v_mfma_f32_16x16x32_bf16 v[8:11], v[108:111], v[140:143], v[8:11]
	v_mfma_f32_16x16x32_bf16 v[12:15], v[108:111], v[152:155], v[12:15]
	v_mfma_f32_16x16x32_bf16 v[16:19], v[108:111], v[156:159], v[16:19]
	v_mfma_f32_16x16x32_bf16 v[20:23], v[132:135], v[136:139], v[20:23]
	v_mfma_f32_16x16x32_bf16 v[24:27], v[132:135], v[140:143], v[24:27]
	v_mfma_f32_16x16x32_bf16 v[28:31], v[132:135], v[152:155], v[28:31]
	v_mfma_f32_16x16x32_bf16 v[32:35], v[132:135], v[156:159], v[32:35]
	v_mfma_f32_16x16x32_bf16 v[36:39], v[144:147], v[136:139], v[36:39]
	v_mfma_f32_16x16x32_bf16 v[40:43], v[144:147], v[140:143], v[40:43]
	v_mfma_f32_16x16x32_bf16 v[44:47], v[144:147], v[152:155], v[44:47]
	v_mfma_f32_16x16x32_bf16 v[48:51], v[144:147], v[156:159], v[48:51]
	v_mfma_f32_16x16x32_bf16 v[52:55], v[148:151], v[136:139], v[52:55]
	v_mfma_f32_16x16x32_bf16 v[56:59], v[148:151], v[140:143], v[56:59]
	v_mfma_f32_16x16x32_bf16 v[60:63], v[148:151], v[152:155], v[60:63]
	v_mfma_f32_16x16x32_bf16 v[64:67], v[148:151], v[156:159], v[64:67]
	v_xor_b32_e32 v196, 0x8000, v196
	v_xor_b32_e32 v197, 0x8000, v197
	v_xor_b32_e32 v198, 0x8000, v198
	v_xor_b32_e32 v199, 0x8000, v199
	s_waitcnt vmcnt(0) lgkmcnt(0)
	s_barrier
.Lkp_b187_loop:
	s_add_u32 s34, s34, 0x80
	s_addc_u32 s35, s35, 0
	s_cmpk_eq_i32 s34, 0x380
	s_cbranch_scc1 .Lkp_b187_last
	v_mfma_f32_16x16x32_bf16 v[4:7], v[160:163], v[168:171], v[4:7]
	s_add_u32 m0, s101, 0x0
	v_lshl_add_u64 v[200:201], v[70:71], 0, s[34:35]
	global_load_lds_dwordx4 v[200:201], off
	v_mfma_f32_16x16x32_bf16 v[8:11], v[160:163], v[172:175], v[8:11]
	s_add_u32 m0, s101, 0x4000
	v_lshl_add_u64 v[200:201], v[72:73], 0, s[34:35]
	global_load_lds_dwordx4 v[200:201], off
	v_mfma_f32_16x16x32_bf16 v[12:15], v[160:163], v[184:187], v[12:15]
	s_add_u32 m0, s101, 0x1000
	v_lshl_add_u64 v[200:201], v[74:75], 0, s[34:35]
	global_load_lds_dwordx4 v[200:201], off
	v_mfma_f32_16x16x32_bf16 v[16:19], v[160:163], v[188:191], v[16:19]
	s_add_u32 m0, s101, 0x5000
	v_lshl_add_u64 v[200:201], v[76:77], 0, s[34:35]
	global_load_lds_dwordx4 v[200:201], off
	v_mfma_f32_16x16x32_bf16 v[20:23], v[164:167], v[168:171], v[20:23]
	s_add_u32 m0, s101, 0x2000
	v_lshl_add_u64 v[200:201], v[78:79], 0, s[34:35]
	global_load_lds_dwordx4 v[200:201], off
	ds_read_b128 v[108:111], v196
	v_mfma_f32_16x16x32_bf16 v[24:27], v[164:167], v[172:175], v[24:27]
	s_add_u32 m0, s101, 0x6000
	v_lshl_add_u64 v[200:201], v[80:81], 0, s[34:35]
	global_load_lds_dwordx4 v[200:201], off
	ds_read_b128 v[132:135], v196 offset:2048
	v_mfma_f32_16x16x32_bf16 v[28:31], v[164:167], v[184:187], v[28:31]
	s_add_u32 m0, s101, 0x3000
	v_lshl_add_u64 v[200:201], v[82:83], 0, s[34:35]
	global_load_lds_dwordx4 v[200:201], off
	ds_read_b128 v[136:139], v197 offset:16384
	v_mfma_f32_16x16x32_bf16 v[32:35], v[164:167], v[188:191], v[32:35]
	s_add_u32 m0, s101, 0x7000
	v_lshl_add_u64 v[200:201], v[84:85], 0, s[34:35]
	global_load_lds_dwordx4 v[200:201], off
	ds_read_b128 v[140:143], v197 offset:18432
	v_mfma_f32_16x16x32_bf16 v[36:39], v[176:179], v[168:171], v[36:39]
	ds_read_b128 v[144:147], v196 offset:4096
	v_mfma_f32_16x16x32_bf16 v[40:43], v[176:179], v[172:175], v[40:43]
	ds_read_b128 v[148:151], v196 offset:6144
	v_mfma_f32_16x16x32_bf16 v[44:47], v[176:179], v[184:187], v[44:47]
	ds_read_b128 v[152:155], v197 offset:20480
	v_mfma_f32_16x16x32_bf16 v[48:51], v[176:179], v[188:191], v[48:51]
	ds_read_b128 v[156:159], v197 offset:22528
	v_mfma_f32_16x16x32_bf16 v[52:55], v[180:183], v[168:171], v[52:55]
	v_mfma_f32_16x16x32_bf16 v[56:59], v[180:183], v[172:175], v[56:59]
	v_mfma_f32_16x16x32_bf16 v[60:63], v[180:183], v[184:187], v[60:63]
	v_mfma_f32_16x16x32_bf16 v[64:67], v[180:183], v[188:191], v[64:67]
	s_xor_b32 s101, s101, 0x8000
	s_waitcnt lgkmcnt(0)
; DEVINL f32x4 mfma16(bf16x8 a, bf16x8 b, f32x4 c) { return __builtin_amdgcn_mfma_f32_16x16x32_bf16(a, b, c, 0, 0, 0); }
; DEVINL void gemm_loop(f32x4 (&acc)[4][4], const u16* __restrict__ A, int lda, const u16* __restrict__ Bt, int ldb,
;                       int m0, int n0, int k0, int nk, char* smem) {
;     ...
;   for (int kt = 0; kt < nk; ++kt) {
;     __syncthreads();
;     char* cur = smem + (kt & 1) * 32768;
;     if (kt + 1 < nk) {
;       char* nxt = smem + ((kt + 1) & 1) * 32768;
; #pragma unroll
;       for (int i = 0; i < 4; ++i) {
;         glds16(ga[i] + (kt + 1) * 64, nxt + i * 4096 + wid * 1024);
;         glds16(gb[i] + (kt + 1) * 64, nxt + 16384 + i * 4096 + wid * 1024);
;       }
;     }
;     bf16x8 af[2][4], bfr[2][4];
; #pragma unroll
;     for (int ks = 0; ks < 2; ++ks)
; #pragma unroll
;       for (int f = 0; f < 4; ++f) {
;         int ra = wr * 64 + f * 16 + fr, rb = wc * 64 + f * 16 + fr;
;         int ch = ks * 4 + fq;
;         af[ks][f] = *(const bf16x8*)(cur + ra * 128 + ((ch ^ ((ra >> 1) & 7)) << 4));
;         bfr[ks][f] = *(const bf16x8*)(cur + 16384 + rb * 128 + ((ch ^ ((rb >> 1) & 7)) << 4));
;       }
;     __builtin_amdgcn_sched_barrier(0);
; #pragma unroll
;     for (int ks = 0; ks < 2; ++ks)
; #pragma unroll
;       for (int mf = 0; mf < 4; ++mf)
; #pragma unroll
;         for (int nf = 0; nf < 4; ++nf) acc[mf][nf] = mfma16(af[ks][mf], bfr[ks][nf], acc[mf][nf]);
;   }
; DEVINL void p4_tile(const Params& p, char* smem, int mt, int nt) {
;     ...
;   u16* mixo = (u16*)(p.ws + OFF_MIXO);
; #pragma unroll
;   for (int mf = 0; mf < 4; ++mf) {
;     const int rb = m0 + wr * 64 + mf * 16 + (lane >> 4) * 4;
; #pragma unroll
;     for (int nf = 0; nf < 4; ++nf) {
;       const int col = n0 + wc * 64 + nf * 16 + (lane & 15);
;       store_pairs(mixo, 1024, rb, col, acc[mf][nf][0], acc[mf][nf][1], acc[mf][nf][2], acc[mf][nf][3]);
;     }
;   }
	v_mfma_f32_16x16x32_bf16 v[4:7], v[108:111], v[136:139], v[4:7]
	ds_read_b128 v[160:163], v198
	v_mfma_f32_16x16x32_bf16 v[8:11], v[108:111], v[140:143], v[8:11]
	ds_read_b128 v[164:167], v198 offset:2048
	v_mfma_f32_16x16x32_bf16 v[12:15], v[108:111], v[152:155], v[12:15]
	ds_read_b128 v[168:171], v199 offset:16384
	v_mfma_f32_16x16x32_bf16 v[16:19], v[108:111], v[156:159], v[16:19]
	ds_read_b128 v[172:175], v199 offset:18432
	v_mfma_f32_16x16x32_bf16 v[20:23], v[132:135], v[136:139], v[20:23]
	ds_read_b128 v[176:179], v198 offset:4096
	v_mfma_f32_16x16x32_bf16 v[24:27], v[132:135], v[140:143], v[24:27]
	ds_read_b128 v[180:183], v198 offset:6144
	v_mfma_f32_16x16x32_bf16 v[28:31], v[132:135], v[152:155], v[28:31]
	ds_read_b128 v[184:187], v199 offset:20480
	v_mfma_f32_16x16x32_bf16 v[32:35], v[132:135], v[156:159], v[32:35]
	ds_read_b128 v[188:191], v199 offset:22528
	v_mfma_f32_16x16x32_bf16 v[36:39], v[144:147], v[136:139], v[36:39]
	v_mfma_f32_16x16x32_bf16 v[40:43], v[144:147], v[140:143], v[40:43]
	v_mfma_f32_16x16x32_bf16 v[44:47], v[144:147], v[152:155], v[44:47]
	v_mfma_f32_16x16x32_bf16 v[48:51], v[144:147], v[156:159], v[48:51]
	v_mfma_f32_16x16x32_bf16 v[52:55], v[148:151], v[136:139], v[52:55]
	v_mfma_f32_16x16x32_bf16 v[56:59], v[148:151], v[140:143], v[56:59]
	v_mfma_f32_16x16x32_bf16 v[60:63], v[148:151], v[152:155], v[60:63]
	v_mfma_f32_16x16x32_bf16 v[64:67], v[148:151], v[156:159], v[64:67]
	v_xor_b32_e32 v196, 0x8000, v196
	v_xor_b32_e32 v197, 0x8000, v197
	v_xor_b32_e32 v198, 0x8000, v198
	v_xor_b32_e32 v199, 0x8000, v199
	s_waitcnt vmcnt(0) lgkmcnt(0)
	s_barrier
	s_branch .Lkp_b187_loop
.Lkp_b187_last:
	v_mfma_f32_16x16x32_bf16 v[4:7], v[160:163], v[168:171], v[4:7]
	v_mfma_f32_16x16x32_bf16 v[8:11], v[160:163], v[172:175], v[8:11]
	v_mfma_f32_16x16x32_bf16 v[12:15], v[160:163], v[184:187], v[12:15]
	v_mfma_f32_16x16x32_bf16 v[16:19], v[160:163], v[188:191], v[16:19]
	v_mfma_f32_16x16x32_bf16 v[20:23], v[164:167], v[168:171], v[20:23]
	v_mfma_f32_16x16x32_bf16 v[24:27], v[164:167], v[172:175], v[24:27]
	v_mfma_f32_16x16x32_bf16 v[28:31], v[164:167], v[184:187], v[28:31]
	v_mfma_f32_16x16x32_bf16 v[32:35], v[164:167], v[188:191], v[32:35]
	v_mfma_f32_16x16x32_bf16 v[36:39], v[176:179], v[168:171], v[36:39]
	v_mfma_f32_16x16x32_bf16 v[40:43], v[176:179], v[172:175], v[40:43]
	v_mfma_f32_16x16x32_bf16 v[44:47], v[176:179], v[184:187], v[44:47]
	v_mfma_f32_16x16x32_bf16 v[48:51], v[176:179], v[188:191], v[48:51]
	v_mfma_f32_16x16x32_bf16 v[52:55], v[180:183], v[168:171], v[52:55]
	v_mfma_f32_16x16x32_bf16 v[56:59], v[180:183], v[172:175], v[56:59]
	v_mfma_f32_16x16x32_bf16 v[60:63], v[180:183], v[184:187], v[60:63]
	v_mfma_f32_16x16x32_bf16 v[64:67], v[180:183], v[188:191], v[64:67]
	s_mov_b32 s1, 0x8000
	v_add_u32_e32 v70, s1, v106
	v_add_u32_e32 v90, v70, v91
	s_waitcnt vmcnt(0)
	s_barrier
	v_add_u32_e32 v131, v70, v102
	ds_read_b128 v[70:73], v90
	ds_read_b128 v[74:77], v90 offset:2048
	ds_read_b128 v[78:81], v131 offset:16384
	ds_read_b128 v[82:85], v131 offset:18432
	ds_read_b128 v[106:109], v90 offset:4096
	ds_read_b128 v[110:113], v90 offset:6144
	ds_read_b128 v[132:135], v131 offset:20480
	ds_read_b128 v[136:139], v131 offset:22528
	v_add_u32_e32 v90, s1, v105
	v_add_u32_e32 v91, v90, v91
	v_add_u32_e32 v90, v90, v102
	ds_read_b128 v[140:143], v91
	ds_read_b128 v[144:147], v91 offset:2048
	ds_read_b128 v[148:151], v90 offset:16384
	ds_read_b128 v[152:155], v90 offset:18432
	ds_read_b128 v[156:159], v91 offset:4096
	ds_read_b128 v[160:163], v91 offset:6144
	ds_read_b128 v[164:167], v90 offset:20480
	ds_read_b128 v[168:171], v90 offset:22528
	v_and_b32_e32 v89, 64, v89
	s_waitcnt lgkmcnt(9)
	v_mfma_f32_16x16x32_bf16 v[12:15], v[70:73], v[132:135], v[12:15]
	v_add_u32_e32 v3, v3, v1
	v_mfma_f32_16x16x32_bf16 v[56:59], v[110:113], v[82:85], v[56:59]
	v_mfma_f32_16x16x32_bf16 v[4:7], v[70:73], v[78:81], v[4:7]
	v_mfma_f32_16x16x32_bf16 v[28:31], v[74:77], v[132:135], v[28:31]
	v_mfma_f32_16x16x32_bf16 v[172:175], v[106:109], v[132:135], v[44:47]
	v_mfma_f32_16x16x32_bf16 v[60:63], v[110:113], v[132:135], v[60:63]
	s_waitcnt lgkmcnt(1)
	v_mfma_f32_16x16x32_bf16 v[132:135], v[140:143], v[164:167], v[12:15]
	v_mfma_f32_16x16x32_bf16 v[12:15], v[160:163], v[152:155], v[56:59]
	s_nop 2
	v_and_b32_e32 v57, 14, v87
	v_mfma_f32_16x16x32_bf16 v[8:11], v[70:73], v[82:85], v[8:11]
	v_or3_b32 v58, v57, v89, v86
	v_and_b32_e32 v57, 1, v87
	v_add_u32_e32 v56, v88, v68
	v_mfma_f32_16x16x32_bf16 v[20:23], v[74:77], v[78:81], v[20:23]
	v_cmp_eq_u32_e64 s[34:35], 0, v57
	v_lshlrev_b32_e32 v57, 1, v57
	v_or3_b32 v56, v56, v57, v69
	v_mfma_f32_16x16x32_bf16 v[24:27], v[74:77], v[82:85], v[24:27]
	v_ashrrev_i32_e32 v57, 31, v56
	v_mfma_f32_16x16x32_bf16 v[32:35], v[74:77], v[136:139], v[32:35]
	v_mfma_f32_16x16x32_bf16 v[74:77], v[106:109], v[82:85], v[40:43]
	v_mfma_f32_16x16x32_bf16 v[64:67], v[110:113], v[136:139], v[64:67]
	v_mfma_f32_16x16x32_bf16 v[82:85], v[140:143], v[148:151], v[4:7]
	v_mfma_f32_16x16x32_bf16 v[16:19], v[70:73], v[136:139], v[16:19]
	v_mfma_f32_16x16x32_bf16 v[70:73], v[106:109], v[78:81], v[36:39]
	s_nop 5
	v_mov_b32_dpp v59, v83 quad_perm:[1,0,3,2] row_mask:0xf bank_mask:0xf bound_ctrl:1
	v_cndmask_b32_e64 v59, v85, v59, s[34:35]
	v_add_u32_e32 v59, 0x8000, v59
	v_mfma_f32_16x16x32_bf16 v[78:81], v[110:113], v[78:81], v[52:55]
	v_mfma_f32_16x16x32_bf16 v[110:113], v[140:143], v[152:155], v[8:11]
	v_mfma_f32_16x16x32_bf16 v[8:11], v[160:163], v[164:167], v[60:63]
	s_waitcnt lgkmcnt(0)
; DEVINL void p4_tile(const Params& p, char* smem, int mt, int nt) {
;     ...
;   u16* mixo = (u16*)(p.ws + OFF_MIXO);
; #pragma unroll
;   for (int mf = 0; mf < 4; ++mf) {
;     const int rb = m0 + wr * 64 + mf * 16 + (lane >> 4) * 4;
; #pragma unroll
;     for (int nf = 0; nf < 4; ++nf) {
;       const int col = n0 + wc * 64 + nf * 16 + (lane & 15);
;       store_pairs(mixo, 1024, rb, col, acc[mf][nf][0], acc[mf][nf][1], acc[mf][nf][2], acc[mf][nf][3]);
;     }
;   }
	v_mfma_f32_16x16x32_bf16 v[4:7], v[160:163], v[168:171], v[64:67]
	s_nop 0
	v_lshlrev_b64 v[60:61], 11, v[56:57]
	v_mov_b32_dpp v57, v82 quad_perm:[1,0,3,2] row_mask:0xf bank_mask:0xf bound_ctrl:1
	v_cndmask_b32_e64 v57, v84, v57, s[34:35]
	v_mov_b32_dpp v64, v84 quad_perm:[1,0,3,2] row_mask:0xf bank_mask:0xf bound_ctrl:1
	v_cndmask_b32_e64 v64, v64, v82, s[34:35]
	v_mov_b32_dpp v65, v85 quad_perm:[1,0,3,2] row_mask:0xf bank_mask:0xf bound_ctrl:1
	v_add_u32_e32 v57, 0x8000, v57
	v_add_u32_e32 v64, 0x8000, v64
	v_perm_b32 v57, v57, v64, s25
	v_cndmask_b32_e64 v64, v65, v83, s[34:35]
	v_add_u32_e32 v64, 0x8000, v64
	v_or_b32_e32 v62, 1, v56
	v_perm_b32 v64, v59, v64, s25
	v_ashrrev_i32_e32 v59, 31, v58
	v_lshl_add_u64 v[60:61], s[22:23], 0, v[60:61]
	v_ashrrev_i32_e32 v63, 31, v62
	v_lshlrev_b64 v[58:59], 1, v[58:59]
	v_lshlrev_b64 v[62:63], 11, v[62:63]
	v_lshl_add_u64 v[60:61], v[60:61], 0, v[58:59]
	v_lshl_add_u64 v[62:63], s[22:23], 0, v[62:63]
	global_store_dword v[60:61], v57, off
	v_mov_b32_dpp v57, v110 quad_perm:[1,0,3,2] row_mask:0xf bank_mask:0xf bound_ctrl:1
	v_mov_b32_dpp v65, v112 quad_perm:[1,0,3,2] row_mask:0xf bank_mask:0xf bound_ctrl:1
	v_lshl_add_u64 v[62:63], v[62:63], 0, v[58:59]
	v_cndmask_b32_e64 v57, v112, v57, s[34:35]
	v_cndmask_b32_e64 v65, v65, v110, s[34:35]
	global_store_dword v[62:63], v64, off
	v_mov_b32_dpp v64, v111 quad_perm:[1,0,3,2] row_mask:0xf bank_mask:0xf bound_ctrl:1
	v_mov_b32_dpp v66, v113 quad_perm:[1,0,3,2] row_mask:0xf bank_mask:0xf bound_ctrl:1
	v_add_u32_e32 v57, 0x8000, v57
	v_add_u32_e32 v65, 0x8000, v65
	v_perm_b32 v57, v57, v65, s25
	v_cndmask_b32_e64 v64, v113, v64, s[34:35]
	v_cndmask_b32_e64 v65, v66, v111, s[34:35]
	v_add_u32_e32 v64, 0x8000, v64
	v_add_u32_e32 v65, 0x8000, v65
	v_perm_b32 v64, v64, v65, s25
	global_store_dword v[60:61], v57, off offset:32
	global_store_dword v[62:63], v64, off offset:32
	v_mov_b32_dpp v57, v132 quad_perm:[1,0,3,2] row_mask:0xf bank_mask:0xf bound_ctrl:1
	v_mov_b32_dpp v65, v134 quad_perm:[1,0,3,2] row_mask:0xf bank_mask:0xf bound_ctrl:1
	v_mfma_f32_16x16x32_bf16 v[52:55], v[140:143], v[168:171], v[16:19]
	v_cndmask_b32_e64 v57, v134, v57, s[34:35]
	v_cndmask_b32_e64 v65, v65, v132, s[34:35]
	v_mov_b32_dpp v64, v133 quad_perm:[1,0,3,2] row_mask:0xf bank_mask:0xf bound_ctrl:1
	v_mov_b32_dpp v66, v135 quad_perm:[1,0,3,2] row_mask:0xf bank_mask:0xf bound_ctrl:1
	v_add_u32_e32 v57, 0x8000, v57
	v_add_u32_e32 v65, 0x8000, v65
	v_perm_b32 v57, v57, v65, s25
	v_cndmask_b32_e64 v64, v135, v64, s[34:35]
	v_cndmask_b32_e64 v65, v66, v133, s[34:35]
	v_add_u32_e32 v64, 0x8000, v64
	v_add_u32_e32 v65, 0x8000, v65
	v_perm_b32 v64, v64, v65, s25
	global_store_dword v[60:61], v57, off offset:64
	global_store_dword v[62:63], v64, off offset:64
	v_mov_b32_dpp v57, v52 quad_perm:[1,0,3,2] row_mask:0xf bank_mask:0xf bound_ctrl:1
	v_mov_b32_dpp v65, v54 quad_perm:[1,0,3,2] row_mask:0xf bank_mask:0xf bound_ctrl:1
	v_mfma_f32_16x16x32_bf16 v[106:109], v[106:109], v[136:139], v[48:51]
	v_cndmask_b32_e64 v54, v54, v57, s[34:35]
	v_cndmask_b32_e64 v52, v65, v52, s[34:35]
	v_mov_b32_dpp v64, v53 quad_perm:[1,0,3,2] row_mask:0xf bank_mask:0xf bound_ctrl:1
	v_mfma_f32_16x16x32_bf16 v[48:51], v[144:147], v[148:151], v[20:23]
	v_mov_b32_dpp v66, v55 quad_perm:[1,0,3,2] row_mask:0xf bank_mask:0xf bound_ctrl:1
	v_add_u32_e32 v54, 0x8000, v54
	v_add_u32_e32 v52, 0x8000, v52
	v_perm_b32 v52, v54, v52, s25
	v_cndmask_b32_e64 v54, v55, v64, s[34:35]
	v_cndmask_b32_e64 v53, v66, v53, s[34:35]
	v_add_u32_e32 v54, 0x8000, v54
	v_add_u32_e32 v53, 0x8000, v53
	v_perm_b32 v53, v54, v53, s25
	global_store_dword v[60:61], v52, off offset:96
	global_store_dword v[62:63], v53, off offset:96
	v_mov_b32_dpp v57, v48 quad_perm:[1,0,3,2] row_mask:0xf bank_mask:0xf bound_ctrl:1
	v_mov_b32_dpp v61, v50 quad_perm:[1,0,3,2] row_mask:0xf bank_mask:0xf bound_ctrl:1
	v_or_b32_e32 v52, 16, v56
	v_cndmask_b32_e64 v50, v50, v57, s[34:35]
	v_cndmask_b32_e64 v48, v61, v48, s[34:35]
	v_mfma_f32_16x16x32_bf16 v[44:47], v[144:147], v[152:155], v[24:27]
	v_ashrrev_i32_e32 v53, 31, v52
	v_or_b32_e32 v54, 17, v56
	v_mov_b32_dpp v60, v49 quad_perm:[1,0,3,2] row_mask:0xf bank_mask:0xf bound_ctrl:1
	v_mov_b32_dpp v62, v51 quad_perm:[1,0,3,2] row_mask:0xf bank_mask:0xf bound_ctrl:1
	v_add_u32_e32 v50, 0x8000, v50
	v_add_u32_e32 v48, 0x8000, v48
	v_lshlrev_b64 v[52:53], 11, v[52:53]
	v_ashrrev_i32_e32 v55, 31, v54
	v_perm_b32 v50, v50, v48, s25
	v_cndmask_b32_e64 v48, v51, v60, s[34:35]
	v_cndmask_b32_e64 v49, v62, v49, s[34:35]
	v_lshl_add_u64 v[52:53], s[22:23], 0, v[52:53]
	v_lshlrev_b64 v[54:55], 11, v[54:55]
	v_add_u32_e32 v48, 0x8000, v48
	v_add_u32_e32 v49, 0x8000, v49
	v_lshl_add_u64 v[54:55], s[22:23], 0, v[54:55]
	v_perm_b32 v57, v48, v49, s25
	v_lshl_add_u64 v[48:49], v[52:53], 0, v[58:59]
	global_store_dword v[48:49], v50, off
	v_lshl_add_u64 v[50:51], v[54:55], 0, v[58:59]
	v_mov_b32_dpp v52, v44 quad_perm:[1,0,3,2] row_mask:0xf bank_mask:0xf bound_ctrl:1
	v_mov_b32_dpp v54, v46 quad_perm:[1,0,3,2] row_mask:0xf bank_mask:0xf bound_ctrl:1
	v_mfma_f32_16x16x32_bf16 v[40:43], v[144:147], v[164:167], v[28:31]
	v_cndmask_b32_e64 v46, v46, v52, s[34:35]
	v_cndmask_b32_e64 v44, v54, v44, s[34:35]
	v_mov_b32_dpp v53, v45 quad_perm:[1,0,3,2] row_mask:0xf bank_mask:0xf bound_ctrl:1
	v_mov_b32_dpp v55, v47 quad_perm:[1,0,3,2] row_mask:0xf bank_mask:0xf bound_ctrl:1
	v_add_u32_e32 v46, 0x8000, v46
	v_add_u32_e32 v44, 0x8000, v44
	v_perm_b32 v44, v46, v44, s25
	v_cndmask_b32_e64 v46, v47, v53, s[34:35]
	v_cndmask_b32_e64 v45, v55, v45, s[34:35]
	v_add_u32_e32 v46, 0x8000, v46
	v_add_u32_e32 v45, 0x8000, v45
; DEVINL void p4_tile(const Params& p, char* smem, int mt, int nt) {
;     ...
;   u16* mixo = (u16*)(p.ws + OFF_MIXO);
; #pragma unroll
;   for (int mf = 0; mf < 4; ++mf) {
;     const int rb = m0 + wr * 64 + mf * 16 + (lane >> 4) * 4;
; #pragma unroll
;     for (int nf = 0; nf < 4; ++nf) {
;       const int col = n0 + wc * 64 + nf * 16 + (lane & 15);
;       store_pairs(mixo, 1024, rb, col, acc[mf][nf][0], acc[mf][nf][1], acc[mf][nf][2], acc[mf][nf][3]);
;     }
;   }
	global_store_dword v[50:51], v57, off
	v_perm_b32 v45, v46, v45, s25
	global_store_dword v[48:49], v44, off offset:32
	global_store_dword v[50:51], v45, off offset:32
	v_mov_b32_dpp v44, v40 quad_perm:[1,0,3,2] row_mask:0xf bank_mask:0xf bound_ctrl:1
	v_mov_b32_dpp v46, v42 quad_perm:[1,0,3,2] row_mask:0xf bank_mask:0xf bound_ctrl:1
	v_mfma_f32_16x16x32_bf16 v[36:39], v[144:147], v[168:171], v[32:35]
	v_cndmask_b32_e64 v42, v42, v44, s[34:35]
	v_cndmask_b32_e64 v40, v46, v40, s[34:35]
	v_mov_b32_dpp v45, v41 quad_perm:[1,0,3,2] row_mask:0xf bank_mask:0xf bound_ctrl:1
	v_mov_b32_dpp v47, v43 quad_perm:[1,0,3,2] row_mask:0xf bank_mask:0xf bound_ctrl:1
	v_add_u32_e32 v42, 0x8000, v42
	v_add_u32_e32 v40, 0x8000, v40
	v_perm_b32 v40, v42, v40, s25
	v_cndmask_b32_e64 v42, v43, v45, s[34:35]
	v_cndmask_b32_e64 v41, v47, v41, s[34:35]
	v_add_u32_e32 v42, 0x8000, v42
	v_add_u32_e32 v41, 0x8000, v41
	v_mfma_f32_16x16x32_bf16 v[32:35], v[156:159], v[148:151], v[70:73]
	v_perm_b32 v41, v42, v41, s25
	global_store_dword v[48:49], v40, off offset:64
	global_store_dword v[50:51], v41, off offset:64
	v_mov_b32_dpp v40, v36 quad_perm:[1,0,3,2] row_mask:0xf bank_mask:0xf bound_ctrl:1
	v_mov_b32_dpp v42, v38 quad_perm:[1,0,3,2] row_mask:0xf bank_mask:0xf bound_ctrl:1
	v_cndmask_b32_e64 v38, v38, v40, s[34:35]
	v_cndmask_b32_e64 v36, v42, v36, s[34:35]
	v_mov_b32_dpp v41, v37 quad_perm:[1,0,3,2] row_mask:0xf bank_mask:0xf bound_ctrl:1
	v_mov_b32_dpp v43, v39 quad_perm:[1,0,3,2] row_mask:0xf bank_mask:0xf bound_ctrl:1
	v_add_u32_e32 v38, 0x8000, v38
	v_add_u32_e32 v36, 0x8000, v36
	v_perm_b32 v36, v38, v36, s25
	v_cndmask_b32_e64 v38, v39, v41, s[34:35]
	v_cndmask_b32_e64 v37, v43, v37, s[34:35]
	v_add_u32_e32 v38, 0x8000, v38
	v_add_u32_e32 v37, 0x8000, v37
	v_mov_b32_dpp v40, v32 quad_perm:[1,0,3,2] row_mask:0xf bank_mask:0xf bound_ctrl:1
	v_mov_b32_dpp v42, v34 quad_perm:[1,0,3,2] row_mask:0xf bank_mask:0xf bound_ctrl:1
	v_perm_b32 v37, v38, v37, s25
	global_store_dword v[48:49], v36, off offset:96
	global_store_dword v[50:51], v37, off offset:96
	v_or_b32_e32 v36, 32, v56
	v_cndmask_b32_e64 v34, v34, v40, s[34:35]
	v_cndmask_b32_e64 v32, v42, v32, s[34:35]
	v_mfma_f32_16x16x32_bf16 v[28:31], v[156:159], v[152:155], v[74:77]
	v_ashrrev_i32_e32 v37, 31, v36
	v_or_b32_e32 v38, 33, v56
	v_mov_b32_dpp v41, v33 quad_perm:[1,0,3,2] row_mask:0xf bank_mask:0xf bound_ctrl:1
	v_mov_b32_dpp v43, v35 quad_perm:[1,0,3,2] row_mask:0xf bank_mask:0xf bound_ctrl:1
	v_add_u32_e32 v34, 0x8000, v34
	v_add_u32_e32 v32, 0x8000, v32
	v_lshlrev_b64 v[36:37], 11, v[36:37]
	v_ashrrev_i32_e32 v39, 31, v38
	v_perm_b32 v34, v34, v32, s25
	v_cndmask_b32_e64 v32, v35, v41, s[34:35]
	v_cndmask_b32_e64 v33, v43, v33, s[34:35]
	v_lshl_add_u64 v[36:37], s[22:23], 0, v[36:37]
	v_lshlrev_b64 v[38:39], 11, v[38:39]
	v_add_u32_e32 v32, 0x8000, v32
	v_add_u32_e32 v33, 0x8000, v33
	v_lshl_add_u64 v[38:39], s[22:23], 0, v[38:39]
	v_perm_b32 v40, v32, v33, s25
	v_lshl_add_u64 v[32:33], v[36:37], 0, v[58:59]
	global_store_dword v[32:33], v34, off
	v_lshl_add_u64 v[34:35], v[38:39], 0, v[58:59]
	v_mov_b32_dpp v36, v28 quad_perm:[1,0,3,2] row_mask:0xf bank_mask:0xf bound_ctrl:1
	v_mov_b32_dpp v38, v30 quad_perm:[1,0,3,2] row_mask:0xf bank_mask:0xf bound_ctrl:1
	v_mfma_f32_16x16x32_bf16 v[24:27], v[156:159], v[164:167], v[172:175]
	v_cndmask_b32_e64 v30, v30, v36, s[34:35]
	v_cndmask_b32_e64 v28, v38, v28, s[34:35]
	v_mov_b32_dpp v37, v29 quad_perm:[1,0,3,2] row_mask:0xf bank_mask:0xf bound_ctrl:1
	v_mov_b32_dpp v39, v31 quad_perm:[1,0,3,2] row_mask:0xf bank_mask:0xf bound_ctrl:1
	v_add_u32_e32 v30, 0x8000, v30
	v_add_u32_e32 v28, 0x8000, v28
	v_perm_b32 v28, v30, v28, s25
	v_cndmask_b32_e64 v30, v31, v37, s[34:35]
	v_cndmask_b32_e64 v29, v39, v29, s[34:35]
	v_add_u32_e32 v30, 0x8000, v30
	v_add_u32_e32 v29, 0x8000, v29
	global_store_dword v[34:35], v40, off
	v_perm_b32 v29, v30, v29, s25
	global_store_dword v[32:33], v28, off offset:32
	global_store_dword v[34:35], v29, off offset:32
	v_mov_b32_dpp v28, v24 quad_perm:[1,0,3,2] row_mask:0xf bank_mask:0xf bound_ctrl:1
	v_mov_b32_dpp v30, v26 quad_perm:[1,0,3,2] row_mask:0xf bank_mask:0xf bound_ctrl:1
	v_mfma_f32_16x16x32_bf16 v[20:23], v[156:159], v[168:171], v[106:109]
	v_cndmask_b32_e64 v26, v26, v28, s[34:35]
	v_cndmask_b32_e64 v24, v30, v24, s[34:35]
	v_mov_b32_dpp v29, v25 quad_perm:[1,0,3,2] row_mask:0xf bank_mask:0xf bound_ctrl:1
	v_mov_b32_dpp v31, v27 quad_perm:[1,0,3,2] row_mask:0xf bank_mask:0xf bound_ctrl:1
	v_add_u32_e32 v26, 0x8000, v26
	v_add_u32_e32 v24, 0x8000, v24
	v_perm_b32 v24, v26, v24, s25
	v_cndmask_b32_e64 v26, v27, v29, s[34:35]
	v_cndmask_b32_e64 v25, v31, v25, s[34:35]
	v_add_u32_e32 v26, 0x8000, v26
; DEVINL void p4_tile(const Params& p, char* smem, int mt, int nt) {
;     ...
;   u16* mixo = (u16*)(p.ws + OFF_MIXO);
; #pragma unroll
;   for (int mf = 0; mf < 4; ++mf) {
;     const int rb = m0 + wr * 64 + mf * 16 + (lane >> 4) * 4;
; #pragma unroll
;     for (int nf = 0; nf < 4; ++nf) {
;       const int col = n0 + wc * 64 + nf * 16 + (lane & 15);
;       store_pairs(mixo, 1024, rb, col, acc[mf][nf][0], acc[mf][nf][1], acc[mf][nf][2], acc[mf][nf][3]);
;     }
;   }
; template <class F>
; DEVINL void gemm_phase(int NT, F&& f) {
;     ...
;   for (int u = u0 + j; u < u1; u += nbx) {
	v_add_u32_e32 v25, 0x8000, v25
	v_mfma_f32_16x16x32_bf16 v[16:19], v[160:163], v[148:151], v[78:81]
	v_perm_b32 v25, v26, v25, s25
	global_store_dword v[32:33], v24, off offset:64
	global_store_dword v[34:35], v25, off offset:64
	v_mov_b32_dpp v24, v20 quad_perm:[1,0,3,2] row_mask:0xf bank_mask:0xf bound_ctrl:1
	v_mov_b32_dpp v26, v22 quad_perm:[1,0,3,2] row_mask:0xf bank_mask:0xf bound_ctrl:1
	v_cndmask_b32_e64 v22, v22, v24, s[34:35]
	v_cndmask_b32_e64 v20, v26, v20, s[34:35]
	v_mov_b32_dpp v25, v21 quad_perm:[1,0,3,2] row_mask:0xf bank_mask:0xf bound_ctrl:1
	v_mov_b32_dpp v27, v23 quad_perm:[1,0,3,2] row_mask:0xf bank_mask:0xf bound_ctrl:1
	v_add_u32_e32 v22, 0x8000, v22
	v_add_u32_e32 v20, 0x8000, v20
	v_perm_b32 v20, v22, v20, s25
	v_cndmask_b32_e64 v22, v23, v25, s[34:35]
	v_cndmask_b32_e64 v21, v27, v21, s[34:35]
	v_add_u32_e32 v22, 0x8000, v22
	v_add_u32_e32 v21, 0x8000, v21
	v_mov_b32_dpp v24, v16 quad_perm:[1,0,3,2] row_mask:0xf bank_mask:0xf bound_ctrl:1
	v_mov_b32_dpp v26, v18 quad_perm:[1,0,3,2] row_mask:0xf bank_mask:0xf bound_ctrl:1
	v_perm_b32 v21, v22, v21, s25
	global_store_dword v[32:33], v20, off offset:96
	global_store_dword v[34:35], v21, off offset:96
	v_or_b32_e32 v20, 48, v56
	v_cndmask_b32_e64 v18, v18, v24, s[34:35]
	v_cndmask_b32_e64 v16, v26, v16, s[34:35]
	v_ashrrev_i32_e32 v21, 31, v20
	v_or_b32_e32 v22, 49, v56
	v_mov_b32_dpp v25, v17 quad_perm:[1,0,3,2] row_mask:0xf bank_mask:0xf bound_ctrl:1
	v_mov_b32_dpp v27, v19 quad_perm:[1,0,3,2] row_mask:0xf bank_mask:0xf bound_ctrl:1
	v_add_u32_e32 v18, 0x8000, v18
	v_add_u32_e32 v16, 0x8000, v16
	v_lshlrev_b64 v[20:21], 11, v[20:21]
	v_ashrrev_i32_e32 v23, 31, v22
	v_perm_b32 v18, v18, v16, s25
	v_cndmask_b32_e64 v16, v19, v25, s[34:35]
	v_cndmask_b32_e64 v17, v27, v17, s[34:35]
	v_lshl_add_u64 v[20:21], s[22:23], 0, v[20:21]
	v_lshlrev_b64 v[22:23], 11, v[22:23]
	v_add_u32_e32 v16, 0x8000, v16
	v_add_u32_e32 v17, 0x8000, v17
	v_lshl_add_u64 v[22:23], s[22:23], 0, v[22:23]
	v_perm_b32 v24, v16, v17, s25
	v_lshl_add_u64 v[16:17], v[20:21], 0, v[58:59]
	global_store_dword v[16:17], v18, off
	v_lshl_add_u64 v[18:19], v[22:23], 0, v[58:59]
	v_mov_b32_dpp v20, v12 quad_perm:[1,0,3,2] row_mask:0xf bank_mask:0xf bound_ctrl:1
	v_mov_b32_dpp v22, v14 quad_perm:[1,0,3,2] row_mask:0xf bank_mask:0xf bound_ctrl:1
	v_cndmask_b32_e64 v14, v14, v20, s[34:35]
	v_cndmask_b32_e64 v12, v22, v12, s[34:35]
	v_mov_b32_dpp v21, v13 quad_perm:[1,0,3,2] row_mask:0xf bank_mask:0xf bound_ctrl:1
	v_mov_b32_dpp v23, v15 quad_perm:[1,0,3,2] row_mask:0xf bank_mask:0xf bound_ctrl:1
	v_add_u32_e32 v14, 0x8000, v14
	v_add_u32_e32 v12, 0x8000, v12
	v_perm_b32 v12, v14, v12, s25
	v_cndmask_b32_e64 v14, v15, v21, s[34:35]
	v_cndmask_b32_e64 v13, v23, v13, s[34:35]
	v_add_u32_e32 v14, 0x8000, v14
	v_add_u32_e32 v13, 0x8000, v13
	global_store_dword v[18:19], v24, off
	v_perm_b32 v13, v14, v13, s25
	global_store_dword v[16:17], v12, off offset:32
	global_store_dword v[18:19], v13, off offset:32
	v_mov_b32_dpp v12, v8 quad_perm:[1,0,3,2] row_mask:0xf bank_mask:0xf bound_ctrl:1
	v_mov_b32_dpp v14, v10 quad_perm:[1,0,3,2] row_mask:0xf bank_mask:0xf bound_ctrl:1
	v_cndmask_b32_e64 v10, v10, v12, s[34:35]
	v_cndmask_b32_e64 v8, v14, v8, s[34:35]
	v_mov_b32_dpp v13, v9 quad_perm:[1,0,3,2] row_mask:0xf bank_mask:0xf bound_ctrl:1
	v_mov_b32_dpp v15, v11 quad_perm:[1,0,3,2] row_mask:0xf bank_mask:0xf bound_ctrl:1
	v_add_u32_e32 v10, 0x8000, v10
	v_add_u32_e32 v8, 0x8000, v8
	v_perm_b32 v8, v10, v8, s25
	v_cndmask_b32_e64 v10, v11, v13, s[34:35]
	v_cndmask_b32_e64 v9, v15, v9, s[34:35]
	v_add_u32_e32 v10, 0x8000, v10
	v_add_u32_e32 v9, 0x8000, v9
	v_perm_b32 v9, v10, v9, s25
	global_store_dword v[16:17], v8, off offset:64
	global_store_dword v[18:19], v9, off offset:64
	v_mov_b32_dpp v8, v4 quad_perm:[1,0,3,2] row_mask:0xf bank_mask:0xf bound_ctrl:1
	v_mov_b32_dpp v10, v6 quad_perm:[1,0,3,2] row_mask:0xf bank_mask:0xf bound_ctrl:1
	v_cndmask_b32_e64 v6, v6, v8, s[34:35]
	v_cndmask_b32_e64 v4, v10, v4, s[34:35]
	v_mov_b32_dpp v9, v5 quad_perm:[1,0,3,2] row_mask:0xf bank_mask:0xf bound_ctrl:1
	v_mov_b32_dpp v11, v7 quad_perm:[1,0,3,2] row_mask:0xf bank_mask:0xf bound_ctrl:1
	v_add_u32_e32 v6, 0x8000, v6
	v_add_u32_e32 v4, 0x8000, v4
	v_perm_b32 v4, v6, v4, s25
	v_cndmask_b32_e64 v6, v7, v9, s[34:35]
	v_cndmask_b32_e64 v5, v11, v5, s[34:35]
	v_cmp_le_i32_e64 s[34:35], s40, v3
	v_add_u32_e32 v6, 0x8000, v6
	v_add_u32_e32 v5, 0x8000, v5
	s_or_b64 s[38:39], s[34:35], s[38:39]
	v_perm_b32 v5, v6, v5, s25
	global_store_dword v[16:17], v4, off offset:96
	global_store_dword v[18:19], v5, off offset:96
	s_andn2_b64 exec, exec, s[38:39]
	s_cbranch_execnz .LBB0_182
	s_or_b64 exec, exec, s[38:39]

; DEVINL f32x4 mfma16(bf16x8 a, bf16x8 b, f32x4 c) { return __builtin_amdgcn_mfma_f32_16x16x32_bf16(a, b, c, 0, 0, 0); }
; DEVINL void gemm_loop(f32x4 (&acc)[4][4], const u16* __restrict__ A, int lda, const u16* __restrict__ Bt, int ldb,
;                       int m0, int n0, int k0, int nk, char* smem) {
;     ...
;   __syncthreads();
; #pragma unroll
;   for (int i = 0; i < 4; ++i) {
;     glds16(ga[i], smem + i * 4096 + wid * 1024);
;     glds16(gb[i], smem + 16384 + i * 4096 + wid * 1024);
;   }
;   for (int kt = 0; kt < nk; ++kt) {
;     __syncthreads();
;     char* cur = smem + (kt & 1) * 32768;
;     if (kt + 1 < nk) {
;       char* nxt = smem + ((kt + 1) & 1) * 32768;
; #pragma unroll
;       for (int i = 0; i < 4; ++i) {
;         glds16(ga[i] + (kt + 1) * 64, nxt + i * 4096 + wid * 1024);
;         glds16(gb[i] + (kt + 1) * 64, nxt + 16384 + i * 4096 + wid * 1024);
;       }
;     }
;     bf16x8 af[2][4], bfr[2][4];
; #pragma unroll
;     for (int ks = 0; ks < 2; ++ks)
; #pragma unroll
;       for (int f = 0; f < 4; ++f) {
;         int ra = wr * 64 + f * 16 + fr, rb = wc * 64 + f * 16 + fr;
;         int ch = ks * 4 + fq;
;         af[ks][f] = *(const bf16x8*)(cur + ra * 128 + ((ch ^ ((ra >> 1) & 7)) << 4));
;         bfr[ks][f] = *(const bf16x8*)(cur + 16384 + rb * 128 + ((ch ^ ((rb >> 1) & 7)) << 4));
;       }
;     __builtin_amdgcn_sched_barrier(0);
; #pragma unroll
;     for (int ks = 0; ks < 2; ++ks)
; #pragma unroll
;       for (int mf = 0; mf < 4; ++mf)
; #pragma unroll
;         for (int nf = 0; nf < 4; ++nf) acc[mf][nf] = mfma16(af[ks][mf], bfr[ks][nf], acc[mf][nf]);
;   }
.LBB0_265:
	v_readfirstlane_b32 s100, v85
	v_add_u32_e32 v196, v89, v86
	v_add_u32_e32 v197, v89, v87
	v_add_u32_e32 v198, v88, v86
	v_add_u32_e32 v199, v88, v87
	s_mov_b32 s101, s100
	v_lshlrev_b32_e32 v202, 4, v0
	s_waitcnt vmcnt(0)
	s_barrier
	s_add_u32 m0, s100, 0x8000
	v_lshl_add_u64 v[200:201], v[68:69], 0, s[34:35]
	global_load_lds_dwordx4 v[200:201], off
	s_add_u32 m0, s100, 0xc000
	v_lshl_add_u64 v[200:201], v[70:71], 0, s[34:35]
	global_load_lds_dwordx4 v[200:201], off
	s_add_u32 m0, s100, 0x9000
	v_lshl_add_u64 v[200:201], v[72:73], 0, s[34:35]
	global_load_lds_dwordx4 v[200:201], off
	s_add_u32 m0, s100, 0xd000
	v_lshl_add_u64 v[200:201], v[74:75], 0, s[34:35]
	global_load_lds_dwordx4 v[200:201], off
	s_add_u32 m0, s100, 0xa000
	v_lshl_add_u64 v[200:201], v[76:77], 0, s[34:35]
	global_load_lds_dwordx4 v[200:201], off
	s_add_u32 m0, s100, 0xe000
	v_lshl_add_u64 v[200:201], v[78:79], 0, s[34:35]
	global_load_lds_dwordx4 v[200:201], off
	s_add_u32 m0, s100, 0xb000
	v_lshl_add_u64 v[200:201], v[80:81], 0, s[34:35]
	global_load_lds_dwordx4 v[200:201], off
	s_add_u32 m0, s100, 0xf000
	v_lshl_add_u64 v[200:201], v[82:83], 0, s[34:35]
	global_load_lds_dwordx4 v[200:201], off
	ds_read_b128 v[106:109], v196
	ds_read_b128 v[110:113], v196 offset:2048
	ds_read_b128 v[132:135], v197 offset:16384
	ds_read_b128 v[136:139], v197 offset:18432
	ds_read_b128 v[140:143], v196 offset:4096
	ds_read_b128 v[144:147], v196 offset:6144
	ds_read_b128 v[148:151], v197 offset:20480
	ds_read_b128 v[152:155], v197 offset:22528
	ds_read_b128 v[156:159], v198
	ds_read_b128 v[160:163], v198 offset:2048
	ds_read_b128 v[164:167], v199 offset:16384
	ds_read_b128 v[168:171], v199 offset:18432
	ds_read_b128 v[172:175], v198 offset:4096
	ds_read_b128 v[176:179], v198 offset:6144
	ds_read_b128 v[180:183], v199 offset:20480
	ds_read_b128 v[184:187], v199 offset:22528
	s_waitcnt lgkmcnt(8)
	v_mfma_f32_16x16x32_bf16 v[64:67], v[106:109], v[132:135], v[64:67]
	v_mfma_f32_16x16x32_bf16 v[60:63], v[106:109], v[136:139], v[60:63]
	v_mfma_f32_16x16x32_bf16 v[52:55], v[106:109], v[148:151], v[52:55]
	v_mfma_f32_16x16x32_bf16 v[48:51], v[106:109], v[152:155], v[48:51]
	v_mfma_f32_16x16x32_bf16 v[44:47], v[110:113], v[132:135], v[44:47]
	v_mfma_f32_16x16x32_bf16 v[40:43], v[110:113], v[136:139], v[40:43]
	v_mfma_f32_16x16x32_bf16 v[36:39], v[110:113], v[148:151], v[36:39]
	v_mfma_f32_16x16x32_bf16 v[32:35], v[110:113], v[152:155], v[32:35]
	v_mfma_f32_16x16x32_bf16 v[28:31], v[140:143], v[132:135], v[28:31]
	v_mfma_f32_16x16x32_bf16 v[24:27], v[140:143], v[136:139], v[24:27]
	v_mfma_f32_16x16x32_bf16 v[20:23], v[140:143], v[148:151], v[20:23]
	v_mfma_f32_16x16x32_bf16 v[16:19], v[140:143], v[152:155], v[16:19]
	v_mfma_f32_16x16x32_bf16 v[12:15], v[144:147], v[132:135], v[12:15]
	v_mfma_f32_16x16x32_bf16 v[8:11], v[144:147], v[136:139], v[8:11]
	v_mfma_f32_16x16x32_bf16 v[4:7], v[144:147], v[148:151], v[4:7]
	v_mfma_f32_16x16x32_bf16 v[56:59], v[144:147], v[152:155], v[56:59]
	v_xor_b32_e32 v196, 0x8000, v196
	v_xor_b32_e32 v197, 0x8000, v197
	v_xor_b32_e32 v198, 0x8000, v198
	v_xor_b32_e32 v199, 0x8000, v199
	s_waitcnt vmcnt(0) lgkmcnt(0)
	s_barrier
.Lkp_b265_loop:
	s_add_u32 s34, s34, 0x80
	s_addc_u32 s35, s35, 0
	s_cmpk_eq_i32 s34, 0x380
	s_cbranch_scc1 .Lkp_b265_last
	v_mfma_f32_16x16x32_bf16 v[64:67], v[156:159], v[164:167], v[64:67]
	s_add_u32 m0, s101, 0x0
	v_lshl_add_u64 v[200:201], v[68:69], 0, s[34:35]
	global_load_lds_dwordx4 v[200:201], off
	v_mfma_f32_16x16x32_bf16 v[60:63], v[156:159], v[168:171], v[60:63]
	s_add_u32 m0, s101, 0x4000
	v_lshl_add_u64 v[200:201], v[70:71], 0, s[34:35]
	global_load_lds_dwordx4 v[200:201], off
	v_mfma_f32_16x16x32_bf16 v[52:55], v[156:159], v[180:183], v[52:55]
	s_add_u32 m0, s101, 0x1000
	v_lshl_add_u64 v[200:201], v[72:73], 0, s[34:35]
	global_load_lds_dwordx4 v[200:201], off
	v_mfma_f32_16x16x32_bf16 v[48:51], v[156:159], v[184:187], v[48:51]
	s_add_u32 m0, s101, 0x5000
	v_lshl_add_u64 v[200:201], v[74:75], 0, s[34:35]
	global_load_lds_dwordx4 v[200:201], off
	v_mfma_f32_16x16x32_bf16 v[44:47], v[160:163], v[164:167], v[44:47]
	s_add_u32 m0, s101, 0x2000
	v_lshl_add_u64 v[200:201], v[76:77], 0, s[34:35]
	global_load_lds_dwordx4 v[200:201], off
	ds_read_b128 v[106:109], v196
	v_mfma_f32_16x16x32_bf16 v[40:43], v[160:163], v[168:171], v[40:43]
	s_add_u32 m0, s101, 0x6000
	v_lshl_add_u64 v[200:201], v[78:79], 0, s[34:35]
	global_load_lds_dwordx4 v[200:201], off
	ds_read_b128 v[110:113], v196 offset:2048
	v_mfma_f32_16x16x32_bf16 v[36:39], v[160:163], v[180:183], v[36:39]
	s_add_u32 m0, s101, 0x3000
	v_lshl_add_u64 v[200:201], v[80:81], 0, s[34:35]
	global_load_lds_dwordx4 v[200:201], off
	ds_read_b128 v[132:135], v197 offset:16384
	v_mfma_f32_16x16x32_bf16 v[32:35], v[160:163], v[184:187], v[32:35]
	s_add_u32 m0, s101, 0x7000
	v_lshl_add_u64 v[200:201], v[82:83], 0, s[34:35]
	global_load_lds_dwordx4 v[200:201], off
	ds_read_b128 v[136:139], v197 offset:18432
	v_mfma_f32_16x16x32_bf16 v[28:31], v[172:175], v[164:167], v[28:31]
	ds_read_b128 v[140:143], v196 offset:4096
	v_mfma_f32_16x16x32_bf16 v[24:27], v[172:175], v[168:171], v[24:27]
	ds_read_b128 v[144:147], v196 offset:6144
	v_mfma_f32_16x16x32_bf16 v[20:23], v[172:175], v[180:183], v[20:23]
	ds_read_b128 v[148:151], v197 offset:20480
	v_mfma_f32_16x16x32_bf16 v[16:19], v[172:175], v[184:187], v[16:19]
	ds_read_b128 v[152:155], v197 offset:22528
	v_mfma_f32_16x16x32_bf16 v[12:15], v[176:179], v[164:167], v[12:15]
	v_mfma_f32_16x16x32_bf16 v[8:11], v[176:179], v[168:171], v[8:11]
	v_mfma_f32_16x16x32_bf16 v[4:7], v[176:179], v[180:183], v[4:7]
	v_mfma_f32_16x16x32_bf16 v[56:59], v[176:179], v[184:187], v[56:59]
	s_xor_b32 s101, s101, 0x8000
	s_waitcnt lgkmcnt(0)
; DEVINL f32x4 mfma16(bf16x8 a, bf16x8 b, f32x4 c) { return __builtin_amdgcn_mfma_f32_16x16x32_bf16(a, b, c, 0, 0, 0); }
; DEVINL void gemm_loop(f32x4 (&acc)[4][4], const u16* __restrict__ A, int lda, const u16* __restrict__ Bt, int ldb,
;                       int m0, int n0, int k0, int nk, char* smem) {
;     ...
;   for (int kt = 0; kt < nk; ++kt) {
;     __syncthreads();
;     char* cur = smem + (kt & 1) * 32768;
;     if (kt + 1 < nk) {
;       char* nxt = smem + ((kt + 1) & 1) * 32768;
; #pragma unroll
;       for (int i = 0; i < 4; ++i) {
;         glds16(ga[i] + (kt + 1) * 64, nxt + i * 4096 + wid * 1024);
;         glds16(gb[i] + (kt + 1) * 64, nxt + 16384 + i * 4096 + wid * 1024);
;       }
;     }
;     bf16x8 af[2][4], bfr[2][4];
; #pragma unroll
;     for (int ks = 0; ks < 2; ++ks)
; #pragma unroll
;       for (int f = 0; f < 4; ++f) {
;         int ra = wr * 64 + f * 16 + fr, rb = wc * 64 + f * 16 + fr;
;         int ch = ks * 4 + fq;
;         af[ks][f] = *(const bf16x8*)(cur + ra * 128 + ((ch ^ ((ra >> 1) & 7)) << 4));
;         bfr[ks][f] = *(const bf16x8*)(cur + 16384 + rb * 128 + ((ch ^ ((rb >> 1) & 7)) << 4));
;       }
;     __builtin_amdgcn_sched_barrier(0);
; #pragma unroll
;     for (int ks = 0; ks < 2; ++ks)
; #pragma unroll
;       for (int mf = 0; mf < 4; ++mf)
; #pragma unroll
;         for (int nf = 0; nf < 4; ++nf) acc[mf][nf] = mfma16(af[ks][mf], bfr[ks][nf], acc[mf][nf]);
;   }
	v_mfma_f32_16x16x32_bf16 v[64:67], v[106:109], v[132:135], v[64:67]
	ds_read_b128 v[156:159], v198
	v_mfma_f32_16x16x32_bf16 v[60:63], v[106:109], v[136:139], v[60:63]
	ds_read_b128 v[160:163], v198 offset:2048
	v_mfma_f32_16x16x32_bf16 v[52:55], v[106:109], v[148:151], v[52:55]
	ds_read_b128 v[164:167], v199 offset:16384
	v_mfma_f32_16x16x32_bf16 v[48:51], v[106:109], v[152:155], v[48:51]
	ds_read_b128 v[168:171], v199 offset:18432
	v_mfma_f32_16x16x32_bf16 v[44:47], v[110:113], v[132:135], v[44:47]
	ds_read_b128 v[172:175], v198 offset:4096
	v_mfma_f32_16x16x32_bf16 v[40:43], v[110:113], v[136:139], v[40:43]
	ds_read_b128 v[176:179], v198 offset:6144
	v_mfma_f32_16x16x32_bf16 v[36:39], v[110:113], v[148:151], v[36:39]
	ds_read_b128 v[180:183], v199 offset:20480
	v_mfma_f32_16x16x32_bf16 v[32:35], v[110:113], v[152:155], v[32:35]
	ds_read_b128 v[184:187], v199 offset:22528
	v_mfma_f32_16x16x32_bf16 v[28:31], v[140:143], v[132:135], v[28:31]
	v_mfma_f32_16x16x32_bf16 v[24:27], v[140:143], v[136:139], v[24:27]
	v_mfma_f32_16x16x32_bf16 v[20:23], v[140:143], v[148:151], v[20:23]
	v_mfma_f32_16x16x32_bf16 v[16:19], v[140:143], v[152:155], v[16:19]
	v_mfma_f32_16x16x32_bf16 v[12:15], v[144:147], v[132:135], v[12:15]
	v_mfma_f32_16x16x32_bf16 v[8:11], v[144:147], v[136:139], v[8:11]
	v_mfma_f32_16x16x32_bf16 v[4:7], v[144:147], v[148:151], v[4:7]
	v_mfma_f32_16x16x32_bf16 v[56:59], v[144:147], v[152:155], v[56:59]
	v_xor_b32_e32 v196, 0x8000, v196
	v_xor_b32_e32 v197, 0x8000, v197
	v_xor_b32_e32 v198, 0x8000, v198
	v_xor_b32_e32 v199, 0x8000, v199
	s_waitcnt vmcnt(0) lgkmcnt(0)
	s_barrier
	s_branch .Lkp_b265_loop
.Lkp_b265_last:
	v_mfma_f32_16x16x32_bf16 v[64:67], v[156:159], v[164:167], v[64:67]
	v_mfma_f32_16x16x32_bf16 v[60:63], v[156:159], v[168:171], v[60:63]
	v_mfma_f32_16x16x32_bf16 v[52:55], v[156:159], v[180:183], v[52:55]
	v_mfma_f32_16x16x32_bf16 v[48:51], v[156:159], v[184:187], v[48:51]
	v_mfma_f32_16x16x32_bf16 v[44:47], v[160:163], v[164:167], v[44:47]
	v_mfma_f32_16x16x32_bf16 v[40:43], v[160:163], v[168:171], v[40:43]
	v_mfma_f32_16x16x32_bf16 v[36:39], v[160:163], v[180:183], v[36:39]
	v_mfma_f32_16x16x32_bf16 v[32:35], v[160:163], v[184:187], v[32:35]
	v_mfma_f32_16x16x32_bf16 v[28:31], v[172:175], v[164:167], v[28:31]
	v_mfma_f32_16x16x32_bf16 v[24:27], v[172:175], v[168:171], v[24:27]
	v_mfma_f32_16x16x32_bf16 v[20:23], v[172:175], v[180:183], v[20:23]
	v_mfma_f32_16x16x32_bf16 v[16:19], v[172:175], v[184:187], v[16:19]
	v_mfma_f32_16x16x32_bf16 v[12:15], v[176:179], v[164:167], v[12:15]
	v_mfma_f32_16x16x32_bf16 v[8:11], v[176:179], v[168:171], v[8:11]
	v_mfma_f32_16x16x32_bf16 v[4:7], v[176:179], v[180:183], v[4:7]
	v_mfma_f32_16x16x32_bf16 v[56:59], v[176:179], v[184:187], v[56:59]
	s_mov_b32 s1, 0x8000
	v_add_u32_e32 v68, s1, v89
	v_add_u32_e32 v85, v68, v86
	s_waitcnt vmcnt(0)
	s_barrier
	v_add_u32_e32 v89, v68, v87
	ds_read_b128 v[68:71], v85
	ds_read_b128 v[72:75], v85 offset:2048
	ds_read_b128 v[76:79], v89 offset:16384
	ds_read_b128 v[80:83], v89 offset:18432
	ds_read_b128 v[106:109], v85 offset:4096
	ds_read_b128 v[110:113], v85 offset:6144
	ds_read_b128 v[132:135], v89 offset:20480
	ds_read_b128 v[136:139], v89 offset:22528
	v_add_u32_e32 v85, s1, v88
	v_add_u32_e32 v90, v85, v86
	v_add_u32_e32 v85, v85, v87
	ds_read_b128 v[86:89], v90
	ds_read_b128 v[140:143], v90 offset:2048
	ds_read_b128 v[144:147], v85 offset:16384
	ds_read_b128 v[148:151], v85 offset:18432
	ds_read_b128 v[152:155], v90 offset:4096
	ds_read_b128 v[156:159], v90 offset:6144
	ds_read_b128 v[160:163], v85 offset:20480
	ds_read_b128 v[164:167], v85 offset:22528
	s_waitcnt lgkmcnt(13)
	v_mfma_f32_16x16x32_bf16 v[64:67], v[68:71], v[76:79], v[64:67]
	s_movk_i32 s0, 0x4480
	s_movk_i32 s43, 0xffce
	s_waitcnt lgkmcnt(12)
	v_mfma_f32_16x16x32_bf16 v[60:63], v[68:71], v[80:83], v[60:63]
	s_waitcnt lgkmcnt(9)
	v_mfma_f32_16x16x32_bf16 v[52:55], v[68:71], v[132:135], v[52:55]
	s_waitcnt lgkmcnt(8)
	v_mfma_f32_16x16x32_bf16 v[48:51], v[68:71], v[136:139], v[48:51]
	v_mfma_f32_16x16x32_bf16 v[44:47], v[72:75], v[76:79], v[44:47]
	v_mfma_f32_16x16x32_bf16 v[40:43], v[72:75], v[80:83], v[40:43]
	v_mfma_f32_16x16x32_bf16 v[36:39], v[72:75], v[132:135], v[36:39]
	v_mfma_f32_16x16x32_bf16 v[32:35], v[72:75], v[136:139], v[32:35]
	v_mfma_f32_16x16x32_bf16 v[28:31], v[106:109], v[76:79], v[28:31]
	v_mfma_f32_16x16x32_bf16 v[24:27], v[106:109], v[80:83], v[24:27]
	v_mfma_f32_16x16x32_bf16 v[20:23], v[106:109], v[132:135], v[20:23]
	v_mfma_f32_16x16x32_bf16 v[16:19], v[106:109], v[136:139], v[16:19]
	v_mfma_f32_16x16x32_bf16 v[12:15], v[110:113], v[76:79], v[12:15]
	v_mfma_f32_16x16x32_bf16 v[8:11], v[110:113], v[80:83], v[8:11]
	v_mfma_f32_16x16x32_bf16 v[4:7], v[110:113], v[132:135], v[4:7]
	v_mfma_f32_16x16x32_bf16 v[68:71], v[110:113], v[136:139], v[56:59]
	s_waitcnt lgkmcnt(1)
	v_mfma_f32_16x16x32_bf16 v[56:59], v[86:89], v[160:163], v[52:55]
	s_waitcnt lgkmcnt(0)
; DEVINL float bf2f(u16 h) { return __uint_as_float(((unsigned)h) << 16); }
; DEVINL float sigmoidf_(float x) { return __builtin_amdgcn_rcpf(1.f + __expf(-x)); }
; DEVINL void p3_tile(const Params& p, char* smem, int mt, int nt) {
;     ...
; #pragma unroll
;   for (int mf = 0; mf < 4; ++mf) {
;     const int rb = m0 + wr * 64 + mf * 16 + (lane >> 4) * 4;
;     float ssq[4] = {0.f, 0.f, 0.f, 0.f};
; #pragma unroll
;     for (int nf = 0; nf < 4; ++nf) {
;       const int col = n0 + wc * 64 + nf * 16 + (lane & 15);
;       float val[4];
; #pragma unroll
;       for (int j = 0; j < 4; ++j) {
;         val[j] = bf2f(yg[(size_t)(rb + j) * 512 + col]) * sigmoidf_(acc[mf][nf][j]);
;         ssq[j] += val[j] * val[j];
;       }
;       store_pairs(mixin, 1024, rb, 512 + col, val[0], val[1], val[2], val[3]);
;     }
;     {
;       float* ss5p = (float*)(p.ws + OFF_SS5P);
; #pragma unroll
;       for (int j = 0; j < 4; ++j) {
;         const float v = red16(ssq[j]);
;         if ((lane & 15) == 0) ss5p[((size_t)nt * M + rb + j) * 2 + wc] = v;
	v_mfma_f32_16x16x32_bf16 v[52:55], v[86:89], v[164:167], v[48:51]
	v_mfma_f32_16x16x32_bf16 v[48:51], v[140:143], v[144:147], v[44:47]
	s_nop 4
	v_mul_f32_e32 v56, 0xbfb8aa3b, v56
	v_exp_f32_e32 v56, v56
	v_mul_f32_e32 v57, 0xbfb8aa3b, v57
	v_mfma_f32_16x16x32_bf16 v[44:47], v[140:143], v[148:151], v[40:43]
	v_exp_f32_e32 v57, v57
	v_add_f32_e32 v56, 1.0, v56
	v_rcp_f32_e32 v56, v56
	v_mfma_f32_16x16x32_bf16 v[40:43], v[140:143], v[160:163], v[36:39]
	v_add_f32_e32 v57, 1.0, v57
	v_rcp_f32_e32 v57, v57
	v_mul_f32_e32 v52, 0xbfb8aa3b, v52
	v_mfma_f32_16x16x32_bf16 v[36:39], v[140:143], v[164:167], v[32:35]
	v_exp_f32_e32 v52, v52
	v_mul_f32_e32 v53, 0xbfb8aa3b, v53
	v_exp_f32_e32 v53, v53
	v_mfma_f32_16x16x32_bf16 v[32:35], v[152:155], v[144:147], v[28:31]
	v_add_f32_e32 v52, 1.0, v52
	v_rcp_f32_e32 v52, v52
	v_add_f32_e32 v53, 1.0, v53
	v_mfma_f32_16x16x32_bf16 v[28:31], v[152:155], v[148:151], v[24:27]
	v_rcp_f32_e32 v53, v53
	v_mfma_f32_16x16x32_bf16 v[24:27], v[152:155], v[160:163], v[20:23]
	v_mfma_f32_16x16x32_bf16 v[20:23], v[152:155], v[164:167], v[16:19]
	v_mfma_f32_16x16x32_bf16 v[16:19], v[156:159], v[144:147], v[12:15]
	v_mfma_f32_16x16x32_bf16 v[12:15], v[156:159], v[148:151], v[8:11]
	v_mfma_f32_16x16x32_bf16 v[8:11], v[156:159], v[160:163], v[4:7]
	v_mfma_f32_16x16x32_bf16 v[4:7], v[156:159], v[164:167], v[68:71]
	s_nop 2
	v_mov_b32_e32 v68, v0
	v_mov_b32_e32 v69, v0
	v_mul_lo_u32 v70, v84, s0
	v_bfe_u32 v73, v69, 6, 1
	v_ashrrev_i32_e32 v69, 1, v69
	v_and_b32_e32 v69, 0xffffffc0, v69
	v_add_u32_e32 v3, v69, v3
	v_lshrrev_b32_e32 v69, 2, v68
	v_and_or_b32 v72, v69, 12, v3
	v_and_b32_e32 v3, 1, v68
	v_cmp_eq_u32_e64 s[36:37], 0, v3
	v_lshlrev_b32_e32 v3, 1, v3
	v_or_b32_e32 v74, v72, v3
	v_and_b32_e32 v69, 15, v68
	v_readlane_b32 s0, v194, 21
	v_ashrrev_i32_e32 v75, 31, v74
	v_lshl_or_b32 v105, v73, 6, v69
	v_cmp_eq_u32_e64 s[34:35], 0, v69
	v_lshlrev_b32_e32 v68, 2, v73
	v_mov_b32_e32 v69, v2
	v_readlane_b32 s1, v194, 22
	v_lshlrev_b64 v[78:79], 11, v[74:75]
	v_or_b32_e32 v74, 1, v74
	v_lshl_add_u64 v[68:69], s[0:1], 0, v[68:69]
	v_readlane_b32 s0, v194, 19
	v_ashrrev_i32_e32 v75, 31, v74
	v_readlane_b32 s1, v194, 20
	v_lshlrev_b64 v[74:75], 11, v[74:75]
	v_or_b32_e32 v76, v105, v102
	v_lshl_add_u64 v[78:79], s[0:1], 0, v[78:79]
	v_lshl_add_u64 v[80:81], s[0:1], 0, v[74:75]
	v_readlane_b32 s0, v194, 29
	v_ashrrev_i32_e32 v73, 31, v72
	v_ashrrev_i32_e32 v77, 31, v76
	v_readlane_b32 s1, v194, 30
	v_lshlrev_b64 v[82:83], 10, v[72:73]
	v_mfma_f32_16x16x32_bf16 v[64:67], v[86:89], v[144:147], v[64:67]
	v_lshl_add_u64 v[74:75], v[76:77], 1, s[0:1]
	v_lshl_add_u64 v[84:85], v[74:75], 0, v[82:83]
	global_load_ushort v77, v[84:85], off
	v_or_b32_e32 v84, 1, v72
	v_ashrrev_i32_e32 v85, 31, v84
	s_nop 2
	v_mul_f32_e32 v64, 0xbfb8aa3b, v64
	v_exp_f32_e32 v64, v64
	v_mfma_f32_16x16x32_bf16 v[60:63], v[86:89], v[148:151], v[60:63]
	v_lshlrev_b64 v[86:87], 10, v[84:85]
	v_lshl_add_u64 v[84:85], v[74:75], 0, v[86:87]
	v_add_f32_e32 v64, 1.0, v64
	v_rcp_f32_e32 v64, v64
	v_mul_f32_e32 v65, 0xbfb8aa3b, v65
	v_exp_f32_e32 v65, v65
	v_lshl_add_u64 v[82:83], s[0:1], 0, v[82:83]
	s_nop 0
	v_mul_f32_e32 v60, 0xbfb8aa3b, v60
	v_exp_f32_e32 v60, v60
	v_add_f32_e32 v65, 1.0, v65
	v_rcp_f32_e32 v65, v65
	v_lshl_add_u64 v[86:87], s[0:1], 0, v[86:87]
	v_add_f32_e32 v60, 1.0, v60
	v_rcp_f32_e32 v60, v60
	v_mul_f32_e32 v61, 0xbfb8aa3b, v61
	v_exp_f32_e32 v61, v61
	v_ashrrev_i32_e32 v71, 31, v70
	v_add_f32_e32 v61, 1.0, v61
	v_rcp_f32_e32 v61, v61
	s_waitcnt vmcnt(0)
	v_lshlrev_b32_e32 v77, 16, v77
	v_mul_f32_e32 v108, v64, v77
	global_load_ushort v64, v[84:85], off
	s_waitcnt vmcnt(0)
	v_lshlrev_b32_e32 v64, 16, v64
	v_mul_f32_e32 v77, v65, v64
	v_or_b32_e32 v64, 2, v72
	v_ashrrev_i32_e32 v65, 31, v64
	v_lshlrev_b64 v[84:85], 10, v[64:65]
	v_lshl_add_u64 v[64:65], v[74:75], 0, v[84:85]
	global_load_ushort v64, v[64:65], off
	v_mul_f32_e32 v65, 0xbfb8aa3b, v66
	v_exp_f32_e32 v65, v65
	v_lshl_add_u64 v[84:85], s[0:1], 0, v[84:85]
	v_add_f32_e32 v65, 1.0, v65
	v_rcp_f32_e32 v65, v65
	s_waitcnt vmcnt(0)
	v_lshlrev_b32_e32 v64, 16, v64
	v_mul_f32_e32 v90, v65, v64
	v_or_b32_e32 v64, 3, v72
	v_ashrrev_i32_e32 v65, 31, v64
	v_lshlrev_b64 v[88:89], 10, v[64:65]
	v_lshl_add_u64 v[64:65], v[74:75], 0, v[88:89]
	global_load_ushort v64, v[64:65], off
	v_mul_f32_e32 v65, 0xbfb8aa3b, v67
	v_exp_f32_e32 v65, v65
	v_mov_b32_dpp v66, v90 quad_perm:[1,0,3,2] row_mask:0xf bank_mask:0xf bound_ctrl:1
	v_cndmask_b32_e64 v66, v66, v108, s[36:37]
	v_add_u32_e32 v66, 0x8000, v66
	v_add_f32_e32 v65, 1.0, v65
	v_rcp_f32_e32 v65, v65
	v_lshl_add_u64 v[88:89], s[0:1], 0, v[88:89]
	s_movk_i32 s0, 0xffde
	s_waitcnt vmcnt(0)
	v_lshlrev_b32_e32 v64, 16, v64
	v_mul_f32_e32 v91, v65, v64
	s_nop 0
	v_mov_b32_dpp v64, v108 quad_perm:[1,0,3,2] row_mask:0xf bank_mask:0xf bound_ctrl:1
	v_cndmask_b32_e64 v64, v90, v64, s[36:37]
	v_mov_b32_dpp v65, v77 quad_perm:[1,0,3,2] row_mask:0xf bank_mask:0xf bound_ctrl:1
	v_mov_b32_dpp v67, v91 quad_perm:[1,0,3,2] row_mask:0xf bank_mask:0xf bound_ctrl:1
	v_add_u32_e32 v64, 0x8000, v64
	v_perm_b32 v106, v64, v66, s25
	v_cndmask_b32_e64 v64, v91, v65, s[36:37]
	v_cndmask_b32_e64 v65, v67, v77, s[36:37]
	v_add_u32_e32 v64, 0x8000, v64
	v_add_u32_e32 v65, 0x8000, v65
	v_perm_b32 v107, v64, v65, s25
	v_bitop3_b32 v64, v105, s43, v102 bitop3:0xc8
	v_ashrrev_i32_e32 v65, 31, v64
	v_lshlrev_b64 v[64:65], 1, v[64:65]
	v_lshl_add_u64 v[66:67], v[78:79], 0, v[64:65]
	global_store_dword v[66:67], v106, off offset:1024
	v_lshl_add_u64 v[66:67], v[80:81], 0, v[64:65]
	global_store_dword v[66:67], v107, off offset:1024
	v_or_b32_e32 v66, 16, v76
	v_ashrrev_i32_e32 v67, 31, v66
	v_lshlrev_b64 v[66:67], 1, v[66:67]
	v_lshl_add_u64 v[106:107], v[82:83], 0, v[66:67]
	global_load_ushort v102, v[106:107], off
	v_lshl_add_u64 v[106:107], v[86:87], 0, v[66:67]
	s_waitcnt vmcnt(0)
; DEVINL float bf2f(u16 h) { return __uint_as_float(((unsigned)h) << 16); }
; DEVINL float sigmoidf_(float x) { return __builtin_amdgcn_rcpf(1.f + __expf(-x)); }
; DEVINL void p3_tile(const Params& p, char* smem, int mt, int nt) {
;     ...
;     for (int nf = 0; nf < 4; ++nf) {
;       const int col = n0 + wc * 64 + nf * 16 + (lane & 15);
;       float val[4];
; #pragma unroll
;       for (int j = 0; j < 4; ++j) {
;         val[j] = bf2f(yg[(size_t)(rb + j) * 512 + col]) * sigmoidf_(acc[mf][nf][j]);
;         ssq[j] += val[j] * val[j];
;       }
;       store_pairs(mixin, 1024, rb, 512 + col, val[0], val[1], val[2], val[3]);
;     }
;     {
;       float* ss5p = (float*)(p.ws + OFF_SS5P);
; #pragma unroll
;       for (int j = 0; j < 4; ++j) {
;         const float v = red16(ssq[j]);
;         if ((lane & 15) == 0) ss5p[((size_t)nt * M + rb + j) * 2 + wc] = v;
;       }
;     }
	v_lshlrev_b32_e32 v102, 16, v102
	v_mul_f32_e32 v109, v60, v102
	global_load_ushort v60, v[106:107], off
	v_mul_f32_e32 v102, v109, v109
	v_fmac_f32_e32 v102, v108, v108
	s_waitcnt vmcnt(0)
	v_lshlrev_b32_e32 v60, 16, v60
	v_mul_f32_e32 v105, v61, v60
	v_lshl_add_u64 v[60:61], v[84:85], 0, v[66:67]
	global_load_ushort v60, v[60:61], off
	v_mul_f32_e32 v61, 0xbfb8aa3b, v62
	v_exp_f32_e32 v61, v61
	s_waitcnt vmcnt(0)
	v_lshlrev_b32_e32 v60, 16, v60
	v_add_f32_e32 v61, 1.0, v61
	v_rcp_f32_e32 v61, v61
	s_nop 0
	v_mul_f32_e32 v106, v61, v60
	v_lshl_add_u64 v[60:61], v[88:89], 0, v[66:67]
	global_load_ushort v60, v[60:61], off
	v_mul_f32_e32 v61, 0xbfb8aa3b, v63
	v_exp_f32_e32 v61, v61
	v_mov_b32_dpp v62, v106 quad_perm:[1,0,3,2] row_mask:0xf bank_mask:0xf bound_ctrl:1
	v_cndmask_b32_e64 v62, v62, v109, s[36:37]
	v_add_u32_e32 v62, 0x8000, v62
	v_add_f32_e32 v61, 1.0, v61
	v_rcp_f32_e32 v61, v61
	s_waitcnt vmcnt(0)
	v_lshlrev_b32_e32 v60, 16, v60
	v_mul_f32_e32 v107, v61, v60
	s_nop 0
	v_mov_b32_dpp v60, v109 quad_perm:[1,0,3,2] row_mask:0xf bank_mask:0xf bound_ctrl:1
	v_cndmask_b32_e64 v60, v106, v60, s[36:37]
	v_mov_b32_dpp v61, v105 quad_perm:[1,0,3,2] row_mask:0xf bank_mask:0xf bound_ctrl:1
	v_mov_b32_dpp v63, v107 quad_perm:[1,0,3,2] row_mask:0xf bank_mask:0xf bound_ctrl:1
	v_add_u32_e32 v60, 0x8000, v60
	v_perm_b32 v108, v60, v62, s25
	v_cndmask_b32_e64 v60, v107, v61, s[36:37]
	v_cndmask_b32_e64 v61, v63, v105, s[36:37]
	v_add_u32_e32 v60, 0x8000, v60
	v_add_u32_e32 v61, 0x8000, v61
	v_perm_b32 v109, v60, v61, s25
	v_bitop3_b32 v60, v76, s0, 16 bitop3:0xc8
	v_ashrrev_i32_e32 v61, 31, v60
	v_lshlrev_b64 v[60:61], 1, v[60:61]
	v_lshl_add_u64 v[62:63], v[78:79], 0, v[60:61]
	global_store_dword v[62:63], v108, off offset:1024
	v_lshl_add_u64 v[62:63], v[80:81], 0, v[60:61]
	global_store_dword v[62:63], v109, off offset:1024
	v_or_b32_e32 v62, 32, v76
	v_ashrrev_i32_e32 v63, 31, v62
	v_lshlrev_b64 v[62:63], 1, v[62:63]
	v_lshl_add_u64 v[108:109], v[82:83], 0, v[62:63]
	global_load_ushort v108, v[108:109], off
	s_movk_i32 s0, 0xffee
	s_waitcnt vmcnt(0)
	v_lshlrev_b32_e32 v108, 16, v108
	v_mul_f32_e32 v111, v56, v108
	v_lshl_add_u64 v[108:109], v[86:87], 0, v[62:63]
	global_load_ushort v56, v[108:109], off
	v_fmac_f32_e32 v102, v111, v111
	s_waitcnt vmcnt(0)
	v_lshlrev_b32_e32 v56, 16, v56
	v_mul_f32_e32 v108, v57, v56
	v_lshl_add_u64 v[56:57], v[84:85], 0, v[62:63]
	global_load_ushort v56, v[56:57], off
	v_mul_f32_e32 v57, 0xbfb8aa3b, v58
	v_exp_f32_e32 v57, v57
	s_waitcnt vmcnt(0)
	v_lshlrev_b32_e32 v56, 16, v56
	v_add_f32_e32 v57, 1.0, v57
	v_rcp_f32_e32 v57, v57
	s_nop 0
	v_mul_f32_e32 v109, v57, v56
	v_lshl_add_u64 v[56:57], v[88:89], 0, v[62:63]
	global_load_ushort v56, v[56:57], off
	v_mul_f32_e32 v57, 0xbfb8aa3b, v59
	v_exp_f32_e32 v57, v57
	v_mov_b32_dpp v58, v109 quad_perm:[1,0,3,2] row_mask:0xf bank_mask:0xf bound_ctrl:1
	v_cndmask_b32_e64 v58, v58, v111, s[36:37]
	v_add_u32_e32 v58, 0x8000, v58
	v_add_f32_e32 v57, 1.0, v57
	v_rcp_f32_e32 v57, v57
	s_waitcnt vmcnt(0)
	v_lshlrev_b32_e32 v56, 16, v56
	v_mul_f32_e32 v110, v57, v56
	s_nop 0
	v_mov_b32_dpp v56, v111 quad_perm:[1,0,3,2] row_mask:0xf bank_mask:0xf bound_ctrl:1
	v_cndmask_b32_e64 v56, v109, v56, s[36:37]
	v_mov_b32_dpp v57, v108 quad_perm:[1,0,3,2] row_mask:0xf bank_mask:0xf bound_ctrl:1
	v_mov_b32_dpp v59, v110 quad_perm:[1,0,3,2] row_mask:0xf bank_mask:0xf bound_ctrl:1
	v_add_u32_e32 v56, 0x8000, v56
	v_perm_b32 v111, v56, v58, s25
	v_cndmask_b32_e64 v56, v110, v57, s[36:37]
	v_cndmask_b32_e64 v57, v59, v108, s[36:37]
	v_add_u32_e32 v56, 0x8000, v56
	v_add_u32_e32 v57, 0x8000, v57
	v_perm_b32 v112, v56, v57, s25
	v_bitop3_b32 v56, v76, s0, 32 bitop3:0xc8
	v_ashrrev_i32_e32 v57, 31, v56
	v_lshlrev_b64 v[56:57], 1, v[56:57]
	v_lshl_add_u64 v[58:59], v[78:79], 0, v[56:57]
	global_store_dword v[58:59], v111, off offset:1024
	v_lshl_add_u64 v[58:59], v[80:81], 0, v[56:57]
	global_store_dword v[58:59], v112, off offset:1024
	v_or_b32_e32 v58, 48, v76
	v_ashrrev_i32_e32 v59, 31, v58
	v_lshlrev_b64 v[58:59], 1, v[58:59]
	v_lshl_add_u64 v[82:83], v[82:83], 0, v[58:59]
	global_load_ushort v82, v[82:83], off
	s_waitcnt vmcnt(0)
	v_lshlrev_b32_e32 v82, 16, v82
	v_mul_f32_e32 v111, v52, v82
	v_lshl_add_u64 v[82:83], v[86:87], 0, v[58:59]
	global_load_ushort v52, v[82:83], off
	v_fmac_f32_e32 v102, v111, v111
	s_waitcnt vmcnt(0)
	v_lshlrev_b32_e32 v52, 16, v52
	v_mul_f32_e32 v82, v53, v52
	v_lshl_add_u64 v[52:53], v[84:85], 0, v[58:59]
	global_load_ushort v52, v[52:53], off
	v_mul_f32_e32 v53, 0xbfb8aa3b, v54
	v_exp_f32_e32 v53, v53
	s_waitcnt vmcnt(0)
	v_lshlrev_b32_e32 v52, 16, v52
	v_add_f32_e32 v53, 1.0, v53
	v_rcp_f32_e32 v53, v53
	s_nop 0
	v_mul_f32_e32 v83, v53, v52
	v_lshl_add_u64 v[52:53], v[88:89], 0, v[58:59]
	global_load_ushort v52, v[52:53], off
	v_mul_f32_e32 v53, 0xbfb8aa3b, v55
	v_exp_f32_e32 v53, v53
	v_mov_b32_dpp v54, v83 quad_perm:[1,0,3,2] row_mask:0xf bank_mask:0xf bound_ctrl:1
	v_cndmask_b32_e64 v54, v54, v111, s[36:37]
	v_add_u32_e32 v54, 0x8000, v54
	v_add_f32_e32 v53, 1.0, v53
	v_rcp_f32_e32 v53, v53
	s_waitcnt vmcnt(0)
	v_lshlrev_b32_e32 v52, 16, v52
	v_mul_f32_e32 v84, v53, v52
	s_nop 0
	v_mov_b32_dpp v52, v111 quad_perm:[1,0,3,2] row_mask:0xf bank_mask:0xf bound_ctrl:1
	v_cndmask_b32_e64 v52, v83, v52, s[36:37]
	v_mov_b32_dpp v53, v82 quad_perm:[1,0,3,2] row_mask:0xf bank_mask:0xf bound_ctrl:1
	v_mov_b32_dpp v55, v84 quad_perm:[1,0,3,2] row_mask:0xf bank_mask:0xf bound_ctrl:1
	v_add_u32_e32 v52, 0x8000, v52
	v_perm_b32 v85, v52, v54, s25
	v_cndmask_b32_e64 v52, v84, v53, s[36:37]
	v_cndmask_b32_e64 v53, v55, v82, s[36:37]
	v_add_u32_e32 v52, 0x8000, v52
	v_add_u32_e32 v53, 0x8000, v53
	v_perm_b32 v86, v52, v53, s25
	v_bitop3_b32 v52, v76, -2, 48 bitop3:0xc8
	v_ashrrev_i32_e32 v53, 31, v52
	v_lshlrev_b64 v[52:53], 1, v[52:53]
	v_lshl_add_u64 v[54:55], v[78:79], 0, v[52:53]
	global_store_dword v[54:55], v85, off offset:1024
	v_lshl_add_u64 v[54:55], v[80:81], 0, v[52:53]
	global_store_dword v[54:55], v86, off offset:1024
	v_lshl_add_u64 v[54:55], v[72:73], 0, v[70:71]
	v_add_f32_dpp v73, v102, v102 quad_perm:[1,0,3,2] row_mask:0xf bank_mask:0xf bound_ctrl:1
	v_lshl_add_u64 v[54:55], v[54:55], 3, v[68:69]
	s_nop 0
	v_add_f32_dpp v73, v73, v73 quad_perm:[2,3,0,1] row_mask:0xf bank_mask:0xf bound_ctrl:1
	s_nop 1
	v_add_f32_dpp v73, v73, v73 row_half_mirror row_mask:0xf bank_mask:0xf bound_ctrl:1
	s_nop 1
	v_mov_b32_dpp v76, v73 row_mirror row_mask:0xf bank_mask:0xf bound_ctrl:1
	s_and_saveexec_b64 s[0:1], s[34:35]
	s_cbranch_execz .LBB0_268
	v_add_f32_e32 v73, v73, v76
	global_store_dword v[54:55], v73, off

; DEVINL f32x4 mfma16(bf16x8 a, bf16x8 b, f32x4 c) { return __builtin_amdgcn_mfma_f32_16x16x32_bf16(a, b, c, 0, 0, 0); }
; DEVINL void gemm_loop(f32x4 (&acc)[4][4], const u16* __restrict__ A, int lda, const u16* __restrict__ Bt, int ldb,
;                       int m0, int n0, int k0, int nk, char* smem) {
;     ...
;   __syncthreads();
; #pragma unroll
;   for (int i = 0; i < 4; ++i) {
;     glds16(ga[i], smem + i * 4096 + wid * 1024);
;     glds16(gb[i], smem + 16384 + i * 4096 + wid * 1024);
;   }
;   for (int kt = 0; kt < nk; ++kt) {
;     __syncthreads();
;     char* cur = smem + (kt & 1) * 32768;
;     if (kt + 1 < nk) {
;       char* nxt = smem + ((kt + 1) & 1) * 32768;
; #pragma unroll
;       for (int i = 0; i < 4; ++i) {
;         glds16(ga[i] + (kt + 1) * 64, nxt + i * 4096 + wid * 1024);
;         glds16(gb[i] + (kt + 1) * 64, nxt + 16384 + i * 4096 + wid * 1024);
;       }
;     }
;     bf16x8 af[2][4], bfr[2][4];
; #pragma unroll
;     for (int ks = 0; ks < 2; ++ks)
; #pragma unroll
;       for (int f = 0; f < 4; ++f) {
;         int ra = wr * 64 + f * 16 + fr, rb = wc * 64 + f * 16 + fr;
;         int ch = ks * 4 + fq;
;         af[ks][f] = *(const bf16x8*)(cur + ra * 128 + ((ch ^ ((ra >> 1) & 7)) << 4));
;         bfr[ks][f] = *(const bf16x8*)(cur + 16384 + rb * 128 + ((ch ^ ((rb >> 1) & 7)) << 4));
;       }
;     __builtin_amdgcn_sched_barrier(0);
; #pragma unroll
;     for (int ks = 0; ks < 2; ++ks)
; #pragma unroll
;       for (int mf = 0; mf < 4; ++mf)
; #pragma unroll
;         for (int nf = 0; nf < 4; ++nf) acc[mf][nf] = mfma16(af[ks][mf], bfr[ks][nf], acc[mf][nf]);
;   }
.LBB0_306:
	v_readfirstlane_b32 s100, v86
	v_add_u32_e32 v196, v90, v87
	v_add_u32_e32 v197, v90, v88
	v_add_u32_e32 v198, v89, v87
	v_add_u32_e32 v199, v89, v88
	s_mov_b32 s101, s100
	v_lshlrev_b32_e32 v202, 4, v0
	s_waitcnt vmcnt(0)
	s_barrier
	s_add_u32 m0, s100, 0x8000
	v_lshl_add_u64 v[200:201], v[68:69], 0, s[34:35]
	global_load_lds_dwordx4 v[200:201], off
	s_add_u32 m0, s100, 0xc000
	v_lshl_add_u64 v[200:201], v[70:71], 0, s[34:35]
	global_load_lds_dwordx4 v[200:201], off
	s_add_u32 m0, s100, 0x9000
	v_lshl_add_u64 v[200:201], v[72:73], 0, s[34:35]
	global_load_lds_dwordx4 v[200:201], off
	s_add_u32 m0, s100, 0xd000
	v_lshl_add_u64 v[200:201], v[74:75], 0, s[34:35]
	global_load_lds_dwordx4 v[200:201], off
	s_add_u32 m0, s100, 0xa000
	v_lshl_add_u64 v[200:201], v[76:77], 0, s[34:35]
	global_load_lds_dwordx4 v[200:201], off
	s_add_u32 m0, s100, 0xe000
	v_lshl_add_u64 v[200:201], v[78:79], 0, s[34:35]
	global_load_lds_dwordx4 v[200:201], off
	s_add_u32 m0, s100, 0xb000
	v_lshl_add_u64 v[200:201], v[80:81], 0, s[34:35]
	global_load_lds_dwordx4 v[200:201], off
	s_add_u32 m0, s100, 0xf000
	v_lshl_add_u64 v[200:201], v[82:83], 0, s[34:35]
	global_load_lds_dwordx4 v[200:201], off
	ds_read_b128 v[106:109], v196
	ds_read_b128 v[110:113], v196 offset:2048
	ds_read_b128 v[132:135], v197 offset:16384
	ds_read_b128 v[136:139], v197 offset:18432
	ds_read_b128 v[140:143], v196 offset:4096
	ds_read_b128 v[144:147], v196 offset:6144
	ds_read_b128 v[148:151], v197 offset:20480
	ds_read_b128 v[152:155], v197 offset:22528
	ds_read_b128 v[156:159], v198
	ds_read_b128 v[160:163], v198 offset:2048
	ds_read_b128 v[164:167], v199 offset:16384
	ds_read_b128 v[168:171], v199 offset:18432
	ds_read_b128 v[172:175], v198 offset:4096
	ds_read_b128 v[176:179], v198 offset:6144
	ds_read_b128 v[180:183], v199 offset:20480
	ds_read_b128 v[184:187], v199 offset:22528
	s_waitcnt lgkmcnt(8)
	v_mfma_f32_16x16x32_bf16 v[64:67], v[106:109], v[132:135], v[64:67]
	v_mfma_f32_16x16x32_bf16 v[60:63], v[106:109], v[136:139], v[60:63]
	v_mfma_f32_16x16x32_bf16 v[52:55], v[106:109], v[148:151], v[52:55]
	v_mfma_f32_16x16x32_bf16 v[48:51], v[106:109], v[152:155], v[48:51]
	v_mfma_f32_16x16x32_bf16 v[44:47], v[110:113], v[132:135], v[44:47]
	v_mfma_f32_16x16x32_bf16 v[40:43], v[110:113], v[136:139], v[40:43]
	v_mfma_f32_16x16x32_bf16 v[36:39], v[110:113], v[148:151], v[36:39]
	v_mfma_f32_16x16x32_bf16 v[32:35], v[110:113], v[152:155], v[32:35]
	v_mfma_f32_16x16x32_bf16 v[28:31], v[140:143], v[132:135], v[28:31]
	v_mfma_f32_16x16x32_bf16 v[24:27], v[140:143], v[136:139], v[24:27]
	v_mfma_f32_16x16x32_bf16 v[20:23], v[140:143], v[148:151], v[20:23]
	v_mfma_f32_16x16x32_bf16 v[16:19], v[140:143], v[152:155], v[16:19]
	v_mfma_f32_16x16x32_bf16 v[12:15], v[144:147], v[132:135], v[12:15]
	v_mfma_f32_16x16x32_bf16 v[8:11], v[144:147], v[136:139], v[8:11]
	v_mfma_f32_16x16x32_bf16 v[4:7], v[144:147], v[148:151], v[4:7]
	v_mfma_f32_16x16x32_bf16 v[56:59], v[144:147], v[152:155], v[56:59]
	v_xor_b32_e32 v196, 0x8000, v196
	v_xor_b32_e32 v197, 0x8000, v197
	v_xor_b32_e32 v198, 0x8000, v198
	v_xor_b32_e32 v199, 0x8000, v199
	s_waitcnt vmcnt(0) lgkmcnt(0)
	s_barrier

; DEVINL float bf2f(u16 h) { return __uint_as_float(((unsigned)h) << 16); }
; DEVINL float sigmoidf_(float x) { return __builtin_amdgcn_rcpf(1.f + __expf(-x)); }
; DEVINL f32x4 mfma16(bf16x8 a, bf16x8 b, f32x4 c) { return __builtin_amdgcn_mfma_f32_16x16x32_bf16(a, b, c, 0, 0, 0); }
; DEVINL void gemm_loop(f32x4 (&acc)[4][4], const u16* __restrict__ A, int lda, const u16* __restrict__ Bt, int ldb,
;                       int m0, int n0, int k0, int nk, char* smem) {
;     ...
;     __builtin_amdgcn_sched_barrier(0);
; #pragma unroll
;     for (int ks = 0; ks < 2; ++ks)
; #pragma unroll
;       for (int mf = 0; mf < 4; ++mf)
; #pragma unroll
;         for (int nf = 0; nf < 4; ++nf) acc[mf][nf] = mfma16(af[ks][mf], bfr[ks][nf], acc[mf][nf]);
;   }
; DEVINL void p3_tile(const Params& p, char* smem, int mt, int nt) {
;     ...
; #pragma unroll
;   for (int mf = 0; mf < 4; ++mf) {
;     const int rb = m0 + wr * 64 + mf * 16 + (lane >> 4) * 4;
;     float ssq[4] = {0.f, 0.f, 0.f, 0.f};
; #pragma unroll
;     for (int nf = 0; nf < 4; ++nf) {
;       const int col = n0 + wc * 64 + nf * 16 + (lane & 15);
;       float val[4];
; #pragma unroll
;       for (int j = 0; j < 4; ++j) {
;         val[j] = bf2f(yg[(size_t)(rb + j) * 512 + col]) * sigmoidf_(acc[mf][nf][j]);
;         ssq[j] += val[j] * val[j];
;       }
;       store_pairs(mixin, 1024, rb, 512 + col, val[0], val[1], val[2], val[3]);
.Lkp_b306_last:
	v_mfma_f32_16x16x32_bf16 v[64:67], v[156:159], v[164:167], v[64:67]
	v_mfma_f32_16x16x32_bf16 v[60:63], v[156:159], v[168:171], v[60:63]
	v_mfma_f32_16x16x32_bf16 v[52:55], v[156:159], v[180:183], v[52:55]
	v_mfma_f32_16x16x32_bf16 v[48:51], v[156:159], v[184:187], v[48:51]
	v_mfma_f32_16x16x32_bf16 v[44:47], v[160:163], v[164:167], v[44:47]
	v_mfma_f32_16x16x32_bf16 v[40:43], v[160:163], v[168:171], v[40:43]
	v_mfma_f32_16x16x32_bf16 v[36:39], v[160:163], v[180:183], v[36:39]
	v_mfma_f32_16x16x32_bf16 v[32:35], v[160:163], v[184:187], v[32:35]
	v_mfma_f32_16x16x32_bf16 v[28:31], v[172:175], v[164:167], v[28:31]
	v_mfma_f32_16x16x32_bf16 v[24:27], v[172:175], v[168:171], v[24:27]
	v_mfma_f32_16x16x32_bf16 v[20:23], v[172:175], v[180:183], v[20:23]
	v_mfma_f32_16x16x32_bf16 v[16:19], v[172:175], v[184:187], v[16:19]
	v_mfma_f32_16x16x32_bf16 v[12:15], v[176:179], v[164:167], v[12:15]
	v_mfma_f32_16x16x32_bf16 v[8:11], v[176:179], v[168:171], v[8:11]
	v_mfma_f32_16x16x32_bf16 v[4:7], v[176:179], v[180:183], v[4:7]
	v_mfma_f32_16x16x32_bf16 v[56:59], v[176:179], v[184:187], v[56:59]
	s_mov_b32 s1, 0x8000
	v_add_u32_e32 v68, s1, v90
	v_add_u32_e32 v86, v68, v87
	s_waitcnt vmcnt(0)
	s_barrier
	v_add_u32_e32 v90, v68, v88
	ds_read_b128 v[68:71], v86
	ds_read_b128 v[72:75], v86 offset:2048
	ds_read_b128 v[76:79], v90 offset:16384
	ds_read_b128 v[80:83], v90 offset:18432
	ds_read_b128 v[106:109], v86 offset:4096
	ds_read_b128 v[110:113], v86 offset:6144
	ds_read_b128 v[132:135], v90 offset:20480
	ds_read_b128 v[136:139], v90 offset:22528
	v_add_u32_e32 v86, s1, v89
	v_add_u32_e32 v90, v86, v87
	v_add_u32_e32 v102, v86, v88
	ds_read_b128 v[86:89], v90
	ds_read_b128 v[140:143], v90 offset:2048
	ds_read_b128 v[144:147], v102 offset:16384
	ds_read_b128 v[148:151], v102 offset:18432
	ds_read_b128 v[152:155], v90 offset:4096
	ds_read_b128 v[156:159], v90 offset:6144
	ds_read_b128 v[160:163], v102 offset:20480
	ds_read_b128 v[164:167], v102 offset:22528
	s_waitcnt lgkmcnt(13)
	v_mfma_f32_16x16x32_bf16 v[64:67], v[68:71], v[76:79], v[64:67]
	v_readlane_b32 s0, v194, 21
	v_readlane_b32 s1, v194, 22
	s_movk_i32 s43, 0xffce
	s_waitcnt lgkmcnt(12)
	v_mfma_f32_16x16x32_bf16 v[60:63], v[68:71], v[80:83], v[60:63]
	s_waitcnt lgkmcnt(9)
	v_mfma_f32_16x16x32_bf16 v[52:55], v[68:71], v[132:135], v[52:55]
	s_waitcnt lgkmcnt(8)
	v_mfma_f32_16x16x32_bf16 v[48:51], v[68:71], v[136:139], v[48:51]
	v_mfma_f32_16x16x32_bf16 v[44:47], v[72:75], v[76:79], v[44:47]
	v_mfma_f32_16x16x32_bf16 v[40:43], v[72:75], v[80:83], v[40:43]
	v_mfma_f32_16x16x32_bf16 v[36:39], v[72:75], v[132:135], v[36:39]
	v_mfma_f32_16x16x32_bf16 v[32:35], v[72:75], v[136:139], v[32:35]
	v_mfma_f32_16x16x32_bf16 v[28:31], v[106:109], v[76:79], v[28:31]
	v_mfma_f32_16x16x32_bf16 v[24:27], v[106:109], v[80:83], v[24:27]
	v_mfma_f32_16x16x32_bf16 v[20:23], v[106:109], v[132:135], v[20:23]
	v_mfma_f32_16x16x32_bf16 v[16:19], v[106:109], v[136:139], v[16:19]
	v_mfma_f32_16x16x32_bf16 v[12:15], v[110:113], v[76:79], v[12:15]
	v_mfma_f32_16x16x32_bf16 v[8:11], v[110:113], v[80:83], v[8:11]
	v_mfma_f32_16x16x32_bf16 v[4:7], v[110:113], v[132:135], v[4:7]
	v_mfma_f32_16x16x32_bf16 v[68:71], v[110:113], v[136:139], v[56:59]
	s_waitcnt lgkmcnt(1)
	v_mfma_f32_16x16x32_bf16 v[56:59], v[86:89], v[160:163], v[52:55]
	s_waitcnt lgkmcnt(0)
	v_mfma_f32_16x16x32_bf16 v[52:55], v[86:89], v[164:167], v[48:51]
	v_mfma_f32_16x16x32_bf16 v[48:51], v[140:143], v[144:147], v[44:47]
	s_nop 4
	v_mul_f32_e32 v56, 0xbfb8aa3b, v56
	v_exp_f32_e32 v56, v56
	v_mul_f32_e32 v57, 0xbfb8aa3b, v57
	v_mfma_f32_16x16x32_bf16 v[44:47], v[140:143], v[148:151], v[40:43]
	v_exp_f32_e32 v57, v57
	v_add_f32_e32 v56, 1.0, v56
	v_rcp_f32_e32 v56, v56
	v_mfma_f32_16x16x32_bf16 v[40:43], v[140:143], v[160:163], v[36:39]
	v_add_f32_e32 v57, 1.0, v57
	v_rcp_f32_e32 v57, v57
	v_mul_f32_e32 v52, 0xbfb8aa3b, v52
	v_mfma_f32_16x16x32_bf16 v[36:39], v[140:143], v[164:167], v[32:35]
	v_exp_f32_e32 v52, v52
	v_mul_f32_e32 v53, 0xbfb8aa3b, v53
	v_exp_f32_e32 v53, v53
	v_mfma_f32_16x16x32_bf16 v[32:35], v[152:155], v[144:147], v[28:31]
	v_add_f32_e32 v52, 1.0, v52
	v_rcp_f32_e32 v52, v52
	v_add_f32_e32 v53, 1.0, v53
	v_mfma_f32_16x16x32_bf16 v[28:31], v[152:155], v[148:151], v[24:27]
	v_rcp_f32_e32 v53, v53
	v_mfma_f32_16x16x32_bf16 v[24:27], v[152:155], v[160:163], v[20:23]
	v_mfma_f32_16x16x32_bf16 v[20:23], v[152:155], v[164:167], v[16:19]
	v_mfma_f32_16x16x32_bf16 v[16:19], v[156:159], v[144:147], v[12:15]
	v_mfma_f32_16x16x32_bf16 v[12:15], v[156:159], v[148:151], v[8:11]
	v_mfma_f32_16x16x32_bf16 v[8:11], v[156:159], v[160:163], v[4:7]
	v_mfma_f32_16x16x32_bf16 v[4:7], v[156:159], v[164:167], v[68:71]
	s_nop 2
	v_mov_b32_e32 v68, v0
	v_mov_b32_e32 v69, v0
	v_mfma_f32_16x16x32_bf16 v[64:67], v[86:89], v[144:147], v[64:67]
	v_bfe_u32 v71, v69, 6, 1
	v_ashrrev_i32_e32 v69, 1, v69
	v_and_b32_e32 v69, 0xffffffc0, v69
	v_add_u32_e32 v69, v69, v85
	v_lshrrev_b32_e32 v70, 2, v68
	v_and_or_b32 v70, v70, 12, v69
	v_and_b32_e32 v69, 15, v68
	v_and_b32_e32 v68, 1, v68
	v_lshlrev_b32_e32 v90, 1, v68
	v_or_b32_e32 v72, v70, v90
	v_ashrrev_i32_e32 v73, 31, v72
	v_lshl_or_b32 v85, v71, 6, v69
	v_cmp_eq_u32_e64 s[36:37], 0, v68
	v_cmp_eq_u32_e64 s[34:35], 0, v69
	v_lshlrev_b32_e32 v68, 2, v71
	v_mov_b32_e32 v69, v2
	v_lshlrev_b64 v[76:77], 11, v[72:73]
	v_or_b32_e32 v72, 1, v72
	v_lshl_add_u64 v[68:69], s[0:1], 0, v[68:69]
	v_readlane_b32 s0, v194, 19
	v_ashrrev_i32_e32 v73, 31, v72
	v_readlane_b32 s1, v194, 20
	v_lshlrev_b64 v[72:73], 11, v[72:73]
	v_or_b32_e32 v74, v85, v84
	v_lshl_add_u64 v[76:77], s[0:1], 0, v[76:77]
	v_lshl_add_u64 v[78:79], s[0:1], 0, v[72:73]
	v_readlane_b32 s0, v194, 29
	v_ashrrev_i32_e32 v71, 31, v70
	v_ashrrev_i32_e32 v75, 31, v74
	v_readlane_b32 s1, v194, 30
	v_lshlrev_b64 v[80:81], 10, v[70:71]
	v_mul_f32_e32 v64, 0xbfb8aa3b, v64
	v_lshl_add_u64 v[72:73], v[74:75], 1, s[0:1]
	v_lshl_add_u64 v[82:83], v[72:73], 0, v[80:81]
	global_load_ushort v75, v[82:83], off
	v_exp_f32_e32 v64, v64
	v_or_b32_e32 v82, 1, v70
	v_ashrrev_i32_e32 v83, 31, v82
	v_lshlrev_b64 v[82:83], 10, v[82:83]
	v_add_f32_e32 v64, 1.0, v64
	v_rcp_f32_e32 v64, v64
	v_mfma_f32_16x16x32_bf16 v[60:63], v[86:89], v[148:151], v[60:63]
	v_lshl_add_u64 v[86:87], v[72:73], 0, v[82:83]
	v_mul_f32_e32 v65, 0xbfb8aa3b, v65
	v_exp_f32_e32 v65, v65
	v_lshl_add_u64 v[80:81], s[0:1], 0, v[80:81]
	v_add_f32_e32 v65, 1.0, v65
	v_rcp_f32_e32 v65, v65
	s_nop 1
	v_mul_f32_e32 v60, 0xbfb8aa3b, v60
	v_exp_f32_e32 v60, v60
	v_mul_f32_e32 v61, 0xbfb8aa3b, v61
	v_exp_f32_e32 v61, v61
	v_add_f32_e32 v60, 1.0, v60
	v_rcp_f32_e32 v60, v60
	v_add_f32_e32 v61, 1.0, v61
	v_rcp_f32_e32 v61, v61
	s_waitcnt vmcnt(0)
; DEVINL float bf2f(u16 h) { return __uint_as_float(((unsigned)h) << 16); }
; DEVINL float sigmoidf_(float x) { return __builtin_amdgcn_rcpf(1.f + __expf(-x)); }
; DEVINL void p3_tile(const Params& p, char* smem, int mt, int nt) {
;     ...
;     for (int nf = 0; nf < 4; ++nf) {
;       const int col = n0 + wc * 64 + nf * 16 + (lane & 15);
;       float val[4];
; #pragma unroll
;       for (int j = 0; j < 4; ++j) {
;         val[j] = bf2f(yg[(size_t)(rb + j) * 512 + col]) * sigmoidf_(acc[mf][nf][j]);
;         ssq[j] += val[j] * val[j];
;       }
;       store_pairs(mixin, 1024, rb, 512 + col, val[0], val[1], val[2], val[3]);
;     }
	v_lshlrev_b32_e32 v75, 16, v75
	v_mul_f32_e32 v107, v64, v75
	global_load_ushort v64, v[86:87], off
	s_waitcnt vmcnt(0)
	v_lshlrev_b32_e32 v64, 16, v64
	v_mul_f32_e32 v75, v65, v64
	v_or_b32_e32 v64, 2, v70
	v_ashrrev_i32_e32 v65, 31, v64
	v_lshlrev_b64 v[88:89], 10, v[64:65]
	v_lshl_add_u64 v[64:65], v[72:73], 0, v[88:89]
	global_load_ushort v64, v[64:65], off
	v_mul_f32_e32 v65, 0xbfb8aa3b, v66
	v_exp_f32_e32 v65, v65
	s_waitcnt vmcnt(0)
	v_lshlrev_b32_e32 v64, 16, v64
	v_add_f32_e32 v65, 1.0, v65
	v_rcp_f32_e32 v65, v65
	s_nop 0
	v_mul_f32_e32 v102, v65, v64
	v_or_b32_e32 v64, 3, v70
	v_ashrrev_i32_e32 v65, 31, v64
	v_lshlrev_b64 v[86:87], 10, v[64:65]
	v_lshl_add_u64 v[64:65], v[72:73], 0, v[86:87]
	global_load_ushort v64, v[64:65], off
	v_mul_f32_e32 v65, 0xbfb8aa3b, v67
	v_exp_f32_e32 v65, v65
	v_mov_b32_dpp v66, v102 quad_perm:[1,0,3,2] row_mask:0xf bank_mask:0xf bound_ctrl:1
	v_cndmask_b32_e64 v66, v66, v107, s[36:37]
	v_add_u32_e32 v66, 0x8000, v66
	v_add_f32_e32 v65, 1.0, v65
	v_rcp_f32_e32 v65, v65
	v_lshl_add_u64 v[86:87], s[0:1], 0, v[86:87]
	s_waitcnt vmcnt(0)
	v_lshlrev_b32_e32 v64, 16, v64
	v_mul_f32_e32 v105, v65, v64
	s_nop 0
	v_mov_b32_dpp v64, v107 quad_perm:[1,0,3,2] row_mask:0xf bank_mask:0xf bound_ctrl:1
	v_cndmask_b32_e64 v64, v102, v64, s[36:37]
	v_mov_b32_dpp v65, v75 quad_perm:[1,0,3,2] row_mask:0xf bank_mask:0xf bound_ctrl:1
	v_mov_b32_dpp v67, v105 quad_perm:[1,0,3,2] row_mask:0xf bank_mask:0xf bound_ctrl:1
	v_add_u32_e32 v64, 0x8000, v64
	v_perm_b32 v106, v64, v66, s25
	v_cndmask_b32_e64 v64, v105, v65, s[36:37]
	v_cndmask_b32_e64 v65, v67, v75, s[36:37]
	v_add_u32_e32 v64, 0x8000, v64
	v_add_u32_e32 v65, 0x8000, v65
	v_perm_b32 v108, v64, v65, s25
	v_bitop3_b32 v64, v85, s43, v84 bitop3:0xc8
	v_ashrrev_i32_e32 v65, 31, v64
	v_lshlrev_b64 v[64:65], 1, v[64:65]
	v_lshl_add_u64 v[66:67], v[76:77], 0, v[64:65]
	global_store_dword v[66:67], v106, off offset:1024
	v_lshl_add_u64 v[66:67], v[78:79], 0, v[64:65]
	global_store_dword v[66:67], v108, off offset:1024
	v_or_b32_e32 v66, 16, v74
	v_ashrrev_i32_e32 v67, 31, v66
	v_lshlrev_b64 v[66:67], 1, v[66:67]
	v_lshl_add_u64 v[84:85], v[80:81], 0, v[66:67]
	global_load_ushort v84, v[84:85], off
	s_waitcnt vmcnt(0)
	v_lshlrev_b32_e32 v84, 16, v84
	v_mul_f32_e32 v108, v60, v84
	v_lshl_add_u64 v[84:85], s[0:1], 0, v[82:83]
	v_lshl_add_u64 v[82:83], v[84:85], 0, v[66:67]
	global_load_ushort v60, v[82:83], off
	v_mul_f32_e32 v106, v108, v108
	v_lshl_add_u64 v[82:83], s[0:1], 0, v[88:89]
	v_fmac_f32_e32 v106, v107, v107
	s_movk_i32 s0, 0xffde
	s_waitcnt vmcnt(0)
	v_lshlrev_b32_e32 v60, 16, v60
	v_mul_f32_e32 v107, v61, v60
	v_lshl_add_u64 v[60:61], v[82:83], 0, v[66:67]
	global_load_ushort v60, v[60:61], off
	v_mul_f32_e32 v61, 0xbfb8aa3b, v62
	v_exp_f32_e32 v61, v61
	s_waitcnt vmcnt(0)
	v_lshlrev_b32_e32 v60, 16, v60
	v_add_f32_e32 v61, 1.0, v61
	v_rcp_f32_e32 v61, v61
	s_nop 0
	v_mul_f32_e32 v88, v61, v60
	v_lshl_add_u64 v[60:61], v[86:87], 0, v[66:67]
	global_load_ushort v60, v[60:61], off
	v_mul_f32_e32 v61, 0xbfb8aa3b, v63
	v_exp_f32_e32 v61, v61
	v_mov_b32_dpp v62, v88 quad_perm:[1,0,3,2] row_mask:0xf bank_mask:0xf bound_ctrl:1
	v_cndmask_b32_e64 v62, v62, v108, s[36:37]
	v_add_u32_e32 v62, 0x8000, v62
	v_add_f32_e32 v61, 1.0, v61
	v_rcp_f32_e32 v61, v61
	s_waitcnt vmcnt(0)
	v_lshlrev_b32_e32 v60, 16, v60
	v_mul_f32_e32 v89, v61, v60
	s_nop 0
	v_mov_b32_dpp v60, v108 quad_perm:[1,0,3,2] row_mask:0xf bank_mask:0xf bound_ctrl:1
	v_cndmask_b32_e64 v60, v88, v60, s[36:37]
	v_mov_b32_dpp v61, v107 quad_perm:[1,0,3,2] row_mask:0xf bank_mask:0xf bound_ctrl:1
	v_mov_b32_dpp v63, v89 quad_perm:[1,0,3,2] row_mask:0xf bank_mask:0xf bound_ctrl:1
	v_add_u32_e32 v60, 0x8000, v60
	v_perm_b32 v108, v60, v62, s25
	v_cndmask_b32_e64 v60, v89, v61, s[36:37]
	v_cndmask_b32_e64 v61, v63, v107, s[36:37]
	v_add_u32_e32 v60, 0x8000, v60
	v_add_u32_e32 v61, 0x8000, v61
	v_perm_b32 v109, v60, v61, s25
	v_bitop3_b32 v60, v74, s0, 16 bitop3:0xc8
	v_ashrrev_i32_e32 v61, 31, v60
	v_lshlrev_b64 v[60:61], 1, v[60:61]
	v_lshl_add_u64 v[62:63], v[76:77], 0, v[60:61]
	global_store_dword v[62:63], v108, off offset:1024
	v_lshl_add_u64 v[62:63], v[78:79], 0, v[60:61]
	global_store_dword v[62:63], v109, off offset:1024
	v_or_b32_e32 v62, 32, v74
	v_ashrrev_i32_e32 v63, 31, v62
	v_lshlrev_b64 v[62:63], 1, v[62:63]
	v_lshl_add_u64 v[108:109], v[80:81], 0, v[62:63]
	global_load_ushort v108, v[108:109], off
	s_movk_i32 s0, 0xffee
	s_waitcnt vmcnt(0)
; DEVINL float bf2f(u16 h) { return __uint_as_float(((unsigned)h) << 16); }
; DEVINL float sigmoidf_(float x) { return __builtin_amdgcn_rcpf(1.f + __expf(-x)); }
; DEVINL void p3_tile(const Params& p, char* smem, int mt, int nt) {
;     ...
;     for (int nf = 0; nf < 4; ++nf) {
;       const int col = n0 + wc * 64 + nf * 16 + (lane & 15);
;       float val[4];
; #pragma unroll
;       for (int j = 0; j < 4; ++j) {
;         val[j] = bf2f(yg[(size_t)(rb + j) * 512 + col]) * sigmoidf_(acc[mf][nf][j]);
;         ssq[j] += val[j] * val[j];
;       }
;       store_pairs(mixin, 1024, rb, 512 + col, val[0], val[1], val[2], val[3]);
;     }
;     {
;       float* ss5p = (float*)(p.ws + OFF_SS5P);
; #pragma unroll
;       for (int j = 0; j < 4; ++j) {
;         const float v = red16(ssq[j]);
;         if ((lane & 15) == 0) ss5p[((size_t)nt * M + rb + j) * 2 + wc] = v;
;       }
;     }
	v_lshlrev_b32_e32 v108, 16, v108
	v_mul_f32_e32 v111, v56, v108
	v_lshl_add_u64 v[108:109], v[84:85], 0, v[62:63]
	global_load_ushort v56, v[108:109], off
	v_fmac_f32_e32 v106, v111, v111
	s_waitcnt vmcnt(0)
	v_lshlrev_b32_e32 v56, 16, v56
	v_mul_f32_e32 v108, v57, v56
	v_lshl_add_u64 v[56:57], v[82:83], 0, v[62:63]
	global_load_ushort v56, v[56:57], off
	v_mul_f32_e32 v57, 0xbfb8aa3b, v58
	v_exp_f32_e32 v57, v57
	s_waitcnt vmcnt(0)
	v_lshlrev_b32_e32 v56, 16, v56
	v_add_f32_e32 v57, 1.0, v57
	v_rcp_f32_e32 v57, v57
	s_nop 0
	v_mul_f32_e32 v109, v57, v56
	v_lshl_add_u64 v[56:57], v[86:87], 0, v[62:63]
	global_load_ushort v56, v[56:57], off
	v_mul_f32_e32 v57, 0xbfb8aa3b, v59
	v_exp_f32_e32 v57, v57
	v_mov_b32_dpp v58, v109 quad_perm:[1,0,3,2] row_mask:0xf bank_mask:0xf bound_ctrl:1
	v_cndmask_b32_e64 v58, v58, v111, s[36:37]
	v_add_u32_e32 v58, 0x8000, v58
	v_add_f32_e32 v57, 1.0, v57
	v_rcp_f32_e32 v57, v57
	s_waitcnt vmcnt(0)
	v_lshlrev_b32_e32 v56, 16, v56
	v_mul_f32_e32 v110, v57, v56
	s_nop 0
	v_mov_b32_dpp v56, v111 quad_perm:[1,0,3,2] row_mask:0xf bank_mask:0xf bound_ctrl:1
	v_cndmask_b32_e64 v56, v109, v56, s[36:37]
	v_mov_b32_dpp v57, v108 quad_perm:[1,0,3,2] row_mask:0xf bank_mask:0xf bound_ctrl:1
	v_mov_b32_dpp v59, v110 quad_perm:[1,0,3,2] row_mask:0xf bank_mask:0xf bound_ctrl:1
	v_add_u32_e32 v56, 0x8000, v56
	v_perm_b32 v111, v56, v58, s25
	v_cndmask_b32_e64 v56, v110, v57, s[36:37]
	v_cndmask_b32_e64 v57, v59, v108, s[36:37]
	v_add_u32_e32 v56, 0x8000, v56
	v_add_u32_e32 v57, 0x8000, v57
	v_perm_b32 v112, v56, v57, s25
	v_bitop3_b32 v56, v74, s0, 32 bitop3:0xc8
	v_ashrrev_i32_e32 v57, 31, v56
	v_lshlrev_b64 v[56:57], 1, v[56:57]
	v_lshl_add_u64 v[58:59], v[76:77], 0, v[56:57]
	global_store_dword v[58:59], v111, off offset:1024
	v_lshl_add_u64 v[58:59], v[78:79], 0, v[56:57]
	global_store_dword v[58:59], v112, off offset:1024
	v_or_b32_e32 v58, 48, v74
	v_ashrrev_i32_e32 v59, 31, v58
	v_lshlrev_b64 v[58:59], 1, v[58:59]
	v_lshl_add_u64 v[80:81], v[80:81], 0, v[58:59]
	global_load_ushort v80, v[80:81], off
	s_movk_i32 s0, 0x4480
	s_waitcnt vmcnt(0)
	v_lshlrev_b32_e32 v80, 16, v80
	v_mul_f32_e32 v111, v52, v80
	v_lshl_add_u64 v[80:81], v[84:85], 0, v[58:59]
	global_load_ushort v52, v[80:81], off
	v_fmac_f32_e32 v106, v111, v111
	s_waitcnt vmcnt(0)
	v_lshlrev_b32_e32 v52, 16, v52
	v_mul_f32_e32 v80, v53, v52
	v_lshl_add_u64 v[52:53], v[82:83], 0, v[58:59]
	global_load_ushort v52, v[52:53], off
	v_mul_f32_e32 v53, 0xbfb8aa3b, v54
	v_exp_f32_e32 v53, v53
	s_waitcnt vmcnt(0)
	v_lshlrev_b32_e32 v52, 16, v52
	v_add_f32_e32 v53, 1.0, v53
	v_rcp_f32_e32 v53, v53
	s_nop 0
	v_mul_f32_e32 v81, v53, v52
	v_lshl_add_u64 v[52:53], v[86:87], 0, v[58:59]
	global_load_ushort v52, v[52:53], off
	v_mul_f32_e32 v53, 0xbfb8aa3b, v55
	v_exp_f32_e32 v53, v53
	v_mov_b32_dpp v54, v81 quad_perm:[1,0,3,2] row_mask:0xf bank_mask:0xf bound_ctrl:1
	v_cndmask_b32_e64 v54, v54, v111, s[36:37]
	v_add_u32_e32 v54, 0x8000, v54
	v_add_f32_e32 v53, 1.0, v53
	v_rcp_f32_e32 v53, v53
	s_waitcnt vmcnt(0)
	v_lshlrev_b32_e32 v52, 16, v52
	v_mul_f32_e32 v82, v53, v52
	s_nop 0
	v_mov_b32_dpp v52, v111 quad_perm:[1,0,3,2] row_mask:0xf bank_mask:0xf bound_ctrl:1
	v_cndmask_b32_e64 v52, v81, v52, s[36:37]
	v_mov_b32_dpp v53, v80 quad_perm:[1,0,3,2] row_mask:0xf bank_mask:0xf bound_ctrl:1
	v_mov_b32_dpp v55, v82 quad_perm:[1,0,3,2] row_mask:0xf bank_mask:0xf bound_ctrl:1
	v_add_u32_e32 v52, 0x8000, v52
	v_perm_b32 v83, v52, v54, s25
	v_cndmask_b32_e64 v52, v82, v53, s[36:37]
	v_cndmask_b32_e64 v53, v55, v80, s[36:37]
	v_add_u32_e32 v52, 0x8000, v52
	v_add_u32_e32 v53, 0x8000, v53
	v_perm_b32 v84, v52, v53, s25
	v_bitop3_b32 v52, v74, -2, 48 bitop3:0xc8
	v_ashrrev_i32_e32 v53, 31, v52
	v_lshlrev_b64 v[52:53], 1, v[52:53]
	v_lshl_add_u64 v[54:55], v[76:77], 0, v[52:53]
	global_store_dword v[54:55], v83, off offset:1024
	v_lshl_add_u64 v[54:55], v[78:79], 0, v[52:53]
	global_store_dword v[54:55], v84, off offset:1024
	v_mad_i64_i32 v[54:55], s[0:1], v91, s0, v[70:71]
	v_add_f32_dpp v71, v106, v106 quad_perm:[1,0,3,2] row_mask:0xf bank_mask:0xf bound_ctrl:1
	v_lshl_add_u64 v[54:55], v[54:55], 3, v[68:69]
	s_nop 0
	v_add_f32_dpp v71, v71, v71 quad_perm:[2,3,0,1] row_mask:0xf bank_mask:0xf bound_ctrl:1
	s_nop 1
	v_add_f32_dpp v71, v71, v71 row_half_mirror row_mask:0xf bank_mask:0xf bound_ctrl:1
	s_nop 1
	v_mov_b32_dpp v74, v71 row_mirror row_mask:0xf bank_mask:0xf bound_ctrl:1
	s_and_saveexec_b64 s[0:1], s[34:35]
	s_cbranch_execz .LBB0_309
	v_add_f32_e32 v71, v71, v74
	global_store_dword v[54:55], v71, off

; DEVINL f32x4 mfma16(bf16x8 a, bf16x8 b, f32x4 c) { return __builtin_amdgcn_mfma_f32_16x16x32_bf16(a, b, c, 0, 0, 0); }
; DEVINL void gemm_loop(f32x4 (&acc)[4][4], const u16* __restrict__ A, int lda, const u16* __restrict__ Bt, int ldb,
;                       int m0, int n0, int k0, int nk, char* smem) {
;     ...
;   __syncthreads();
; #pragma unroll
;   for (int i = 0; i < 4; ++i) {
;     glds16(ga[i], smem + i * 4096 + wid * 1024);
;     glds16(gb[i], smem + 16384 + i * 4096 + wid * 1024);
;   }
;   for (int kt = 0; kt < nk; ++kt) {
;     __syncthreads();
;     char* cur = smem + (kt & 1) * 32768;
;     if (kt + 1 < nk) {
;       char* nxt = smem + ((kt + 1) & 1) * 32768;
; #pragma unroll
;       for (int i = 0; i < 4; ++i) {
;         glds16(ga[i] + (kt + 1) * 64, nxt + i * 4096 + wid * 1024);
;         glds16(gb[i] + (kt + 1) * 64, nxt + 16384 + i * 4096 + wid * 1024);
;       }
;     }
;     bf16x8 af[2][4], bfr[2][4];
; #pragma unroll
;     for (int ks = 0; ks < 2; ++ks)
; #pragma unroll
;       for (int f = 0; f < 4; ++f) {
;         int ra = wr * 64 + f * 16 + fr, rb = wc * 64 + f * 16 + fr;
;         int ch = ks * 4 + fq;
;         af[ks][f] = *(const bf16x8*)(cur + ra * 128 + ((ch ^ ((ra >> 1) & 7)) << 4));
;         bfr[ks][f] = *(const bf16x8*)(cur + 16384 + rb * 128 + ((ch ^ ((rb >> 1) & 7)) << 4));
;       }
;     __builtin_amdgcn_sched_barrier(0);
; #pragma unroll
;     for (int ks = 0; ks < 2; ++ks)
; #pragma unroll
;       for (int mf = 0; mf < 4; ++mf)
; #pragma unroll
;         for (int nf = 0; nf < 4; ++nf) acc[mf][nf] = mfma16(af[ks][mf], bfr[ks][nf], acc[mf][nf]);
;   }
.LBB0_748:
	v_readfirstlane_b32 s100, v86
	v_add_u32_e32 v196, v90, v87
	v_add_u32_e32 v197, v90, v88
	v_add_u32_e32 v198, v89, v87
	v_add_u32_e32 v199, v89, v88
	s_mov_b32 s101, s100
	v_lshlrev_b32_e32 v202, 4, v0
	s_waitcnt vmcnt(0)
	s_barrier
	s_add_u32 m0, s100, 0x8000
	v_lshl_add_u64 v[200:201], v[68:69], 0, s[36:37]
	global_load_lds_dwordx4 v[200:201], off
	s_add_u32 m0, s100, 0xc000
	v_lshl_add_u64 v[200:201], v[70:71], 0, s[36:37]
	global_load_lds_dwordx4 v[200:201], off
	s_add_u32 m0, s100, 0x9000
	v_lshl_add_u64 v[200:201], v[72:73], 0, s[36:37]
	global_load_lds_dwordx4 v[200:201], off
	s_add_u32 m0, s100, 0xd000
	v_lshl_add_u64 v[200:201], v[74:75], 0, s[36:37]
	global_load_lds_dwordx4 v[200:201], off
	s_add_u32 m0, s100, 0xa000
	v_lshl_add_u64 v[200:201], v[76:77], 0, s[36:37]
	global_load_lds_dwordx4 v[200:201], off
	s_add_u32 m0, s100, 0xe000
	v_lshl_add_u64 v[200:201], v[78:79], 0, s[36:37]
	global_load_lds_dwordx4 v[200:201], off
	s_add_u32 m0, s100, 0xb000
	v_lshl_add_u64 v[200:201], v[80:81], 0, s[36:37]
	global_load_lds_dwordx4 v[200:201], off
	s_add_u32 m0, s100, 0xf000
	v_lshl_add_u64 v[200:201], v[82:83], 0, s[36:37]
	global_load_lds_dwordx4 v[200:201], off
	ds_read_b128 v[106:109], v196
	ds_read_b128 v[110:113], v196 offset:2048
	ds_read_b128 v[132:135], v197 offset:16384
	ds_read_b128 v[136:139], v197 offset:18432
	ds_read_b128 v[140:143], v196 offset:4096
	ds_read_b128 v[144:147], v196 offset:6144
	ds_read_b128 v[148:151], v197 offset:20480
	ds_read_b128 v[152:155], v197 offset:22528
	ds_read_b128 v[156:159], v198
	ds_read_b128 v[160:163], v198 offset:2048
	ds_read_b128 v[164:167], v199 offset:16384
	ds_read_b128 v[168:171], v199 offset:18432
	ds_read_b128 v[172:175], v198 offset:4096
	ds_read_b128 v[176:179], v198 offset:6144
	ds_read_b128 v[180:183], v199 offset:20480
	ds_read_b128 v[184:187], v199 offset:22528
	s_waitcnt lgkmcnt(8)
	v_mfma_f32_16x16x32_bf16 v[64:67], v[106:109], v[132:135], v[64:67]
	v_mfma_f32_16x16x32_bf16 v[60:63], v[106:109], v[136:139], v[60:63]
	v_mfma_f32_16x16x32_bf16 v[52:55], v[106:109], v[148:151], v[52:55]
	v_mfma_f32_16x16x32_bf16 v[48:51], v[106:109], v[152:155], v[48:51]
	v_mfma_f32_16x16x32_bf16 v[44:47], v[110:113], v[132:135], v[44:47]
	v_mfma_f32_16x16x32_bf16 v[40:43], v[110:113], v[136:139], v[40:43]
	v_mfma_f32_16x16x32_bf16 v[36:39], v[110:113], v[148:151], v[36:39]
	v_mfma_f32_16x16x32_bf16 v[32:35], v[110:113], v[152:155], v[32:35]
	v_mfma_f32_16x16x32_bf16 v[28:31], v[140:143], v[132:135], v[28:31]
	v_mfma_f32_16x16x32_bf16 v[24:27], v[140:143], v[136:139], v[24:27]
	v_mfma_f32_16x16x32_bf16 v[20:23], v[140:143], v[148:151], v[20:23]
	v_mfma_f32_16x16x32_bf16 v[16:19], v[140:143], v[152:155], v[16:19]
	v_mfma_f32_16x16x32_bf16 v[12:15], v[144:147], v[132:135], v[12:15]
	v_mfma_f32_16x16x32_bf16 v[8:11], v[144:147], v[136:139], v[8:11]
	v_mfma_f32_16x16x32_bf16 v[4:7], v[144:147], v[148:151], v[4:7]
	v_mfma_f32_16x16x32_bf16 v[56:59], v[144:147], v[152:155], v[56:59]
	v_xor_b32_e32 v196, 0x8000, v196
	v_xor_b32_e32 v197, 0x8000, v197
	v_xor_b32_e32 v198, 0x8000, v198
	v_xor_b32_e32 v199, 0x8000, v199
	s_waitcnt vmcnt(0) lgkmcnt(0)
	s_barrier
.Lkp_b748_loop:
	s_add_u32 s36, s36, 0x80
	s_addc_u32 s37, s37, 0
	s_cmpk_eq_i32 s36, 0x780
	s_cbranch_scc1 .Lkp_b748_last
	v_mfma_f32_16x16x32_bf16 v[64:67], v[156:159], v[164:167], v[64:67]
	s_add_u32 m0, s101, 0x0
	v_lshl_add_u64 v[200:201], v[68:69], 0, s[36:37]
	global_load_lds_dwordx4 v[200:201], off
	v_mfma_f32_16x16x32_bf16 v[60:63], v[156:159], v[168:171], v[60:63]
	s_add_u32 m0, s101, 0x4000
	v_lshl_add_u64 v[200:201], v[70:71], 0, s[36:37]
	global_load_lds_dwordx4 v[200:201], off
	v_mfma_f32_16x16x32_bf16 v[52:55], v[156:159], v[180:183], v[52:55]
	s_add_u32 m0, s101, 0x1000
	v_lshl_add_u64 v[200:201], v[72:73], 0, s[36:37]
	global_load_lds_dwordx4 v[200:201], off
	v_mfma_f32_16x16x32_bf16 v[48:51], v[156:159], v[184:187], v[48:51]
	s_add_u32 m0, s101, 0x5000
	v_lshl_add_u64 v[200:201], v[74:75], 0, s[36:37]
	global_load_lds_dwordx4 v[200:201], off
	v_mfma_f32_16x16x32_bf16 v[44:47], v[160:163], v[164:167], v[44:47]
	s_add_u32 m0, s101, 0x2000
	v_lshl_add_u64 v[200:201], v[76:77], 0, s[36:37]
	global_load_lds_dwordx4 v[200:201], off
	ds_read_b128 v[106:109], v196
	v_mfma_f32_16x16x32_bf16 v[40:43], v[160:163], v[168:171], v[40:43]
	s_add_u32 m0, s101, 0x6000
	v_lshl_add_u64 v[200:201], v[78:79], 0, s[36:37]
	global_load_lds_dwordx4 v[200:201], off
	ds_read_b128 v[110:113], v196 offset:2048
	v_mfma_f32_16x16x32_bf16 v[36:39], v[160:163], v[180:183], v[36:39]
	s_add_u32 m0, s101, 0x3000
	v_lshl_add_u64 v[200:201], v[80:81], 0, s[36:37]
	global_load_lds_dwordx4 v[200:201], off
	ds_read_b128 v[132:135], v197 offset:16384
	v_mfma_f32_16x16x32_bf16 v[32:35], v[160:163], v[184:187], v[32:35]
	s_add_u32 m0, s101, 0x7000
	v_lshl_add_u64 v[200:201], v[82:83], 0, s[36:37]
	global_load_lds_dwordx4 v[200:201], off
	ds_read_b128 v[136:139], v197 offset:18432
	v_mfma_f32_16x16x32_bf16 v[28:31], v[172:175], v[164:167], v[28:31]
	ds_read_b128 v[140:143], v196 offset:4096
	v_mfma_f32_16x16x32_bf16 v[24:27], v[172:175], v[168:171], v[24:27]
	ds_read_b128 v[144:147], v196 offset:6144
	v_mfma_f32_16x16x32_bf16 v[20:23], v[172:175], v[180:183], v[20:23]
	ds_read_b128 v[148:151], v197 offset:20480
	v_mfma_f32_16x16x32_bf16 v[16:19], v[172:175], v[184:187], v[16:19]
	ds_read_b128 v[152:155], v197 offset:22528
	v_mfma_f32_16x16x32_bf16 v[12:15], v[176:179], v[164:167], v[12:15]
	v_mfma_f32_16x16x32_bf16 v[8:11], v[176:179], v[168:171], v[8:11]
	v_mfma_f32_16x16x32_bf16 v[4:7], v[176:179], v[180:183], v[4:7]
	v_mfma_f32_16x16x32_bf16 v[56:59], v[176:179], v[184:187], v[56:59]
	s_xor_b32 s101, s101, 0x8000
	s_waitcnt lgkmcnt(0)
; DEVINL f32x4 mfma16(bf16x8 a, bf16x8 b, f32x4 c) { return __builtin_amdgcn_mfma_f32_16x16x32_bf16(a, b, c, 0, 0, 0); }
; DEVINL void gemm_loop(f32x4 (&acc)[4][4], const u16* __restrict__ A, int lda, const u16* __restrict__ Bt, int ldb,
;                       int m0, int n0, int k0, int nk, char* smem) {
;     ...
;   for (int kt = 0; kt < nk; ++kt) {
;     __syncthreads();
;     char* cur = smem + (kt & 1) * 32768;
;     if (kt + 1 < nk) {
;       char* nxt = smem + ((kt + 1) & 1) * 32768;
; #pragma unroll
;       for (int i = 0; i < 4; ++i) {
;         glds16(ga[i] + (kt + 1) * 64, nxt + i * 4096 + wid * 1024);
;         glds16(gb[i] + (kt + 1) * 64, nxt + 16384 + i * 4096 + wid * 1024);
;       }
;     }
;     bf16x8 af[2][4], bfr[2][4];
; #pragma unroll
;     for (int ks = 0; ks < 2; ++ks)
; #pragma unroll
;       for (int f = 0; f < 4; ++f) {
;         int ra = wr * 64 + f * 16 + fr, rb = wc * 64 + f * 16 + fr;
;         int ch = ks * 4 + fq;
;         af[ks][f] = *(const bf16x8*)(cur + ra * 128 + ((ch ^ ((ra >> 1) & 7)) << 4));
;         bfr[ks][f] = *(const bf16x8*)(cur + 16384 + rb * 128 + ((ch ^ ((rb >> 1) & 7)) << 4));
;       }
;     __builtin_amdgcn_sched_barrier(0);
; #pragma unroll
;     for (int ks = 0; ks < 2; ++ks)
; #pragma unroll
;       for (int mf = 0; mf < 4; ++mf)
; #pragma unroll
;         for (int nf = 0; nf < 4; ++nf) acc[mf][nf] = mfma16(af[ks][mf], bfr[ks][nf], acc[mf][nf]);
;   }
	v_mfma_f32_16x16x32_bf16 v[64:67], v[106:109], v[132:135], v[64:67]
	ds_read_b128 v[156:159], v198
	v_mfma_f32_16x16x32_bf16 v[60:63], v[106:109], v[136:139], v[60:63]
	ds_read_b128 v[160:163], v198 offset:2048
	v_mfma_f32_16x16x32_bf16 v[52:55], v[106:109], v[148:151], v[52:55]
	ds_read_b128 v[164:167], v199 offset:16384
	v_mfma_f32_16x16x32_bf16 v[48:51], v[106:109], v[152:155], v[48:51]
	ds_read_b128 v[168:171], v199 offset:18432
	v_mfma_f32_16x16x32_bf16 v[44:47], v[110:113], v[132:135], v[44:47]
	ds_read_b128 v[172:175], v198 offset:4096
	v_mfma_f32_16x16x32_bf16 v[40:43], v[110:113], v[136:139], v[40:43]
	ds_read_b128 v[176:179], v198 offset:6144
	v_mfma_f32_16x16x32_bf16 v[36:39], v[110:113], v[148:151], v[36:39]
	ds_read_b128 v[180:183], v199 offset:20480
	v_mfma_f32_16x16x32_bf16 v[32:35], v[110:113], v[152:155], v[32:35]
	ds_read_b128 v[184:187], v199 offset:22528
	v_mfma_f32_16x16x32_bf16 v[28:31], v[140:143], v[132:135], v[28:31]
	v_mfma_f32_16x16x32_bf16 v[24:27], v[140:143], v[136:139], v[24:27]
	v_mfma_f32_16x16x32_bf16 v[20:23], v[140:143], v[148:151], v[20:23]
	v_mfma_f32_16x16x32_bf16 v[16:19], v[140:143], v[152:155], v[16:19]
	v_mfma_f32_16x16x32_bf16 v[12:15], v[144:147], v[132:135], v[12:15]
	v_mfma_f32_16x16x32_bf16 v[8:11], v[144:147], v[136:139], v[8:11]
	v_mfma_f32_16x16x32_bf16 v[4:7], v[144:147], v[148:151], v[4:7]
	v_mfma_f32_16x16x32_bf16 v[56:59], v[144:147], v[152:155], v[56:59]
	v_xor_b32_e32 v196, 0x8000, v196
	v_xor_b32_e32 v197, 0x8000, v197
	v_xor_b32_e32 v198, 0x8000, v198
	v_xor_b32_e32 v199, 0x8000, v199
	s_waitcnt vmcnt(0) lgkmcnt(0)
	s_barrier
	s_branch .Lkp_b748_loop
.Lkp_b748_last:
	v_mfma_f32_16x16x32_bf16 v[64:67], v[156:159], v[164:167], v[64:67]
	v_mfma_f32_16x16x32_bf16 v[60:63], v[156:159], v[168:171], v[60:63]
	v_mfma_f32_16x16x32_bf16 v[52:55], v[156:159], v[180:183], v[52:55]
	v_mfma_f32_16x16x32_bf16 v[48:51], v[156:159], v[184:187], v[48:51]
	v_mfma_f32_16x16x32_bf16 v[44:47], v[160:163], v[164:167], v[44:47]
	v_mfma_f32_16x16x32_bf16 v[40:43], v[160:163], v[168:171], v[40:43]
	v_mfma_f32_16x16x32_bf16 v[36:39], v[160:163], v[180:183], v[36:39]
	v_mfma_f32_16x16x32_bf16 v[32:35], v[160:163], v[184:187], v[32:35]
	v_mfma_f32_16x16x32_bf16 v[28:31], v[172:175], v[164:167], v[28:31]
	v_mfma_f32_16x16x32_bf16 v[24:27], v[172:175], v[168:171], v[24:27]
	v_mfma_f32_16x16x32_bf16 v[20:23], v[172:175], v[180:183], v[20:23]
	v_mfma_f32_16x16x32_bf16 v[16:19], v[172:175], v[184:187], v[16:19]
	v_mfma_f32_16x16x32_bf16 v[12:15], v[176:179], v[164:167], v[12:15]
	v_mfma_f32_16x16x32_bf16 v[8:11], v[176:179], v[168:171], v[8:11]
	v_mfma_f32_16x16x32_bf16 v[4:7], v[176:179], v[180:183], v[4:7]
	v_mfma_f32_16x16x32_bf16 v[56:59], v[176:179], v[184:187], v[56:59]
	s_mov_b32 s1, 0x8000
	v_add_u32_e32 v68, s1, v90
	v_add_u32_e32 v86, v68, v87
	s_waitcnt vmcnt(0)
	s_barrier
; DEVINL f32x4 mfma16(bf16x8 a, bf16x8 b, f32x4 c) { return __builtin_amdgcn_mfma_f32_16x16x32_bf16(a, b, c, 0, 0, 0); }
; DEVINL int ridx(int r) { return ((r >> 4) << 5) | (r & 15); }
; DEVINL void gemm_loop(f32x4 (&acc)[4][4], const u16* __restrict__ A, int lda, const u16* __restrict__ Bt, int ldb,
;                       int m0, int n0, int k0, int nk, char* smem) {
;     ...
;         af[ks][f] = *(const bf16x8*)(cur + ra * 128 + ((ch ^ ((ra >> 1) & 7)) << 4));
;         bfr[ks][f] = *(const bf16x8*)(cur + 16384 + rb * 128 + ((ch ^ ((rb >> 1) & 7)) << 4));
;       }
;     __builtin_amdgcn_sched_barrier(0);
; #pragma unroll
;     for (int ks = 0; ks < 2; ++ks)
; #pragma unroll
;       for (int mf = 0; mf < 4; ++mf)
; #pragma unroll
;         for (int nf = 0; nf < 4; ++nf) acc[mf][nf] = mfma16(af[ks][mf], bfr[ks][nf], acc[mf][nf]);
; DEVINL void p1_tile(const Params& p, char* smem, int mt, int nt) {
;     ...
; #pragma unroll
;   for (int mf = 0; mf < 4; ++mf) {
;     const int rb = m0 + wr * 64 + mf * 16 + (lane >> 4) * 4;
;     float rs[4];
; #pragma unroll
;     for (int j = 0; j < 4; ++j) rs[j] = rstd0[ridx(rb) + j];
; #pragma unroll
;     for (int nf = 0; nf < 4; ++nf) {
;       const int col = n0 + wc * 64 + nf * 16 + (lane & 15);
;       float v[4];
; #pragma unroll
;       for (int j = 0; j < 4; ++j) v[j] = acc[mf][nf][j] * rs[j];
;       if (nt < 4) {
;         store_pairs(qk, 512, rb, col, v[0], v[1], v[2], v[3]);
;         if (nt >= 2) *(uint2*)(kT + (size_t)(col - 256) * LDT + rb) = make_uint2(pack2(v[0], v[1]), pack2(v[2], v[3]));
;       } else if (nt < 8) {
;         *(uint2*)(vT + (size_t)(col - 512) * LDT + rb) = make_uint2(pack2(v[0], v[1]), pack2(v[2], v[3]));
;       } else if (nt < 12) {
;         store_pairs(gb, 512, rb, col - 1024, v[0], v[1], v[2], v[3]);
;       } else if (nt < 16) {
;         store_pairs(ub, 512, rb, col - 1536, v[0], v[1], v[2], v[3]);
;       } else if (col < 2064) {
; #pragma unroll
;         for (int j = 0; j < 4; ++j) gk[(size_t)(rb + j) * 16 + (col - 2048)] = v[j];
;       }
	v_add_u32_e32 v90, v68, v88
	ds_read_b128 v[68:71], v86
	ds_read_b128 v[72:75], v86 offset:2048
	ds_read_b128 v[76:79], v90 offset:16384
	ds_read_b128 v[80:83], v90 offset:18432
	ds_read_b128 v[106:109], v86 offset:4096
	ds_read_b128 v[110:113], v86 offset:6144
	ds_read_b128 v[132:135], v90 offset:20480
	ds_read_b128 v[136:139], v90 offset:22528
	v_add_u32_e32 v86, s1, v89
	v_add_u32_e32 v90, v86, v87
	v_add_u32_e32 v91, v86, v88
	ds_read_b128 v[86:89], v90
	ds_read_b128 v[140:143], v90 offset:2048
	ds_read_b128 v[144:147], v91 offset:16384
	ds_read_b128 v[148:151], v91 offset:18432
	ds_read_b128 v[152:155], v90 offset:4096
	ds_read_b128 v[156:159], v90 offset:6144
	ds_read_b128 v[160:163], v91 offset:20480
	ds_read_b128 v[164:167], v91 offset:22528
	s_waitcnt lgkmcnt(13)
	v_mfma_f32_16x16x32_bf16 v[64:67], v[68:71], v[76:79], v[64:67]
	v_readlane_b32 s0, v194, 59
	v_readlane_b32 s1, v194, 60
	v_cmp_lt_i32_e64 s[46:47], 3, v3
	s_waitcnt lgkmcnt(12)
	v_mfma_f32_16x16x32_bf16 v[60:63], v[68:71], v[80:83], v[60:63]
	v_cmp_lt_u32_e64 s[44:45], 7, v3
	v_cmp_lt_u32_e64 s[42:43], 11, v3
	v_cmp_lt_u32_e64 s[40:41], 15, v3
	s_waitcnt lgkmcnt(9)
	v_mfma_f32_16x16x32_bf16 v[52:55], v[68:71], v[132:135], v[52:55]
	v_cmp_lt_i32_e64 s[36:37], 1, v3
	s_waitcnt lgkmcnt(8)
	v_mfma_f32_16x16x32_bf16 v[48:51], v[68:71], v[136:139], v[48:51]
	v_mov_b32_e32 v69, v0
	v_mov_b32_e32 v68, v0
	v_mfma_f32_16x16x32_bf16 v[44:47], v[72:75], v[76:79], v[44:47]
	v_and_b32_e32 v70, 15, v69
	v_mfma_f32_16x16x32_bf16 v[40:43], v[72:75], v[80:83], v[40:43]
	v_mfma_f32_16x16x32_bf16 v[28:31], v[106:109], v[76:79], v[28:31]
	v_mfma_f32_16x16x32_bf16 v[24:27], v[106:109], v[80:83], v[24:27]
	v_mfma_f32_16x16x32_bf16 v[20:23], v[106:109], v[132:135], v[20:23]
	v_mfma_f32_16x16x32_bf16 v[16:19], v[106:109], v[136:139], v[16:19]
	v_mfma_f32_16x16x32_bf16 v[12:15], v[110:113], v[76:79], v[12:15]
	v_mfma_f32_16x16x32_bf16 v[8:11], v[110:113], v[80:83], v[8:11]
	v_mfma_f32_16x16x32_bf16 v[4:7], v[110:113], v[132:135], v[4:7]
	v_mfma_f32_16x16x32_bf16 v[106:109], v[110:113], v[136:139], v[56:59]
	s_waitcnt lgkmcnt(5)
	v_mfma_f32_16x16x32_bf16 v[110:113], v[86:89], v[144:147], v[64:67]
	s_waitcnt lgkmcnt(4)
	v_mfma_f32_16x16x32_bf16 v[64:67], v[86:89], v[148:151], v[60:63]
	s_waitcnt lgkmcnt(1)
	v_mfma_f32_16x16x32_bf16 v[60:63], v[86:89], v[160:163], v[52:55]
	s_waitcnt lgkmcnt(0)
	v_mfma_f32_16x16x32_bf16 v[52:55], v[86:89], v[164:167], v[48:51]
	s_nop 2
	v_ashrrev_i32_e32 v48, 1, v68
	v_and_b32_e32 v56, 0xffffffc0, v48
	v_mfma_f32_16x16x32_bf16 v[48:51], v[140:143], v[144:147], v[44:47]
	v_add_u32_e32 v91, v56, v85
	v_and_b32_e32 v68, 64, v68
	v_or3_b32 v68, v70, v68, v84
	v_lshrrev_b32_e32 v44, 2, v69
	v_and_b32_e32 v90, 12, v44
	v_mfma_f32_16x16x32_bf16 v[44:47], v[140:143], v[148:151], v[40:43]
	v_and_b32_e32 v69, 1, v69
	v_lshlrev_b32_e32 v102, 1, v69
	v_cmp_eq_u32_e64 s[38:39], 0, v69
	v_lshl_or_b32 v40, v91, 1, v90
	v_ashrrev_i32_e32 v41, 31, v40
	v_lshl_add_u64 v[56:57], v[40:41], 2, s[0:1]
	global_load_dwordx4 v[56:59], v[56:57], off
	v_mfma_f32_16x16x32_bf16 v[36:39], v[72:75], v[132:135], v[36:39]
	s_waitcnt vmcnt(0)
	v_mul_f32_e32 v105, v110, v56
	v_mfma_f32_16x16x32_bf16 v[32:35], v[72:75], v[136:139], v[32:35]
	v_or_b32_e32 v72, v91, v90
	v_or_b32_e32 v76, v72, v102
	v_ashrrev_i32_e32 v77, 31, v76
	v_mfma_f32_16x16x32_bf16 v[40:43], v[140:143], v[160:163], v[36:39]
	v_lshlrev_b64 v[70:71], 10, v[76:77]
	v_or_b32_e32 v76, 1, v76
	v_ashrrev_i32_e32 v77, 31, v76
	v_mfma_f32_16x16x32_bf16 v[36:39], v[140:143], v[164:167], v[32:35]
	v_lshlrev_b64 v[82:83], 10, v[76:77]
	v_lshl_add_u64 v[74:75], s[96:97], 0, v[70:71]
	v_lshl_add_u64 v[76:77], s[96:97], 0, v[82:83]
	v_mfma_f32_16x16x32_bf16 v[32:35], v[152:155], v[144:147], v[28:31]
	v_lshl_add_u64 v[78:79], s[92:93], 0, v[70:71]
	v_lshl_add_u64 v[80:81], s[92:93], 0, v[82:83]
	v_ashrrev_i32_e32 v73, 31, v72
	v_mfma_f32_16x16x32_bf16 v[28:31], v[152:155], v[148:151], v[24:27]
	v_mul_f32_e32 v89, v111, v57
	v_mul_f32_e32 v88, v112, v58
	v_mul_f32_e32 v3, v113, v59
	v_mfma_f32_16x16x32_bf16 v[24:27], v[152:155], v[160:163], v[20:23]
	v_mfma_f32_16x16x32_bf16 v[20:23], v[152:155], v[164:167], v[16:19]
	v_mfma_f32_16x16x32_bf16 v[16:19], v[156:159], v[144:147], v[12:15]
	v_mfma_f32_16x16x32_bf16 v[12:15], v[156:159], v[148:151], v[8:11]
	v_mfma_f32_16x16x32_bf16 v[8:11], v[156:159], v[160:163], v[4:7]
	v_mfma_f32_16x16x32_bf16 v[4:7], v[156:159], v[164:167], v[106:109]
	s_and_saveexec_b64 s[0:1], s[46:47]
	s_xor_b64 s[66:67], exec, s[0:1]
	s_cbranch_execz .LBB0_765
	s_and_saveexec_b64 s[0:1], s[44:45]
	s_xor_b64 s[90:91], exec, s[0:1]
	s_cbranch_execz .LBB0_762
	s_and_saveexec_b64 s[0:1], s[42:43]
	s_xor_b64 s[86:87], exec, s[0:1]
	s_cbranch_execz .LBB0_759
	s_and_saveexec_b64 s[0:1], s[40:41]
	s_xor_b64 s[88:89], exec, s[0:1]
	s_cbranch_execz .LBB0_756
	s_movk_i32 s0, 0x810
	v_cmp_gt_i32_e32 vcc, s0, v68
	s_and_saveexec_b64 s[0:1], vcc
	s_cbranch_execz .LBB0_755
	v_mov_b32_e32 v69, v2
	v_lshl_add_u64 v[84:85], v[68:69], 2, s[50:51]
	v_lshlrev_b64 v[86:87], 6, v[72:73]
	v_lshl_add_u64 v[86:87], v[84:85], 0, v[86:87]
	v_add_co_u32_e32 v86, vcc, 0x1921000, v86
	s_nop 1
	v_addc_co_u32_e32 v87, vcc, 0, v87, vcc
	global_store_dword v[86:87], v105, off offset:2560
	v_or_b32_e32 v86, 1, v72
	v_ashrrev_i32_e32 v87, 31, v86
	v_lshlrev_b64 v[86:87], 6, v[86:87]
	v_lshl_add_u64 v[86:87], v[84:85], 0, v[86:87]
	v_add_co_u32_e32 v86, vcc, 0x1921000, v86
	s_nop 1
	v_addc_co_u32_e32 v87, vcc, 0, v87, vcc
	global_store_dword v[86:87], v89, off offset:2560
	v_or_b32_e32 v86, 2, v72
	v_ashrrev_i32_e32 v87, 31, v86
	v_lshlrev_b64 v[86:87], 6, v[86:87]
	v_lshl_add_u64 v[86:87], v[84:85], 0, v[86:87]
	v_add_co_u32_e32 v86, vcc, 0x1921000, v86
	s_nop 1
	v_addc_co_u32_e32 v87, vcc, 0, v87, vcc
	global_store_dword v[86:87], v88, off offset:2560
	v_or_b32_e32 v86, 3, v72
	v_ashrrev_i32_e32 v87, 31, v86
	v_lshlrev_b64 v[86:87], 6, v[86:87]
	v_lshl_add_u64 v[84:85], v[84:85], 0, v[86:87]
	v_add_co_u32_e32 v84, vcc, 0x1921000, v84
	s_nop 1
	v_addc_co_u32_e32 v85, vcc, 0, v85, vcc
	global_store_dword v[84:85], v3, off offset:2560

; DEVINL f32x4 mfma16(bf16x8 a, bf16x8 b, f32x4 c) { return __builtin_amdgcn_mfma_f32_16x16x32_bf16(a, b, c, 0, 0, 0); }
; DEVINL void gemm_loop(f32x4 (&acc)[4][4], const u16* __restrict__ A, int lda, const u16* __restrict__ Bt, int ldb,
;                       int m0, int n0, int k0, int nk, char* smem) {
;     ...
;   for (int kt = 0; kt < nk; ++kt) {
;     __syncthreads();
;     char* cur = smem + (kt & 1) * 32768;
;     if (kt + 1 < nk) {
;       char* nxt = smem + ((kt + 1) & 1) * 32768;
; #pragma unroll
;       for (int i = 0; i < 4; ++i) {
;         glds16(ga[i] + (kt + 1) * 64, nxt + i * 4096 + wid * 1024);
;         glds16(gb[i] + (kt + 1) * 64, nxt + 16384 + i * 4096 + wid * 1024);
;       }
;     }
;     bf16x8 af[2][4], bfr[2][4];
; #pragma unroll
;     for (int ks = 0; ks < 2; ++ks)
; #pragma unroll
;       for (int f = 0; f < 4; ++f) {
;         int ra = wr * 64 + f * 16 + fr, rb = wc * 64 + f * 16 + fr;
;         int ch = ks * 4 + fq;
;         af[ks][f] = *(const bf16x8*)(cur + ra * 128 + ((ch ^ ((ra >> 1) & 7)) << 4));
;         bfr[ks][f] = *(const bf16x8*)(cur + 16384 + rb * 128 + ((ch ^ ((rb >> 1) & 7)) << 4));
;       }
;     __builtin_amdgcn_sched_barrier(0);
; #pragma unroll
;     for (int ks = 0; ks < 2; ++ks)
; #pragma unroll
;       for (int mf = 0; mf < 4; ++mf)
; #pragma unroll
;         for (int nf = 0; nf < 4; ++nf) acc[mf][nf] = mfma16(af[ks][mf], bfr[ks][nf], acc[mf][nf]);
.LBB0_1075:
	v_readfirstlane_b32 s100, v87
	v_add_u32_e32 v196, v91, v88
	v_add_u32_e32 v197, v91, v89
	v_add_u32_e32 v198, v90, v88
	v_add_u32_e32 v199, v90, v89
	s_mov_b32 s101, s100
	v_lshlrev_b32_e32 v202, 4, v0
	s_waitcnt vmcnt(0)
	s_barrier
	s_add_u32 m0, s100, 0x8000
	v_lshl_add_u64 v[200:201], v[68:69], 0, s[36:37]
	global_load_lds_dwordx4 v[200:201], off
	s_add_u32 m0, s100, 0xc000
	v_lshl_add_u64 v[200:201], v[70:71], 0, s[36:37]
	global_load_lds_dwordx4 v[200:201], off
	s_add_u32 m0, s100, 0x9000
	v_lshl_add_u64 v[200:201], v[72:73], 0, s[36:37]
	global_load_lds_dwordx4 v[200:201], off
	s_add_u32 m0, s100, 0xd000
	v_lshl_add_u64 v[200:201], v[74:75], 0, s[36:37]
	global_load_lds_dwordx4 v[200:201], off
	s_add_u32 m0, s100, 0xa000
	v_lshl_add_u64 v[200:201], v[76:77], 0, s[36:37]
	global_load_lds_dwordx4 v[200:201], off
	s_add_u32 m0, s100, 0xe000
	v_lshl_add_u64 v[200:201], v[78:79], 0, s[36:37]
	global_load_lds_dwordx4 v[200:201], off
	s_add_u32 m0, s100, 0xb000
	v_lshl_add_u64 v[200:201], v[80:81], 0, s[36:37]
	global_load_lds_dwordx4 v[200:201], off
	s_add_u32 m0, s100, 0xf000
	v_lshl_add_u64 v[200:201], v[82:83], 0, s[36:37]
	global_load_lds_dwordx4 v[200:201], off
	ds_read_b128 v[106:109], v196
	ds_read_b128 v[110:113], v196 offset:2048
	ds_read_b128 v[132:135], v197 offset:16384
	ds_read_b128 v[136:139], v197 offset:18432
	ds_read_b128 v[140:143], v196 offset:4096
	ds_read_b128 v[144:147], v196 offset:6144
	ds_read_b128 v[148:151], v197 offset:20480
	ds_read_b128 v[152:155], v197 offset:22528
	ds_read_b128 v[156:159], v198
	ds_read_b128 v[160:163], v198 offset:2048
	ds_read_b128 v[164:167], v199 offset:16384
	ds_read_b128 v[168:171], v199 offset:18432
	ds_read_b128 v[172:175], v198 offset:4096
	ds_read_b128 v[176:179], v198 offset:6144
	ds_read_b128 v[180:183], v199 offset:20480
	ds_read_b128 v[184:187], v199 offset:22528
	s_waitcnt lgkmcnt(8)
	v_mfma_f32_16x16x32_bf16 v[64:67], v[106:109], v[132:135], v[64:67]
	v_mfma_f32_16x16x32_bf16 v[60:63], v[106:109], v[136:139], v[60:63]
	v_mfma_f32_16x16x32_bf16 v[52:55], v[106:109], v[148:151], v[52:55]
	v_mfma_f32_16x16x32_bf16 v[48:51], v[106:109], v[152:155], v[48:51]
	v_mfma_f32_16x16x32_bf16 v[44:47], v[110:113], v[132:135], v[44:47]
	v_mfma_f32_16x16x32_bf16 v[40:43], v[110:113], v[136:139], v[40:43]
	v_mfma_f32_16x16x32_bf16 v[36:39], v[110:113], v[148:151], v[36:39]
	v_mfma_f32_16x16x32_bf16 v[32:35], v[110:113], v[152:155], v[32:35]
	v_mfma_f32_16x16x32_bf16 v[28:31], v[140:143], v[132:135], v[28:31]
	v_mfma_f32_16x16x32_bf16 v[24:27], v[140:143], v[136:139], v[24:27]
	v_mfma_f32_16x16x32_bf16 v[20:23], v[140:143], v[148:151], v[20:23]
	v_mfma_f32_16x16x32_bf16 v[16:19], v[140:143], v[152:155], v[16:19]
	v_mfma_f32_16x16x32_bf16 v[12:15], v[144:147], v[132:135], v[12:15]
	v_mfma_f32_16x16x32_bf16 v[8:11], v[144:147], v[136:139], v[8:11]
	v_mfma_f32_16x16x32_bf16 v[4:7], v[144:147], v[148:151], v[4:7]
	v_mfma_f32_16x16x32_bf16 v[56:59], v[144:147], v[152:155], v[56:59]
	v_xor_b32_e32 v196, 0x8000, v196
	v_xor_b32_e32 v197, 0x8000, v197
	v_xor_b32_e32 v198, 0x8000, v198
	v_xor_b32_e32 v199, 0x8000, v199
	s_waitcnt vmcnt(0) lgkmcnt(0)
	s_barrier

; DEVINL f32x4 mfma16(bf16x8 a, bf16x8 b, f32x4 c) { return __builtin_amdgcn_mfma_f32_16x16x32_bf16(a, b, c, 0, 0, 0); }
; DEVINL int ridx(int r) { return ((r >> 4) << 5) | (r & 15); }
; DEVINL void gemm_loop(f32x4 (&acc)[4][4], const u16* __restrict__ A, int lda, const u16* __restrict__ Bt, int ldb,
;                       int m0, int n0, int k0, int nk, char* smem) {
;     ...
;     for (int ks = 0; ks < 2; ++ks)
; #pragma unroll
;       for (int f = 0; f < 4; ++f) {
;         int ra = wr * 64 + f * 16 + fr, rb = wc * 64 + f * 16 + fr;
;         int ch = ks * 4 + fq;
;         af[ks][f] = *(const bf16x8*)(cur + ra * 128 + ((ch ^ ((ra >> 1) & 7)) << 4));
;         bfr[ks][f] = *(const bf16x8*)(cur + 16384 + rb * 128 + ((ch ^ ((rb >> 1) & 7)) << 4));
;       }
;     __builtin_amdgcn_sched_barrier(0);
; #pragma unroll
;     for (int ks = 0; ks < 2; ++ks)
; #pragma unroll
;       for (int mf = 0; mf < 4; ++mf)
; #pragma unroll
;         for (int nf = 0; nf < 4; ++nf) acc[mf][nf] = mfma16(af[ks][mf], bfr[ks][nf], acc[mf][nf]);
; DEVINL void p1_tile(const Params& p, char* smem, int mt, int nt) {
;     ...
; #pragma unroll
;   for (int mf = 0; mf < 4; ++mf) {
;     const int rb = m0 + wr * 64 + mf * 16 + (lane >> 4) * 4;
;     float rs[4];
; #pragma unroll
;     for (int j = 0; j < 4; ++j) rs[j] = rstd0[ridx(rb) + j];
; #pragma unroll
;     for (int nf = 0; nf < 4; ++nf) {
;       const int col = n0 + wc * 64 + nf * 16 + (lane & 15);
;       float v[4];
; #pragma unroll
;       for (int j = 0; j < 4; ++j) v[j] = acc[mf][nf][j] * rs[j];
;       if (nt < 4) {
;         store_pairs(qk, 512, rb, col, v[0], v[1], v[2], v[3]);
;         if (nt >= 2) *(uint2*)(kT + (size_t)(col - 256) * LDT + rb) = make_uint2(pack2(v[0], v[1]), pack2(v[2], v[3]));
;       } else if (nt < 8) {
;         *(uint2*)(vT + (size_t)(col - 512) * LDT + rb) = make_uint2(pack2(v[0], v[1]), pack2(v[2], v[3]));
;       } else if (nt < 12) {
;         store_pairs(gb, 512, rb, col - 1024, v[0], v[1], v[2], v[3]);
;       } else if (nt < 16) {
;         store_pairs(ub, 512, rb, col - 1536, v[0], v[1], v[2], v[3]);
;       } else if (col < 2064) {
; #pragma unroll
;         for (int j = 0; j < 4; ++j) gk[(size_t)(rb + j) * 16 + (col - 2048)] = v[j];
;       }
.Lkp_b1075_last:
	v_mfma_f32_16x16x32_bf16 v[64:67], v[156:159], v[164:167], v[64:67]
	v_mfma_f32_16x16x32_bf16 v[60:63], v[156:159], v[168:171], v[60:63]
	v_mfma_f32_16x16x32_bf16 v[52:55], v[156:159], v[180:183], v[52:55]
	v_mfma_f32_16x16x32_bf16 v[48:51], v[156:159], v[184:187], v[48:51]
	v_mfma_f32_16x16x32_bf16 v[44:47], v[160:163], v[164:167], v[44:47]
	v_mfma_f32_16x16x32_bf16 v[40:43], v[160:163], v[168:171], v[40:43]
	v_mfma_f32_16x16x32_bf16 v[36:39], v[160:163], v[180:183], v[36:39]
	v_mfma_f32_16x16x32_bf16 v[32:35], v[160:163], v[184:187], v[32:35]
	v_mfma_f32_16x16x32_bf16 v[28:31], v[172:175], v[164:167], v[28:31]
	v_mfma_f32_16x16x32_bf16 v[24:27], v[172:175], v[168:171], v[24:27]
	v_mfma_f32_16x16x32_bf16 v[20:23], v[172:175], v[180:183], v[20:23]
	v_mfma_f32_16x16x32_bf16 v[16:19], v[172:175], v[184:187], v[16:19]
	v_mfma_f32_16x16x32_bf16 v[12:15], v[176:179], v[164:167], v[12:15]
	v_mfma_f32_16x16x32_bf16 v[8:11], v[176:179], v[168:171], v[8:11]
	v_mfma_f32_16x16x32_bf16 v[4:7], v[176:179], v[180:183], v[4:7]
	v_mfma_f32_16x16x32_bf16 v[56:59], v[176:179], v[184:187], v[56:59]
	s_mov_b32 s1, 0x8000
	v_add_u32_e32 v68, s1, v91
	v_add_u32_e32 v87, v68, v88
	s_waitcnt vmcnt(0)
	s_barrier
	v_add_u32_e32 v91, v68, v89
	ds_read_b128 v[68:71], v87
	ds_read_b128 v[72:75], v87 offset:2048
	ds_read_b128 v[76:79], v91 offset:16384
	ds_read_b128 v[80:83], v91 offset:18432
	ds_read_b128 v[106:109], v87 offset:4096
	ds_read_b128 v[110:113], v87 offset:6144
	ds_read_b128 v[132:135], v91 offset:20480
	ds_read_b128 v[136:139], v91 offset:22528
	v_add_u32_e32 v87, s1, v90
	v_add_u32_e32 v102, v87, v88
	v_add_u32_e32 v87, v87, v89
	ds_read_b128 v[88:91], v102
	ds_read_b128 v[140:143], v102 offset:2048
	ds_read_b128 v[144:147], v87 offset:16384
	ds_read_b128 v[148:151], v87 offset:18432
	ds_read_b128 v[152:155], v102 offset:4096
	ds_read_b128 v[156:159], v102 offset:6144
	ds_read_b128 v[160:163], v87 offset:20480
	ds_read_b128 v[164:167], v87 offset:22528
	s_waitcnt lgkmcnt(13)
	v_mfma_f32_16x16x32_bf16 v[64:67], v[68:71], v[76:79], v[64:67]
	v_readlane_b32 s0, v194, 59
	v_readlane_b32 s1, v194, 60
	v_cmp_lt_i32_e64 s[46:47], 3, v84
	s_waitcnt lgkmcnt(12)
	v_mfma_f32_16x16x32_bf16 v[60:63], v[68:71], v[80:83], v[60:63]
	v_cmp_lt_u32_e64 s[44:45], 7, v84
	v_cmp_lt_u32_e64 s[42:43], 11, v84
	v_cmp_lt_u32_e64 s[40:41], 15, v84
	s_waitcnt lgkmcnt(9)
	v_mfma_f32_16x16x32_bf16 v[52:55], v[68:71], v[132:135], v[52:55]
	v_cmp_lt_i32_e64 s[36:37], 1, v84
	s_waitcnt lgkmcnt(8)
	v_mfma_f32_16x16x32_bf16 v[48:51], v[68:71], v[136:139], v[48:51]
	v_mov_b32_e32 v69, v0
	v_mov_b32_e32 v68, v0
	v_mfma_f32_16x16x32_bf16 v[44:47], v[72:75], v[76:79], v[44:47]
	v_and_b32_e32 v70, 15, v69
	v_mfma_f32_16x16x32_bf16 v[40:43], v[72:75], v[80:83], v[40:43]
	v_mfma_f32_16x16x32_bf16 v[36:39], v[72:75], v[132:135], v[36:39]
	v_mfma_f32_16x16x32_bf16 v[20:23], v[106:109], v[132:135], v[20:23]
	v_mfma_f32_16x16x32_bf16 v[4:7], v[110:113], v[132:135], v[4:7]
	s_waitcnt lgkmcnt(5)
	v_mfma_f32_16x16x32_bf16 v[132:135], v[88:91], v[144:147], v[64:67]
	s_waitcnt lgkmcnt(4)
	v_mfma_f32_16x16x32_bf16 v[64:67], v[88:91], v[148:151], v[60:63]
	s_waitcnt lgkmcnt(1)
	v_mfma_f32_16x16x32_bf16 v[60:63], v[88:91], v[160:163], v[52:55]
	s_waitcnt lgkmcnt(0)
	v_mfma_f32_16x16x32_bf16 v[52:55], v[88:91], v[164:167], v[48:51]
	s_nop 2
	v_ashrrev_i32_e32 v48, 1, v68
	v_mfma_f32_16x16x32_bf16 v[28:31], v[106:109], v[76:79], v[28:31]
	v_and_b32_e32 v68, 64, v68
	v_or3_b32 v68, v70, v68, v85
	v_mfma_f32_16x16x32_bf16 v[24:27], v[106:109], v[80:83], v[24:27]
	v_mfma_f32_16x16x32_bf16 v[16:19], v[106:109], v[136:139], v[16:19]
	v_mfma_f32_16x16x32_bf16 v[12:15], v[110:113], v[76:79], v[12:15]
	v_mfma_f32_16x16x32_bf16 v[8:11], v[110:113], v[80:83], v[8:11]
	v_mfma_f32_16x16x32_bf16 v[108:111], v[110:113], v[136:139], v[56:59]
	s_nop 2
	v_and_b32_e32 v56, 0xffffffc0, v48
	v_mfma_f32_16x16x32_bf16 v[48:51], v[140:143], v[144:147], v[44:47]
	v_add_u32_e32 v102, v56, v86
	s_nop 1
	v_lshrrev_b32_e32 v44, 2, v69
	v_and_b32_e32 v91, 12, v44
	v_mfma_f32_16x16x32_bf16 v[44:47], v[140:143], v[148:151], v[40:43]
	v_and_b32_e32 v69, 1, v69
	v_lshlrev_b32_e32 v105, 1, v69
	v_cmp_eq_u32_e64 s[38:39], 0, v69
	v_lshl_or_b32 v40, v102, 1, v91
	v_ashrrev_i32_e32 v41, 31, v40
	v_lshl_add_u64 v[56:57], v[40:41], 2, s[0:1]
	global_load_dwordx4 v[56:59], v[56:57], off
	v_mfma_f32_16x16x32_bf16 v[32:35], v[72:75], v[136:139], v[32:35]
	v_or_b32_e32 v72, v102, v91
	v_or_b32_e32 v76, v72, v105
	v_ashrrev_i32_e32 v77, 31, v76
	v_mfma_f32_16x16x32_bf16 v[40:43], v[140:143], v[160:163], v[36:39]
	v_lshlrev_b64 v[70:71], 10, v[76:77]
	v_or_b32_e32 v76, 1, v76
	v_ashrrev_i32_e32 v77, 31, v76
	v_mfma_f32_16x16x32_bf16 v[36:39], v[140:143], v[164:167], v[32:35]
	v_lshlrev_b64 v[82:83], 10, v[76:77]
	v_lshl_add_u64 v[74:75], s[96:97], 0, v[70:71]
	v_lshl_add_u64 v[76:77], s[96:97], 0, v[82:83]
	v_mfma_f32_16x16x32_bf16 v[32:35], v[152:155], v[144:147], v[28:31]
	v_lshl_add_u64 v[78:79], s[92:93], 0, v[70:71]
	v_lshl_add_u64 v[80:81], s[92:93], 0, v[82:83]
	v_ashrrev_i32_e32 v73, 31, v72
	v_mfma_f32_16x16x32_bf16 v[28:31], v[152:155], v[148:151], v[24:27]
	s_waitcnt vmcnt(0)
	v_mul_f32_e32 v106, v132, v56
	v_mfma_f32_16x16x32_bf16 v[24:27], v[152:155], v[160:163], v[20:23]
	v_mul_f32_e32 v90, v133, v57
	v_mul_f32_e32 v89, v134, v58
	v_mul_f32_e32 v88, v135, v59
	v_mfma_f32_16x16x32_bf16 v[20:23], v[152:155], v[164:167], v[16:19]
	v_mfma_f32_16x16x32_bf16 v[16:19], v[156:159], v[144:147], v[12:15]
	v_mfma_f32_16x16x32_bf16 v[12:15], v[156:159], v[148:151], v[8:11]
	v_mfma_f32_16x16x32_bf16 v[8:11], v[156:159], v[160:163], v[4:7]
	v_mfma_f32_16x16x32_bf16 v[4:7], v[156:159], v[164:167], v[108:111]
	s_and_saveexec_b64 s[0:1], s[46:47]
	s_xor_b64 s[66:67], exec, s[0:1]
	s_cbranch_execz .LBB0_1092
; DEVINL void p1_tile(const Params& p, char* smem, int mt, int nt) {
;     ...
;       if (nt < 4) {
;         store_pairs(qk, 512, rb, col, v[0], v[1], v[2], v[3]);
;         if (nt >= 2) *(uint2*)(kT + (size_t)(col - 256) * LDT + rb) = make_uint2(pack2(v[0], v[1]), pack2(v[2], v[3]));
;       } else if (nt < 8) {
;         *(uint2*)(vT + (size_t)(col - 512) * LDT + rb) = make_uint2(pack2(v[0], v[1]), pack2(v[2], v[3]));
;       } else if (nt < 12) {
;         store_pairs(gb, 512, rb, col - 1024, v[0], v[1], v[2], v[3]);
;       } else if (nt < 16) {
;         store_pairs(ub, 512, rb, col - 1536, v[0], v[1], v[2], v[3]);
;       } else if (col < 2064) {
; #pragma unroll
;         for (int j = 0; j < 4; ++j) gk[(size_t)(rb + j) * 16 + (col - 2048)] = v[j];
;       }
	s_and_saveexec_b64 s[0:1], s[44:45]
	s_xor_b64 s[90:91], exec, s[0:1]
	s_cbranch_execz .LBB0_1089
	s_and_saveexec_b64 s[0:1], s[42:43]
	s_xor_b64 s[86:87], exec, s[0:1]
	s_cbranch_execz .LBB0_1086
	s_and_saveexec_b64 s[0:1], s[40:41]
	s_xor_b64 s[88:89], exec, s[0:1]
	s_cbranch_execz .LBB0_1083
	s_movk_i32 s0, 0x810
	v_cmp_gt_i32_e32 vcc, s0, v68
	s_and_saveexec_b64 s[0:1], vcc
	s_cbranch_execz .LBB0_1082
	v_mov_b32_e32 v69, v2
	v_lshl_add_u64 v[84:85], v[68:69], 2, s[50:51]
	v_lshlrev_b64 v[86:87], 6, v[72:73]
	v_lshl_add_u64 v[86:87], v[84:85], 0, v[86:87]
	v_add_co_u32_e32 v86, vcc, 0x1921000, v86
	s_nop 1
	v_addc_co_u32_e32 v87, vcc, 0, v87, vcc
	global_store_dword v[86:87], v106, off offset:2560
	v_or_b32_e32 v86, 1, v72
	v_ashrrev_i32_e32 v87, 31, v86
	v_lshlrev_b64 v[86:87], 6, v[86:87]
	v_lshl_add_u64 v[86:87], v[84:85], 0, v[86:87]
	v_add_co_u32_e32 v86, vcc, 0x1921000, v86
	s_nop 1
	v_addc_co_u32_e32 v87, vcc, 0, v87, vcc
	global_store_dword v[86:87], v90, off offset:2560
	v_or_b32_e32 v86, 2, v72
	v_ashrrev_i32_e32 v87, 31, v86
	v_lshlrev_b64 v[86:87], 6, v[86:87]
	v_lshl_add_u64 v[86:87], v[84:85], 0, v[86:87]
	v_add_co_u32_e32 v86, vcc, 0x1921000, v86
	s_nop 1
	v_addc_co_u32_e32 v87, vcc, 0, v87, vcc
	global_store_dword v[86:87], v89, off offset:2560
	v_or_b32_e32 v86, 3, v72
	v_ashrrev_i32_e32 v87, 31, v86
	v_lshlrev_b64 v[86:87], 6, v[86:87]
	v_lshl_add_u64 v[84:85], v[84:85], 0, v[86:87]
	v_add_co_u32_e32 v84, vcc, 0x1921000, v84
	s_nop 1
	v_addc_co_u32_e32 v85, vcc, 0, v85, vcc
	global_store_dword v[84:85], v88, off offset:2560

; __global__ void __launch_bounds__(256, 2) mega_kernel(Params p) {
;   __shared__ __attribute__((aligned(16))) char smem[65536];
	.amdhsa_kernel _Z11mega_kernel6Params
		.amdhsa_group_segment_fixed_size 81920
		.amdhsa_private_segment_fixed_size 0
		.amdhsa_kernarg_size 496
		.amdhsa_user_sgpr_count 2
		.amdhsa_user_sgpr_dispatch_ptr 0
		.amdhsa_user_sgpr_queue_ptr 0
		.amdhsa_user_sgpr_kernarg_segment_ptr 1
		.amdhsa_user_sgpr_dispatch_id 0
		.amdhsa_user_sgpr_kernarg_preload_length 0
		.amdhsa_user_sgpr_kernarg_preload_offset 0
		.amdhsa_user_sgpr_private_segment_size 0
		.amdhsa_uses_dynamic_stack 0
		.amdhsa_enable_private_segment 0
		.amdhsa_system_sgpr_workgroup_id_x 1
		.amdhsa_system_sgpr_workgroup_id_y 0
		.amdhsa_system_sgpr_workgroup_id_z 0
		.amdhsa_system_sgpr_workgroup_info 0
		.amdhsa_system_vgpr_workitem_id 0
		.amdhsa_next_free_vgpr 256
		.amdhsa_next_free_sgpr 102
		.amdhsa_accum_offset 256
		.amdhsa_reserve_vcc 1
		.amdhsa_float_round_mode_32 0
		.amdhsa_float_round_mode_16_64 0
		.amdhsa_float_denorm_mode_32 3
		.amdhsa_float_denorm_mode_16_64 3
		.amdhsa_dx10_clamp 1
		.amdhsa_ieee_mode 1
		.amdhsa_fp16_overflow 0
		.amdhsa_tg_split 0
		.amdhsa_exception_fp_ieee_invalid_op 0
		.amdhsa_exception_fp_denorm_src 0
		.amdhsa_exception_fp_ieee_div_zero 0
		.amdhsa_exception_fp_ieee_overflow 0
		.amdhsa_exception_fp_ieee_underflow 0
		.amdhsa_exception_fp_ieee_inexact 0
		.amdhsa_exception_int_div_zero 0
	.end_amdhsa_kernel

; __global__ void __launch_bounds__(256, 2) mega_kernel(Params p) {
;   __shared__ __attribute__((aligned(16))) char smem[65536];
amdhsa.kernels:
  - .agpr_count:     0
    .args:
      - .offset:         0
        .size:           240
        .value_kind:     by_value
      - .offset:         240
        .size:           4
        .value_kind:     hidden_block_count_x
      - .offset:         244
        .size:           4
        .value_kind:     hidden_block_count_y
      - .offset:         248
        .size:           4
        .value_kind:     hidden_block_count_z
      - .offset:         252
        .size:           2
        .value_kind:     hidden_group_size_x
      - .offset:         254
        .size:           2
        .value_kind:     hidden_group_size_y
      - .offset:         256
        .size:           2
        .value_kind:     hidden_group_size_z
      - .offset:         258
        .size:           2
        .value_kind:     hidden_remainder_x
      - .offset:         260
        .size:           2
        .value_kind:     hidden_remainder_y
      - .offset:         262
        .size:           2
        .value_kind:     hidden_remainder_z
      - .offset:         280
        .size:           8
        .value_kind:     hidden_global_offset_x
      - .offset:         288
        .size:           8
        .value_kind:     hidden_global_offset_y
      - .offset:         296
        .size:           8
        .value_kind:     hidden_global_offset_z
      - .offset:         304
        .size:           2
        .value_kind:     hidden_grid_dims
    .group_segment_fixed_size: 81920
    .kernarg_segment_align: 8
    .kernarg_segment_size: 496
    .language:       OpenCL C
    .language_version:
      - 2
      - 0
    .max_flat_workgroup_size: 256
    .name:           _Z11mega_kernel6Params
    .private_segment_fixed_size: 0
    .sgpr_count:     108
    .sgpr_spill_count: 187
    .symbol:         _Z11mega_kernel6Params.kd
    .uniform_work_group_size: 1
    .uses_dynamic_stack: false
    .vgpr_count:     256
    .vgpr_spill_count: 0
    .wavefront_size: 64
